# speedup vs baseline: 1.0534x; 1.0023x over previous
; __device__ __forceinline__ void pool_window(const bf16_t* __restrict__ U  , bf16_t* __restrict__ A3, const int gtid, const int nthr) {
;     ...
;     for (int it = gtid; it < (T / 32) * 256; it += nthr) {
;         const int cg8 = it & 255, tb = it >> 8, c = cg8 * 8, g = c >> 9, w = 2 << g, t0 = tb * 32, s0 = t0 & (SEQ - 1);
;         float sum[8];
; #pragma unroll
;         for (int e = 0; e < 8; ++e) sum[e] = 0.f;
;         if (s0 > 0) {
;             for (int k = 1; k < w; ++k) { const u32x4 uu = *(const u32x4*)(U + (size_t)(t0 - k) * LDU + c);
;                 sum[0] += bflo(uu.x); sum[1] += bfhi(uu.x); sum[2] += bflo(uu.y); sum[3] += bfhi(uu.y); sum[4] += bflo(uu.z); sum[5] += bfhi(uu.z); sum[6] += bflo(uu.w); sum[7] += bfhi(uu.w); }
;         }
.LBB0_1332:
	v_lshlrev_b32_e32 v8, 3, v22
	v_ashrrev_i32_e32 v3, 3, v22
	v_lshlrev_b32_e32 v0, 1, v23
	v_bfe_u32 v2, v8, 9, 2
	v_and_b32_e32 v4, 0xffffffe0, v3
	v_and_b32_e32 v25, 0x1fe0, v3
	v_and_b32_e32 v0, 0xff0, v0
	v_lshlrev_b32_e64 v24, v2, 2
	v_cmp_ne_u32_e32 vcc, 0, v25
	v_ashrrev_i32_e32 v5, 31, v4
	s_xor_b64 s[24:25], vcc, exec
	s_cmp_eq_u64 s[24:25], 0
	s_cbranch_scc1 .Lpw_fast
	s_and_saveexec_b64 s[0:1], vcc
	s_xor_b64 s[14:15], exec, s[0:1]
	s_cbranch_execz .LBB0_1336
	v_lshlrev_b64 v[6:7], 13, v[4:5]
	v_or_b32_e32 v2, v6, v0
	v_mov_b32_e32 v3, v7
	v_mov_b32_e32 v12, 0
	v_add_u32_e32 v9, -1, v24
	v_lshl_add_u64 v[2:3], s[4:5], 0, v[2:3]
	v_mov_b64_e32 v[42:43], v[2:3]
	global_load_dword v44, v[42:43], off
	v_lshl_add_u64 v[42:43], v[42:43], 0, s[8:9]
	global_load_dword v44, v[42:43], off
	v_lshl_add_u64 v[42:43], v[42:43], 0, s[8:9]
	global_load_dword v44, v[42:43], off
	v_lshl_add_u64 v[42:43], v[42:43], 0, s[8:9]
	global_load_dword v44, v[42:43], off
	v_lshl_add_u64 v[42:43], v[42:43], 0, s[8:9]
	global_load_dword v44, v[42:43], off
	v_lshl_add_u64 v[42:43], v[42:43], 0, s[8:9]
	global_load_dword v44, v[42:43], off
	v_lshl_add_u64 v[42:43], v[42:43], 0, s[8:9]
	global_load_dword v44, v[42:43], off
	v_lshl_add_u64 v[42:43], v[42:43], 0, s[8:9]
	global_load_dword v44, v[42:43], off
	v_lshl_add_u64 v[42:43], v[42:43], 0, s[8:9]
	global_load_dword v44, v[42:43], off
	v_lshl_add_u64 v[42:43], v[42:43], 0, s[8:9]
	global_load_dword v44, v[42:43], off
	v_lshl_add_u64 v[42:43], v[42:43], 0, s[8:9]
	global_load_dword v44, v[42:43], off
	v_lshl_add_u64 v[42:43], v[42:43], 0, s[8:9]
	global_load_dword v44, v[42:43], off
	v_lshl_add_u64 v[42:43], v[42:43], 0, s[8:9]
	global_load_dword v44, v[42:43], off
	v_lshl_add_u64 v[42:43], v[42:43], 0, s[8:9]
	global_load_dword v44, v[42:43], off
	v_lshl_add_u64 v[42:43], v[42:43], 0, s[8:9]
	global_load_dword v44, v[42:43], off
	v_lshl_add_u64 v[42:43], v[2:3], 0, s[22:23]
	global_load_dword v44, v[42:43], off
	v_lshl_add_u64 v[42:43], v[42:43], 0, s[22:23]
	global_load_dword v44, v[42:43], off
	v_lshl_add_u64 v[42:43], v[42:43], 0, s[22:23]
	global_load_dword v44, v[42:43], off
	v_lshl_add_u64 v[42:43], v[42:43], 0, s[22:23]
	global_load_dword v44, v[42:43], off
	v_lshl_add_u64 v[42:43], v[42:43], 0, s[22:23]
	global_load_dword v44, v[42:43], off
	v_lshl_add_u64 v[42:43], v[42:43], 0, s[22:23]
	global_load_dword v44, v[42:43], off
	v_lshl_add_u64 v[42:43], v[42:43], 0, s[22:23]
	global_load_dword v44, v[42:43], off
	v_lshl_add_u64 v[42:43], v[42:43], 0, s[22:23]
	global_load_dword v44, v[42:43], off
	s_mov_b64 s[16:17], 0
	v_mov_b32_e32 v13, v12
	v_mov_b32_e32 v14, v12
	v_mov_b32_e32 v15, v12
	v_mov_b32_e32 v16, v12
	v_mov_b32_e32 v17, v12
	v_mov_b32_e32 v18, v12
	v_mov_b32_e32 v19, v12

; __device__ __forceinline__ void pool_window(const bf16_t* __restrict__ U  , bf16_t* __restrict__ A3, const int gtid, const int nthr) {
;     ...
;     for (int it = gtid; it < (T / 32) * 256; it += nthr) {
;         const int cg8 = it & 255, tb = it >> 8, c = cg8 * 8, g = c >> 9, w = 2 << g, t0 = tb * 32, s0 = t0 & (SEQ - 1);
;         float sum[8];
; #pragma unroll
;         for (int e = 0; e < 8; ++e) sum[e] = 0.f;
;         if (s0 > 0) {
;             for (int k = 1; k < w; ++k) { const u32x4 uu = *(const u32x4*)(U + (size_t)(t0 - k) * LDU + c);
;                 sum[0] += bflo(uu.x); sum[1] += bfhi(uu.x); sum[2] += bflo(uu.y); sum[3] += bfhi(uu.y); sum[4] += bflo(uu.z); sum[5] += bfhi(uu.z); sum[6] += bflo(uu.w); sum[7] += bfhi(uu.w); }
;         }
.Lpw_fast:
	v_readfirstlane_b32 s24, v2
	v_lshlrev_b64 v[6:7], 13, v[4:5]
	v_lshl_add_u64 v[6:7], s[72:73], 0, v[6:7]
	v_lshl_add_u64 v[6:7], v[6:7], 0, v[0:1]
	s_mov_b32 s26, 0x197e2000
	s_mov_b32 s27, 0
	v_lshl_add_u64 v[8:9], v[6:7], 0, s[26:27]
	global_load_dwordx4 v[64:67], v[8:9], off
	v_lshl_add_u64 v[8:9], v[8:9], 0, s[22:23]
	global_load_dwordx4 v[68:71], v[8:9], off
	v_lshl_add_u64 v[8:9], v[8:9], 0, s[22:23]
	global_load_dwordx4 v[72:75], v[8:9], off
	v_lshl_add_u64 v[8:9], v[8:9], 0, s[22:23]
	global_load_dwordx4 v[76:79], v[8:9], off
	v_lshl_add_u64 v[8:9], v[8:9], 0, s[22:23]
	global_load_dwordx4 v[80:83], v[8:9], off
	v_lshl_add_u64 v[8:9], v[8:9], 0, s[22:23]
	global_load_dwordx4 v[84:87], v[8:9], off
	v_lshl_add_u64 v[8:9], v[8:9], 0, s[22:23]
	global_load_dwordx4 v[88:91], v[8:9], off
	v_lshl_add_u64 v[8:9], v[8:9], 0, s[22:23]
	global_load_dwordx4 v[92:95], v[8:9], off
	v_lshl_add_u64 v[8:9], v[8:9], 0, s[22:23]
	global_load_dwordx4 v[96:99], v[8:9], off
	v_lshl_add_u64 v[8:9], v[8:9], 0, s[22:23]
	global_load_dwordx4 v[100:103], v[8:9], off
	v_lshl_add_u64 v[8:9], v[8:9], 0, s[22:23]
	global_load_dwordx4 v[104:107], v[8:9], off
	v_lshl_add_u64 v[8:9], v[8:9], 0, s[22:23]
	global_load_dwordx4 v[108:111], v[8:9], off
	v_lshl_add_u64 v[8:9], v[8:9], 0, s[22:23]
	global_load_dwordx4 v[112:115], v[8:9], off
	v_lshl_add_u64 v[8:9], v[8:9], 0, s[22:23]
	global_load_dwordx4 v[116:119], v[8:9], off
	v_lshl_add_u64 v[8:9], v[8:9], 0, s[22:23]
	global_load_dwordx4 v[120:123], v[8:9], off
	v_lshl_add_u64 v[8:9], v[8:9], 0, s[22:23]
	global_load_dwordx4 v[124:127], v[8:9], off
	v_lshl_add_u64 v[8:9], v[8:9], 0, s[22:23]
	global_load_dwordx4 v[128:131], v[8:9], off
	v_lshl_add_u64 v[8:9], v[8:9], 0, s[22:23]
	global_load_dwordx4 v[132:135], v[8:9], off
	v_lshl_add_u64 v[8:9], v[8:9], 0, s[22:23]
	global_load_dwordx4 v[136:139], v[8:9], off
	v_lshl_add_u64 v[8:9], v[8:9], 0, s[22:23]
	global_load_dwordx4 v[140:143], v[8:9], off
	v_lshl_add_u64 v[8:9], v[8:9], 0, s[22:23]
	global_load_dwordx4 v[144:147], v[8:9], off
	v_lshl_add_u64 v[8:9], v[8:9], 0, s[22:23]
	global_load_dwordx4 v[148:151], v[8:9], off
	v_lshl_add_u64 v[8:9], v[8:9], 0, s[22:23]
	global_load_dwordx4 v[152:155], v[8:9], off
	v_lshl_add_u64 v[8:9], v[8:9], 0, s[22:23]
	global_load_dwordx4 v[156:159], v[8:9], off
	v_lshl_add_u64 v[8:9], v[8:9], 0, s[22:23]
	global_load_dwordx4 v[160:163], v[8:9], off
	v_lshl_add_u64 v[8:9], v[8:9], 0, s[22:23]
	global_load_dwordx4 v[164:167], v[8:9], off
	v_lshl_add_u64 v[8:9], v[8:9], 0, s[22:23]
	global_load_dwordx4 v[168:171], v[8:9], off
	v_lshl_add_u64 v[8:9], v[8:9], 0, s[22:23]
	global_load_dwordx4 v[172:175], v[8:9], off
	v_lshl_add_u64 v[8:9], v[8:9], 0, s[22:23]
	global_load_dwordx4 v[176:179], v[8:9], off
	v_lshl_add_u64 v[8:9], v[8:9], 0, s[22:23]
	global_load_dwordx4 v[180:183], v[8:9], off
	v_lshl_add_u64 v[8:9], v[8:9], 0, s[22:23]
	global_load_dwordx4 v[184:187], v[8:9], off
	v_lshl_add_u64 v[8:9], v[8:9], 0, s[22:23]
	global_load_dwordx4 v[188:191], v[8:9], off
	v_lshl_add_u64 v[8:9], v[8:9], 0, s[22:23]
	global_load_dwordx4 v[192:195], v[8:9], off
	v_lshl_add_u64 v[8:9], v[8:9], 0, s[22:23]
	global_load_dwordx4 v[196:199], v[8:9], off
	v_lshl_add_u64 v[8:9], v[8:9], 0, s[22:23]
	global_load_dwordx4 v[200:203], v[8:9], off
	v_lshl_add_u64 v[8:9], v[8:9], 0, s[22:23]
	global_load_dwordx4 v[204:207], v[8:9], off
	v_lshl_add_u64 v[8:9], v[8:9], 0, s[22:23]
	global_load_dwordx4 v[208:211], v[8:9], off
	v_lshl_add_u64 v[8:9], v[8:9], 0, s[22:23]
	global_load_dwordx4 v[214:217], v[8:9], off
	v_lshl_add_u64 v[8:9], v[8:9], 0, s[22:23]
	global_load_dwordx4 v[218:221], v[8:9], off
	v_lshl_add_u64 v[8:9], v[8:9], 0, s[22:23]
	global_load_dwordx4 v[222:225], v[8:9], off
	v_lshl_add_u64 v[8:9], v[8:9], 0, s[22:23]
	global_load_dwordx4 v[226:229], v[8:9], off
	v_lshl_add_u64 v[8:9], v[8:9], 0, s[22:23]
	global_load_dwordx4 v[230:233], v[8:9], off
	v_lshl_add_u64 v[8:9], v[8:9], 0, s[22:23]
	global_load_dwordx4 v[234:237], v[8:9], off
	v_lshl_add_u64 v[8:9], v[8:9], 0, s[22:23]
	global_load_dwordx4 v[238:241], v[8:9], off
	v_lshl_add_u64 v[8:9], v[8:9], 0, s[22:23]
	global_load_dwordx4 v[242:245], v[8:9], off
	v_lshl_add_u64 v[8:9], v[8:9], 0, s[22:23]
	global_load_dwordx4 v[246:249], v[8:9], off
	v_lshl_add_u64 v[8:9], v[8:9], 0, s[22:23]
	global_load_dwordx4 v[250:253], v[8:9], off
	v_lshlrev_b64 v[10:11], 12, v[4:5]
	v_lshl_add_u64 v[10:11], s[72:73], 0, v[10:11]
	v_lshl_add_u64 v[10:11], v[10:11], 0, v[0:1]
	s_mov_b32 s26, 0x9800000
	v_lshl_add_u64 v[10:11], v[10:11], 0, s[26:27]
	s_mov_b32 s26, 0x1000
	v_mov_b32_e32 v12, 0
	v_mov_b32_e32 v13, 0
	v_mov_b32_e32 v14, 0
	v_mov_b32_e32 v15, 0
	v_mov_b32_e32 v16, 0
	v_mov_b32_e32 v17, 0
	v_mov_b32_e32 v18, 0
	v_mov_b32_e32 v19, 0
	s_cmp_eq_u32 s24, 0
	s_cbranch_scc1 .Lpw_w2
	s_cmp_eq_u32 s24, 1
	s_cbranch_scc1 .Lpw_w4
	s_cmp_eq_u32 s24, 2
	s_cbranch_scc1 .Lpw_w8
; __device__ __forceinline__ void pool_window(const bf16_t* __restrict__ U  , bf16_t* __restrict__ A3, const int gtid, const int nthr) {
;     ...
;         if (s0 > 0) {
;             for (int k = 1; k < w; ++k) { const u32x4 uu = *(const u32x4*)(U + (size_t)(t0 - k) * LDU + c);
;                 sum[0] += bflo(uu.x); sum[1] += bfhi(uu.x); sum[2] += bflo(uu.y); sum[3] += bfhi(uu.y); sum[4] += bflo(uu.z); sum[5] += bfhi(uu.z); sum[6] += bflo(uu.w); sum[7] += bfhi(uu.w); }
;         }
	v_mov_b32_e32 v34, 0x3d800000
	s_waitcnt vmcnt(0)
	v_lshlrev_b32_e32 v44, 16, v120
	v_and_b32_e32 v45, 0xffff0000, v120
	v_lshlrev_b32_e32 v46, 16, v121
	v_and_b32_e32 v47, 0xffff0000, v121
	v_lshlrev_b32_e32 v48, 16, v122
	v_and_b32_e32 v49, 0xffff0000, v122
	v_lshlrev_b32_e32 v50, 16, v123
	v_and_b32_e32 v51, 0xffff0000, v123
	v_pk_add_f32 v[14:15], v[14:15], v[44:45]
	v_pk_add_f32 v[16:17], v[16:17], v[46:47]
	v_pk_add_f32 v[18:19], v[18:19], v[48:49]
	v_pk_add_f32 v[12:13], v[12:13], v[50:51]
	v_lshlrev_b32_e32 v44, 16, v116
	v_and_b32_e32 v45, 0xffff0000, v116
	v_lshlrev_b32_e32 v46, 16, v117
	v_and_b32_e32 v47, 0xffff0000, v117
	v_lshlrev_b32_e32 v48, 16, v118
	v_and_b32_e32 v49, 0xffff0000, v118
	v_lshlrev_b32_e32 v50, 16, v119
	v_and_b32_e32 v51, 0xffff0000, v119
	v_pk_add_f32 v[14:15], v[14:15], v[44:45]
	v_pk_add_f32 v[16:17], v[16:17], v[46:47]
	v_pk_add_f32 v[18:19], v[18:19], v[48:49]
	v_pk_add_f32 v[12:13], v[12:13], v[50:51]
	v_lshlrev_b32_e32 v44, 16, v112
	v_and_b32_e32 v45, 0xffff0000, v112
	v_lshlrev_b32_e32 v46, 16, v113
	v_and_b32_e32 v47, 0xffff0000, v113
	v_lshlrev_b32_e32 v48, 16, v114
	v_and_b32_e32 v49, 0xffff0000, v114
	v_lshlrev_b32_e32 v50, 16, v115
	v_and_b32_e32 v51, 0xffff0000, v115
	v_pk_add_f32 v[14:15], v[14:15], v[44:45]
	v_pk_add_f32 v[16:17], v[16:17], v[46:47]
	v_pk_add_f32 v[18:19], v[18:19], v[48:49]
	v_pk_add_f32 v[12:13], v[12:13], v[50:51]
	v_lshlrev_b32_e32 v44, 16, v108
	v_and_b32_e32 v45, 0xffff0000, v108
	v_lshlrev_b32_e32 v46, 16, v109
	v_and_b32_e32 v47, 0xffff0000, v109
	v_lshlrev_b32_e32 v48, 16, v110
	v_and_b32_e32 v49, 0xffff0000, v110
	v_lshlrev_b32_e32 v50, 16, v111
	v_and_b32_e32 v51, 0xffff0000, v111
	v_pk_add_f32 v[14:15], v[14:15], v[44:45]
	v_pk_add_f32 v[16:17], v[16:17], v[46:47]
	v_pk_add_f32 v[18:19], v[18:19], v[48:49]
	v_pk_add_f32 v[12:13], v[12:13], v[50:51]
	v_lshlrev_b32_e32 v44, 16, v104
	v_and_b32_e32 v45, 0xffff0000, v104
	v_lshlrev_b32_e32 v46, 16, v105
	v_and_b32_e32 v47, 0xffff0000, v105
	v_lshlrev_b32_e32 v48, 16, v106
	v_and_b32_e32 v49, 0xffff0000, v106
	v_lshlrev_b32_e32 v50, 16, v107
	v_and_b32_e32 v51, 0xffff0000, v107
	v_pk_add_f32 v[14:15], v[14:15], v[44:45]
	v_pk_add_f32 v[16:17], v[16:17], v[46:47]
	v_pk_add_f32 v[18:19], v[18:19], v[48:49]
	v_pk_add_f32 v[12:13], v[12:13], v[50:51]
	v_lshlrev_b32_e32 v44, 16, v100
	v_and_b32_e32 v45, 0xffff0000, v100
	v_lshlrev_b32_e32 v46, 16, v101
	v_and_b32_e32 v47, 0xffff0000, v101
	v_lshlrev_b32_e32 v48, 16, v102
	v_and_b32_e32 v49, 0xffff0000, v102
	v_lshlrev_b32_e32 v50, 16, v103
	v_and_b32_e32 v51, 0xffff0000, v103
	v_pk_add_f32 v[14:15], v[14:15], v[44:45]
	v_pk_add_f32 v[16:17], v[16:17], v[46:47]
	v_pk_add_f32 v[18:19], v[18:19], v[48:49]
	v_pk_add_f32 v[12:13], v[12:13], v[50:51]
	v_lshlrev_b32_e32 v44, 16, v96
	v_and_b32_e32 v45, 0xffff0000, v96
	v_lshlrev_b32_e32 v46, 16, v97
	v_and_b32_e32 v47, 0xffff0000, v97
	v_lshlrev_b32_e32 v48, 16, v98
	v_and_b32_e32 v49, 0xffff0000, v98
	v_lshlrev_b32_e32 v50, 16, v99
	v_and_b32_e32 v51, 0xffff0000, v99
	v_pk_add_f32 v[14:15], v[14:15], v[44:45]
	v_pk_add_f32 v[16:17], v[16:17], v[46:47]
	v_pk_add_f32 v[18:19], v[18:19], v[48:49]
	v_pk_add_f32 v[12:13], v[12:13], v[50:51]
	v_lshlrev_b32_e32 v44, 16, v92
	v_and_b32_e32 v45, 0xffff0000, v92
	v_lshlrev_b32_e32 v46, 16, v93
	v_and_b32_e32 v47, 0xffff0000, v93
	v_lshlrev_b32_e32 v48, 16, v94
	v_and_b32_e32 v49, 0xffff0000, v94
	v_lshlrev_b32_e32 v50, 16, v95
	v_and_b32_e32 v51, 0xffff0000, v95
	v_pk_add_f32 v[14:15], v[14:15], v[44:45]
	v_pk_add_f32 v[16:17], v[16:17], v[46:47]
	v_pk_add_f32 v[18:19], v[18:19], v[48:49]
	v_pk_add_f32 v[12:13], v[12:13], v[50:51]
	v_lshlrev_b32_e32 v44, 16, v88
	v_and_b32_e32 v45, 0xffff0000, v88
	v_lshlrev_b32_e32 v46, 16, v89
	v_and_b32_e32 v47, 0xffff0000, v89
	v_lshlrev_b32_e32 v48, 16, v90
	v_and_b32_e32 v49, 0xffff0000, v90
	v_lshlrev_b32_e32 v50, 16, v91
	v_and_b32_e32 v51, 0xffff0000, v91
	v_pk_add_f32 v[14:15], v[14:15], v[44:45]
	v_pk_add_f32 v[16:17], v[16:17], v[46:47]
	v_pk_add_f32 v[18:19], v[18:19], v[48:49]
	v_pk_add_f32 v[12:13], v[12:13], v[50:51]
	v_lshlrev_b32_e32 v44, 16, v84
	v_and_b32_e32 v45, 0xffff0000, v84
	v_lshlrev_b32_e32 v46, 16, v85
	v_and_b32_e32 v47, 0xffff0000, v85
	v_lshlrev_b32_e32 v48, 16, v86
	v_and_b32_e32 v49, 0xffff0000, v86
	v_lshlrev_b32_e32 v50, 16, v87
	v_and_b32_e32 v51, 0xffff0000, v87
	v_pk_add_f32 v[14:15], v[14:15], v[44:45]
	v_pk_add_f32 v[16:17], v[16:17], v[46:47]
	v_pk_add_f32 v[18:19], v[18:19], v[48:49]
	v_pk_add_f32 v[12:13], v[12:13], v[50:51]
	v_lshlrev_b32_e32 v44, 16, v80
	v_and_b32_e32 v45, 0xffff0000, v80
	v_lshlrev_b32_e32 v46, 16, v81
	v_and_b32_e32 v47, 0xffff0000, v81
	v_lshlrev_b32_e32 v48, 16, v82
	v_and_b32_e32 v49, 0xffff0000, v82
	v_lshlrev_b32_e32 v50, 16, v83
	v_and_b32_e32 v51, 0xffff0000, v83
	v_pk_add_f32 v[14:15], v[14:15], v[44:45]
	v_pk_add_f32 v[16:17], v[16:17], v[46:47]
	v_pk_add_f32 v[18:19], v[18:19], v[48:49]
	v_pk_add_f32 v[12:13], v[12:13], v[50:51]
	v_lshlrev_b32_e32 v44, 16, v76
	v_and_b32_e32 v45, 0xffff0000, v76
	v_lshlrev_b32_e32 v46, 16, v77
	v_and_b32_e32 v47, 0xffff0000, v77
	v_lshlrev_b32_e32 v48, 16, v78
	v_and_b32_e32 v49, 0xffff0000, v78
	v_lshlrev_b32_e32 v50, 16, v79
	v_and_b32_e32 v51, 0xffff0000, v79
	v_pk_add_f32 v[14:15], v[14:15], v[44:45]
	v_pk_add_f32 v[16:17], v[16:17], v[46:47]
	v_pk_add_f32 v[18:19], v[18:19], v[48:49]
	v_pk_add_f32 v[12:13], v[12:13], v[50:51]
	v_lshlrev_b32_e32 v44, 16, v72
	v_and_b32_e32 v45, 0xffff0000, v72
	v_lshlrev_b32_e32 v46, 16, v73
	v_and_b32_e32 v47, 0xffff0000, v73
	v_lshlrev_b32_e32 v48, 16, v74
	v_and_b32_e32 v49, 0xffff0000, v74
; __device__ __forceinline__ unsigned pk2(float lo, float hi) { f32x2 v = {lo, hi}; bf16x2_t b = __builtin_convertvector(v, bf16x2_t); return __builtin_bit_cast(unsigned, b); }
; __device__ __forceinline__ void pool_window(const bf16_t* __restrict__ U  , bf16_t* __restrict__ A3, const int gtid, const int nthr) {
;     ...
;             for (int k = 1; k < w; ++k) { const u32x4 uu = *(const u32x4*)(U + (size_t)(t0 - k) * LDU + c);
;                 sum[0] += bflo(uu.x); sum[1] += bfhi(uu.x); sum[2] += bflo(uu.y); sum[3] += bfhi(uu.y); sum[4] += bflo(uu.z); sum[5] += bfhi(uu.z); sum[6] += bflo(uu.w); sum[7] += bfhi(uu.w); }
;         }
; #pragma unroll 8
;         for (int i = 0; i < 32; ++i) {
;             const int t = t0 + i, s = s0 + i;
;             const u32x4 uu = *(const u32x4*)(U + (size_t)t * LDU + c);
;             float cu[8] = {bflo(uu.x), bfhi(uu.x), bflo(uu.y), bfhi(uu.y), bflo(uu.z), bfhi(uu.z), bflo(uu.w), bfhi(uu.w)};
;             const float rc = 1.0f / (float)((s + 1) < w ? (s + 1) : w);
;             float o[8];
; #pragma unroll
;             for (int e = 0; e < 8; ++e) { sum[e] += cu[e]; o[e] = sum[e] * rc - cu[e]; }
;             u32x4 ww; ww.x = pk2(o[0], o[1]); ww.y = pk2(o[2], o[3]); ww.z = pk2(o[4], o[5]); ww.w = pk2(o[6], o[7]);
;             *(u32x4*)(A3 + (size_t)t * DM + c) = ww;
;             if (s + 1 >= w) { const u32x4 ud = *(const u32x4*)(U + (size_t)(t - w + 1) * LDU + c);
;                 sum[0] -= bflo(ud.x); sum[1] -= bfhi(ud.x); sum[2] -= bflo(ud.y); sum[3] -= bfhi(ud.y); sum[4] -= bflo(ud.z); sum[5] -= bfhi(ud.z); sum[6] -= bflo(ud.w); sum[7] -= bfhi(ud.w); }
	v_lshlrev_b32_e32 v50, 16, v75
	v_and_b32_e32 v51, 0xffff0000, v75
	v_pk_add_f32 v[14:15], v[14:15], v[44:45]
	v_pk_add_f32 v[16:17], v[16:17], v[46:47]
	v_pk_add_f32 v[18:19], v[18:19], v[48:49]
	v_pk_add_f32 v[12:13], v[12:13], v[50:51]
	v_lshlrev_b32_e32 v44, 16, v68
	v_and_b32_e32 v45, 0xffff0000, v68
	v_lshlrev_b32_e32 v46, 16, v69
	v_and_b32_e32 v47, 0xffff0000, v69
	v_lshlrev_b32_e32 v48, 16, v70
	v_and_b32_e32 v49, 0xffff0000, v70
	v_lshlrev_b32_e32 v50, 16, v71
	v_and_b32_e32 v51, 0xffff0000, v71
	v_pk_add_f32 v[14:15], v[14:15], v[44:45]
	v_pk_add_f32 v[16:17], v[16:17], v[46:47]
	v_pk_add_f32 v[18:19], v[18:19], v[48:49]
	v_pk_add_f32 v[12:13], v[12:13], v[50:51]
	v_lshlrev_b32_e32 v44, 16, v64
	v_and_b32_e32 v45, 0xffff0000, v64
	v_lshlrev_b32_e32 v46, 16, v65
	v_and_b32_e32 v47, 0xffff0000, v65
	v_lshlrev_b32_e32 v48, 16, v66
	v_and_b32_e32 v49, 0xffff0000, v66
	v_lshlrev_b32_e32 v50, 16, v67
	v_and_b32_e32 v51, 0xffff0000, v67
	v_pk_add_f32 v[14:15], v[14:15], v[44:45]
	v_pk_add_f32 v[16:17], v[16:17], v[46:47]
	v_pk_add_f32 v[18:19], v[18:19], v[48:49]
	v_pk_add_f32 v[12:13], v[12:13], v[50:51]
	v_lshlrev_b32_e32 v44, 16, v124
	v_and_b32_e32 v45, 0xffff0000, v124
	v_lshlrev_b32_e32 v46, 16, v125
	v_and_b32_e32 v47, 0xffff0000, v125
	v_lshlrev_b32_e32 v48, 16, v126
	v_and_b32_e32 v49, 0xffff0000, v126
	v_lshlrev_b32_e32 v50, 16, v127
	v_and_b32_e32 v51, 0xffff0000, v127
	v_pk_add_f32 v[14:15], v[14:15], v[44:45]
	v_pk_add_f32 v[16:17], v[16:17], v[46:47]
	v_pk_add_f32 v[18:19], v[18:19], v[48:49]
	v_pk_add_f32 v[12:13], v[12:13], v[50:51]
	v_pk_fma_f32 v[36:37], v[34:35], v[14:15], v[44:45] op_sel_hi:[0,1,1] neg_lo:[0,0,1] neg_hi:[0,0,1]
	v_pk_fma_f32 v[38:39], v[34:35], v[16:17], v[46:47] op_sel_hi:[0,1,1] neg_lo:[0,0,1] neg_hi:[0,0,1]
	v_pk_fma_f32 v[40:41], v[34:35], v[18:19], v[48:49] op_sel_hi:[0,1,1] neg_lo:[0,0,1] neg_hi:[0,0,1]
	v_pk_fma_f32 v[42:43], v[34:35], v[12:13], v[50:51] op_sel_hi:[0,1,1] neg_lo:[0,0,1] neg_hi:[0,0,1]
	v_cvt_pk_bf16_f32 v28, v36, v37
	v_cvt_pk_bf16_f32 v29, v38, v39
	v_cvt_pk_bf16_f32 v30, v40, v41
	v_cvt_pk_bf16_f32 v31, v42, v43
	global_store_dwordx4 v[10:11], v[28:31], off
	v_lshlrev_b32_e32 v44, 16, v64
	v_and_b32_e32 v45, 0xffff0000, v64
	v_lshlrev_b32_e32 v46, 16, v65
	v_and_b32_e32 v47, 0xffff0000, v65
	v_lshlrev_b32_e32 v48, 16, v66
	v_and_b32_e32 v49, 0xffff0000, v66
	v_lshlrev_b32_e32 v50, 16, v67
	v_and_b32_e32 v51, 0xffff0000, v67
	v_pk_add_f32 v[14:15], v[14:15], v[44:45] neg_lo:[0,1] neg_hi:[0,1]
	v_pk_add_f32 v[16:17], v[16:17], v[46:47] neg_lo:[0,1] neg_hi:[0,1]
	v_pk_add_f32 v[18:19], v[18:19], v[48:49] neg_lo:[0,1] neg_hi:[0,1]
	v_pk_add_f32 v[12:13], v[12:13], v[50:51] neg_lo:[0,1] neg_hi:[0,1]
	v_lshl_add_u64 v[10:11], v[10:11], 0, s[26:27]
	v_lshlrev_b32_e32 v44, 16, v128
	v_and_b32_e32 v45, 0xffff0000, v128
	v_lshlrev_b32_e32 v46, 16, v129
	v_and_b32_e32 v47, 0xffff0000, v129
	v_lshlrev_b32_e32 v48, 16, v130
	v_and_b32_e32 v49, 0xffff0000, v130
	v_lshlrev_b32_e32 v50, 16, v131
	v_and_b32_e32 v51, 0xffff0000, v131
	v_pk_add_f32 v[14:15], v[14:15], v[44:45]
	v_pk_add_f32 v[16:17], v[16:17], v[46:47]
	v_pk_add_f32 v[18:19], v[18:19], v[48:49]
	v_pk_add_f32 v[12:13], v[12:13], v[50:51]
	v_pk_fma_f32 v[36:37], v[34:35], v[14:15], v[44:45] op_sel_hi:[0,1,1] neg_lo:[0,0,1] neg_hi:[0,0,1]
	v_pk_fma_f32 v[38:39], v[34:35], v[16:17], v[46:47] op_sel_hi:[0,1,1] neg_lo:[0,0,1] neg_hi:[0,0,1]
	v_pk_fma_f32 v[40:41], v[34:35], v[18:19], v[48:49] op_sel_hi:[0,1,1] neg_lo:[0,0,1] neg_hi:[0,0,1]
	v_pk_fma_f32 v[42:43], v[34:35], v[12:13], v[50:51] op_sel_hi:[0,1,1] neg_lo:[0,0,1] neg_hi:[0,0,1]
	v_cvt_pk_bf16_f32 v28, v36, v37
	v_cvt_pk_bf16_f32 v29, v38, v39
	v_cvt_pk_bf16_f32 v30, v40, v41
	v_cvt_pk_bf16_f32 v31, v42, v43
	global_store_dwordx4 v[10:11], v[28:31], off
	v_lshlrev_b32_e32 v44, 16, v68
	v_and_b32_e32 v45, 0xffff0000, v68
	v_lshlrev_b32_e32 v46, 16, v69
	v_and_b32_e32 v47, 0xffff0000, v69
	v_lshlrev_b32_e32 v48, 16, v70
	v_and_b32_e32 v49, 0xffff0000, v70
	v_lshlrev_b32_e32 v50, 16, v71
	v_and_b32_e32 v51, 0xffff0000, v71
	v_pk_add_f32 v[14:15], v[14:15], v[44:45] neg_lo:[0,1] neg_hi:[0,1]
	v_pk_add_f32 v[16:17], v[16:17], v[46:47] neg_lo:[0,1] neg_hi:[0,1]
	v_pk_add_f32 v[18:19], v[18:19], v[48:49] neg_lo:[0,1] neg_hi:[0,1]
	v_pk_add_f32 v[12:13], v[12:13], v[50:51] neg_lo:[0,1] neg_hi:[0,1]
	v_lshl_add_u64 v[10:11], v[10:11], 0, s[26:27]
	v_lshlrev_b32_e32 v44, 16, v132
	v_and_b32_e32 v45, 0xffff0000, v132
	v_lshlrev_b32_e32 v46, 16, v133
	v_and_b32_e32 v47, 0xffff0000, v133
	v_lshlrev_b32_e32 v48, 16, v134
	v_and_b32_e32 v49, 0xffff0000, v134
	v_lshlrev_b32_e32 v50, 16, v135
	v_and_b32_e32 v51, 0xffff0000, v135
	v_pk_add_f32 v[14:15], v[14:15], v[44:45]
	v_pk_add_f32 v[16:17], v[16:17], v[46:47]
	v_pk_add_f32 v[18:19], v[18:19], v[48:49]
	v_pk_add_f32 v[12:13], v[12:13], v[50:51]
	v_pk_fma_f32 v[36:37], v[34:35], v[14:15], v[44:45] op_sel_hi:[0,1,1] neg_lo:[0,0,1] neg_hi:[0,0,1]
	v_pk_fma_f32 v[38:39], v[34:35], v[16:17], v[46:47] op_sel_hi:[0,1,1] neg_lo:[0,0,1] neg_hi:[0,0,1]
	v_pk_fma_f32 v[40:41], v[34:35], v[18:19], v[48:49] op_sel_hi:[0,1,1] neg_lo:[0,0,1] neg_hi:[0,0,1]
	v_pk_fma_f32 v[42:43], v[34:35], v[12:13], v[50:51] op_sel_hi:[0,1,1] neg_lo:[0,0,1] neg_hi:[0,0,1]
	v_cvt_pk_bf16_f32 v28, v36, v37
	v_cvt_pk_bf16_f32 v29, v38, v39
	v_cvt_pk_bf16_f32 v30, v40, v41
	v_cvt_pk_bf16_f32 v31, v42, v43
	global_store_dwordx4 v[10:11], v[28:31], off
	v_lshlrev_b32_e32 v44, 16, v72
	v_and_b32_e32 v45, 0xffff0000, v72
	v_lshlrev_b32_e32 v46, 16, v73
	v_and_b32_e32 v47, 0xffff0000, v73
	v_lshlrev_b32_e32 v48, 16, v74
	v_and_b32_e32 v49, 0xffff0000, v74
; __device__ __forceinline__ unsigned pk2(float lo, float hi) { f32x2 v = {lo, hi}; bf16x2_t b = __builtin_convertvector(v, bf16x2_t); return __builtin_bit_cast(unsigned, b); }
; __device__ __forceinline__ void pool_window(const bf16_t* __restrict__ U  , bf16_t* __restrict__ A3, const int gtid, const int nthr) {
;     ...
;         for (int i = 0; i < 32; ++i) {
;             const int t = t0 + i, s = s0 + i;
;             const u32x4 uu = *(const u32x4*)(U + (size_t)t * LDU + c);
;             float cu[8] = {bflo(uu.x), bfhi(uu.x), bflo(uu.y), bfhi(uu.y), bflo(uu.z), bfhi(uu.z), bflo(uu.w), bfhi(uu.w)};
;             const float rc = 1.0f / (float)((s + 1) < w ? (s + 1) : w);
;             float o[8];
; #pragma unroll
;             for (int e = 0; e < 8; ++e) { sum[e] += cu[e]; o[e] = sum[e] * rc - cu[e]; }
;             u32x4 ww; ww.x = pk2(o[0], o[1]); ww.y = pk2(o[2], o[3]); ww.z = pk2(o[4], o[5]); ww.w = pk2(o[6], o[7]);
;             *(u32x4*)(A3 + (size_t)t * DM + c) = ww;
;             if (s + 1 >= w) { const u32x4 ud = *(const u32x4*)(U + (size_t)(t - w + 1) * LDU + c);
;                 sum[0] -= bflo(ud.x); sum[1] -= bfhi(ud.x); sum[2] -= bflo(ud.y); sum[3] -= bfhi(ud.y); sum[4] -= bflo(ud.z); sum[5] -= bfhi(ud.z); sum[6] -= bflo(ud.w); sum[7] -= bfhi(ud.w); }
	v_lshlrev_b32_e32 v50, 16, v75
	v_and_b32_e32 v51, 0xffff0000, v75
	v_pk_add_f32 v[14:15], v[14:15], v[44:45] neg_lo:[0,1] neg_hi:[0,1]
	v_pk_add_f32 v[16:17], v[16:17], v[46:47] neg_lo:[0,1] neg_hi:[0,1]
	v_pk_add_f32 v[18:19], v[18:19], v[48:49] neg_lo:[0,1] neg_hi:[0,1]
	v_pk_add_f32 v[12:13], v[12:13], v[50:51] neg_lo:[0,1] neg_hi:[0,1]
	v_lshl_add_u64 v[10:11], v[10:11], 0, s[26:27]
	v_lshlrev_b32_e32 v44, 16, v136
	v_and_b32_e32 v45, 0xffff0000, v136
	v_lshlrev_b32_e32 v46, 16, v137
	v_and_b32_e32 v47, 0xffff0000, v137
	v_lshlrev_b32_e32 v48, 16, v138
	v_and_b32_e32 v49, 0xffff0000, v138
	v_lshlrev_b32_e32 v50, 16, v139
	v_and_b32_e32 v51, 0xffff0000, v139
	v_pk_add_f32 v[14:15], v[14:15], v[44:45]
	v_pk_add_f32 v[16:17], v[16:17], v[46:47]
	v_pk_add_f32 v[18:19], v[18:19], v[48:49]
	v_pk_add_f32 v[12:13], v[12:13], v[50:51]
	v_pk_fma_f32 v[36:37], v[34:35], v[14:15], v[44:45] op_sel_hi:[0,1,1] neg_lo:[0,0,1] neg_hi:[0,0,1]
	v_pk_fma_f32 v[38:39], v[34:35], v[16:17], v[46:47] op_sel_hi:[0,1,1] neg_lo:[0,0,1] neg_hi:[0,0,1]
	v_pk_fma_f32 v[40:41], v[34:35], v[18:19], v[48:49] op_sel_hi:[0,1,1] neg_lo:[0,0,1] neg_hi:[0,0,1]
	v_pk_fma_f32 v[42:43], v[34:35], v[12:13], v[50:51] op_sel_hi:[0,1,1] neg_lo:[0,0,1] neg_hi:[0,0,1]
	v_cvt_pk_bf16_f32 v28, v36, v37
	v_cvt_pk_bf16_f32 v29, v38, v39
	v_cvt_pk_bf16_f32 v30, v40, v41
	v_cvt_pk_bf16_f32 v31, v42, v43
	global_store_dwordx4 v[10:11], v[28:31], off
	v_lshlrev_b32_e32 v44, 16, v76
	v_and_b32_e32 v45, 0xffff0000, v76
	v_lshlrev_b32_e32 v46, 16, v77
	v_and_b32_e32 v47, 0xffff0000, v77
	v_lshlrev_b32_e32 v48, 16, v78
	v_and_b32_e32 v49, 0xffff0000, v78
	v_lshlrev_b32_e32 v50, 16, v79
	v_and_b32_e32 v51, 0xffff0000, v79
	v_pk_add_f32 v[14:15], v[14:15], v[44:45] neg_lo:[0,1] neg_hi:[0,1]
	v_pk_add_f32 v[16:17], v[16:17], v[46:47] neg_lo:[0,1] neg_hi:[0,1]
	v_pk_add_f32 v[18:19], v[18:19], v[48:49] neg_lo:[0,1] neg_hi:[0,1]
	v_pk_add_f32 v[12:13], v[12:13], v[50:51] neg_lo:[0,1] neg_hi:[0,1]
	v_lshl_add_u64 v[10:11], v[10:11], 0, s[26:27]
	v_lshlrev_b32_e32 v44, 16, v140
	v_and_b32_e32 v45, 0xffff0000, v140
	v_lshlrev_b32_e32 v46, 16, v141
	v_and_b32_e32 v47, 0xffff0000, v141
	v_lshlrev_b32_e32 v48, 16, v142
	v_and_b32_e32 v49, 0xffff0000, v142
	v_lshlrev_b32_e32 v50, 16, v143
	v_and_b32_e32 v51, 0xffff0000, v143
	v_pk_add_f32 v[14:15], v[14:15], v[44:45]
	v_pk_add_f32 v[16:17], v[16:17], v[46:47]
	v_pk_add_f32 v[18:19], v[18:19], v[48:49]
	v_pk_add_f32 v[12:13], v[12:13], v[50:51]
	v_pk_fma_f32 v[36:37], v[34:35], v[14:15], v[44:45] op_sel_hi:[0,1,1] neg_lo:[0,0,1] neg_hi:[0,0,1]
	v_pk_fma_f32 v[38:39], v[34:35], v[16:17], v[46:47] op_sel_hi:[0,1,1] neg_lo:[0,0,1] neg_hi:[0,0,1]
	v_pk_fma_f32 v[40:41], v[34:35], v[18:19], v[48:49] op_sel_hi:[0,1,1] neg_lo:[0,0,1] neg_hi:[0,0,1]
	v_pk_fma_f32 v[42:43], v[34:35], v[12:13], v[50:51] op_sel_hi:[0,1,1] neg_lo:[0,0,1] neg_hi:[0,0,1]
	v_cvt_pk_bf16_f32 v28, v36, v37
	v_cvt_pk_bf16_f32 v29, v38, v39
	v_cvt_pk_bf16_f32 v30, v40, v41
	v_cvt_pk_bf16_f32 v31, v42, v43
	global_store_dwordx4 v[10:11], v[28:31], off
	v_lshlrev_b32_e32 v44, 16, v80
	v_and_b32_e32 v45, 0xffff0000, v80
	v_lshlrev_b32_e32 v46, 16, v81
	v_and_b32_e32 v47, 0xffff0000, v81
	v_lshlrev_b32_e32 v48, 16, v82
	v_and_b32_e32 v49, 0xffff0000, v82
	v_lshlrev_b32_e32 v50, 16, v83
	v_and_b32_e32 v51, 0xffff0000, v83
	v_pk_add_f32 v[14:15], v[14:15], v[44:45] neg_lo:[0,1] neg_hi:[0,1]
	v_pk_add_f32 v[16:17], v[16:17], v[46:47] neg_lo:[0,1] neg_hi:[0,1]
	v_pk_add_f32 v[18:19], v[18:19], v[48:49] neg_lo:[0,1] neg_hi:[0,1]
	v_pk_add_f32 v[12:13], v[12:13], v[50:51] neg_lo:[0,1] neg_hi:[0,1]
	v_lshl_add_u64 v[10:11], v[10:11], 0, s[26:27]
	v_lshlrev_b32_e32 v44, 16, v144
	v_and_b32_e32 v45, 0xffff0000, v144
	v_lshlrev_b32_e32 v46, 16, v145
	v_and_b32_e32 v47, 0xffff0000, v145
	v_lshlrev_b32_e32 v48, 16, v146
	v_and_b32_e32 v49, 0xffff0000, v146
	v_lshlrev_b32_e32 v50, 16, v147
	v_and_b32_e32 v51, 0xffff0000, v147
	v_pk_add_f32 v[14:15], v[14:15], v[44:45]
	v_pk_add_f32 v[16:17], v[16:17], v[46:47]
	v_pk_add_f32 v[18:19], v[18:19], v[48:49]
	v_pk_add_f32 v[12:13], v[12:13], v[50:51]
	v_pk_fma_f32 v[36:37], v[34:35], v[14:15], v[44:45] op_sel_hi:[0,1,1] neg_lo:[0,0,1] neg_hi:[0,0,1]
	v_pk_fma_f32 v[38:39], v[34:35], v[16:17], v[46:47] op_sel_hi:[0,1,1] neg_lo:[0,0,1] neg_hi:[0,0,1]
	v_pk_fma_f32 v[40:41], v[34:35], v[18:19], v[48:49] op_sel_hi:[0,1,1] neg_lo:[0,0,1] neg_hi:[0,0,1]
	v_pk_fma_f32 v[42:43], v[34:35], v[12:13], v[50:51] op_sel_hi:[0,1,1] neg_lo:[0,0,1] neg_hi:[0,0,1]
	v_cvt_pk_bf16_f32 v28, v36, v37
	v_cvt_pk_bf16_f32 v29, v38, v39
	v_cvt_pk_bf16_f32 v30, v40, v41
	v_cvt_pk_bf16_f32 v31, v42, v43
	global_store_dwordx4 v[10:11], v[28:31], off
	v_lshlrev_b32_e32 v44, 16, v84
	v_and_b32_e32 v45, 0xffff0000, v84
	v_lshlrev_b32_e32 v46, 16, v85
	v_and_b32_e32 v47, 0xffff0000, v85
	v_lshlrev_b32_e32 v48, 16, v86
	v_and_b32_e32 v49, 0xffff0000, v86
	v_lshlrev_b32_e32 v50, 16, v87
	v_and_b32_e32 v51, 0xffff0000, v87
	v_pk_add_f32 v[14:15], v[14:15], v[44:45] neg_lo:[0,1] neg_hi:[0,1]
	v_pk_add_f32 v[16:17], v[16:17], v[46:47] neg_lo:[0,1] neg_hi:[0,1]
	v_pk_add_f32 v[18:19], v[18:19], v[48:49] neg_lo:[0,1] neg_hi:[0,1]
	v_pk_add_f32 v[12:13], v[12:13], v[50:51] neg_lo:[0,1] neg_hi:[0,1]
	v_lshl_add_u64 v[10:11], v[10:11], 0, s[26:27]
	v_lshlrev_b32_e32 v44, 16, v148
	v_and_b32_e32 v45, 0xffff0000, v148
	v_lshlrev_b32_e32 v46, 16, v149
	v_and_b32_e32 v47, 0xffff0000, v149
	v_lshlrev_b32_e32 v48, 16, v150
	v_and_b32_e32 v49, 0xffff0000, v150
	v_lshlrev_b32_e32 v50, 16, v151
	v_and_b32_e32 v51, 0xffff0000, v151
	v_pk_add_f32 v[14:15], v[14:15], v[44:45]
	v_pk_add_f32 v[16:17], v[16:17], v[46:47]
; __device__ __forceinline__ unsigned pk2(float lo, float hi) { f32x2 v = {lo, hi}; bf16x2_t b = __builtin_convertvector(v, bf16x2_t); return __builtin_bit_cast(unsigned, b); }
; __device__ __forceinline__ void pool_window(const bf16_t* __restrict__ U  , bf16_t* __restrict__ A3, const int gtid, const int nthr) {
;     ...
;         for (int i = 0; i < 32; ++i) {
;             const int t = t0 + i, s = s0 + i;
;             const u32x4 uu = *(const u32x4*)(U + (size_t)t * LDU + c);
;             float cu[8] = {bflo(uu.x), bfhi(uu.x), bflo(uu.y), bfhi(uu.y), bflo(uu.z), bfhi(uu.z), bflo(uu.w), bfhi(uu.w)};
;             const float rc = 1.0f / (float)((s + 1) < w ? (s + 1) : w);
;             float o[8];
; #pragma unroll
;             for (int e = 0; e < 8; ++e) { sum[e] += cu[e]; o[e] = sum[e] * rc - cu[e]; }
;             u32x4 ww; ww.x = pk2(o[0], o[1]); ww.y = pk2(o[2], o[3]); ww.z = pk2(o[4], o[5]); ww.w = pk2(o[6], o[7]);
;             *(u32x4*)(A3 + (size_t)t * DM + c) = ww;
;             if (s + 1 >= w) { const u32x4 ud = *(const u32x4*)(U + (size_t)(t - w + 1) * LDU + c);
;                 sum[0] -= bflo(ud.x); sum[1] -= bfhi(ud.x); sum[2] -= bflo(ud.y); sum[3] -= bfhi(ud.y); sum[4] -= bflo(ud.z); sum[5] -= bfhi(ud.z); sum[6] -= bflo(ud.w); sum[7] -= bfhi(ud.w); }
	v_pk_add_f32 v[18:19], v[18:19], v[48:49]
	v_pk_add_f32 v[12:13], v[12:13], v[50:51]
	v_pk_fma_f32 v[36:37], v[34:35], v[14:15], v[44:45] op_sel_hi:[0,1,1] neg_lo:[0,0,1] neg_hi:[0,0,1]
	v_pk_fma_f32 v[38:39], v[34:35], v[16:17], v[46:47] op_sel_hi:[0,1,1] neg_lo:[0,0,1] neg_hi:[0,0,1]
	v_pk_fma_f32 v[40:41], v[34:35], v[18:19], v[48:49] op_sel_hi:[0,1,1] neg_lo:[0,0,1] neg_hi:[0,0,1]
	v_pk_fma_f32 v[42:43], v[34:35], v[12:13], v[50:51] op_sel_hi:[0,1,1] neg_lo:[0,0,1] neg_hi:[0,0,1]
	v_cvt_pk_bf16_f32 v28, v36, v37
	v_cvt_pk_bf16_f32 v29, v38, v39
	v_cvt_pk_bf16_f32 v30, v40, v41
	v_cvt_pk_bf16_f32 v31, v42, v43
	global_store_dwordx4 v[10:11], v[28:31], off
	v_lshlrev_b32_e32 v44, 16, v88
	v_and_b32_e32 v45, 0xffff0000, v88
	v_lshlrev_b32_e32 v46, 16, v89
	v_and_b32_e32 v47, 0xffff0000, v89
	v_lshlrev_b32_e32 v48, 16, v90
	v_and_b32_e32 v49, 0xffff0000, v90
	v_lshlrev_b32_e32 v50, 16, v91
	v_and_b32_e32 v51, 0xffff0000, v91
	v_pk_add_f32 v[14:15], v[14:15], v[44:45] neg_lo:[0,1] neg_hi:[0,1]
	v_pk_add_f32 v[16:17], v[16:17], v[46:47] neg_lo:[0,1] neg_hi:[0,1]
	v_pk_add_f32 v[18:19], v[18:19], v[48:49] neg_lo:[0,1] neg_hi:[0,1]
	v_pk_add_f32 v[12:13], v[12:13], v[50:51] neg_lo:[0,1] neg_hi:[0,1]
	v_lshl_add_u64 v[10:11], v[10:11], 0, s[26:27]
	v_lshlrev_b32_e32 v44, 16, v152
	v_and_b32_e32 v45, 0xffff0000, v152
	v_lshlrev_b32_e32 v46, 16, v153
	v_and_b32_e32 v47, 0xffff0000, v153
	v_lshlrev_b32_e32 v48, 16, v154
	v_and_b32_e32 v49, 0xffff0000, v154
	v_lshlrev_b32_e32 v50, 16, v155
	v_and_b32_e32 v51, 0xffff0000, v155
	v_pk_add_f32 v[14:15], v[14:15], v[44:45]
	v_pk_add_f32 v[16:17], v[16:17], v[46:47]
	v_pk_add_f32 v[18:19], v[18:19], v[48:49]
	v_pk_add_f32 v[12:13], v[12:13], v[50:51]
	v_pk_fma_f32 v[36:37], v[34:35], v[14:15], v[44:45] op_sel_hi:[0,1,1] neg_lo:[0,0,1] neg_hi:[0,0,1]
	v_pk_fma_f32 v[38:39], v[34:35], v[16:17], v[46:47] op_sel_hi:[0,1,1] neg_lo:[0,0,1] neg_hi:[0,0,1]
	v_pk_fma_f32 v[40:41], v[34:35], v[18:19], v[48:49] op_sel_hi:[0,1,1] neg_lo:[0,0,1] neg_hi:[0,0,1]
	v_pk_fma_f32 v[42:43], v[34:35], v[12:13], v[50:51] op_sel_hi:[0,1,1] neg_lo:[0,0,1] neg_hi:[0,0,1]
	v_cvt_pk_bf16_f32 v28, v36, v37
	v_cvt_pk_bf16_f32 v29, v38, v39
	v_cvt_pk_bf16_f32 v30, v40, v41
	v_cvt_pk_bf16_f32 v31, v42, v43
	global_store_dwordx4 v[10:11], v[28:31], off
	v_lshlrev_b32_e32 v44, 16, v92
	v_and_b32_e32 v45, 0xffff0000, v92
	v_lshlrev_b32_e32 v46, 16, v93
	v_and_b32_e32 v47, 0xffff0000, v93
	v_lshlrev_b32_e32 v48, 16, v94
	v_and_b32_e32 v49, 0xffff0000, v94
	v_lshlrev_b32_e32 v50, 16, v95
	v_and_b32_e32 v51, 0xffff0000, v95
	v_pk_add_f32 v[14:15], v[14:15], v[44:45] neg_lo:[0,1] neg_hi:[0,1]
	v_pk_add_f32 v[16:17], v[16:17], v[46:47] neg_lo:[0,1] neg_hi:[0,1]
	v_pk_add_f32 v[18:19], v[18:19], v[48:49] neg_lo:[0,1] neg_hi:[0,1]
	v_pk_add_f32 v[12:13], v[12:13], v[50:51] neg_lo:[0,1] neg_hi:[0,1]
	v_lshl_add_u64 v[10:11], v[10:11], 0, s[26:27]
	v_lshlrev_b32_e32 v44, 16, v156
	v_and_b32_e32 v45, 0xffff0000, v156
	v_lshlrev_b32_e32 v46, 16, v157
	v_and_b32_e32 v47, 0xffff0000, v157
	v_lshlrev_b32_e32 v48, 16, v158
	v_and_b32_e32 v49, 0xffff0000, v158
	v_lshlrev_b32_e32 v50, 16, v159
	v_and_b32_e32 v51, 0xffff0000, v159
	v_pk_add_f32 v[14:15], v[14:15], v[44:45]
	v_pk_add_f32 v[16:17], v[16:17], v[46:47]
	v_pk_add_f32 v[18:19], v[18:19], v[48:49]
	v_pk_add_f32 v[12:13], v[12:13], v[50:51]
	v_pk_fma_f32 v[36:37], v[34:35], v[14:15], v[44:45] op_sel_hi:[0,1,1] neg_lo:[0,0,1] neg_hi:[0,0,1]
	v_pk_fma_f32 v[38:39], v[34:35], v[16:17], v[46:47] op_sel_hi:[0,1,1] neg_lo:[0,0,1] neg_hi:[0,0,1]
	v_pk_fma_f32 v[40:41], v[34:35], v[18:19], v[48:49] op_sel_hi:[0,1,1] neg_lo:[0,0,1] neg_hi:[0,0,1]
	v_pk_fma_f32 v[42:43], v[34:35], v[12:13], v[50:51] op_sel_hi:[0,1,1] neg_lo:[0,0,1] neg_hi:[0,0,1]
	v_cvt_pk_bf16_f32 v28, v36, v37
	v_cvt_pk_bf16_f32 v29, v38, v39
	v_cvt_pk_bf16_f32 v30, v40, v41
	v_cvt_pk_bf16_f32 v31, v42, v43
	global_store_dwordx4 v[10:11], v[28:31], off
	v_lshlrev_b32_e32 v44, 16, v96
	v_and_b32_e32 v45, 0xffff0000, v96
	v_lshlrev_b32_e32 v46, 16, v97
	v_and_b32_e32 v47, 0xffff0000, v97
	v_lshlrev_b32_e32 v48, 16, v98
	v_and_b32_e32 v49, 0xffff0000, v98
	v_lshlrev_b32_e32 v50, 16, v99
	v_and_b32_e32 v51, 0xffff0000, v99
	v_pk_add_f32 v[14:15], v[14:15], v[44:45] neg_lo:[0,1] neg_hi:[0,1]
	v_pk_add_f32 v[16:17], v[16:17], v[46:47] neg_lo:[0,1] neg_hi:[0,1]
	v_pk_add_f32 v[18:19], v[18:19], v[48:49] neg_lo:[0,1] neg_hi:[0,1]
	v_pk_add_f32 v[12:13], v[12:13], v[50:51] neg_lo:[0,1] neg_hi:[0,1]
	v_lshl_add_u64 v[10:11], v[10:11], 0, s[26:27]
	v_lshlrev_b32_e32 v44, 16, v160
	v_and_b32_e32 v45, 0xffff0000, v160
	v_lshlrev_b32_e32 v46, 16, v161
	v_and_b32_e32 v47, 0xffff0000, v161
	v_lshlrev_b32_e32 v48, 16, v162
	v_and_b32_e32 v49, 0xffff0000, v162
	v_lshlrev_b32_e32 v50, 16, v163
	v_and_b32_e32 v51, 0xffff0000, v163
	v_pk_add_f32 v[14:15], v[14:15], v[44:45]
	v_pk_add_f32 v[16:17], v[16:17], v[46:47]
	v_pk_add_f32 v[18:19], v[18:19], v[48:49]
	v_pk_add_f32 v[12:13], v[12:13], v[50:51]
	v_pk_fma_f32 v[36:37], v[34:35], v[14:15], v[44:45] op_sel_hi:[0,1,1] neg_lo:[0,0,1] neg_hi:[0,0,1]
	v_pk_fma_f32 v[38:39], v[34:35], v[16:17], v[46:47] op_sel_hi:[0,1,1] neg_lo:[0,0,1] neg_hi:[0,0,1]
	v_pk_fma_f32 v[40:41], v[34:35], v[18:19], v[48:49] op_sel_hi:[0,1,1] neg_lo:[0,0,1] neg_hi:[0,0,1]
	v_pk_fma_f32 v[42:43], v[34:35], v[12:13], v[50:51] op_sel_hi:[0,1,1] neg_lo:[0,0,1] neg_hi:[0,0,1]
	v_cvt_pk_bf16_f32 v28, v36, v37
	v_cvt_pk_bf16_f32 v29, v38, v39
	v_cvt_pk_bf16_f32 v30, v40, v41
	v_cvt_pk_bf16_f32 v31, v42, v43
	global_store_dwordx4 v[10:11], v[28:31], off
	v_lshlrev_b32_e32 v44, 16, v100
	v_and_b32_e32 v45, 0xffff0000, v100
; __device__ __forceinline__ unsigned pk2(float lo, float hi) { f32x2 v = {lo, hi}; bf16x2_t b = __builtin_convertvector(v, bf16x2_t); return __builtin_bit_cast(unsigned, b); }
; __device__ __forceinline__ void pool_window(const bf16_t* __restrict__ U  , bf16_t* __restrict__ A3, const int gtid, const int nthr) {
;     ...
;         for (int i = 0; i < 32; ++i) {
;             const int t = t0 + i, s = s0 + i;
;             const u32x4 uu = *(const u32x4*)(U + (size_t)t * LDU + c);
;             float cu[8] = {bflo(uu.x), bfhi(uu.x), bflo(uu.y), bfhi(uu.y), bflo(uu.z), bfhi(uu.z), bflo(uu.w), bfhi(uu.w)};
;             const float rc = 1.0f / (float)((s + 1) < w ? (s + 1) : w);
;             float o[8];
; #pragma unroll
;             for (int e = 0; e < 8; ++e) { sum[e] += cu[e]; o[e] = sum[e] * rc - cu[e]; }
;             u32x4 ww; ww.x = pk2(o[0], o[1]); ww.y = pk2(o[2], o[3]); ww.z = pk2(o[4], o[5]); ww.w = pk2(o[6], o[7]);
;             *(u32x4*)(A3 + (size_t)t * DM + c) = ww;
;             if (s + 1 >= w) { const u32x4 ud = *(const u32x4*)(U + (size_t)(t - w + 1) * LDU + c);
;                 sum[0] -= bflo(ud.x); sum[1] -= bfhi(ud.x); sum[2] -= bflo(ud.y); sum[3] -= bfhi(ud.y); sum[4] -= bflo(ud.z); sum[5] -= bfhi(ud.z); sum[6] -= bflo(ud.w); sum[7] -= bfhi(ud.w); }
	v_lshlrev_b32_e32 v46, 16, v101
	v_and_b32_e32 v47, 0xffff0000, v101
	v_lshlrev_b32_e32 v48, 16, v102
	v_and_b32_e32 v49, 0xffff0000, v102
	v_lshlrev_b32_e32 v50, 16, v103
	v_and_b32_e32 v51, 0xffff0000, v103
	v_pk_add_f32 v[14:15], v[14:15], v[44:45] neg_lo:[0,1] neg_hi:[0,1]
	v_pk_add_f32 v[16:17], v[16:17], v[46:47] neg_lo:[0,1] neg_hi:[0,1]
	v_pk_add_f32 v[18:19], v[18:19], v[48:49] neg_lo:[0,1] neg_hi:[0,1]
	v_pk_add_f32 v[12:13], v[12:13], v[50:51] neg_lo:[0,1] neg_hi:[0,1]
	v_lshl_add_u64 v[10:11], v[10:11], 0, s[26:27]
	v_lshlrev_b32_e32 v44, 16, v164
	v_and_b32_e32 v45, 0xffff0000, v164
	v_lshlrev_b32_e32 v46, 16, v165
	v_and_b32_e32 v47, 0xffff0000, v165
	v_lshlrev_b32_e32 v48, 16, v166
	v_and_b32_e32 v49, 0xffff0000, v166
	v_lshlrev_b32_e32 v50, 16, v167
	v_and_b32_e32 v51, 0xffff0000, v167
	v_pk_add_f32 v[14:15], v[14:15], v[44:45]
	v_pk_add_f32 v[16:17], v[16:17], v[46:47]
	v_pk_add_f32 v[18:19], v[18:19], v[48:49]
	v_pk_add_f32 v[12:13], v[12:13], v[50:51]
	v_pk_fma_f32 v[36:37], v[34:35], v[14:15], v[44:45] op_sel_hi:[0,1,1] neg_lo:[0,0,1] neg_hi:[0,0,1]
	v_pk_fma_f32 v[38:39], v[34:35], v[16:17], v[46:47] op_sel_hi:[0,1,1] neg_lo:[0,0,1] neg_hi:[0,0,1]
	v_pk_fma_f32 v[40:41], v[34:35], v[18:19], v[48:49] op_sel_hi:[0,1,1] neg_lo:[0,0,1] neg_hi:[0,0,1]
	v_pk_fma_f32 v[42:43], v[34:35], v[12:13], v[50:51] op_sel_hi:[0,1,1] neg_lo:[0,0,1] neg_hi:[0,0,1]
	v_cvt_pk_bf16_f32 v28, v36, v37
	v_cvt_pk_bf16_f32 v29, v38, v39
	v_cvt_pk_bf16_f32 v30, v40, v41
	v_cvt_pk_bf16_f32 v31, v42, v43
	global_store_dwordx4 v[10:11], v[28:31], off
	v_lshlrev_b32_e32 v44, 16, v104
	v_and_b32_e32 v45, 0xffff0000, v104
	v_lshlrev_b32_e32 v46, 16, v105
	v_and_b32_e32 v47, 0xffff0000, v105
	v_lshlrev_b32_e32 v48, 16, v106
	v_and_b32_e32 v49, 0xffff0000, v106
	v_lshlrev_b32_e32 v50, 16, v107
	v_and_b32_e32 v51, 0xffff0000, v107
	v_pk_add_f32 v[14:15], v[14:15], v[44:45] neg_lo:[0,1] neg_hi:[0,1]
	v_pk_add_f32 v[16:17], v[16:17], v[46:47] neg_lo:[0,1] neg_hi:[0,1]
	v_pk_add_f32 v[18:19], v[18:19], v[48:49] neg_lo:[0,1] neg_hi:[0,1]
	v_pk_add_f32 v[12:13], v[12:13], v[50:51] neg_lo:[0,1] neg_hi:[0,1]
	v_lshl_add_u64 v[10:11], v[10:11], 0, s[26:27]
	v_lshlrev_b32_e32 v44, 16, v168
	v_and_b32_e32 v45, 0xffff0000, v168
	v_lshlrev_b32_e32 v46, 16, v169
	v_and_b32_e32 v47, 0xffff0000, v169
	v_lshlrev_b32_e32 v48, 16, v170
	v_and_b32_e32 v49, 0xffff0000, v170
	v_lshlrev_b32_e32 v50, 16, v171
	v_and_b32_e32 v51, 0xffff0000, v171
	v_pk_add_f32 v[14:15], v[14:15], v[44:45]
	v_pk_add_f32 v[16:17], v[16:17], v[46:47]
	v_pk_add_f32 v[18:19], v[18:19], v[48:49]
	v_pk_add_f32 v[12:13], v[12:13], v[50:51]
	v_pk_fma_f32 v[36:37], v[34:35], v[14:15], v[44:45] op_sel_hi:[0,1,1] neg_lo:[0,0,1] neg_hi:[0,0,1]
	v_pk_fma_f32 v[38:39], v[34:35], v[16:17], v[46:47] op_sel_hi:[0,1,1] neg_lo:[0,0,1] neg_hi:[0,0,1]
	v_pk_fma_f32 v[40:41], v[34:35], v[18:19], v[48:49] op_sel_hi:[0,1,1] neg_lo:[0,0,1] neg_hi:[0,0,1]
	v_pk_fma_f32 v[42:43], v[34:35], v[12:13], v[50:51] op_sel_hi:[0,1,1] neg_lo:[0,0,1] neg_hi:[0,0,1]
	v_cvt_pk_bf16_f32 v28, v36, v37
	v_cvt_pk_bf16_f32 v29, v38, v39
	v_cvt_pk_bf16_f32 v30, v40, v41
	v_cvt_pk_bf16_f32 v31, v42, v43
	global_store_dwordx4 v[10:11], v[28:31], off
	v_lshlrev_b32_e32 v44, 16, v108
	v_and_b32_e32 v45, 0xffff0000, v108
	v_lshlrev_b32_e32 v46, 16, v109
	v_and_b32_e32 v47, 0xffff0000, v109
	v_lshlrev_b32_e32 v48, 16, v110
	v_and_b32_e32 v49, 0xffff0000, v110
	v_lshlrev_b32_e32 v50, 16, v111
	v_and_b32_e32 v51, 0xffff0000, v111
	v_pk_add_f32 v[14:15], v[14:15], v[44:45] neg_lo:[0,1] neg_hi:[0,1]
	v_pk_add_f32 v[16:17], v[16:17], v[46:47] neg_lo:[0,1] neg_hi:[0,1]
	v_pk_add_f32 v[18:19], v[18:19], v[48:49] neg_lo:[0,1] neg_hi:[0,1]
	v_pk_add_f32 v[12:13], v[12:13], v[50:51] neg_lo:[0,1] neg_hi:[0,1]
	v_lshl_add_u64 v[10:11], v[10:11], 0, s[26:27]
	v_lshlrev_b32_e32 v44, 16, v172
	v_and_b32_e32 v45, 0xffff0000, v172
	v_lshlrev_b32_e32 v46, 16, v173
	v_and_b32_e32 v47, 0xffff0000, v173
	v_lshlrev_b32_e32 v48, 16, v174
	v_and_b32_e32 v49, 0xffff0000, v174
	v_lshlrev_b32_e32 v50, 16, v175
	v_and_b32_e32 v51, 0xffff0000, v175
	v_pk_add_f32 v[14:15], v[14:15], v[44:45]
	v_pk_add_f32 v[16:17], v[16:17], v[46:47]
	v_pk_add_f32 v[18:19], v[18:19], v[48:49]
	v_pk_add_f32 v[12:13], v[12:13], v[50:51]
	v_pk_fma_f32 v[36:37], v[34:35], v[14:15], v[44:45] op_sel_hi:[0,1,1] neg_lo:[0,0,1] neg_hi:[0,0,1]
	v_pk_fma_f32 v[38:39], v[34:35], v[16:17], v[46:47] op_sel_hi:[0,1,1] neg_lo:[0,0,1] neg_hi:[0,0,1]
	v_pk_fma_f32 v[40:41], v[34:35], v[18:19], v[48:49] op_sel_hi:[0,1,1] neg_lo:[0,0,1] neg_hi:[0,0,1]
	v_pk_fma_f32 v[42:43], v[34:35], v[12:13], v[50:51] op_sel_hi:[0,1,1] neg_lo:[0,0,1] neg_hi:[0,0,1]
	v_cvt_pk_bf16_f32 v28, v36, v37
	v_cvt_pk_bf16_f32 v29, v38, v39
	v_cvt_pk_bf16_f32 v30, v40, v41
	v_cvt_pk_bf16_f32 v31, v42, v43
	global_store_dwordx4 v[10:11], v[28:31], off
	v_lshlrev_b32_e32 v44, 16, v112
	v_and_b32_e32 v45, 0xffff0000, v112
	v_lshlrev_b32_e32 v46, 16, v113
	v_and_b32_e32 v47, 0xffff0000, v113
	v_lshlrev_b32_e32 v48, 16, v114
	v_and_b32_e32 v49, 0xffff0000, v114
	v_lshlrev_b32_e32 v50, 16, v115
	v_and_b32_e32 v51, 0xffff0000, v115
	v_pk_add_f32 v[14:15], v[14:15], v[44:45] neg_lo:[0,1] neg_hi:[0,1]
	v_pk_add_f32 v[16:17], v[16:17], v[46:47] neg_lo:[0,1] neg_hi:[0,1]
	v_pk_add_f32 v[18:19], v[18:19], v[48:49] neg_lo:[0,1] neg_hi:[0,1]
	v_pk_add_f32 v[12:13], v[12:13], v[50:51] neg_lo:[0,1] neg_hi:[0,1]
	v_lshl_add_u64 v[10:11], v[10:11], 0, s[26:27]
	v_lshlrev_b32_e32 v44, 16, v176
	v_and_b32_e32 v45, 0xffff0000, v176
	v_lshlrev_b32_e32 v46, 16, v177
	v_and_b32_e32 v47, 0xffff0000, v177
	v_lshlrev_b32_e32 v48, 16, v178
	v_and_b32_e32 v49, 0xffff0000, v178
; __device__ __forceinline__ unsigned pk2(float lo, float hi) { f32x2 v = {lo, hi}; bf16x2_t b = __builtin_convertvector(v, bf16x2_t); return __builtin_bit_cast(unsigned, b); }
; __device__ __forceinline__ void pool_window(const bf16_t* __restrict__ U  , bf16_t* __restrict__ A3, const int gtid, const int nthr) {
;     ...
;         for (int i = 0; i < 32; ++i) {
;             const int t = t0 + i, s = s0 + i;
;             const u32x4 uu = *(const u32x4*)(U + (size_t)t * LDU + c);
;             float cu[8] = {bflo(uu.x), bfhi(uu.x), bflo(uu.y), bfhi(uu.y), bflo(uu.z), bfhi(uu.z), bflo(uu.w), bfhi(uu.w)};
;             const float rc = 1.0f / (float)((s + 1) < w ? (s + 1) : w);
;             float o[8];
; #pragma unroll
;             for (int e = 0; e < 8; ++e) { sum[e] += cu[e]; o[e] = sum[e] * rc - cu[e]; }
;             u32x4 ww; ww.x = pk2(o[0], o[1]); ww.y = pk2(o[2], o[3]); ww.z = pk2(o[4], o[5]); ww.w = pk2(o[6], o[7]);
;             *(u32x4*)(A3 + (size_t)t * DM + c) = ww;
;             if (s + 1 >= w) { const u32x4 ud = *(const u32x4*)(U + (size_t)(t - w + 1) * LDU + c);
;                 sum[0] -= bflo(ud.x); sum[1] -= bfhi(ud.x); sum[2] -= bflo(ud.y); sum[3] -= bfhi(ud.y); sum[4] -= bflo(ud.z); sum[5] -= bfhi(ud.z); sum[6] -= bflo(ud.w); sum[7] -= bfhi(ud.w); }
	v_lshlrev_b32_e32 v50, 16, v179
	v_and_b32_e32 v51, 0xffff0000, v179
	v_pk_add_f32 v[14:15], v[14:15], v[44:45]
	v_pk_add_f32 v[16:17], v[16:17], v[46:47]
	v_pk_add_f32 v[18:19], v[18:19], v[48:49]
	v_pk_add_f32 v[12:13], v[12:13], v[50:51]
	v_pk_fma_f32 v[36:37], v[34:35], v[14:15], v[44:45] op_sel_hi:[0,1,1] neg_lo:[0,0,1] neg_hi:[0,0,1]
	v_pk_fma_f32 v[38:39], v[34:35], v[16:17], v[46:47] op_sel_hi:[0,1,1] neg_lo:[0,0,1] neg_hi:[0,0,1]
	v_pk_fma_f32 v[40:41], v[34:35], v[18:19], v[48:49] op_sel_hi:[0,1,1] neg_lo:[0,0,1] neg_hi:[0,0,1]
	v_pk_fma_f32 v[42:43], v[34:35], v[12:13], v[50:51] op_sel_hi:[0,1,1] neg_lo:[0,0,1] neg_hi:[0,0,1]
	v_cvt_pk_bf16_f32 v28, v36, v37
	v_cvt_pk_bf16_f32 v29, v38, v39
	v_cvt_pk_bf16_f32 v30, v40, v41
	v_cvt_pk_bf16_f32 v31, v42, v43
	global_store_dwordx4 v[10:11], v[28:31], off
	v_lshlrev_b32_e32 v44, 16, v116
	v_and_b32_e32 v45, 0xffff0000, v116
	v_lshlrev_b32_e32 v46, 16, v117
	v_and_b32_e32 v47, 0xffff0000, v117
	v_lshlrev_b32_e32 v48, 16, v118
	v_and_b32_e32 v49, 0xffff0000, v118
	v_lshlrev_b32_e32 v50, 16, v119
	v_and_b32_e32 v51, 0xffff0000, v119
	v_pk_add_f32 v[14:15], v[14:15], v[44:45] neg_lo:[0,1] neg_hi:[0,1]
	v_pk_add_f32 v[16:17], v[16:17], v[46:47] neg_lo:[0,1] neg_hi:[0,1]
	v_pk_add_f32 v[18:19], v[18:19], v[48:49] neg_lo:[0,1] neg_hi:[0,1]
	v_pk_add_f32 v[12:13], v[12:13], v[50:51] neg_lo:[0,1] neg_hi:[0,1]
	v_lshl_add_u64 v[10:11], v[10:11], 0, s[26:27]
	v_lshlrev_b32_e32 v44, 16, v180
	v_and_b32_e32 v45, 0xffff0000, v180
	v_lshlrev_b32_e32 v46, 16, v181
	v_and_b32_e32 v47, 0xffff0000, v181
	v_lshlrev_b32_e32 v48, 16, v182
	v_and_b32_e32 v49, 0xffff0000, v182
	v_lshlrev_b32_e32 v50, 16, v183
	v_and_b32_e32 v51, 0xffff0000, v183
	v_pk_add_f32 v[14:15], v[14:15], v[44:45]
	v_pk_add_f32 v[16:17], v[16:17], v[46:47]
	v_pk_add_f32 v[18:19], v[18:19], v[48:49]
	v_pk_add_f32 v[12:13], v[12:13], v[50:51]
	v_pk_fma_f32 v[36:37], v[34:35], v[14:15], v[44:45] op_sel_hi:[0,1,1] neg_lo:[0,0,1] neg_hi:[0,0,1]
	v_pk_fma_f32 v[38:39], v[34:35], v[16:17], v[46:47] op_sel_hi:[0,1,1] neg_lo:[0,0,1] neg_hi:[0,0,1]
	v_pk_fma_f32 v[40:41], v[34:35], v[18:19], v[48:49] op_sel_hi:[0,1,1] neg_lo:[0,0,1] neg_hi:[0,0,1]
	v_pk_fma_f32 v[42:43], v[34:35], v[12:13], v[50:51] op_sel_hi:[0,1,1] neg_lo:[0,0,1] neg_hi:[0,0,1]
	v_cvt_pk_bf16_f32 v28, v36, v37
	v_cvt_pk_bf16_f32 v29, v38, v39
	v_cvt_pk_bf16_f32 v30, v40, v41
	v_cvt_pk_bf16_f32 v31, v42, v43
	global_store_dwordx4 v[10:11], v[28:31], off
	v_lshlrev_b32_e32 v44, 16, v120
	v_and_b32_e32 v45, 0xffff0000, v120
	v_lshlrev_b32_e32 v46, 16, v121
	v_and_b32_e32 v47, 0xffff0000, v121
	v_lshlrev_b32_e32 v48, 16, v122
	v_and_b32_e32 v49, 0xffff0000, v122
	v_lshlrev_b32_e32 v50, 16, v123
	v_and_b32_e32 v51, 0xffff0000, v123
	v_pk_add_f32 v[14:15], v[14:15], v[44:45] neg_lo:[0,1] neg_hi:[0,1]
	v_pk_add_f32 v[16:17], v[16:17], v[46:47] neg_lo:[0,1] neg_hi:[0,1]
	v_pk_add_f32 v[18:19], v[18:19], v[48:49] neg_lo:[0,1] neg_hi:[0,1]
	v_pk_add_f32 v[12:13], v[12:13], v[50:51] neg_lo:[0,1] neg_hi:[0,1]
	v_lshl_add_u64 v[10:11], v[10:11], 0, s[26:27]
	v_lshlrev_b32_e32 v44, 16, v184
	v_and_b32_e32 v45, 0xffff0000, v184
	v_lshlrev_b32_e32 v46, 16, v185
	v_and_b32_e32 v47, 0xffff0000, v185
	v_lshlrev_b32_e32 v48, 16, v186
	v_and_b32_e32 v49, 0xffff0000, v186
	v_lshlrev_b32_e32 v50, 16, v187
	v_and_b32_e32 v51, 0xffff0000, v187
	v_pk_add_f32 v[14:15], v[14:15], v[44:45]
	v_pk_add_f32 v[16:17], v[16:17], v[46:47]
	v_pk_add_f32 v[18:19], v[18:19], v[48:49]
	v_pk_add_f32 v[12:13], v[12:13], v[50:51]
	v_pk_fma_f32 v[36:37], v[34:35], v[14:15], v[44:45] op_sel_hi:[0,1,1] neg_lo:[0,0,1] neg_hi:[0,0,1]
	v_pk_fma_f32 v[38:39], v[34:35], v[16:17], v[46:47] op_sel_hi:[0,1,1] neg_lo:[0,0,1] neg_hi:[0,0,1]
	v_pk_fma_f32 v[40:41], v[34:35], v[18:19], v[48:49] op_sel_hi:[0,1,1] neg_lo:[0,0,1] neg_hi:[0,0,1]
	v_pk_fma_f32 v[42:43], v[34:35], v[12:13], v[50:51] op_sel_hi:[0,1,1] neg_lo:[0,0,1] neg_hi:[0,0,1]
	v_cvt_pk_bf16_f32 v28, v36, v37
	v_cvt_pk_bf16_f32 v29, v38, v39
	v_cvt_pk_bf16_f32 v30, v40, v41
	v_cvt_pk_bf16_f32 v31, v42, v43
	global_store_dwordx4 v[10:11], v[28:31], off
	v_lshlrev_b32_e32 v44, 16, v124
	v_and_b32_e32 v45, 0xffff0000, v124
	v_lshlrev_b32_e32 v46, 16, v125
	v_and_b32_e32 v47, 0xffff0000, v125
	v_lshlrev_b32_e32 v48, 16, v126
	v_and_b32_e32 v49, 0xffff0000, v126
	v_lshlrev_b32_e32 v50, 16, v127
	v_and_b32_e32 v51, 0xffff0000, v127
	v_pk_add_f32 v[14:15], v[14:15], v[44:45] neg_lo:[0,1] neg_hi:[0,1]
	v_pk_add_f32 v[16:17], v[16:17], v[46:47] neg_lo:[0,1] neg_hi:[0,1]
	v_pk_add_f32 v[18:19], v[18:19], v[48:49] neg_lo:[0,1] neg_hi:[0,1]
	v_pk_add_f32 v[12:13], v[12:13], v[50:51] neg_lo:[0,1] neg_hi:[0,1]
	v_lshl_add_u64 v[10:11], v[10:11], 0, s[26:27]
	v_lshlrev_b32_e32 v44, 16, v188
	v_and_b32_e32 v45, 0xffff0000, v188
	v_lshlrev_b32_e32 v46, 16, v189
	v_and_b32_e32 v47, 0xffff0000, v189
	v_lshlrev_b32_e32 v48, 16, v190
	v_and_b32_e32 v49, 0xffff0000, v190
	v_lshlrev_b32_e32 v50, 16, v191
	v_and_b32_e32 v51, 0xffff0000, v191
	v_pk_add_f32 v[14:15], v[14:15], v[44:45]
	v_pk_add_f32 v[16:17], v[16:17], v[46:47]
	v_pk_add_f32 v[18:19], v[18:19], v[48:49]
	v_pk_add_f32 v[12:13], v[12:13], v[50:51]
	v_pk_fma_f32 v[36:37], v[34:35], v[14:15], v[44:45] op_sel_hi:[0,1,1] neg_lo:[0,0,1] neg_hi:[0,0,1]
	v_pk_fma_f32 v[38:39], v[34:35], v[16:17], v[46:47] op_sel_hi:[0,1,1] neg_lo:[0,0,1] neg_hi:[0,0,1]
	v_pk_fma_f32 v[40:41], v[34:35], v[18:19], v[48:49] op_sel_hi:[0,1,1] neg_lo:[0,0,1] neg_hi:[0,0,1]
	v_pk_fma_f32 v[42:43], v[34:35], v[12:13], v[50:51] op_sel_hi:[0,1,1] neg_lo:[0,0,1] neg_hi:[0,0,1]
	v_cvt_pk_bf16_f32 v28, v36, v37
	v_cvt_pk_bf16_f32 v29, v38, v39
; __device__ __forceinline__ unsigned pk2(float lo, float hi) { f32x2 v = {lo, hi}; bf16x2_t b = __builtin_convertvector(v, bf16x2_t); return __builtin_bit_cast(unsigned, b); }
; __device__ __forceinline__ void pool_window(const bf16_t* __restrict__ U  , bf16_t* __restrict__ A3, const int gtid, const int nthr) {
;     ...
;         for (int i = 0; i < 32; ++i) {
;             const int t = t0 + i, s = s0 + i;
;             const u32x4 uu = *(const u32x4*)(U + (size_t)t * LDU + c);
;             float cu[8] = {bflo(uu.x), bfhi(uu.x), bflo(uu.y), bfhi(uu.y), bflo(uu.z), bfhi(uu.z), bflo(uu.w), bfhi(uu.w)};
;             const float rc = 1.0f / (float)((s + 1) < w ? (s + 1) : w);
;             float o[8];
; #pragma unroll
;             for (int e = 0; e < 8; ++e) { sum[e] += cu[e]; o[e] = sum[e] * rc - cu[e]; }
;             u32x4 ww; ww.x = pk2(o[0], o[1]); ww.y = pk2(o[2], o[3]); ww.z = pk2(o[4], o[5]); ww.w = pk2(o[6], o[7]);
;             *(u32x4*)(A3 + (size_t)t * DM + c) = ww;
;             if (s + 1 >= w) { const u32x4 ud = *(const u32x4*)(U + (size_t)(t - w + 1) * LDU + c);
;                 sum[0] -= bflo(ud.x); sum[1] -= bfhi(ud.x); sum[2] -= bflo(ud.y); sum[3] -= bfhi(ud.y); sum[4] -= bflo(ud.z); sum[5] -= bfhi(ud.z); sum[6] -= bflo(ud.w); sum[7] -= bfhi(ud.w); }
	v_cvt_pk_bf16_f32 v30, v40, v41
	v_cvt_pk_bf16_f32 v31, v42, v43
	global_store_dwordx4 v[10:11], v[28:31], off
	v_lshlrev_b32_e32 v44, 16, v128
	v_and_b32_e32 v45, 0xffff0000, v128
	v_lshlrev_b32_e32 v46, 16, v129
	v_and_b32_e32 v47, 0xffff0000, v129
	v_lshlrev_b32_e32 v48, 16, v130
	v_and_b32_e32 v49, 0xffff0000, v130
	v_lshlrev_b32_e32 v50, 16, v131
	v_and_b32_e32 v51, 0xffff0000, v131
	v_pk_add_f32 v[14:15], v[14:15], v[44:45] neg_lo:[0,1] neg_hi:[0,1]
	v_pk_add_f32 v[16:17], v[16:17], v[46:47] neg_lo:[0,1] neg_hi:[0,1]
	v_pk_add_f32 v[18:19], v[18:19], v[48:49] neg_lo:[0,1] neg_hi:[0,1]
	v_pk_add_f32 v[12:13], v[12:13], v[50:51] neg_lo:[0,1] neg_hi:[0,1]
	v_lshl_add_u64 v[10:11], v[10:11], 0, s[26:27]
	v_lshlrev_b32_e32 v44, 16, v192
	v_and_b32_e32 v45, 0xffff0000, v192
	v_lshlrev_b32_e32 v46, 16, v193
	v_and_b32_e32 v47, 0xffff0000, v193
	v_lshlrev_b32_e32 v48, 16, v194
	v_and_b32_e32 v49, 0xffff0000, v194
	v_lshlrev_b32_e32 v50, 16, v195
	v_and_b32_e32 v51, 0xffff0000, v195
	v_pk_add_f32 v[14:15], v[14:15], v[44:45]
	v_pk_add_f32 v[16:17], v[16:17], v[46:47]
	v_pk_add_f32 v[18:19], v[18:19], v[48:49]
	v_pk_add_f32 v[12:13], v[12:13], v[50:51]
	v_pk_fma_f32 v[36:37], v[34:35], v[14:15], v[44:45] op_sel_hi:[0,1,1] neg_lo:[0,0,1] neg_hi:[0,0,1]
	v_pk_fma_f32 v[38:39], v[34:35], v[16:17], v[46:47] op_sel_hi:[0,1,1] neg_lo:[0,0,1] neg_hi:[0,0,1]
	v_pk_fma_f32 v[40:41], v[34:35], v[18:19], v[48:49] op_sel_hi:[0,1,1] neg_lo:[0,0,1] neg_hi:[0,0,1]
	v_pk_fma_f32 v[42:43], v[34:35], v[12:13], v[50:51] op_sel_hi:[0,1,1] neg_lo:[0,0,1] neg_hi:[0,0,1]
	v_cvt_pk_bf16_f32 v28, v36, v37
	v_cvt_pk_bf16_f32 v29, v38, v39
	v_cvt_pk_bf16_f32 v30, v40, v41
	v_cvt_pk_bf16_f32 v31, v42, v43
	global_store_dwordx4 v[10:11], v[28:31], off
	v_lshlrev_b32_e32 v44, 16, v132
	v_and_b32_e32 v45, 0xffff0000, v132
	v_lshlrev_b32_e32 v46, 16, v133
	v_and_b32_e32 v47, 0xffff0000, v133
	v_lshlrev_b32_e32 v48, 16, v134
	v_and_b32_e32 v49, 0xffff0000, v134
	v_lshlrev_b32_e32 v50, 16, v135
	v_and_b32_e32 v51, 0xffff0000, v135
	v_pk_add_f32 v[14:15], v[14:15], v[44:45] neg_lo:[0,1] neg_hi:[0,1]
	v_pk_add_f32 v[16:17], v[16:17], v[46:47] neg_lo:[0,1] neg_hi:[0,1]
	v_pk_add_f32 v[18:19], v[18:19], v[48:49] neg_lo:[0,1] neg_hi:[0,1]
	v_pk_add_f32 v[12:13], v[12:13], v[50:51] neg_lo:[0,1] neg_hi:[0,1]
	v_lshl_add_u64 v[10:11], v[10:11], 0, s[26:27]
	v_lshlrev_b32_e32 v44, 16, v196
	v_and_b32_e32 v45, 0xffff0000, v196
	v_lshlrev_b32_e32 v46, 16, v197
	v_and_b32_e32 v47, 0xffff0000, v197
	v_lshlrev_b32_e32 v48, 16, v198
	v_and_b32_e32 v49, 0xffff0000, v198
	v_lshlrev_b32_e32 v50, 16, v199
	v_and_b32_e32 v51, 0xffff0000, v199
	v_pk_add_f32 v[14:15], v[14:15], v[44:45]
	v_pk_add_f32 v[16:17], v[16:17], v[46:47]
	v_pk_add_f32 v[18:19], v[18:19], v[48:49]
	v_pk_add_f32 v[12:13], v[12:13], v[50:51]
	v_pk_fma_f32 v[36:37], v[34:35], v[14:15], v[44:45] op_sel_hi:[0,1,1] neg_lo:[0,0,1] neg_hi:[0,0,1]
	v_pk_fma_f32 v[38:39], v[34:35], v[16:17], v[46:47] op_sel_hi:[0,1,1] neg_lo:[0,0,1] neg_hi:[0,0,1]
	v_pk_fma_f32 v[40:41], v[34:35], v[18:19], v[48:49] op_sel_hi:[0,1,1] neg_lo:[0,0,1] neg_hi:[0,0,1]
	v_pk_fma_f32 v[42:43], v[34:35], v[12:13], v[50:51] op_sel_hi:[0,1,1] neg_lo:[0,0,1] neg_hi:[0,0,1]
	v_cvt_pk_bf16_f32 v28, v36, v37
	v_cvt_pk_bf16_f32 v29, v38, v39
	v_cvt_pk_bf16_f32 v30, v40, v41
	v_cvt_pk_bf16_f32 v31, v42, v43
	global_store_dwordx4 v[10:11], v[28:31], off
	v_lshlrev_b32_e32 v44, 16, v136
	v_and_b32_e32 v45, 0xffff0000, v136
	v_lshlrev_b32_e32 v46, 16, v137
	v_and_b32_e32 v47, 0xffff0000, v137
	v_lshlrev_b32_e32 v48, 16, v138
	v_and_b32_e32 v49, 0xffff0000, v138
	v_lshlrev_b32_e32 v50, 16, v139
	v_and_b32_e32 v51, 0xffff0000, v139
	v_pk_add_f32 v[14:15], v[14:15], v[44:45] neg_lo:[0,1] neg_hi:[0,1]
	v_pk_add_f32 v[16:17], v[16:17], v[46:47] neg_lo:[0,1] neg_hi:[0,1]
	v_pk_add_f32 v[18:19], v[18:19], v[48:49] neg_lo:[0,1] neg_hi:[0,1]
	v_pk_add_f32 v[12:13], v[12:13], v[50:51] neg_lo:[0,1] neg_hi:[0,1]
	v_lshl_add_u64 v[10:11], v[10:11], 0, s[26:27]
	v_lshlrev_b32_e32 v44, 16, v200
	v_and_b32_e32 v45, 0xffff0000, v200
	v_lshlrev_b32_e32 v46, 16, v201
	v_and_b32_e32 v47, 0xffff0000, v201
	v_lshlrev_b32_e32 v48, 16, v202
	v_and_b32_e32 v49, 0xffff0000, v202
	v_lshlrev_b32_e32 v50, 16, v203
	v_and_b32_e32 v51, 0xffff0000, v203
	v_pk_add_f32 v[14:15], v[14:15], v[44:45]
	v_pk_add_f32 v[16:17], v[16:17], v[46:47]
	v_pk_add_f32 v[18:19], v[18:19], v[48:49]
	v_pk_add_f32 v[12:13], v[12:13], v[50:51]
	v_pk_fma_f32 v[36:37], v[34:35], v[14:15], v[44:45] op_sel_hi:[0,1,1] neg_lo:[0,0,1] neg_hi:[0,0,1]
	v_pk_fma_f32 v[38:39], v[34:35], v[16:17], v[46:47] op_sel_hi:[0,1,1] neg_lo:[0,0,1] neg_hi:[0,0,1]
	v_pk_fma_f32 v[40:41], v[34:35], v[18:19], v[48:49] op_sel_hi:[0,1,1] neg_lo:[0,0,1] neg_hi:[0,0,1]
	v_pk_fma_f32 v[42:43], v[34:35], v[12:13], v[50:51] op_sel_hi:[0,1,1] neg_lo:[0,0,1] neg_hi:[0,0,1]
	v_cvt_pk_bf16_f32 v28, v36, v37
	v_cvt_pk_bf16_f32 v29, v38, v39
	v_cvt_pk_bf16_f32 v30, v40, v41
	v_cvt_pk_bf16_f32 v31, v42, v43
	global_store_dwordx4 v[10:11], v[28:31], off
	v_lshlrev_b32_e32 v44, 16, v140
	v_and_b32_e32 v45, 0xffff0000, v140
	v_lshlrev_b32_e32 v46, 16, v141
	v_and_b32_e32 v47, 0xffff0000, v141
	v_lshlrev_b32_e32 v48, 16, v142
	v_and_b32_e32 v49, 0xffff0000, v142
	v_lshlrev_b32_e32 v50, 16, v143
	v_and_b32_e32 v51, 0xffff0000, v143
	v_pk_add_f32 v[14:15], v[14:15], v[44:45] neg_lo:[0,1] neg_hi:[0,1]
	v_pk_add_f32 v[16:17], v[16:17], v[46:47] neg_lo:[0,1] neg_hi:[0,1]
	v_pk_add_f32 v[18:19], v[18:19], v[48:49] neg_lo:[0,1] neg_hi:[0,1]
	v_pk_add_f32 v[12:13], v[12:13], v[50:51] neg_lo:[0,1] neg_hi:[0,1]
	v_lshl_add_u64 v[10:11], v[10:11], 0, s[26:27]
; __device__ __forceinline__ unsigned pk2(float lo, float hi) { f32x2 v = {lo, hi}; bf16x2_t b = __builtin_convertvector(v, bf16x2_t); return __builtin_bit_cast(unsigned, b); }
; __device__ __forceinline__ void pool_window(const bf16_t* __restrict__ U  , bf16_t* __restrict__ A3, const int gtid, const int nthr) {
;     ...
;         for (int i = 0; i < 32; ++i) {
;             const int t = t0 + i, s = s0 + i;
;             const u32x4 uu = *(const u32x4*)(U + (size_t)t * LDU + c);
;             float cu[8] = {bflo(uu.x), bfhi(uu.x), bflo(uu.y), bfhi(uu.y), bflo(uu.z), bfhi(uu.z), bflo(uu.w), bfhi(uu.w)};
;             const float rc = 1.0f / (float)((s + 1) < w ? (s + 1) : w);
;             float o[8];
; #pragma unroll
;             for (int e = 0; e < 8; ++e) { sum[e] += cu[e]; o[e] = sum[e] * rc - cu[e]; }
;             u32x4 ww; ww.x = pk2(o[0], o[1]); ww.y = pk2(o[2], o[3]); ww.z = pk2(o[4], o[5]); ww.w = pk2(o[6], o[7]);
;             *(u32x4*)(A3 + (size_t)t * DM + c) = ww;
;             if (s + 1 >= w) { const u32x4 ud = *(const u32x4*)(U + (size_t)(t - w + 1) * LDU + c);
;                 sum[0] -= bflo(ud.x); sum[1] -= bfhi(ud.x); sum[2] -= bflo(ud.y); sum[3] -= bfhi(ud.y); sum[4] -= bflo(ud.z); sum[5] -= bfhi(ud.z); sum[6] -= bflo(ud.w); sum[7] -= bfhi(ud.w); }
	v_lshlrev_b32_e32 v44, 16, v204
	v_and_b32_e32 v45, 0xffff0000, v204
	v_lshlrev_b32_e32 v46, 16, v205
	v_and_b32_e32 v47, 0xffff0000, v205
	v_lshlrev_b32_e32 v48, 16, v206
	v_and_b32_e32 v49, 0xffff0000, v206
	v_lshlrev_b32_e32 v50, 16, v207
	v_and_b32_e32 v51, 0xffff0000, v207
	v_pk_add_f32 v[14:15], v[14:15], v[44:45]
	v_pk_add_f32 v[16:17], v[16:17], v[46:47]
	v_pk_add_f32 v[18:19], v[18:19], v[48:49]
	v_pk_add_f32 v[12:13], v[12:13], v[50:51]
	v_pk_fma_f32 v[36:37], v[34:35], v[14:15], v[44:45] op_sel_hi:[0,1,1] neg_lo:[0,0,1] neg_hi:[0,0,1]
	v_pk_fma_f32 v[38:39], v[34:35], v[16:17], v[46:47] op_sel_hi:[0,1,1] neg_lo:[0,0,1] neg_hi:[0,0,1]
	v_pk_fma_f32 v[40:41], v[34:35], v[18:19], v[48:49] op_sel_hi:[0,1,1] neg_lo:[0,0,1] neg_hi:[0,0,1]
	v_pk_fma_f32 v[42:43], v[34:35], v[12:13], v[50:51] op_sel_hi:[0,1,1] neg_lo:[0,0,1] neg_hi:[0,0,1]
	v_cvt_pk_bf16_f32 v28, v36, v37
	v_cvt_pk_bf16_f32 v29, v38, v39
	v_cvt_pk_bf16_f32 v30, v40, v41
	v_cvt_pk_bf16_f32 v31, v42, v43
	global_store_dwordx4 v[10:11], v[28:31], off
	v_lshlrev_b32_e32 v44, 16, v144
	v_and_b32_e32 v45, 0xffff0000, v144
	v_lshlrev_b32_e32 v46, 16, v145
	v_and_b32_e32 v47, 0xffff0000, v145
	v_lshlrev_b32_e32 v48, 16, v146
	v_and_b32_e32 v49, 0xffff0000, v146
	v_lshlrev_b32_e32 v50, 16, v147
	v_and_b32_e32 v51, 0xffff0000, v147
	v_pk_add_f32 v[14:15], v[14:15], v[44:45] neg_lo:[0,1] neg_hi:[0,1]
	v_pk_add_f32 v[16:17], v[16:17], v[46:47] neg_lo:[0,1] neg_hi:[0,1]
	v_pk_add_f32 v[18:19], v[18:19], v[48:49] neg_lo:[0,1] neg_hi:[0,1]
	v_pk_add_f32 v[12:13], v[12:13], v[50:51] neg_lo:[0,1] neg_hi:[0,1]
	v_lshl_add_u64 v[10:11], v[10:11], 0, s[26:27]
	v_lshlrev_b32_e32 v44, 16, v208
	v_and_b32_e32 v45, 0xffff0000, v208
	v_lshlrev_b32_e32 v46, 16, v209
	v_and_b32_e32 v47, 0xffff0000, v209
	v_lshlrev_b32_e32 v48, 16, v210
	v_and_b32_e32 v49, 0xffff0000, v210
	v_lshlrev_b32_e32 v50, 16, v211
	v_and_b32_e32 v51, 0xffff0000, v211
	v_pk_add_f32 v[14:15], v[14:15], v[44:45]
	v_pk_add_f32 v[16:17], v[16:17], v[46:47]
	v_pk_add_f32 v[18:19], v[18:19], v[48:49]
	v_pk_add_f32 v[12:13], v[12:13], v[50:51]
	v_pk_fma_f32 v[36:37], v[34:35], v[14:15], v[44:45] op_sel_hi:[0,1,1] neg_lo:[0,0,1] neg_hi:[0,0,1]
	v_pk_fma_f32 v[38:39], v[34:35], v[16:17], v[46:47] op_sel_hi:[0,1,1] neg_lo:[0,0,1] neg_hi:[0,0,1]
	v_pk_fma_f32 v[40:41], v[34:35], v[18:19], v[48:49] op_sel_hi:[0,1,1] neg_lo:[0,0,1] neg_hi:[0,0,1]
	v_pk_fma_f32 v[42:43], v[34:35], v[12:13], v[50:51] op_sel_hi:[0,1,1] neg_lo:[0,0,1] neg_hi:[0,0,1]
	v_cvt_pk_bf16_f32 v28, v36, v37
	v_cvt_pk_bf16_f32 v29, v38, v39
	v_cvt_pk_bf16_f32 v30, v40, v41
	v_cvt_pk_bf16_f32 v31, v42, v43
	global_store_dwordx4 v[10:11], v[28:31], off
	v_lshlrev_b32_e32 v44, 16, v148
	v_and_b32_e32 v45, 0xffff0000, v148
	v_lshlrev_b32_e32 v46, 16, v149
	v_and_b32_e32 v47, 0xffff0000, v149
	v_lshlrev_b32_e32 v48, 16, v150
	v_and_b32_e32 v49, 0xffff0000, v150
	v_lshlrev_b32_e32 v50, 16, v151
	v_and_b32_e32 v51, 0xffff0000, v151
	v_pk_add_f32 v[14:15], v[14:15], v[44:45] neg_lo:[0,1] neg_hi:[0,1]
	v_pk_add_f32 v[16:17], v[16:17], v[46:47] neg_lo:[0,1] neg_hi:[0,1]
	v_pk_add_f32 v[18:19], v[18:19], v[48:49] neg_lo:[0,1] neg_hi:[0,1]
	v_pk_add_f32 v[12:13], v[12:13], v[50:51] neg_lo:[0,1] neg_hi:[0,1]
	v_lshl_add_u64 v[10:11], v[10:11], 0, s[26:27]
	v_lshlrev_b32_e32 v44, 16, v214
	v_and_b32_e32 v45, 0xffff0000, v214
	v_lshlrev_b32_e32 v46, 16, v215
	v_and_b32_e32 v47, 0xffff0000, v215
	v_lshlrev_b32_e32 v48, 16, v216
	v_and_b32_e32 v49, 0xffff0000, v216
	v_lshlrev_b32_e32 v50, 16, v217
	v_and_b32_e32 v51, 0xffff0000, v217
	v_pk_add_f32 v[14:15], v[14:15], v[44:45]
	v_pk_add_f32 v[16:17], v[16:17], v[46:47]
	v_pk_add_f32 v[18:19], v[18:19], v[48:49]
	v_pk_add_f32 v[12:13], v[12:13], v[50:51]
	v_pk_fma_f32 v[36:37], v[34:35], v[14:15], v[44:45] op_sel_hi:[0,1,1] neg_lo:[0,0,1] neg_hi:[0,0,1]
	v_pk_fma_f32 v[38:39], v[34:35], v[16:17], v[46:47] op_sel_hi:[0,1,1] neg_lo:[0,0,1] neg_hi:[0,0,1]
	v_pk_fma_f32 v[40:41], v[34:35], v[18:19], v[48:49] op_sel_hi:[0,1,1] neg_lo:[0,0,1] neg_hi:[0,0,1]
	v_pk_fma_f32 v[42:43], v[34:35], v[12:13], v[50:51] op_sel_hi:[0,1,1] neg_lo:[0,0,1] neg_hi:[0,0,1]
	v_cvt_pk_bf16_f32 v28, v36, v37
	v_cvt_pk_bf16_f32 v29, v38, v39
	v_cvt_pk_bf16_f32 v30, v40, v41
	v_cvt_pk_bf16_f32 v31, v42, v43
	global_store_dwordx4 v[10:11], v[28:31], off
	v_lshlrev_b32_e32 v44, 16, v152
	v_and_b32_e32 v45, 0xffff0000, v152
	v_lshlrev_b32_e32 v46, 16, v153
	v_and_b32_e32 v47, 0xffff0000, v153
	v_lshlrev_b32_e32 v48, 16, v154
	v_and_b32_e32 v49, 0xffff0000, v154
	v_lshlrev_b32_e32 v50, 16, v155
	v_and_b32_e32 v51, 0xffff0000, v155
	v_pk_add_f32 v[14:15], v[14:15], v[44:45] neg_lo:[0,1] neg_hi:[0,1]
	v_pk_add_f32 v[16:17], v[16:17], v[46:47] neg_lo:[0,1] neg_hi:[0,1]
	v_pk_add_f32 v[18:19], v[18:19], v[48:49] neg_lo:[0,1] neg_hi:[0,1]
	v_pk_add_f32 v[12:13], v[12:13], v[50:51] neg_lo:[0,1] neg_hi:[0,1]
	v_lshl_add_u64 v[10:11], v[10:11], 0, s[26:27]
	v_lshlrev_b32_e32 v44, 16, v218
	v_and_b32_e32 v45, 0xffff0000, v218
	v_lshlrev_b32_e32 v46, 16, v219
	v_and_b32_e32 v47, 0xffff0000, v219
	v_lshlrev_b32_e32 v48, 16, v220
	v_and_b32_e32 v49, 0xffff0000, v220
	v_lshlrev_b32_e32 v50, 16, v221
	v_and_b32_e32 v51, 0xffff0000, v221
	v_pk_add_f32 v[14:15], v[14:15], v[44:45]
	v_pk_add_f32 v[16:17], v[16:17], v[46:47]
	v_pk_add_f32 v[18:19], v[18:19], v[48:49]
	v_pk_add_f32 v[12:13], v[12:13], v[50:51]
	v_pk_fma_f32 v[36:37], v[34:35], v[14:15], v[44:45] op_sel_hi:[0,1,1] neg_lo:[0,0,1] neg_hi:[0,0,1]
	v_pk_fma_f32 v[38:39], v[34:35], v[16:17], v[46:47] op_sel_hi:[0,1,1] neg_lo:[0,0,1] neg_hi:[0,0,1]
	v_pk_fma_f32 v[40:41], v[34:35], v[18:19], v[48:49] op_sel_hi:[0,1,1] neg_lo:[0,0,1] neg_hi:[0,0,1]
; __device__ __forceinline__ unsigned pk2(float lo, float hi) { f32x2 v = {lo, hi}; bf16x2_t b = __builtin_convertvector(v, bf16x2_t); return __builtin_bit_cast(unsigned, b); }
; __device__ __forceinline__ void pool_window(const bf16_t* __restrict__ U  , bf16_t* __restrict__ A3, const int gtid, const int nthr) {
;     ...
;         for (int i = 0; i < 32; ++i) {
;             const int t = t0 + i, s = s0 + i;
;             const u32x4 uu = *(const u32x4*)(U + (size_t)t * LDU + c);
;             float cu[8] = {bflo(uu.x), bfhi(uu.x), bflo(uu.y), bfhi(uu.y), bflo(uu.z), bfhi(uu.z), bflo(uu.w), bfhi(uu.w)};
;             const float rc = 1.0f / (float)((s + 1) < w ? (s + 1) : w);
;             float o[8];
; #pragma unroll
;             for (int e = 0; e < 8; ++e) { sum[e] += cu[e]; o[e] = sum[e] * rc - cu[e]; }
;             u32x4 ww; ww.x = pk2(o[0], o[1]); ww.y = pk2(o[2], o[3]); ww.z = pk2(o[4], o[5]); ww.w = pk2(o[6], o[7]);
;             *(u32x4*)(A3 + (size_t)t * DM + c) = ww;
;             if (s + 1 >= w) { const u32x4 ud = *(const u32x4*)(U + (size_t)(t - w + 1) * LDU + c);
;                 sum[0] -= bflo(ud.x); sum[1] -= bfhi(ud.x); sum[2] -= bflo(ud.y); sum[3] -= bfhi(ud.y); sum[4] -= bflo(ud.z); sum[5] -= bfhi(ud.z); sum[6] -= bflo(ud.w); sum[7] -= bfhi(ud.w); }
	v_pk_fma_f32 v[42:43], v[34:35], v[12:13], v[50:51] op_sel_hi:[0,1,1] neg_lo:[0,0,1] neg_hi:[0,0,1]
	v_cvt_pk_bf16_f32 v28, v36, v37
	v_cvt_pk_bf16_f32 v29, v38, v39
	v_cvt_pk_bf16_f32 v30, v40, v41
	v_cvt_pk_bf16_f32 v31, v42, v43
	global_store_dwordx4 v[10:11], v[28:31], off
	v_lshlrev_b32_e32 v44, 16, v156
	v_and_b32_e32 v45, 0xffff0000, v156
	v_lshlrev_b32_e32 v46, 16, v157
	v_and_b32_e32 v47, 0xffff0000, v157
	v_lshlrev_b32_e32 v48, 16, v158
	v_and_b32_e32 v49, 0xffff0000, v158
	v_lshlrev_b32_e32 v50, 16, v159
	v_and_b32_e32 v51, 0xffff0000, v159
	v_pk_add_f32 v[14:15], v[14:15], v[44:45] neg_lo:[0,1] neg_hi:[0,1]
	v_pk_add_f32 v[16:17], v[16:17], v[46:47] neg_lo:[0,1] neg_hi:[0,1]
	v_pk_add_f32 v[18:19], v[18:19], v[48:49] neg_lo:[0,1] neg_hi:[0,1]
	v_pk_add_f32 v[12:13], v[12:13], v[50:51] neg_lo:[0,1] neg_hi:[0,1]
	v_lshl_add_u64 v[10:11], v[10:11], 0, s[26:27]
	v_lshlrev_b32_e32 v44, 16, v222
	v_and_b32_e32 v45, 0xffff0000, v222
	v_lshlrev_b32_e32 v46, 16, v223
	v_and_b32_e32 v47, 0xffff0000, v223
	v_lshlrev_b32_e32 v48, 16, v224
	v_and_b32_e32 v49, 0xffff0000, v224
	v_lshlrev_b32_e32 v50, 16, v225
	v_and_b32_e32 v51, 0xffff0000, v225
	v_pk_add_f32 v[14:15], v[14:15], v[44:45]
	v_pk_add_f32 v[16:17], v[16:17], v[46:47]
	v_pk_add_f32 v[18:19], v[18:19], v[48:49]
	v_pk_add_f32 v[12:13], v[12:13], v[50:51]
	v_pk_fma_f32 v[36:37], v[34:35], v[14:15], v[44:45] op_sel_hi:[0,1,1] neg_lo:[0,0,1] neg_hi:[0,0,1]
	v_pk_fma_f32 v[38:39], v[34:35], v[16:17], v[46:47] op_sel_hi:[0,1,1] neg_lo:[0,0,1] neg_hi:[0,0,1]
	v_pk_fma_f32 v[40:41], v[34:35], v[18:19], v[48:49] op_sel_hi:[0,1,1] neg_lo:[0,0,1] neg_hi:[0,0,1]
	v_pk_fma_f32 v[42:43], v[34:35], v[12:13], v[50:51] op_sel_hi:[0,1,1] neg_lo:[0,0,1] neg_hi:[0,0,1]
	v_cvt_pk_bf16_f32 v28, v36, v37
	v_cvt_pk_bf16_f32 v29, v38, v39
	v_cvt_pk_bf16_f32 v30, v40, v41
	v_cvt_pk_bf16_f32 v31, v42, v43
	global_store_dwordx4 v[10:11], v[28:31], off
	v_lshlrev_b32_e32 v44, 16, v160
	v_and_b32_e32 v45, 0xffff0000, v160
	v_lshlrev_b32_e32 v46, 16, v161
	v_and_b32_e32 v47, 0xffff0000, v161
	v_lshlrev_b32_e32 v48, 16, v162
	v_and_b32_e32 v49, 0xffff0000, v162
	v_lshlrev_b32_e32 v50, 16, v163
	v_and_b32_e32 v51, 0xffff0000, v163
	v_pk_add_f32 v[14:15], v[14:15], v[44:45] neg_lo:[0,1] neg_hi:[0,1]
	v_pk_add_f32 v[16:17], v[16:17], v[46:47] neg_lo:[0,1] neg_hi:[0,1]
	v_pk_add_f32 v[18:19], v[18:19], v[48:49] neg_lo:[0,1] neg_hi:[0,1]
	v_pk_add_f32 v[12:13], v[12:13], v[50:51] neg_lo:[0,1] neg_hi:[0,1]
	v_lshl_add_u64 v[10:11], v[10:11], 0, s[26:27]
	v_lshlrev_b32_e32 v44, 16, v226
	v_and_b32_e32 v45, 0xffff0000, v226
	v_lshlrev_b32_e32 v46, 16, v227
	v_and_b32_e32 v47, 0xffff0000, v227
	v_lshlrev_b32_e32 v48, 16, v228
	v_and_b32_e32 v49, 0xffff0000, v228
	v_lshlrev_b32_e32 v50, 16, v229
	v_and_b32_e32 v51, 0xffff0000, v229
	v_pk_add_f32 v[14:15], v[14:15], v[44:45]
	v_pk_add_f32 v[16:17], v[16:17], v[46:47]
	v_pk_add_f32 v[18:19], v[18:19], v[48:49]
	v_pk_add_f32 v[12:13], v[12:13], v[50:51]
	v_pk_fma_f32 v[36:37], v[34:35], v[14:15], v[44:45] op_sel_hi:[0,1,1] neg_lo:[0,0,1] neg_hi:[0,0,1]
	v_pk_fma_f32 v[38:39], v[34:35], v[16:17], v[46:47] op_sel_hi:[0,1,1] neg_lo:[0,0,1] neg_hi:[0,0,1]
	v_pk_fma_f32 v[40:41], v[34:35], v[18:19], v[48:49] op_sel_hi:[0,1,1] neg_lo:[0,0,1] neg_hi:[0,0,1]
	v_pk_fma_f32 v[42:43], v[34:35], v[12:13], v[50:51] op_sel_hi:[0,1,1] neg_lo:[0,0,1] neg_hi:[0,0,1]
	v_cvt_pk_bf16_f32 v28, v36, v37
	v_cvt_pk_bf16_f32 v29, v38, v39
	v_cvt_pk_bf16_f32 v30, v40, v41
	v_cvt_pk_bf16_f32 v31, v42, v43
	global_store_dwordx4 v[10:11], v[28:31], off
	v_lshlrev_b32_e32 v44, 16, v164
	v_and_b32_e32 v45, 0xffff0000, v164
	v_lshlrev_b32_e32 v46, 16, v165
	v_and_b32_e32 v47, 0xffff0000, v165
	v_lshlrev_b32_e32 v48, 16, v166
	v_and_b32_e32 v49, 0xffff0000, v166
	v_lshlrev_b32_e32 v50, 16, v167
	v_and_b32_e32 v51, 0xffff0000, v167
	v_pk_add_f32 v[14:15], v[14:15], v[44:45] neg_lo:[0,1] neg_hi:[0,1]
	v_pk_add_f32 v[16:17], v[16:17], v[46:47] neg_lo:[0,1] neg_hi:[0,1]
	v_pk_add_f32 v[18:19], v[18:19], v[48:49] neg_lo:[0,1] neg_hi:[0,1]
	v_pk_add_f32 v[12:13], v[12:13], v[50:51] neg_lo:[0,1] neg_hi:[0,1]
	v_lshl_add_u64 v[10:11], v[10:11], 0, s[26:27]
	v_lshlrev_b32_e32 v44, 16, v230
	v_and_b32_e32 v45, 0xffff0000, v230
	v_lshlrev_b32_e32 v46, 16, v231
	v_and_b32_e32 v47, 0xffff0000, v231
	v_lshlrev_b32_e32 v48, 16, v232
	v_and_b32_e32 v49, 0xffff0000, v232
	v_lshlrev_b32_e32 v50, 16, v233
	v_and_b32_e32 v51, 0xffff0000, v233
	v_pk_add_f32 v[14:15], v[14:15], v[44:45]
	v_pk_add_f32 v[16:17], v[16:17], v[46:47]
	v_pk_add_f32 v[18:19], v[18:19], v[48:49]
	v_pk_add_f32 v[12:13], v[12:13], v[50:51]
	v_pk_fma_f32 v[36:37], v[34:35], v[14:15], v[44:45] op_sel_hi:[0,1,1] neg_lo:[0,0,1] neg_hi:[0,0,1]
	v_pk_fma_f32 v[38:39], v[34:35], v[16:17], v[46:47] op_sel_hi:[0,1,1] neg_lo:[0,0,1] neg_hi:[0,0,1]
	v_pk_fma_f32 v[40:41], v[34:35], v[18:19], v[48:49] op_sel_hi:[0,1,1] neg_lo:[0,0,1] neg_hi:[0,0,1]
	v_pk_fma_f32 v[42:43], v[34:35], v[12:13], v[50:51] op_sel_hi:[0,1,1] neg_lo:[0,0,1] neg_hi:[0,0,1]
	v_cvt_pk_bf16_f32 v28, v36, v37
	v_cvt_pk_bf16_f32 v29, v38, v39
	v_cvt_pk_bf16_f32 v30, v40, v41
	v_cvt_pk_bf16_f32 v31, v42, v43
	global_store_dwordx4 v[10:11], v[28:31], off
	v_lshlrev_b32_e32 v44, 16, v168
	v_and_b32_e32 v45, 0xffff0000, v168
	v_lshlrev_b32_e32 v46, 16, v169
	v_and_b32_e32 v47, 0xffff0000, v169
	v_lshlrev_b32_e32 v48, 16, v170
	v_and_b32_e32 v49, 0xffff0000, v170
	v_lshlrev_b32_e32 v50, 16, v171
	v_and_b32_e32 v51, 0xffff0000, v171
	v_pk_add_f32 v[14:15], v[14:15], v[44:45] neg_lo:[0,1] neg_hi:[0,1]
	v_pk_add_f32 v[16:17], v[16:17], v[46:47] neg_lo:[0,1] neg_hi:[0,1]
; __device__ __forceinline__ unsigned pk2(float lo, float hi) { f32x2 v = {lo, hi}; bf16x2_t b = __builtin_convertvector(v, bf16x2_t); return __builtin_bit_cast(unsigned, b); }
; __device__ __forceinline__ void pool_window(const bf16_t* __restrict__ U  , bf16_t* __restrict__ A3, const int gtid, const int nthr) {
;     ...
;         for (int i = 0; i < 32; ++i) {
;             const int t = t0 + i, s = s0 + i;
;             const u32x4 uu = *(const u32x4*)(U + (size_t)t * LDU + c);
;             float cu[8] = {bflo(uu.x), bfhi(uu.x), bflo(uu.y), bfhi(uu.y), bflo(uu.z), bfhi(uu.z), bflo(uu.w), bfhi(uu.w)};
;             const float rc = 1.0f / (float)((s + 1) < w ? (s + 1) : w);
;             float o[8];
; #pragma unroll
;             for (int e = 0; e < 8; ++e) { sum[e] += cu[e]; o[e] = sum[e] * rc - cu[e]; }
;             u32x4 ww; ww.x = pk2(o[0], o[1]); ww.y = pk2(o[2], o[3]); ww.z = pk2(o[4], o[5]); ww.w = pk2(o[6], o[7]);
;             *(u32x4*)(A3 + (size_t)t * DM + c) = ww;
;             if (s + 1 >= w) { const u32x4 ud = *(const u32x4*)(U + (size_t)(t - w + 1) * LDU + c);
;                 sum[0] -= bflo(ud.x); sum[1] -= bfhi(ud.x); sum[2] -= bflo(ud.y); sum[3] -= bfhi(ud.y); sum[4] -= bflo(ud.z); sum[5] -= bfhi(ud.z); sum[6] -= bflo(ud.w); sum[7] -= bfhi(ud.w); }
	v_pk_add_f32 v[18:19], v[18:19], v[48:49] neg_lo:[0,1] neg_hi:[0,1]
	v_pk_add_f32 v[12:13], v[12:13], v[50:51] neg_lo:[0,1] neg_hi:[0,1]
	v_lshl_add_u64 v[10:11], v[10:11], 0, s[26:27]
	v_lshlrev_b32_e32 v44, 16, v234
	v_and_b32_e32 v45, 0xffff0000, v234
	v_lshlrev_b32_e32 v46, 16, v235
	v_and_b32_e32 v47, 0xffff0000, v235
	v_lshlrev_b32_e32 v48, 16, v236
	v_and_b32_e32 v49, 0xffff0000, v236
	v_lshlrev_b32_e32 v50, 16, v237
	v_and_b32_e32 v51, 0xffff0000, v237
	v_pk_add_f32 v[14:15], v[14:15], v[44:45]
	v_pk_add_f32 v[16:17], v[16:17], v[46:47]
	v_pk_add_f32 v[18:19], v[18:19], v[48:49]
	v_pk_add_f32 v[12:13], v[12:13], v[50:51]
	v_pk_fma_f32 v[36:37], v[34:35], v[14:15], v[44:45] op_sel_hi:[0,1,1] neg_lo:[0,0,1] neg_hi:[0,0,1]
	v_pk_fma_f32 v[38:39], v[34:35], v[16:17], v[46:47] op_sel_hi:[0,1,1] neg_lo:[0,0,1] neg_hi:[0,0,1]
	v_pk_fma_f32 v[40:41], v[34:35], v[18:19], v[48:49] op_sel_hi:[0,1,1] neg_lo:[0,0,1] neg_hi:[0,0,1]
	v_pk_fma_f32 v[42:43], v[34:35], v[12:13], v[50:51] op_sel_hi:[0,1,1] neg_lo:[0,0,1] neg_hi:[0,0,1]
	v_cvt_pk_bf16_f32 v28, v36, v37
	v_cvt_pk_bf16_f32 v29, v38, v39
	v_cvt_pk_bf16_f32 v30, v40, v41
	v_cvt_pk_bf16_f32 v31, v42, v43
	global_store_dwordx4 v[10:11], v[28:31], off
	v_lshlrev_b32_e32 v44, 16, v172
	v_and_b32_e32 v45, 0xffff0000, v172
	v_lshlrev_b32_e32 v46, 16, v173
	v_and_b32_e32 v47, 0xffff0000, v173
	v_lshlrev_b32_e32 v48, 16, v174
	v_and_b32_e32 v49, 0xffff0000, v174
	v_lshlrev_b32_e32 v50, 16, v175
	v_and_b32_e32 v51, 0xffff0000, v175
	v_pk_add_f32 v[14:15], v[14:15], v[44:45] neg_lo:[0,1] neg_hi:[0,1]
	v_pk_add_f32 v[16:17], v[16:17], v[46:47] neg_lo:[0,1] neg_hi:[0,1]
	v_pk_add_f32 v[18:19], v[18:19], v[48:49] neg_lo:[0,1] neg_hi:[0,1]
	v_pk_add_f32 v[12:13], v[12:13], v[50:51] neg_lo:[0,1] neg_hi:[0,1]
	v_lshl_add_u64 v[10:11], v[10:11], 0, s[26:27]
	v_lshlrev_b32_e32 v44, 16, v238
	v_and_b32_e32 v45, 0xffff0000, v238
	v_lshlrev_b32_e32 v46, 16, v239
	v_and_b32_e32 v47, 0xffff0000, v239
	v_lshlrev_b32_e32 v48, 16, v240
	v_and_b32_e32 v49, 0xffff0000, v240
	v_lshlrev_b32_e32 v50, 16, v241
	v_and_b32_e32 v51, 0xffff0000, v241
	v_pk_add_f32 v[14:15], v[14:15], v[44:45]
	v_pk_add_f32 v[16:17], v[16:17], v[46:47]
	v_pk_add_f32 v[18:19], v[18:19], v[48:49]
	v_pk_add_f32 v[12:13], v[12:13], v[50:51]
	v_pk_fma_f32 v[36:37], v[34:35], v[14:15], v[44:45] op_sel_hi:[0,1,1] neg_lo:[0,0,1] neg_hi:[0,0,1]
	v_pk_fma_f32 v[38:39], v[34:35], v[16:17], v[46:47] op_sel_hi:[0,1,1] neg_lo:[0,0,1] neg_hi:[0,0,1]
	v_pk_fma_f32 v[40:41], v[34:35], v[18:19], v[48:49] op_sel_hi:[0,1,1] neg_lo:[0,0,1] neg_hi:[0,0,1]
	v_pk_fma_f32 v[42:43], v[34:35], v[12:13], v[50:51] op_sel_hi:[0,1,1] neg_lo:[0,0,1] neg_hi:[0,0,1]
	v_cvt_pk_bf16_f32 v28, v36, v37
	v_cvt_pk_bf16_f32 v29, v38, v39
	v_cvt_pk_bf16_f32 v30, v40, v41
	v_cvt_pk_bf16_f32 v31, v42, v43
	global_store_dwordx4 v[10:11], v[28:31], off
	v_lshlrev_b32_e32 v44, 16, v176
	v_and_b32_e32 v45, 0xffff0000, v176
	v_lshlrev_b32_e32 v46, 16, v177
	v_and_b32_e32 v47, 0xffff0000, v177
	v_lshlrev_b32_e32 v48, 16, v178
	v_and_b32_e32 v49, 0xffff0000, v178
	v_lshlrev_b32_e32 v50, 16, v179
	v_and_b32_e32 v51, 0xffff0000, v179
	v_pk_add_f32 v[14:15], v[14:15], v[44:45] neg_lo:[0,1] neg_hi:[0,1]
	v_pk_add_f32 v[16:17], v[16:17], v[46:47] neg_lo:[0,1] neg_hi:[0,1]
	v_pk_add_f32 v[18:19], v[18:19], v[48:49] neg_lo:[0,1] neg_hi:[0,1]
	v_pk_add_f32 v[12:13], v[12:13], v[50:51] neg_lo:[0,1] neg_hi:[0,1]
	v_lshl_add_u64 v[10:11], v[10:11], 0, s[26:27]
	v_lshlrev_b32_e32 v44, 16, v242
	v_and_b32_e32 v45, 0xffff0000, v242
	v_lshlrev_b32_e32 v46, 16, v243
	v_and_b32_e32 v47, 0xffff0000, v243
	v_lshlrev_b32_e32 v48, 16, v244
	v_and_b32_e32 v49, 0xffff0000, v244
	v_lshlrev_b32_e32 v50, 16, v245
	v_and_b32_e32 v51, 0xffff0000, v245
	v_pk_add_f32 v[14:15], v[14:15], v[44:45]
	v_pk_add_f32 v[16:17], v[16:17], v[46:47]
	v_pk_add_f32 v[18:19], v[18:19], v[48:49]
	v_pk_add_f32 v[12:13], v[12:13], v[50:51]
	v_pk_fma_f32 v[36:37], v[34:35], v[14:15], v[44:45] op_sel_hi:[0,1,1] neg_lo:[0,0,1] neg_hi:[0,0,1]
	v_pk_fma_f32 v[38:39], v[34:35], v[16:17], v[46:47] op_sel_hi:[0,1,1] neg_lo:[0,0,1] neg_hi:[0,0,1]
	v_pk_fma_f32 v[40:41], v[34:35], v[18:19], v[48:49] op_sel_hi:[0,1,1] neg_lo:[0,0,1] neg_hi:[0,0,1]
	v_pk_fma_f32 v[42:43], v[34:35], v[12:13], v[50:51] op_sel_hi:[0,1,1] neg_lo:[0,0,1] neg_hi:[0,0,1]
	v_cvt_pk_bf16_f32 v28, v36, v37
	v_cvt_pk_bf16_f32 v29, v38, v39
	v_cvt_pk_bf16_f32 v30, v40, v41
	v_cvt_pk_bf16_f32 v31, v42, v43
	global_store_dwordx4 v[10:11], v[28:31], off
	v_lshlrev_b32_e32 v44, 16, v180
	v_and_b32_e32 v45, 0xffff0000, v180
	v_lshlrev_b32_e32 v46, 16, v181
	v_and_b32_e32 v47, 0xffff0000, v181
	v_lshlrev_b32_e32 v48, 16, v182
	v_and_b32_e32 v49, 0xffff0000, v182
	v_lshlrev_b32_e32 v50, 16, v183
	v_and_b32_e32 v51, 0xffff0000, v183
	v_pk_add_f32 v[14:15], v[14:15], v[44:45] neg_lo:[0,1] neg_hi:[0,1]
	v_pk_add_f32 v[16:17], v[16:17], v[46:47] neg_lo:[0,1] neg_hi:[0,1]
	v_pk_add_f32 v[18:19], v[18:19], v[48:49] neg_lo:[0,1] neg_hi:[0,1]
	v_pk_add_f32 v[12:13], v[12:13], v[50:51] neg_lo:[0,1] neg_hi:[0,1]
	v_lshl_add_u64 v[10:11], v[10:11], 0, s[26:27]
	v_lshlrev_b32_e32 v44, 16, v246
	v_and_b32_e32 v45, 0xffff0000, v246
	v_lshlrev_b32_e32 v46, 16, v247
	v_and_b32_e32 v47, 0xffff0000, v247
	v_lshlrev_b32_e32 v48, 16, v248
	v_and_b32_e32 v49, 0xffff0000, v248
	v_lshlrev_b32_e32 v50, 16, v249
	v_and_b32_e32 v51, 0xffff0000, v249
	v_pk_add_f32 v[14:15], v[14:15], v[44:45]
	v_pk_add_f32 v[16:17], v[16:17], v[46:47]
	v_pk_add_f32 v[18:19], v[18:19], v[48:49]
	v_pk_add_f32 v[12:13], v[12:13], v[50:51]
	v_pk_fma_f32 v[36:37], v[34:35], v[14:15], v[44:45] op_sel_hi:[0,1,1] neg_lo:[0,0,1] neg_hi:[0,0,1]
; __device__ __forceinline__ unsigned pk2(float lo, float hi) { f32x2 v = {lo, hi}; bf16x2_t b = __builtin_convertvector(v, bf16x2_t); return __builtin_bit_cast(unsigned, b); }
; __device__ __forceinline__ void pool_window(const bf16_t* __restrict__ U  , bf16_t* __restrict__ A3, const int gtid, const int nthr) {
;     ...
;             for (int k = 1; k < w; ++k) { const u32x4 uu = *(const u32x4*)(U + (size_t)(t0 - k) * LDU + c);
;                 sum[0] += bflo(uu.x); sum[1] += bfhi(uu.x); sum[2] += bflo(uu.y); sum[3] += bfhi(uu.y); sum[4] += bflo(uu.z); sum[5] += bfhi(uu.z); sum[6] += bflo(uu.w); sum[7] += bfhi(uu.w); }
;         }
; #pragma unroll 8
;         for (int i = 0; i < 32; ++i) {
;             const int t = t0 + i, s = s0 + i;
;             const u32x4 uu = *(const u32x4*)(U + (size_t)t * LDU + c);
;             float cu[8] = {bflo(uu.x), bfhi(uu.x), bflo(uu.y), bfhi(uu.y), bflo(uu.z), bfhi(uu.z), bflo(uu.w), bfhi(uu.w)};
;             const float rc = 1.0f / (float)((s + 1) < w ? (s + 1) : w);
;             float o[8];
; #pragma unroll
;             for (int e = 0; e < 8; ++e) { sum[e] += cu[e]; o[e] = sum[e] * rc - cu[e]; }
;             u32x4 ww; ww.x = pk2(o[0], o[1]); ww.y = pk2(o[2], o[3]); ww.z = pk2(o[4], o[5]); ww.w = pk2(o[6], o[7]);
;             *(u32x4*)(A3 + (size_t)t * DM + c) = ww;
;             if (s + 1 >= w) { const u32x4 ud = *(const u32x4*)(U + (size_t)(t - w + 1) * LDU + c);
;                 sum[0] -= bflo(ud.x); sum[1] -= bfhi(ud.x); sum[2] -= bflo(ud.y); sum[3] -= bfhi(ud.y); sum[4] -= bflo(ud.z); sum[5] -= bfhi(ud.z); sum[6] -= bflo(ud.w); sum[7] -= bfhi(ud.w); }
	v_pk_fma_f32 v[38:39], v[34:35], v[16:17], v[46:47] op_sel_hi:[0,1,1] neg_lo:[0,0,1] neg_hi:[0,0,1]
	v_pk_fma_f32 v[40:41], v[34:35], v[18:19], v[48:49] op_sel_hi:[0,1,1] neg_lo:[0,0,1] neg_hi:[0,0,1]
	v_pk_fma_f32 v[42:43], v[34:35], v[12:13], v[50:51] op_sel_hi:[0,1,1] neg_lo:[0,0,1] neg_hi:[0,0,1]
	v_cvt_pk_bf16_f32 v28, v36, v37
	v_cvt_pk_bf16_f32 v29, v38, v39
	v_cvt_pk_bf16_f32 v30, v40, v41
	v_cvt_pk_bf16_f32 v31, v42, v43
	global_store_dwordx4 v[10:11], v[28:31], off
	v_lshlrev_b32_e32 v44, 16, v184
	v_and_b32_e32 v45, 0xffff0000, v184
	v_lshlrev_b32_e32 v46, 16, v185
	v_and_b32_e32 v47, 0xffff0000, v185
	v_lshlrev_b32_e32 v48, 16, v186
	v_and_b32_e32 v49, 0xffff0000, v186
	v_lshlrev_b32_e32 v50, 16, v187
	v_and_b32_e32 v51, 0xffff0000, v187
	v_pk_add_f32 v[14:15], v[14:15], v[44:45] neg_lo:[0,1] neg_hi:[0,1]
	v_pk_add_f32 v[16:17], v[16:17], v[46:47] neg_lo:[0,1] neg_hi:[0,1]
	v_pk_add_f32 v[18:19], v[18:19], v[48:49] neg_lo:[0,1] neg_hi:[0,1]
	v_pk_add_f32 v[12:13], v[12:13], v[50:51] neg_lo:[0,1] neg_hi:[0,1]
	v_lshl_add_u64 v[10:11], v[10:11], 0, s[26:27]
	v_lshlrev_b32_e32 v44, 16, v250
	v_and_b32_e32 v45, 0xffff0000, v250
	v_lshlrev_b32_e32 v46, 16, v251
	v_and_b32_e32 v47, 0xffff0000, v251
	v_lshlrev_b32_e32 v48, 16, v252
	v_and_b32_e32 v49, 0xffff0000, v252
	v_lshlrev_b32_e32 v50, 16, v253
	v_and_b32_e32 v51, 0xffff0000, v253
	v_pk_add_f32 v[14:15], v[14:15], v[44:45]
	v_pk_add_f32 v[16:17], v[16:17], v[46:47]
	v_pk_add_f32 v[18:19], v[18:19], v[48:49]
	v_pk_add_f32 v[12:13], v[12:13], v[50:51]
	v_pk_fma_f32 v[36:37], v[34:35], v[14:15], v[44:45] op_sel_hi:[0,1,1] neg_lo:[0,0,1] neg_hi:[0,0,1]
	v_pk_fma_f32 v[38:39], v[34:35], v[16:17], v[46:47] op_sel_hi:[0,1,1] neg_lo:[0,0,1] neg_hi:[0,0,1]
	v_pk_fma_f32 v[40:41], v[34:35], v[18:19], v[48:49] op_sel_hi:[0,1,1] neg_lo:[0,0,1] neg_hi:[0,0,1]
	v_pk_fma_f32 v[42:43], v[34:35], v[12:13], v[50:51] op_sel_hi:[0,1,1] neg_lo:[0,0,1] neg_hi:[0,0,1]
	v_cvt_pk_bf16_f32 v28, v36, v37
	v_cvt_pk_bf16_f32 v29, v38, v39
	v_cvt_pk_bf16_f32 v30, v40, v41
	v_cvt_pk_bf16_f32 v31, v42, v43
	global_store_dwordx4 v[10:11], v[28:31], off
	v_lshlrev_b32_e32 v44, 16, v188
	v_and_b32_e32 v45, 0xffff0000, v188
	v_lshlrev_b32_e32 v46, 16, v189
	v_and_b32_e32 v47, 0xffff0000, v189
	v_lshlrev_b32_e32 v48, 16, v190
	v_and_b32_e32 v49, 0xffff0000, v190
	v_lshlrev_b32_e32 v50, 16, v191
	v_and_b32_e32 v51, 0xffff0000, v191
	v_pk_add_f32 v[14:15], v[14:15], v[44:45] neg_lo:[0,1] neg_hi:[0,1]
	v_pk_add_f32 v[16:17], v[16:17], v[46:47] neg_lo:[0,1] neg_hi:[0,1]
	v_pk_add_f32 v[18:19], v[18:19], v[48:49] neg_lo:[0,1] neg_hi:[0,1]
	v_pk_add_f32 v[12:13], v[12:13], v[50:51] neg_lo:[0,1] neg_hi:[0,1]
	s_branch .LBB0_1331
.Lpw_w2:
	v_mov_b32_e32 v34, 0.5
	s_waitcnt vmcnt(0)
	v_lshlrev_b32_e32 v44, 16, v120
	v_and_b32_e32 v45, 0xffff0000, v120
	v_lshlrev_b32_e32 v46, 16, v121
	v_and_b32_e32 v47, 0xffff0000, v121
	v_lshlrev_b32_e32 v48, 16, v122
	v_and_b32_e32 v49, 0xffff0000, v122
	v_lshlrev_b32_e32 v50, 16, v123
	v_and_b32_e32 v51, 0xffff0000, v123
	v_pk_add_f32 v[14:15], v[14:15], v[44:45]
	v_pk_add_f32 v[16:17], v[16:17], v[46:47]
	v_pk_add_f32 v[18:19], v[18:19], v[48:49]
	v_pk_add_f32 v[12:13], v[12:13], v[50:51]
	v_lshlrev_b32_e32 v44, 16, v124
	v_and_b32_e32 v45, 0xffff0000, v124
	v_lshlrev_b32_e32 v46, 16, v125
	v_and_b32_e32 v47, 0xffff0000, v125
	v_lshlrev_b32_e32 v48, 16, v126
	v_and_b32_e32 v49, 0xffff0000, v126
	v_lshlrev_b32_e32 v50, 16, v127
	v_and_b32_e32 v51, 0xffff0000, v127
	v_pk_add_f32 v[14:15], v[14:15], v[44:45]
	v_pk_add_f32 v[16:17], v[16:17], v[46:47]
	v_pk_add_f32 v[18:19], v[18:19], v[48:49]
	v_pk_add_f32 v[12:13], v[12:13], v[50:51]
	v_pk_fma_f32 v[36:37], v[34:35], v[14:15], v[44:45] op_sel_hi:[0,1,1] neg_lo:[0,0,1] neg_hi:[0,0,1]
	v_pk_fma_f32 v[38:39], v[34:35], v[16:17], v[46:47] op_sel_hi:[0,1,1] neg_lo:[0,0,1] neg_hi:[0,0,1]
	v_pk_fma_f32 v[40:41], v[34:35], v[18:19], v[48:49] op_sel_hi:[0,1,1] neg_lo:[0,0,1] neg_hi:[0,0,1]
	v_pk_fma_f32 v[42:43], v[34:35], v[12:13], v[50:51] op_sel_hi:[0,1,1] neg_lo:[0,0,1] neg_hi:[0,0,1]
	v_cvt_pk_bf16_f32 v28, v36, v37
	v_cvt_pk_bf16_f32 v29, v38, v39
	v_cvt_pk_bf16_f32 v30, v40, v41
	v_cvt_pk_bf16_f32 v31, v42, v43
	global_store_dwordx4 v[10:11], v[28:31], off
	v_lshlrev_b32_e32 v44, 16, v120
	v_and_b32_e32 v45, 0xffff0000, v120
	v_lshlrev_b32_e32 v46, 16, v121
	v_and_b32_e32 v47, 0xffff0000, v121
	v_lshlrev_b32_e32 v48, 16, v122
	v_and_b32_e32 v49, 0xffff0000, v122
	v_lshlrev_b32_e32 v50, 16, v123
	v_and_b32_e32 v51, 0xffff0000, v123
	v_pk_add_f32 v[14:15], v[14:15], v[44:45] neg_lo:[0,1] neg_hi:[0,1]
	v_pk_add_f32 v[16:17], v[16:17], v[46:47] neg_lo:[0,1] neg_hi:[0,1]
	v_pk_add_f32 v[18:19], v[18:19], v[48:49] neg_lo:[0,1] neg_hi:[0,1]
	v_pk_add_f32 v[12:13], v[12:13], v[50:51] neg_lo:[0,1] neg_hi:[0,1]
	v_lshl_add_u64 v[10:11], v[10:11], 0, s[26:27]
	v_lshlrev_b32_e32 v44, 16, v128
	v_and_b32_e32 v45, 0xffff0000, v128
	v_lshlrev_b32_e32 v46, 16, v129
	v_and_b32_e32 v47, 0xffff0000, v129
	v_lshlrev_b32_e32 v48, 16, v130
	v_and_b32_e32 v49, 0xffff0000, v130
	v_lshlrev_b32_e32 v50, 16, v131
	v_and_b32_e32 v51, 0xffff0000, v131
	v_pk_add_f32 v[14:15], v[14:15], v[44:45]
	v_pk_add_f32 v[16:17], v[16:17], v[46:47]
	v_pk_add_f32 v[18:19], v[18:19], v[48:49]
	v_pk_add_f32 v[12:13], v[12:13], v[50:51]
	v_pk_fma_f32 v[36:37], v[34:35], v[14:15], v[44:45] op_sel_hi:[0,1,1] neg_lo:[0,0,1] neg_hi:[0,0,1]
	v_pk_fma_f32 v[38:39], v[34:35], v[16:17], v[46:47] op_sel_hi:[0,1,1] neg_lo:[0,0,1] neg_hi:[0,0,1]
	v_pk_fma_f32 v[40:41], v[34:35], v[18:19], v[48:49] op_sel_hi:[0,1,1] neg_lo:[0,0,1] neg_hi:[0,0,1]
; __device__ __forceinline__ unsigned pk2(float lo, float hi) { f32x2 v = {lo, hi}; bf16x2_t b = __builtin_convertvector(v, bf16x2_t); return __builtin_bit_cast(unsigned, b); }
; __device__ __forceinline__ void pool_window(const bf16_t* __restrict__ U  , bf16_t* __restrict__ A3, const int gtid, const int nthr) {
;     ...
;         for (int i = 0; i < 32; ++i) {
;             const int t = t0 + i, s = s0 + i;
;             const u32x4 uu = *(const u32x4*)(U + (size_t)t * LDU + c);
;             float cu[8] = {bflo(uu.x), bfhi(uu.x), bflo(uu.y), bfhi(uu.y), bflo(uu.z), bfhi(uu.z), bflo(uu.w), bfhi(uu.w)};
;             const float rc = 1.0f / (float)((s + 1) < w ? (s + 1) : w);
;             float o[8];
; #pragma unroll
;             for (int e = 0; e < 8; ++e) { sum[e] += cu[e]; o[e] = sum[e] * rc - cu[e]; }
;             u32x4 ww; ww.x = pk2(o[0], o[1]); ww.y = pk2(o[2], o[3]); ww.z = pk2(o[4], o[5]); ww.w = pk2(o[6], o[7]);
;             *(u32x4*)(A3 + (size_t)t * DM + c) = ww;
;             if (s + 1 >= w) { const u32x4 ud = *(const u32x4*)(U + (size_t)(t - w + 1) * LDU + c);
;                 sum[0] -= bflo(ud.x); sum[1] -= bfhi(ud.x); sum[2] -= bflo(ud.y); sum[3] -= bfhi(ud.y); sum[4] -= bflo(ud.z); sum[5] -= bfhi(ud.z); sum[6] -= bflo(ud.w); sum[7] -= bfhi(ud.w); }
	v_pk_fma_f32 v[42:43], v[34:35], v[12:13], v[50:51] op_sel_hi:[0,1,1] neg_lo:[0,0,1] neg_hi:[0,0,1]
	v_cvt_pk_bf16_f32 v28, v36, v37
	v_cvt_pk_bf16_f32 v29, v38, v39
	v_cvt_pk_bf16_f32 v30, v40, v41
	v_cvt_pk_bf16_f32 v31, v42, v43
	global_store_dwordx4 v[10:11], v[28:31], off
	v_lshlrev_b32_e32 v44, 16, v124
	v_and_b32_e32 v45, 0xffff0000, v124
	v_lshlrev_b32_e32 v46, 16, v125
	v_and_b32_e32 v47, 0xffff0000, v125
	v_lshlrev_b32_e32 v48, 16, v126
	v_and_b32_e32 v49, 0xffff0000, v126
	v_lshlrev_b32_e32 v50, 16, v127
	v_and_b32_e32 v51, 0xffff0000, v127
	v_pk_add_f32 v[14:15], v[14:15], v[44:45] neg_lo:[0,1] neg_hi:[0,1]
	v_pk_add_f32 v[16:17], v[16:17], v[46:47] neg_lo:[0,1] neg_hi:[0,1]
	v_pk_add_f32 v[18:19], v[18:19], v[48:49] neg_lo:[0,1] neg_hi:[0,1]
	v_pk_add_f32 v[12:13], v[12:13], v[50:51] neg_lo:[0,1] neg_hi:[0,1]
	v_lshl_add_u64 v[10:11], v[10:11], 0, s[26:27]
	v_lshlrev_b32_e32 v44, 16, v132
	v_and_b32_e32 v45, 0xffff0000, v132
	v_lshlrev_b32_e32 v46, 16, v133
	v_and_b32_e32 v47, 0xffff0000, v133
	v_lshlrev_b32_e32 v48, 16, v134
	v_and_b32_e32 v49, 0xffff0000, v134
	v_lshlrev_b32_e32 v50, 16, v135
	v_and_b32_e32 v51, 0xffff0000, v135
	v_pk_add_f32 v[14:15], v[14:15], v[44:45]
	v_pk_add_f32 v[16:17], v[16:17], v[46:47]
	v_pk_add_f32 v[18:19], v[18:19], v[48:49]
	v_pk_add_f32 v[12:13], v[12:13], v[50:51]
	v_pk_fma_f32 v[36:37], v[34:35], v[14:15], v[44:45] op_sel_hi:[0,1,1] neg_lo:[0,0,1] neg_hi:[0,0,1]
	v_pk_fma_f32 v[38:39], v[34:35], v[16:17], v[46:47] op_sel_hi:[0,1,1] neg_lo:[0,0,1] neg_hi:[0,0,1]
	v_pk_fma_f32 v[40:41], v[34:35], v[18:19], v[48:49] op_sel_hi:[0,1,1] neg_lo:[0,0,1] neg_hi:[0,0,1]
	v_pk_fma_f32 v[42:43], v[34:35], v[12:13], v[50:51] op_sel_hi:[0,1,1] neg_lo:[0,0,1] neg_hi:[0,0,1]
	v_cvt_pk_bf16_f32 v28, v36, v37
	v_cvt_pk_bf16_f32 v29, v38, v39
	v_cvt_pk_bf16_f32 v30, v40, v41
	v_cvt_pk_bf16_f32 v31, v42, v43
	global_store_dwordx4 v[10:11], v[28:31], off
	v_lshlrev_b32_e32 v44, 16, v128
	v_and_b32_e32 v45, 0xffff0000, v128
	v_lshlrev_b32_e32 v46, 16, v129
	v_and_b32_e32 v47, 0xffff0000, v129
	v_lshlrev_b32_e32 v48, 16, v130
	v_and_b32_e32 v49, 0xffff0000, v130
	v_lshlrev_b32_e32 v50, 16, v131
	v_and_b32_e32 v51, 0xffff0000, v131
	v_pk_add_f32 v[14:15], v[14:15], v[44:45] neg_lo:[0,1] neg_hi:[0,1]
	v_pk_add_f32 v[16:17], v[16:17], v[46:47] neg_lo:[0,1] neg_hi:[0,1]
	v_pk_add_f32 v[18:19], v[18:19], v[48:49] neg_lo:[0,1] neg_hi:[0,1]
	v_pk_add_f32 v[12:13], v[12:13], v[50:51] neg_lo:[0,1] neg_hi:[0,1]
	v_lshl_add_u64 v[10:11], v[10:11], 0, s[26:27]
	v_lshlrev_b32_e32 v44, 16, v136
	v_and_b32_e32 v45, 0xffff0000, v136
	v_lshlrev_b32_e32 v46, 16, v137
	v_and_b32_e32 v47, 0xffff0000, v137
	v_lshlrev_b32_e32 v48, 16, v138
	v_and_b32_e32 v49, 0xffff0000, v138
	v_lshlrev_b32_e32 v50, 16, v139
	v_and_b32_e32 v51, 0xffff0000, v139
	v_pk_add_f32 v[14:15], v[14:15], v[44:45]
	v_pk_add_f32 v[16:17], v[16:17], v[46:47]
	v_pk_add_f32 v[18:19], v[18:19], v[48:49]
	v_pk_add_f32 v[12:13], v[12:13], v[50:51]
	v_pk_fma_f32 v[36:37], v[34:35], v[14:15], v[44:45] op_sel_hi:[0,1,1] neg_lo:[0,0,1] neg_hi:[0,0,1]
	v_pk_fma_f32 v[38:39], v[34:35], v[16:17], v[46:47] op_sel_hi:[0,1,1] neg_lo:[0,0,1] neg_hi:[0,0,1]
	v_pk_fma_f32 v[40:41], v[34:35], v[18:19], v[48:49] op_sel_hi:[0,1,1] neg_lo:[0,0,1] neg_hi:[0,0,1]
	v_pk_fma_f32 v[42:43], v[34:35], v[12:13], v[50:51] op_sel_hi:[0,1,1] neg_lo:[0,0,1] neg_hi:[0,0,1]
	v_cvt_pk_bf16_f32 v28, v36, v37
	v_cvt_pk_bf16_f32 v29, v38, v39
	v_cvt_pk_bf16_f32 v30, v40, v41
	v_cvt_pk_bf16_f32 v31, v42, v43
	global_store_dwordx4 v[10:11], v[28:31], off
	v_lshlrev_b32_e32 v44, 16, v132
	v_and_b32_e32 v45, 0xffff0000, v132
	v_lshlrev_b32_e32 v46, 16, v133
	v_and_b32_e32 v47, 0xffff0000, v133
	v_lshlrev_b32_e32 v48, 16, v134
	v_and_b32_e32 v49, 0xffff0000, v134
	v_lshlrev_b32_e32 v50, 16, v135
	v_and_b32_e32 v51, 0xffff0000, v135
	v_pk_add_f32 v[14:15], v[14:15], v[44:45] neg_lo:[0,1] neg_hi:[0,1]
	v_pk_add_f32 v[16:17], v[16:17], v[46:47] neg_lo:[0,1] neg_hi:[0,1]
	v_pk_add_f32 v[18:19], v[18:19], v[48:49] neg_lo:[0,1] neg_hi:[0,1]
	v_pk_add_f32 v[12:13], v[12:13], v[50:51] neg_lo:[0,1] neg_hi:[0,1]
	v_lshl_add_u64 v[10:11], v[10:11], 0, s[26:27]
	v_lshlrev_b32_e32 v44, 16, v140
	v_and_b32_e32 v45, 0xffff0000, v140
	v_lshlrev_b32_e32 v46, 16, v141
	v_and_b32_e32 v47, 0xffff0000, v141
	v_lshlrev_b32_e32 v48, 16, v142
	v_and_b32_e32 v49, 0xffff0000, v142
	v_lshlrev_b32_e32 v50, 16, v143
	v_and_b32_e32 v51, 0xffff0000, v143
	v_pk_add_f32 v[14:15], v[14:15], v[44:45]
	v_pk_add_f32 v[16:17], v[16:17], v[46:47]
	v_pk_add_f32 v[18:19], v[18:19], v[48:49]
	v_pk_add_f32 v[12:13], v[12:13], v[50:51]
	v_pk_fma_f32 v[36:37], v[34:35], v[14:15], v[44:45] op_sel_hi:[0,1,1] neg_lo:[0,0,1] neg_hi:[0,0,1]
	v_pk_fma_f32 v[38:39], v[34:35], v[16:17], v[46:47] op_sel_hi:[0,1,1] neg_lo:[0,0,1] neg_hi:[0,0,1]
	v_pk_fma_f32 v[40:41], v[34:35], v[18:19], v[48:49] op_sel_hi:[0,1,1] neg_lo:[0,0,1] neg_hi:[0,0,1]
	v_pk_fma_f32 v[42:43], v[34:35], v[12:13], v[50:51] op_sel_hi:[0,1,1] neg_lo:[0,0,1] neg_hi:[0,0,1]
	v_cvt_pk_bf16_f32 v28, v36, v37
	v_cvt_pk_bf16_f32 v29, v38, v39
	v_cvt_pk_bf16_f32 v30, v40, v41
	v_cvt_pk_bf16_f32 v31, v42, v43
	global_store_dwordx4 v[10:11], v[28:31], off
	v_lshlrev_b32_e32 v44, 16, v136
	v_and_b32_e32 v45, 0xffff0000, v136
	v_lshlrev_b32_e32 v46, 16, v137
	v_and_b32_e32 v47, 0xffff0000, v137
	v_lshlrev_b32_e32 v48, 16, v138
	v_and_b32_e32 v49, 0xffff0000, v138
	v_lshlrev_b32_e32 v50, 16, v139
	v_and_b32_e32 v51, 0xffff0000, v139
	v_pk_add_f32 v[14:15], v[14:15], v[44:45] neg_lo:[0,1] neg_hi:[0,1]
	v_pk_add_f32 v[16:17], v[16:17], v[46:47] neg_lo:[0,1] neg_hi:[0,1]
; __device__ __forceinline__ unsigned pk2(float lo, float hi) { f32x2 v = {lo, hi}; bf16x2_t b = __builtin_convertvector(v, bf16x2_t); return __builtin_bit_cast(unsigned, b); }
; __device__ __forceinline__ void pool_window(const bf16_t* __restrict__ U  , bf16_t* __restrict__ A3, const int gtid, const int nthr) {
;     ...
;         for (int i = 0; i < 32; ++i) {
;             const int t = t0 + i, s = s0 + i;
;             const u32x4 uu = *(const u32x4*)(U + (size_t)t * LDU + c);
;             float cu[8] = {bflo(uu.x), bfhi(uu.x), bflo(uu.y), bfhi(uu.y), bflo(uu.z), bfhi(uu.z), bflo(uu.w), bfhi(uu.w)};
;             const float rc = 1.0f / (float)((s + 1) < w ? (s + 1) : w);
;             float o[8];
; #pragma unroll
;             for (int e = 0; e < 8; ++e) { sum[e] += cu[e]; o[e] = sum[e] * rc - cu[e]; }
;             u32x4 ww; ww.x = pk2(o[0], o[1]); ww.y = pk2(o[2], o[3]); ww.z = pk2(o[4], o[5]); ww.w = pk2(o[6], o[7]);
;             *(u32x4*)(A3 + (size_t)t * DM + c) = ww;
;             if (s + 1 >= w) { const u32x4 ud = *(const u32x4*)(U + (size_t)(t - w + 1) * LDU + c);
;                 sum[0] -= bflo(ud.x); sum[1] -= bfhi(ud.x); sum[2] -= bflo(ud.y); sum[3] -= bfhi(ud.y); sum[4] -= bflo(ud.z); sum[5] -= bfhi(ud.z); sum[6] -= bflo(ud.w); sum[7] -= bfhi(ud.w); }
	v_pk_add_f32 v[18:19], v[18:19], v[48:49] neg_lo:[0,1] neg_hi:[0,1]
	v_pk_add_f32 v[12:13], v[12:13], v[50:51] neg_lo:[0,1] neg_hi:[0,1]
	v_lshl_add_u64 v[10:11], v[10:11], 0, s[26:27]
	v_lshlrev_b32_e32 v44, 16, v144
	v_and_b32_e32 v45, 0xffff0000, v144
	v_lshlrev_b32_e32 v46, 16, v145
	v_and_b32_e32 v47, 0xffff0000, v145
	v_lshlrev_b32_e32 v48, 16, v146
	v_and_b32_e32 v49, 0xffff0000, v146
	v_lshlrev_b32_e32 v50, 16, v147
	v_and_b32_e32 v51, 0xffff0000, v147
	v_pk_add_f32 v[14:15], v[14:15], v[44:45]
	v_pk_add_f32 v[16:17], v[16:17], v[46:47]
	v_pk_add_f32 v[18:19], v[18:19], v[48:49]
	v_pk_add_f32 v[12:13], v[12:13], v[50:51]
	v_pk_fma_f32 v[36:37], v[34:35], v[14:15], v[44:45] op_sel_hi:[0,1,1] neg_lo:[0,0,1] neg_hi:[0,0,1]
	v_pk_fma_f32 v[38:39], v[34:35], v[16:17], v[46:47] op_sel_hi:[0,1,1] neg_lo:[0,0,1] neg_hi:[0,0,1]
	v_pk_fma_f32 v[40:41], v[34:35], v[18:19], v[48:49] op_sel_hi:[0,1,1] neg_lo:[0,0,1] neg_hi:[0,0,1]
	v_pk_fma_f32 v[42:43], v[34:35], v[12:13], v[50:51] op_sel_hi:[0,1,1] neg_lo:[0,0,1] neg_hi:[0,0,1]
	v_cvt_pk_bf16_f32 v28, v36, v37
	v_cvt_pk_bf16_f32 v29, v38, v39
	v_cvt_pk_bf16_f32 v30, v40, v41
	v_cvt_pk_bf16_f32 v31, v42, v43
	global_store_dwordx4 v[10:11], v[28:31], off
	v_lshlrev_b32_e32 v44, 16, v140
	v_and_b32_e32 v45, 0xffff0000, v140
	v_lshlrev_b32_e32 v46, 16, v141
	v_and_b32_e32 v47, 0xffff0000, v141
	v_lshlrev_b32_e32 v48, 16, v142
	v_and_b32_e32 v49, 0xffff0000, v142
	v_lshlrev_b32_e32 v50, 16, v143
	v_and_b32_e32 v51, 0xffff0000, v143
	v_pk_add_f32 v[14:15], v[14:15], v[44:45] neg_lo:[0,1] neg_hi:[0,1]
	v_pk_add_f32 v[16:17], v[16:17], v[46:47] neg_lo:[0,1] neg_hi:[0,1]
	v_pk_add_f32 v[18:19], v[18:19], v[48:49] neg_lo:[0,1] neg_hi:[0,1]
	v_pk_add_f32 v[12:13], v[12:13], v[50:51] neg_lo:[0,1] neg_hi:[0,1]
	v_lshl_add_u64 v[10:11], v[10:11], 0, s[26:27]
	v_lshlrev_b32_e32 v44, 16, v148
	v_and_b32_e32 v45, 0xffff0000, v148
	v_lshlrev_b32_e32 v46, 16, v149
	v_and_b32_e32 v47, 0xffff0000, v149
	v_lshlrev_b32_e32 v48, 16, v150
	v_and_b32_e32 v49, 0xffff0000, v150
	v_lshlrev_b32_e32 v50, 16, v151
	v_and_b32_e32 v51, 0xffff0000, v151
	v_pk_add_f32 v[14:15], v[14:15], v[44:45]
	v_pk_add_f32 v[16:17], v[16:17], v[46:47]
	v_pk_add_f32 v[18:19], v[18:19], v[48:49]
	v_pk_add_f32 v[12:13], v[12:13], v[50:51]
	v_pk_fma_f32 v[36:37], v[34:35], v[14:15], v[44:45] op_sel_hi:[0,1,1] neg_lo:[0,0,1] neg_hi:[0,0,1]
	v_pk_fma_f32 v[38:39], v[34:35], v[16:17], v[46:47] op_sel_hi:[0,1,1] neg_lo:[0,0,1] neg_hi:[0,0,1]
	v_pk_fma_f32 v[40:41], v[34:35], v[18:19], v[48:49] op_sel_hi:[0,1,1] neg_lo:[0,0,1] neg_hi:[0,0,1]
	v_pk_fma_f32 v[42:43], v[34:35], v[12:13], v[50:51] op_sel_hi:[0,1,1] neg_lo:[0,0,1] neg_hi:[0,0,1]
	v_cvt_pk_bf16_f32 v28, v36, v37
	v_cvt_pk_bf16_f32 v29, v38, v39
	v_cvt_pk_bf16_f32 v30, v40, v41
	v_cvt_pk_bf16_f32 v31, v42, v43
	global_store_dwordx4 v[10:11], v[28:31], off
	v_lshlrev_b32_e32 v44, 16, v144
	v_and_b32_e32 v45, 0xffff0000, v144
	v_lshlrev_b32_e32 v46, 16, v145
	v_and_b32_e32 v47, 0xffff0000, v145
	v_lshlrev_b32_e32 v48, 16, v146
	v_and_b32_e32 v49, 0xffff0000, v146
	v_lshlrev_b32_e32 v50, 16, v147
	v_and_b32_e32 v51, 0xffff0000, v147
	v_pk_add_f32 v[14:15], v[14:15], v[44:45] neg_lo:[0,1] neg_hi:[0,1]
	v_pk_add_f32 v[16:17], v[16:17], v[46:47] neg_lo:[0,1] neg_hi:[0,1]
	v_pk_add_f32 v[18:19], v[18:19], v[48:49] neg_lo:[0,1] neg_hi:[0,1]
	v_pk_add_f32 v[12:13], v[12:13], v[50:51] neg_lo:[0,1] neg_hi:[0,1]
	v_lshl_add_u64 v[10:11], v[10:11], 0, s[26:27]
	v_lshlrev_b32_e32 v44, 16, v152
	v_and_b32_e32 v45, 0xffff0000, v152
	v_lshlrev_b32_e32 v46, 16, v153
	v_and_b32_e32 v47, 0xffff0000, v153
	v_lshlrev_b32_e32 v48, 16, v154
	v_and_b32_e32 v49, 0xffff0000, v154
	v_lshlrev_b32_e32 v50, 16, v155
	v_and_b32_e32 v51, 0xffff0000, v155
	v_pk_add_f32 v[14:15], v[14:15], v[44:45]
	v_pk_add_f32 v[16:17], v[16:17], v[46:47]
	v_pk_add_f32 v[18:19], v[18:19], v[48:49]
	v_pk_add_f32 v[12:13], v[12:13], v[50:51]
	v_pk_fma_f32 v[36:37], v[34:35], v[14:15], v[44:45] op_sel_hi:[0,1,1] neg_lo:[0,0,1] neg_hi:[0,0,1]
	v_pk_fma_f32 v[38:39], v[34:35], v[16:17], v[46:47] op_sel_hi:[0,1,1] neg_lo:[0,0,1] neg_hi:[0,0,1]
	v_pk_fma_f32 v[40:41], v[34:35], v[18:19], v[48:49] op_sel_hi:[0,1,1] neg_lo:[0,0,1] neg_hi:[0,0,1]
	v_pk_fma_f32 v[42:43], v[34:35], v[12:13], v[50:51] op_sel_hi:[0,1,1] neg_lo:[0,0,1] neg_hi:[0,0,1]
	v_cvt_pk_bf16_f32 v28, v36, v37
	v_cvt_pk_bf16_f32 v29, v38, v39
	v_cvt_pk_bf16_f32 v30, v40, v41
	v_cvt_pk_bf16_f32 v31, v42, v43
	global_store_dwordx4 v[10:11], v[28:31], off
	v_lshlrev_b32_e32 v44, 16, v148
	v_and_b32_e32 v45, 0xffff0000, v148
	v_lshlrev_b32_e32 v46, 16, v149
	v_and_b32_e32 v47, 0xffff0000, v149
	v_lshlrev_b32_e32 v48, 16, v150
	v_and_b32_e32 v49, 0xffff0000, v150
	v_lshlrev_b32_e32 v50, 16, v151
	v_and_b32_e32 v51, 0xffff0000, v151
	v_pk_add_f32 v[14:15], v[14:15], v[44:45] neg_lo:[0,1] neg_hi:[0,1]
	v_pk_add_f32 v[16:17], v[16:17], v[46:47] neg_lo:[0,1] neg_hi:[0,1]
	v_pk_add_f32 v[18:19], v[18:19], v[48:49] neg_lo:[0,1] neg_hi:[0,1]
	v_pk_add_f32 v[12:13], v[12:13], v[50:51] neg_lo:[0,1] neg_hi:[0,1]
	v_lshl_add_u64 v[10:11], v[10:11], 0, s[26:27]
	v_lshlrev_b32_e32 v44, 16, v156
	v_and_b32_e32 v45, 0xffff0000, v156
	v_lshlrev_b32_e32 v46, 16, v157
	v_and_b32_e32 v47, 0xffff0000, v157
	v_lshlrev_b32_e32 v48, 16, v158
	v_and_b32_e32 v49, 0xffff0000, v158
	v_lshlrev_b32_e32 v50, 16, v159
	v_and_b32_e32 v51, 0xffff0000, v159
	v_pk_add_f32 v[14:15], v[14:15], v[44:45]
	v_pk_add_f32 v[16:17], v[16:17], v[46:47]
	v_pk_add_f32 v[18:19], v[18:19], v[48:49]
	v_pk_add_f32 v[12:13], v[12:13], v[50:51]
	v_pk_fma_f32 v[36:37], v[34:35], v[14:15], v[44:45] op_sel_hi:[0,1,1] neg_lo:[0,0,1] neg_hi:[0,0,1]
; __device__ __forceinline__ unsigned pk2(float lo, float hi) { f32x2 v = {lo, hi}; bf16x2_t b = __builtin_convertvector(v, bf16x2_t); return __builtin_bit_cast(unsigned, b); }
; __device__ __forceinline__ void pool_window(const bf16_t* __restrict__ U  , bf16_t* __restrict__ A3, const int gtid, const int nthr) {
;     ...
;         for (int i = 0; i < 32; ++i) {
;             const int t = t0 + i, s = s0 + i;
;             const u32x4 uu = *(const u32x4*)(U + (size_t)t * LDU + c);
;             float cu[8] = {bflo(uu.x), bfhi(uu.x), bflo(uu.y), bfhi(uu.y), bflo(uu.z), bfhi(uu.z), bflo(uu.w), bfhi(uu.w)};
;             const float rc = 1.0f / (float)((s + 1) < w ? (s + 1) : w);
;             float o[8];
; #pragma unroll
;             for (int e = 0; e < 8; ++e) { sum[e] += cu[e]; o[e] = sum[e] * rc - cu[e]; }
;             u32x4 ww; ww.x = pk2(o[0], o[1]); ww.y = pk2(o[2], o[3]); ww.z = pk2(o[4], o[5]); ww.w = pk2(o[6], o[7]);
;             *(u32x4*)(A3 + (size_t)t * DM + c) = ww;
;             if (s + 1 >= w) { const u32x4 ud = *(const u32x4*)(U + (size_t)(t - w + 1) * LDU + c);
;                 sum[0] -= bflo(ud.x); sum[1] -= bfhi(ud.x); sum[2] -= bflo(ud.y); sum[3] -= bfhi(ud.y); sum[4] -= bflo(ud.z); sum[5] -= bfhi(ud.z); sum[6] -= bflo(ud.w); sum[7] -= bfhi(ud.w); }
	v_pk_fma_f32 v[38:39], v[34:35], v[16:17], v[46:47] op_sel_hi:[0,1,1] neg_lo:[0,0,1] neg_hi:[0,0,1]
	v_pk_fma_f32 v[40:41], v[34:35], v[18:19], v[48:49] op_sel_hi:[0,1,1] neg_lo:[0,0,1] neg_hi:[0,0,1]
	v_pk_fma_f32 v[42:43], v[34:35], v[12:13], v[50:51] op_sel_hi:[0,1,1] neg_lo:[0,0,1] neg_hi:[0,0,1]
	v_cvt_pk_bf16_f32 v28, v36, v37
	v_cvt_pk_bf16_f32 v29, v38, v39
	v_cvt_pk_bf16_f32 v30, v40, v41
	v_cvt_pk_bf16_f32 v31, v42, v43
	global_store_dwordx4 v[10:11], v[28:31], off
	v_lshlrev_b32_e32 v44, 16, v152
	v_and_b32_e32 v45, 0xffff0000, v152
	v_lshlrev_b32_e32 v46, 16, v153
	v_and_b32_e32 v47, 0xffff0000, v153
	v_lshlrev_b32_e32 v48, 16, v154
	v_and_b32_e32 v49, 0xffff0000, v154
	v_lshlrev_b32_e32 v50, 16, v155
	v_and_b32_e32 v51, 0xffff0000, v155
	v_pk_add_f32 v[14:15], v[14:15], v[44:45] neg_lo:[0,1] neg_hi:[0,1]
	v_pk_add_f32 v[16:17], v[16:17], v[46:47] neg_lo:[0,1] neg_hi:[0,1]
	v_pk_add_f32 v[18:19], v[18:19], v[48:49] neg_lo:[0,1] neg_hi:[0,1]
	v_pk_add_f32 v[12:13], v[12:13], v[50:51] neg_lo:[0,1] neg_hi:[0,1]
	v_lshl_add_u64 v[10:11], v[10:11], 0, s[26:27]
	v_lshlrev_b32_e32 v44, 16, v160
	v_and_b32_e32 v45, 0xffff0000, v160
	v_lshlrev_b32_e32 v46, 16, v161
	v_and_b32_e32 v47, 0xffff0000, v161
	v_lshlrev_b32_e32 v48, 16, v162
	v_and_b32_e32 v49, 0xffff0000, v162
	v_lshlrev_b32_e32 v50, 16, v163
	v_and_b32_e32 v51, 0xffff0000, v163
	v_pk_add_f32 v[14:15], v[14:15], v[44:45]
	v_pk_add_f32 v[16:17], v[16:17], v[46:47]
	v_pk_add_f32 v[18:19], v[18:19], v[48:49]
	v_pk_add_f32 v[12:13], v[12:13], v[50:51]
	v_pk_fma_f32 v[36:37], v[34:35], v[14:15], v[44:45] op_sel_hi:[0,1,1] neg_lo:[0,0,1] neg_hi:[0,0,1]
	v_pk_fma_f32 v[38:39], v[34:35], v[16:17], v[46:47] op_sel_hi:[0,1,1] neg_lo:[0,0,1] neg_hi:[0,0,1]
	v_pk_fma_f32 v[40:41], v[34:35], v[18:19], v[48:49] op_sel_hi:[0,1,1] neg_lo:[0,0,1] neg_hi:[0,0,1]
	v_pk_fma_f32 v[42:43], v[34:35], v[12:13], v[50:51] op_sel_hi:[0,1,1] neg_lo:[0,0,1] neg_hi:[0,0,1]
	v_cvt_pk_bf16_f32 v28, v36, v37
	v_cvt_pk_bf16_f32 v29, v38, v39
	v_cvt_pk_bf16_f32 v30, v40, v41
	v_cvt_pk_bf16_f32 v31, v42, v43
	global_store_dwordx4 v[10:11], v[28:31], off
	v_lshlrev_b32_e32 v44, 16, v156
	v_and_b32_e32 v45, 0xffff0000, v156
	v_lshlrev_b32_e32 v46, 16, v157
	v_and_b32_e32 v47, 0xffff0000, v157
	v_lshlrev_b32_e32 v48, 16, v158
	v_and_b32_e32 v49, 0xffff0000, v158
	v_lshlrev_b32_e32 v50, 16, v159
	v_and_b32_e32 v51, 0xffff0000, v159
	v_pk_add_f32 v[14:15], v[14:15], v[44:45] neg_lo:[0,1] neg_hi:[0,1]
	v_pk_add_f32 v[16:17], v[16:17], v[46:47] neg_lo:[0,1] neg_hi:[0,1]
	v_pk_add_f32 v[18:19], v[18:19], v[48:49] neg_lo:[0,1] neg_hi:[0,1]
	v_pk_add_f32 v[12:13], v[12:13], v[50:51] neg_lo:[0,1] neg_hi:[0,1]
	v_lshl_add_u64 v[10:11], v[10:11], 0, s[26:27]
	v_lshlrev_b32_e32 v44, 16, v164
	v_and_b32_e32 v45, 0xffff0000, v164
	v_lshlrev_b32_e32 v46, 16, v165
	v_and_b32_e32 v47, 0xffff0000, v165
	v_lshlrev_b32_e32 v48, 16, v166
	v_and_b32_e32 v49, 0xffff0000, v166
	v_lshlrev_b32_e32 v50, 16, v167
	v_and_b32_e32 v51, 0xffff0000, v167
	v_pk_add_f32 v[14:15], v[14:15], v[44:45]
	v_pk_add_f32 v[16:17], v[16:17], v[46:47]
	v_pk_add_f32 v[18:19], v[18:19], v[48:49]
	v_pk_add_f32 v[12:13], v[12:13], v[50:51]
	v_pk_fma_f32 v[36:37], v[34:35], v[14:15], v[44:45] op_sel_hi:[0,1,1] neg_lo:[0,0,1] neg_hi:[0,0,1]
	v_pk_fma_f32 v[38:39], v[34:35], v[16:17], v[46:47] op_sel_hi:[0,1,1] neg_lo:[0,0,1] neg_hi:[0,0,1]
	v_pk_fma_f32 v[40:41], v[34:35], v[18:19], v[48:49] op_sel_hi:[0,1,1] neg_lo:[0,0,1] neg_hi:[0,0,1]
	v_pk_fma_f32 v[42:43], v[34:35], v[12:13], v[50:51] op_sel_hi:[0,1,1] neg_lo:[0,0,1] neg_hi:[0,0,1]
	v_cvt_pk_bf16_f32 v28, v36, v37
	v_cvt_pk_bf16_f32 v29, v38, v39
	v_cvt_pk_bf16_f32 v30, v40, v41
	v_cvt_pk_bf16_f32 v31, v42, v43
	global_store_dwordx4 v[10:11], v[28:31], off
	v_lshlrev_b32_e32 v44, 16, v160
	v_and_b32_e32 v45, 0xffff0000, v160
	v_lshlrev_b32_e32 v46, 16, v161
	v_and_b32_e32 v47, 0xffff0000, v161
	v_lshlrev_b32_e32 v48, 16, v162
	v_and_b32_e32 v49, 0xffff0000, v162
	v_lshlrev_b32_e32 v50, 16, v163
	v_and_b32_e32 v51, 0xffff0000, v163
	v_pk_add_f32 v[14:15], v[14:15], v[44:45] neg_lo:[0,1] neg_hi:[0,1]
	v_pk_add_f32 v[16:17], v[16:17], v[46:47] neg_lo:[0,1] neg_hi:[0,1]
	v_pk_add_f32 v[18:19], v[18:19], v[48:49] neg_lo:[0,1] neg_hi:[0,1]
	v_pk_add_f32 v[12:13], v[12:13], v[50:51] neg_lo:[0,1] neg_hi:[0,1]
	v_lshl_add_u64 v[10:11], v[10:11], 0, s[26:27]
	v_lshlrev_b32_e32 v44, 16, v168
	v_and_b32_e32 v45, 0xffff0000, v168
	v_lshlrev_b32_e32 v46, 16, v169
	v_and_b32_e32 v47, 0xffff0000, v169
	v_lshlrev_b32_e32 v48, 16, v170
	v_and_b32_e32 v49, 0xffff0000, v170
	v_lshlrev_b32_e32 v50, 16, v171
	v_and_b32_e32 v51, 0xffff0000, v171
	v_pk_add_f32 v[14:15], v[14:15], v[44:45]
	v_pk_add_f32 v[16:17], v[16:17], v[46:47]
	v_pk_add_f32 v[18:19], v[18:19], v[48:49]
	v_pk_add_f32 v[12:13], v[12:13], v[50:51]
	v_pk_fma_f32 v[36:37], v[34:35], v[14:15], v[44:45] op_sel_hi:[0,1,1] neg_lo:[0,0,1] neg_hi:[0,0,1]
	v_pk_fma_f32 v[38:39], v[34:35], v[16:17], v[46:47] op_sel_hi:[0,1,1] neg_lo:[0,0,1] neg_hi:[0,0,1]
	v_pk_fma_f32 v[40:41], v[34:35], v[18:19], v[48:49] op_sel_hi:[0,1,1] neg_lo:[0,0,1] neg_hi:[0,0,1]
	v_pk_fma_f32 v[42:43], v[34:35], v[12:13], v[50:51] op_sel_hi:[0,1,1] neg_lo:[0,0,1] neg_hi:[0,0,1]
	v_cvt_pk_bf16_f32 v28, v36, v37
	v_cvt_pk_bf16_f32 v29, v38, v39
	v_cvt_pk_bf16_f32 v30, v40, v41
	v_cvt_pk_bf16_f32 v31, v42, v43
	global_store_dwordx4 v[10:11], v[28:31], off
	v_lshlrev_b32_e32 v44, 16, v164
	v_and_b32_e32 v45, 0xffff0000, v164
	v_lshlrev_b32_e32 v46, 16, v165
	v_and_b32_e32 v47, 0xffff0000, v165
	v_lshlrev_b32_e32 v48, 16, v166
	v_and_b32_e32 v49, 0xffff0000, v166
	v_lshlrev_b32_e32 v50, 16, v167
; __device__ __forceinline__ unsigned pk2(float lo, float hi) { f32x2 v = {lo, hi}; bf16x2_t b = __builtin_convertvector(v, bf16x2_t); return __builtin_bit_cast(unsigned, b); }
; __device__ __forceinline__ void pool_window(const bf16_t* __restrict__ U  , bf16_t* __restrict__ A3, const int gtid, const int nthr) {
;     ...
;         for (int i = 0; i < 32; ++i) {
;             const int t = t0 + i, s = s0 + i;
;             const u32x4 uu = *(const u32x4*)(U + (size_t)t * LDU + c);
;             float cu[8] = {bflo(uu.x), bfhi(uu.x), bflo(uu.y), bfhi(uu.y), bflo(uu.z), bfhi(uu.z), bflo(uu.w), bfhi(uu.w)};
;             const float rc = 1.0f / (float)((s + 1) < w ? (s + 1) : w);
;             float o[8];
; #pragma unroll
;             for (int e = 0; e < 8; ++e) { sum[e] += cu[e]; o[e] = sum[e] * rc - cu[e]; }
;             u32x4 ww; ww.x = pk2(o[0], o[1]); ww.y = pk2(o[2], o[3]); ww.z = pk2(o[4], o[5]); ww.w = pk2(o[6], o[7]);
;             *(u32x4*)(A3 + (size_t)t * DM + c) = ww;
;             if (s + 1 >= w) { const u32x4 ud = *(const u32x4*)(U + (size_t)(t - w + 1) * LDU + c);
;                 sum[0] -= bflo(ud.x); sum[1] -= bfhi(ud.x); sum[2] -= bflo(ud.y); sum[3] -= bfhi(ud.y); sum[4] -= bflo(ud.z); sum[5] -= bfhi(ud.z); sum[6] -= bflo(ud.w); sum[7] -= bfhi(ud.w); }
	v_and_b32_e32 v51, 0xffff0000, v167
	v_pk_add_f32 v[14:15], v[14:15], v[44:45] neg_lo:[0,1] neg_hi:[0,1]
	v_pk_add_f32 v[16:17], v[16:17], v[46:47] neg_lo:[0,1] neg_hi:[0,1]
	v_pk_add_f32 v[18:19], v[18:19], v[48:49] neg_lo:[0,1] neg_hi:[0,1]
	v_pk_add_f32 v[12:13], v[12:13], v[50:51] neg_lo:[0,1] neg_hi:[0,1]
	v_lshl_add_u64 v[10:11], v[10:11], 0, s[26:27]
	v_lshlrev_b32_e32 v44, 16, v172
	v_and_b32_e32 v45, 0xffff0000, v172
	v_lshlrev_b32_e32 v46, 16, v173
	v_and_b32_e32 v47, 0xffff0000, v173
	v_lshlrev_b32_e32 v48, 16, v174
	v_and_b32_e32 v49, 0xffff0000, v174
	v_lshlrev_b32_e32 v50, 16, v175
	v_and_b32_e32 v51, 0xffff0000, v175
	v_pk_add_f32 v[14:15], v[14:15], v[44:45]
	v_pk_add_f32 v[16:17], v[16:17], v[46:47]
	v_pk_add_f32 v[18:19], v[18:19], v[48:49]
	v_pk_add_f32 v[12:13], v[12:13], v[50:51]
	v_pk_fma_f32 v[36:37], v[34:35], v[14:15], v[44:45] op_sel_hi:[0,1,1] neg_lo:[0,0,1] neg_hi:[0,0,1]
	v_pk_fma_f32 v[38:39], v[34:35], v[16:17], v[46:47] op_sel_hi:[0,1,1] neg_lo:[0,0,1] neg_hi:[0,0,1]
	v_pk_fma_f32 v[40:41], v[34:35], v[18:19], v[48:49] op_sel_hi:[0,1,1] neg_lo:[0,0,1] neg_hi:[0,0,1]
	v_pk_fma_f32 v[42:43], v[34:35], v[12:13], v[50:51] op_sel_hi:[0,1,1] neg_lo:[0,0,1] neg_hi:[0,0,1]
	v_cvt_pk_bf16_f32 v28, v36, v37
	v_cvt_pk_bf16_f32 v29, v38, v39
	v_cvt_pk_bf16_f32 v30, v40, v41
	v_cvt_pk_bf16_f32 v31, v42, v43
	global_store_dwordx4 v[10:11], v[28:31], off
	v_lshlrev_b32_e32 v44, 16, v168
	v_and_b32_e32 v45, 0xffff0000, v168
	v_lshlrev_b32_e32 v46, 16, v169
	v_and_b32_e32 v47, 0xffff0000, v169
	v_lshlrev_b32_e32 v48, 16, v170
	v_and_b32_e32 v49, 0xffff0000, v170
	v_lshlrev_b32_e32 v50, 16, v171
	v_and_b32_e32 v51, 0xffff0000, v171
	v_pk_add_f32 v[14:15], v[14:15], v[44:45] neg_lo:[0,1] neg_hi:[0,1]
	v_pk_add_f32 v[16:17], v[16:17], v[46:47] neg_lo:[0,1] neg_hi:[0,1]
	v_pk_add_f32 v[18:19], v[18:19], v[48:49] neg_lo:[0,1] neg_hi:[0,1]
	v_pk_add_f32 v[12:13], v[12:13], v[50:51] neg_lo:[0,1] neg_hi:[0,1]
	v_lshl_add_u64 v[10:11], v[10:11], 0, s[26:27]
	v_lshlrev_b32_e32 v44, 16, v176
	v_and_b32_e32 v45, 0xffff0000, v176
	v_lshlrev_b32_e32 v46, 16, v177
	v_and_b32_e32 v47, 0xffff0000, v177
	v_lshlrev_b32_e32 v48, 16, v178
	v_and_b32_e32 v49, 0xffff0000, v178
	v_lshlrev_b32_e32 v50, 16, v179
	v_and_b32_e32 v51, 0xffff0000, v179
	v_pk_add_f32 v[14:15], v[14:15], v[44:45]
	v_pk_add_f32 v[16:17], v[16:17], v[46:47]
	v_pk_add_f32 v[18:19], v[18:19], v[48:49]
	v_pk_add_f32 v[12:13], v[12:13], v[50:51]
	v_pk_fma_f32 v[36:37], v[34:35], v[14:15], v[44:45] op_sel_hi:[0,1,1] neg_lo:[0,0,1] neg_hi:[0,0,1]
	v_pk_fma_f32 v[38:39], v[34:35], v[16:17], v[46:47] op_sel_hi:[0,1,1] neg_lo:[0,0,1] neg_hi:[0,0,1]
	v_pk_fma_f32 v[40:41], v[34:35], v[18:19], v[48:49] op_sel_hi:[0,1,1] neg_lo:[0,0,1] neg_hi:[0,0,1]
	v_pk_fma_f32 v[42:43], v[34:35], v[12:13], v[50:51] op_sel_hi:[0,1,1] neg_lo:[0,0,1] neg_hi:[0,0,1]
	v_cvt_pk_bf16_f32 v28, v36, v37
	v_cvt_pk_bf16_f32 v29, v38, v39
	v_cvt_pk_bf16_f32 v30, v40, v41
	v_cvt_pk_bf16_f32 v31, v42, v43
	global_store_dwordx4 v[10:11], v[28:31], off
	v_lshlrev_b32_e32 v44, 16, v172
	v_and_b32_e32 v45, 0xffff0000, v172
	v_lshlrev_b32_e32 v46, 16, v173
	v_and_b32_e32 v47, 0xffff0000, v173
	v_lshlrev_b32_e32 v48, 16, v174
	v_and_b32_e32 v49, 0xffff0000, v174
	v_lshlrev_b32_e32 v50, 16, v175
	v_and_b32_e32 v51, 0xffff0000, v175
	v_pk_add_f32 v[14:15], v[14:15], v[44:45] neg_lo:[0,1] neg_hi:[0,1]
	v_pk_add_f32 v[16:17], v[16:17], v[46:47] neg_lo:[0,1] neg_hi:[0,1]
	v_pk_add_f32 v[18:19], v[18:19], v[48:49] neg_lo:[0,1] neg_hi:[0,1]
	v_pk_add_f32 v[12:13], v[12:13], v[50:51] neg_lo:[0,1] neg_hi:[0,1]
	v_lshl_add_u64 v[10:11], v[10:11], 0, s[26:27]
	v_lshlrev_b32_e32 v44, 16, v180
	v_and_b32_e32 v45, 0xffff0000, v180
	v_lshlrev_b32_e32 v46, 16, v181
	v_and_b32_e32 v47, 0xffff0000, v181
	v_lshlrev_b32_e32 v48, 16, v182
	v_and_b32_e32 v49, 0xffff0000, v182
	v_lshlrev_b32_e32 v50, 16, v183
	v_and_b32_e32 v51, 0xffff0000, v183
	v_pk_add_f32 v[14:15], v[14:15], v[44:45]
	v_pk_add_f32 v[16:17], v[16:17], v[46:47]
	v_pk_add_f32 v[18:19], v[18:19], v[48:49]
	v_pk_add_f32 v[12:13], v[12:13], v[50:51]
	v_pk_fma_f32 v[36:37], v[34:35], v[14:15], v[44:45] op_sel_hi:[0,1,1] neg_lo:[0,0,1] neg_hi:[0,0,1]
	v_pk_fma_f32 v[38:39], v[34:35], v[16:17], v[46:47] op_sel_hi:[0,1,1] neg_lo:[0,0,1] neg_hi:[0,0,1]
	v_pk_fma_f32 v[40:41], v[34:35], v[18:19], v[48:49] op_sel_hi:[0,1,1] neg_lo:[0,0,1] neg_hi:[0,0,1]
	v_pk_fma_f32 v[42:43], v[34:35], v[12:13], v[50:51] op_sel_hi:[0,1,1] neg_lo:[0,0,1] neg_hi:[0,0,1]
	v_cvt_pk_bf16_f32 v28, v36, v37
	v_cvt_pk_bf16_f32 v29, v38, v39
	v_cvt_pk_bf16_f32 v30, v40, v41
	v_cvt_pk_bf16_f32 v31, v42, v43
	global_store_dwordx4 v[10:11], v[28:31], off
	v_lshlrev_b32_e32 v44, 16, v176
	v_and_b32_e32 v45, 0xffff0000, v176
	v_lshlrev_b32_e32 v46, 16, v177
	v_and_b32_e32 v47, 0xffff0000, v177
	v_lshlrev_b32_e32 v48, 16, v178
	v_and_b32_e32 v49, 0xffff0000, v178
	v_lshlrev_b32_e32 v50, 16, v179
	v_and_b32_e32 v51, 0xffff0000, v179
	v_pk_add_f32 v[14:15], v[14:15], v[44:45] neg_lo:[0,1] neg_hi:[0,1]
	v_pk_add_f32 v[16:17], v[16:17], v[46:47] neg_lo:[0,1] neg_hi:[0,1]
	v_pk_add_f32 v[18:19], v[18:19], v[48:49] neg_lo:[0,1] neg_hi:[0,1]
	v_pk_add_f32 v[12:13], v[12:13], v[50:51] neg_lo:[0,1] neg_hi:[0,1]
	v_lshl_add_u64 v[10:11], v[10:11], 0, s[26:27]
	v_lshlrev_b32_e32 v44, 16, v184
	v_and_b32_e32 v45, 0xffff0000, v184
	v_lshlrev_b32_e32 v46, 16, v185
	v_and_b32_e32 v47, 0xffff0000, v185
	v_lshlrev_b32_e32 v48, 16, v186
	v_and_b32_e32 v49, 0xffff0000, v186
	v_lshlrev_b32_e32 v50, 16, v187
	v_and_b32_e32 v51, 0xffff0000, v187
	v_pk_add_f32 v[14:15], v[14:15], v[44:45]
	v_pk_add_f32 v[16:17], v[16:17], v[46:47]
; __device__ __forceinline__ unsigned pk2(float lo, float hi) { f32x2 v = {lo, hi}; bf16x2_t b = __builtin_convertvector(v, bf16x2_t); return __builtin_bit_cast(unsigned, b); }
; __device__ __forceinline__ void pool_window(const bf16_t* __restrict__ U  , bf16_t* __restrict__ A3, const int gtid, const int nthr) {
;     ...
;         for (int i = 0; i < 32; ++i) {
;             const int t = t0 + i, s = s0 + i;
;             const u32x4 uu = *(const u32x4*)(U + (size_t)t * LDU + c);
;             float cu[8] = {bflo(uu.x), bfhi(uu.x), bflo(uu.y), bfhi(uu.y), bflo(uu.z), bfhi(uu.z), bflo(uu.w), bfhi(uu.w)};
;             const float rc = 1.0f / (float)((s + 1) < w ? (s + 1) : w);
;             float o[8];
; #pragma unroll
;             for (int e = 0; e < 8; ++e) { sum[e] += cu[e]; o[e] = sum[e] * rc - cu[e]; }
;             u32x4 ww; ww.x = pk2(o[0], o[1]); ww.y = pk2(o[2], o[3]); ww.z = pk2(o[4], o[5]); ww.w = pk2(o[6], o[7]);
;             *(u32x4*)(A3 + (size_t)t * DM + c) = ww;
;             if (s + 1 >= w) { const u32x4 ud = *(const u32x4*)(U + (size_t)(t - w + 1) * LDU + c);
;                 sum[0] -= bflo(ud.x); sum[1] -= bfhi(ud.x); sum[2] -= bflo(ud.y); sum[3] -= bfhi(ud.y); sum[4] -= bflo(ud.z); sum[5] -= bfhi(ud.z); sum[6] -= bflo(ud.w); sum[7] -= bfhi(ud.w); }
	v_pk_add_f32 v[18:19], v[18:19], v[48:49]
	v_pk_add_f32 v[12:13], v[12:13], v[50:51]
	v_pk_fma_f32 v[36:37], v[34:35], v[14:15], v[44:45] op_sel_hi:[0,1,1] neg_lo:[0,0,1] neg_hi:[0,0,1]
	v_pk_fma_f32 v[38:39], v[34:35], v[16:17], v[46:47] op_sel_hi:[0,1,1] neg_lo:[0,0,1] neg_hi:[0,0,1]
	v_pk_fma_f32 v[40:41], v[34:35], v[18:19], v[48:49] op_sel_hi:[0,1,1] neg_lo:[0,0,1] neg_hi:[0,0,1]
	v_pk_fma_f32 v[42:43], v[34:35], v[12:13], v[50:51] op_sel_hi:[0,1,1] neg_lo:[0,0,1] neg_hi:[0,0,1]
	v_cvt_pk_bf16_f32 v28, v36, v37
	v_cvt_pk_bf16_f32 v29, v38, v39
	v_cvt_pk_bf16_f32 v30, v40, v41
	v_cvt_pk_bf16_f32 v31, v42, v43
	global_store_dwordx4 v[10:11], v[28:31], off
	v_lshlrev_b32_e32 v44, 16, v180
	v_and_b32_e32 v45, 0xffff0000, v180
	v_lshlrev_b32_e32 v46, 16, v181
	v_and_b32_e32 v47, 0xffff0000, v181
	v_lshlrev_b32_e32 v48, 16, v182
	v_and_b32_e32 v49, 0xffff0000, v182
	v_lshlrev_b32_e32 v50, 16, v183
	v_and_b32_e32 v51, 0xffff0000, v183
	v_pk_add_f32 v[14:15], v[14:15], v[44:45] neg_lo:[0,1] neg_hi:[0,1]
	v_pk_add_f32 v[16:17], v[16:17], v[46:47] neg_lo:[0,1] neg_hi:[0,1]
	v_pk_add_f32 v[18:19], v[18:19], v[48:49] neg_lo:[0,1] neg_hi:[0,1]
	v_pk_add_f32 v[12:13], v[12:13], v[50:51] neg_lo:[0,1] neg_hi:[0,1]
	v_lshl_add_u64 v[10:11], v[10:11], 0, s[26:27]
	v_lshlrev_b32_e32 v44, 16, v188
	v_and_b32_e32 v45, 0xffff0000, v188
	v_lshlrev_b32_e32 v46, 16, v189
	v_and_b32_e32 v47, 0xffff0000, v189
	v_lshlrev_b32_e32 v48, 16, v190
	v_and_b32_e32 v49, 0xffff0000, v190
	v_lshlrev_b32_e32 v50, 16, v191
	v_and_b32_e32 v51, 0xffff0000, v191
	v_pk_add_f32 v[14:15], v[14:15], v[44:45]
	v_pk_add_f32 v[16:17], v[16:17], v[46:47]
	v_pk_add_f32 v[18:19], v[18:19], v[48:49]
	v_pk_add_f32 v[12:13], v[12:13], v[50:51]
	v_pk_fma_f32 v[36:37], v[34:35], v[14:15], v[44:45] op_sel_hi:[0,1,1] neg_lo:[0,0,1] neg_hi:[0,0,1]
	v_pk_fma_f32 v[38:39], v[34:35], v[16:17], v[46:47] op_sel_hi:[0,1,1] neg_lo:[0,0,1] neg_hi:[0,0,1]
	v_pk_fma_f32 v[40:41], v[34:35], v[18:19], v[48:49] op_sel_hi:[0,1,1] neg_lo:[0,0,1] neg_hi:[0,0,1]
	v_pk_fma_f32 v[42:43], v[34:35], v[12:13], v[50:51] op_sel_hi:[0,1,1] neg_lo:[0,0,1] neg_hi:[0,0,1]
	v_cvt_pk_bf16_f32 v28, v36, v37
	v_cvt_pk_bf16_f32 v29, v38, v39
	v_cvt_pk_bf16_f32 v30, v40, v41
	v_cvt_pk_bf16_f32 v31, v42, v43
	global_store_dwordx4 v[10:11], v[28:31], off
	v_lshlrev_b32_e32 v44, 16, v184
	v_and_b32_e32 v45, 0xffff0000, v184
	v_lshlrev_b32_e32 v46, 16, v185
	v_and_b32_e32 v47, 0xffff0000, v185
	v_lshlrev_b32_e32 v48, 16, v186
	v_and_b32_e32 v49, 0xffff0000, v186
	v_lshlrev_b32_e32 v50, 16, v187
	v_and_b32_e32 v51, 0xffff0000, v187
	v_pk_add_f32 v[14:15], v[14:15], v[44:45] neg_lo:[0,1] neg_hi:[0,1]
	v_pk_add_f32 v[16:17], v[16:17], v[46:47] neg_lo:[0,1] neg_hi:[0,1]
	v_pk_add_f32 v[18:19], v[18:19], v[48:49] neg_lo:[0,1] neg_hi:[0,1]
	v_pk_add_f32 v[12:13], v[12:13], v[50:51] neg_lo:[0,1] neg_hi:[0,1]
	v_lshl_add_u64 v[10:11], v[10:11], 0, s[26:27]
	v_lshlrev_b32_e32 v44, 16, v192
	v_and_b32_e32 v45, 0xffff0000, v192
	v_lshlrev_b32_e32 v46, 16, v193
	v_and_b32_e32 v47, 0xffff0000, v193
	v_lshlrev_b32_e32 v48, 16, v194
	v_and_b32_e32 v49, 0xffff0000, v194
	v_lshlrev_b32_e32 v50, 16, v195
	v_and_b32_e32 v51, 0xffff0000, v195
	v_pk_add_f32 v[14:15], v[14:15], v[44:45]
	v_pk_add_f32 v[16:17], v[16:17], v[46:47]
	v_pk_add_f32 v[18:19], v[18:19], v[48:49]
	v_pk_add_f32 v[12:13], v[12:13], v[50:51]
	v_pk_fma_f32 v[36:37], v[34:35], v[14:15], v[44:45] op_sel_hi:[0,1,1] neg_lo:[0,0,1] neg_hi:[0,0,1]
	v_pk_fma_f32 v[38:39], v[34:35], v[16:17], v[46:47] op_sel_hi:[0,1,1] neg_lo:[0,0,1] neg_hi:[0,0,1]
	v_pk_fma_f32 v[40:41], v[34:35], v[18:19], v[48:49] op_sel_hi:[0,1,1] neg_lo:[0,0,1] neg_hi:[0,0,1]
	v_pk_fma_f32 v[42:43], v[34:35], v[12:13], v[50:51] op_sel_hi:[0,1,1] neg_lo:[0,0,1] neg_hi:[0,0,1]
	v_cvt_pk_bf16_f32 v28, v36, v37
	v_cvt_pk_bf16_f32 v29, v38, v39
	v_cvt_pk_bf16_f32 v30, v40, v41
	v_cvt_pk_bf16_f32 v31, v42, v43
	global_store_dwordx4 v[10:11], v[28:31], off
	v_lshlrev_b32_e32 v44, 16, v188
	v_and_b32_e32 v45, 0xffff0000, v188
	v_lshlrev_b32_e32 v46, 16, v189
	v_and_b32_e32 v47, 0xffff0000, v189
	v_lshlrev_b32_e32 v48, 16, v190
	v_and_b32_e32 v49, 0xffff0000, v190
	v_lshlrev_b32_e32 v50, 16, v191
	v_and_b32_e32 v51, 0xffff0000, v191
	v_pk_add_f32 v[14:15], v[14:15], v[44:45] neg_lo:[0,1] neg_hi:[0,1]
	v_pk_add_f32 v[16:17], v[16:17], v[46:47] neg_lo:[0,1] neg_hi:[0,1]
	v_pk_add_f32 v[18:19], v[18:19], v[48:49] neg_lo:[0,1] neg_hi:[0,1]
	v_pk_add_f32 v[12:13], v[12:13], v[50:51] neg_lo:[0,1] neg_hi:[0,1]
	v_lshl_add_u64 v[10:11], v[10:11], 0, s[26:27]
	v_lshlrev_b32_e32 v44, 16, v196
	v_and_b32_e32 v45, 0xffff0000, v196
	v_lshlrev_b32_e32 v46, 16, v197
	v_and_b32_e32 v47, 0xffff0000, v197
	v_lshlrev_b32_e32 v48, 16, v198
	v_and_b32_e32 v49, 0xffff0000, v198
	v_lshlrev_b32_e32 v50, 16, v199
	v_and_b32_e32 v51, 0xffff0000, v199
	v_pk_add_f32 v[14:15], v[14:15], v[44:45]
	v_pk_add_f32 v[16:17], v[16:17], v[46:47]
	v_pk_add_f32 v[18:19], v[18:19], v[48:49]
	v_pk_add_f32 v[12:13], v[12:13], v[50:51]
	v_pk_fma_f32 v[36:37], v[34:35], v[14:15], v[44:45] op_sel_hi:[0,1,1] neg_lo:[0,0,1] neg_hi:[0,0,1]
	v_pk_fma_f32 v[38:39], v[34:35], v[16:17], v[46:47] op_sel_hi:[0,1,1] neg_lo:[0,0,1] neg_hi:[0,0,1]
	v_pk_fma_f32 v[40:41], v[34:35], v[18:19], v[48:49] op_sel_hi:[0,1,1] neg_lo:[0,0,1] neg_hi:[0,0,1]
	v_pk_fma_f32 v[42:43], v[34:35], v[12:13], v[50:51] op_sel_hi:[0,1,1] neg_lo:[0,0,1] neg_hi:[0,0,1]
	v_cvt_pk_bf16_f32 v28, v36, v37
	v_cvt_pk_bf16_f32 v29, v38, v39
	v_cvt_pk_bf16_f32 v30, v40, v41
	v_cvt_pk_bf16_f32 v31, v42, v43
	global_store_dwordx4 v[10:11], v[28:31], off
	v_lshlrev_b32_e32 v44, 16, v192
	v_and_b32_e32 v45, 0xffff0000, v192
; __device__ __forceinline__ unsigned pk2(float lo, float hi) { f32x2 v = {lo, hi}; bf16x2_t b = __builtin_convertvector(v, bf16x2_t); return __builtin_bit_cast(unsigned, b); }
; __device__ __forceinline__ void pool_window(const bf16_t* __restrict__ U  , bf16_t* __restrict__ A3, const int gtid, const int nthr) {
;     ...
;         for (int i = 0; i < 32; ++i) {
;             const int t = t0 + i, s = s0 + i;
;             const u32x4 uu = *(const u32x4*)(U + (size_t)t * LDU + c);
;             float cu[8] = {bflo(uu.x), bfhi(uu.x), bflo(uu.y), bfhi(uu.y), bflo(uu.z), bfhi(uu.z), bflo(uu.w), bfhi(uu.w)};
;             const float rc = 1.0f / (float)((s + 1) < w ? (s + 1) : w);
;             float o[8];
; #pragma unroll
;             for (int e = 0; e < 8; ++e) { sum[e] += cu[e]; o[e] = sum[e] * rc - cu[e]; }
;             u32x4 ww; ww.x = pk2(o[0], o[1]); ww.y = pk2(o[2], o[3]); ww.z = pk2(o[4], o[5]); ww.w = pk2(o[6], o[7]);
;             *(u32x4*)(A3 + (size_t)t * DM + c) = ww;
;             if (s + 1 >= w) { const u32x4 ud = *(const u32x4*)(U + (size_t)(t - w + 1) * LDU + c);
;                 sum[0] -= bflo(ud.x); sum[1] -= bfhi(ud.x); sum[2] -= bflo(ud.y); sum[3] -= bfhi(ud.y); sum[4] -= bflo(ud.z); sum[5] -= bfhi(ud.z); sum[6] -= bflo(ud.w); sum[7] -= bfhi(ud.w); }
	v_lshlrev_b32_e32 v46, 16, v193
	v_and_b32_e32 v47, 0xffff0000, v193
	v_lshlrev_b32_e32 v48, 16, v194
	v_and_b32_e32 v49, 0xffff0000, v194
	v_lshlrev_b32_e32 v50, 16, v195
	v_and_b32_e32 v51, 0xffff0000, v195
	v_pk_add_f32 v[14:15], v[14:15], v[44:45] neg_lo:[0,1] neg_hi:[0,1]
	v_pk_add_f32 v[16:17], v[16:17], v[46:47] neg_lo:[0,1] neg_hi:[0,1]
	v_pk_add_f32 v[18:19], v[18:19], v[48:49] neg_lo:[0,1] neg_hi:[0,1]
	v_pk_add_f32 v[12:13], v[12:13], v[50:51] neg_lo:[0,1] neg_hi:[0,1]
	v_lshl_add_u64 v[10:11], v[10:11], 0, s[26:27]
	v_lshlrev_b32_e32 v44, 16, v200
	v_and_b32_e32 v45, 0xffff0000, v200
	v_lshlrev_b32_e32 v46, 16, v201
	v_and_b32_e32 v47, 0xffff0000, v201
	v_lshlrev_b32_e32 v48, 16, v202
	v_and_b32_e32 v49, 0xffff0000, v202
	v_lshlrev_b32_e32 v50, 16, v203
	v_and_b32_e32 v51, 0xffff0000, v203
	v_pk_add_f32 v[14:15], v[14:15], v[44:45]
	v_pk_add_f32 v[16:17], v[16:17], v[46:47]
	v_pk_add_f32 v[18:19], v[18:19], v[48:49]
	v_pk_add_f32 v[12:13], v[12:13], v[50:51]
	v_pk_fma_f32 v[36:37], v[34:35], v[14:15], v[44:45] op_sel_hi:[0,1,1] neg_lo:[0,0,1] neg_hi:[0,0,1]
	v_pk_fma_f32 v[38:39], v[34:35], v[16:17], v[46:47] op_sel_hi:[0,1,1] neg_lo:[0,0,1] neg_hi:[0,0,1]
	v_pk_fma_f32 v[40:41], v[34:35], v[18:19], v[48:49] op_sel_hi:[0,1,1] neg_lo:[0,0,1] neg_hi:[0,0,1]
	v_pk_fma_f32 v[42:43], v[34:35], v[12:13], v[50:51] op_sel_hi:[0,1,1] neg_lo:[0,0,1] neg_hi:[0,0,1]
	v_cvt_pk_bf16_f32 v28, v36, v37
	v_cvt_pk_bf16_f32 v29, v38, v39
	v_cvt_pk_bf16_f32 v30, v40, v41
	v_cvt_pk_bf16_f32 v31, v42, v43
	global_store_dwordx4 v[10:11], v[28:31], off
	v_lshlrev_b32_e32 v44, 16, v196
	v_and_b32_e32 v45, 0xffff0000, v196
	v_lshlrev_b32_e32 v46, 16, v197
	v_and_b32_e32 v47, 0xffff0000, v197
	v_lshlrev_b32_e32 v48, 16, v198
	v_and_b32_e32 v49, 0xffff0000, v198
	v_lshlrev_b32_e32 v50, 16, v199
	v_and_b32_e32 v51, 0xffff0000, v199
	v_pk_add_f32 v[14:15], v[14:15], v[44:45] neg_lo:[0,1] neg_hi:[0,1]
	v_pk_add_f32 v[16:17], v[16:17], v[46:47] neg_lo:[0,1] neg_hi:[0,1]
	v_pk_add_f32 v[18:19], v[18:19], v[48:49] neg_lo:[0,1] neg_hi:[0,1]
	v_pk_add_f32 v[12:13], v[12:13], v[50:51] neg_lo:[0,1] neg_hi:[0,1]
	v_lshl_add_u64 v[10:11], v[10:11], 0, s[26:27]
	v_lshlrev_b32_e32 v44, 16, v204
	v_and_b32_e32 v45, 0xffff0000, v204
	v_lshlrev_b32_e32 v46, 16, v205
	v_and_b32_e32 v47, 0xffff0000, v205
	v_lshlrev_b32_e32 v48, 16, v206
	v_and_b32_e32 v49, 0xffff0000, v206
	v_lshlrev_b32_e32 v50, 16, v207
	v_and_b32_e32 v51, 0xffff0000, v207
	v_pk_add_f32 v[14:15], v[14:15], v[44:45]
	v_pk_add_f32 v[16:17], v[16:17], v[46:47]
	v_pk_add_f32 v[18:19], v[18:19], v[48:49]
	v_pk_add_f32 v[12:13], v[12:13], v[50:51]
	v_pk_fma_f32 v[36:37], v[34:35], v[14:15], v[44:45] op_sel_hi:[0,1,1] neg_lo:[0,0,1] neg_hi:[0,0,1]
	v_pk_fma_f32 v[38:39], v[34:35], v[16:17], v[46:47] op_sel_hi:[0,1,1] neg_lo:[0,0,1] neg_hi:[0,0,1]
	v_pk_fma_f32 v[40:41], v[34:35], v[18:19], v[48:49] op_sel_hi:[0,1,1] neg_lo:[0,0,1] neg_hi:[0,0,1]
	v_pk_fma_f32 v[42:43], v[34:35], v[12:13], v[50:51] op_sel_hi:[0,1,1] neg_lo:[0,0,1] neg_hi:[0,0,1]
	v_cvt_pk_bf16_f32 v28, v36, v37
	v_cvt_pk_bf16_f32 v29, v38, v39
	v_cvt_pk_bf16_f32 v30, v40, v41
	v_cvt_pk_bf16_f32 v31, v42, v43
	global_store_dwordx4 v[10:11], v[28:31], off
	v_lshlrev_b32_e32 v44, 16, v200
	v_and_b32_e32 v45, 0xffff0000, v200
	v_lshlrev_b32_e32 v46, 16, v201
	v_and_b32_e32 v47, 0xffff0000, v201
	v_lshlrev_b32_e32 v48, 16, v202
	v_and_b32_e32 v49, 0xffff0000, v202
	v_lshlrev_b32_e32 v50, 16, v203
	v_and_b32_e32 v51, 0xffff0000, v203
	v_pk_add_f32 v[14:15], v[14:15], v[44:45] neg_lo:[0,1] neg_hi:[0,1]
	v_pk_add_f32 v[16:17], v[16:17], v[46:47] neg_lo:[0,1] neg_hi:[0,1]
	v_pk_add_f32 v[18:19], v[18:19], v[48:49] neg_lo:[0,1] neg_hi:[0,1]
	v_pk_add_f32 v[12:13], v[12:13], v[50:51] neg_lo:[0,1] neg_hi:[0,1]
	v_lshl_add_u64 v[10:11], v[10:11], 0, s[26:27]
	v_lshlrev_b32_e32 v44, 16, v208
	v_and_b32_e32 v45, 0xffff0000, v208
	v_lshlrev_b32_e32 v46, 16, v209
	v_and_b32_e32 v47, 0xffff0000, v209
	v_lshlrev_b32_e32 v48, 16, v210
	v_and_b32_e32 v49, 0xffff0000, v210
	v_lshlrev_b32_e32 v50, 16, v211
	v_and_b32_e32 v51, 0xffff0000, v211
	v_pk_add_f32 v[14:15], v[14:15], v[44:45]
	v_pk_add_f32 v[16:17], v[16:17], v[46:47]
	v_pk_add_f32 v[18:19], v[18:19], v[48:49]
	v_pk_add_f32 v[12:13], v[12:13], v[50:51]
	v_pk_fma_f32 v[36:37], v[34:35], v[14:15], v[44:45] op_sel_hi:[0,1,1] neg_lo:[0,0,1] neg_hi:[0,0,1]
	v_pk_fma_f32 v[38:39], v[34:35], v[16:17], v[46:47] op_sel_hi:[0,1,1] neg_lo:[0,0,1] neg_hi:[0,0,1]
	v_pk_fma_f32 v[40:41], v[34:35], v[18:19], v[48:49] op_sel_hi:[0,1,1] neg_lo:[0,0,1] neg_hi:[0,0,1]
	v_pk_fma_f32 v[42:43], v[34:35], v[12:13], v[50:51] op_sel_hi:[0,1,1] neg_lo:[0,0,1] neg_hi:[0,0,1]
	v_cvt_pk_bf16_f32 v28, v36, v37
	v_cvt_pk_bf16_f32 v29, v38, v39
	v_cvt_pk_bf16_f32 v30, v40, v41
	v_cvt_pk_bf16_f32 v31, v42, v43
	global_store_dwordx4 v[10:11], v[28:31], off
	v_lshlrev_b32_e32 v44, 16, v204
	v_and_b32_e32 v45, 0xffff0000, v204
	v_lshlrev_b32_e32 v46, 16, v205
	v_and_b32_e32 v47, 0xffff0000, v205
	v_lshlrev_b32_e32 v48, 16, v206
	v_and_b32_e32 v49, 0xffff0000, v206
	v_lshlrev_b32_e32 v50, 16, v207
	v_and_b32_e32 v51, 0xffff0000, v207
	v_pk_add_f32 v[14:15], v[14:15], v[44:45] neg_lo:[0,1] neg_hi:[0,1]
	v_pk_add_f32 v[16:17], v[16:17], v[46:47] neg_lo:[0,1] neg_hi:[0,1]
	v_pk_add_f32 v[18:19], v[18:19], v[48:49] neg_lo:[0,1] neg_hi:[0,1]
	v_pk_add_f32 v[12:13], v[12:13], v[50:51] neg_lo:[0,1] neg_hi:[0,1]
	v_lshl_add_u64 v[10:11], v[10:11], 0, s[26:27]
	v_lshlrev_b32_e32 v44, 16, v214
	v_and_b32_e32 v45, 0xffff0000, v214
	v_lshlrev_b32_e32 v46, 16, v215
	v_and_b32_e32 v47, 0xffff0000, v215
	v_lshlrev_b32_e32 v48, 16, v216
	v_and_b32_e32 v49, 0xffff0000, v216
; __device__ __forceinline__ unsigned pk2(float lo, float hi) { f32x2 v = {lo, hi}; bf16x2_t b = __builtin_convertvector(v, bf16x2_t); return __builtin_bit_cast(unsigned, b); }
; __device__ __forceinline__ void pool_window(const bf16_t* __restrict__ U  , bf16_t* __restrict__ A3, const int gtid, const int nthr) {
;     ...
;         for (int i = 0; i < 32; ++i) {
;             const int t = t0 + i, s = s0 + i;
;             const u32x4 uu = *(const u32x4*)(U + (size_t)t * LDU + c);
;             float cu[8] = {bflo(uu.x), bfhi(uu.x), bflo(uu.y), bfhi(uu.y), bflo(uu.z), bfhi(uu.z), bflo(uu.w), bfhi(uu.w)};
;             const float rc = 1.0f / (float)((s + 1) < w ? (s + 1) : w);
;             float o[8];
; #pragma unroll
;             for (int e = 0; e < 8; ++e) { sum[e] += cu[e]; o[e] = sum[e] * rc - cu[e]; }
;             u32x4 ww; ww.x = pk2(o[0], o[1]); ww.y = pk2(o[2], o[3]); ww.z = pk2(o[4], o[5]); ww.w = pk2(o[6], o[7]);
;             *(u32x4*)(A3 + (size_t)t * DM + c) = ww;
;             if (s + 1 >= w) { const u32x4 ud = *(const u32x4*)(U + (size_t)(t - w + 1) * LDU + c);
;                 sum[0] -= bflo(ud.x); sum[1] -= bfhi(ud.x); sum[2] -= bflo(ud.y); sum[3] -= bfhi(ud.y); sum[4] -= bflo(ud.z); sum[5] -= bfhi(ud.z); sum[6] -= bflo(ud.w); sum[7] -= bfhi(ud.w); }
	v_lshlrev_b32_e32 v50, 16, v217
	v_and_b32_e32 v51, 0xffff0000, v217
	v_pk_add_f32 v[14:15], v[14:15], v[44:45]
	v_pk_add_f32 v[16:17], v[16:17], v[46:47]
	v_pk_add_f32 v[18:19], v[18:19], v[48:49]
	v_pk_add_f32 v[12:13], v[12:13], v[50:51]
	v_pk_fma_f32 v[36:37], v[34:35], v[14:15], v[44:45] op_sel_hi:[0,1,1] neg_lo:[0,0,1] neg_hi:[0,0,1]
	v_pk_fma_f32 v[38:39], v[34:35], v[16:17], v[46:47] op_sel_hi:[0,1,1] neg_lo:[0,0,1] neg_hi:[0,0,1]
	v_pk_fma_f32 v[40:41], v[34:35], v[18:19], v[48:49] op_sel_hi:[0,1,1] neg_lo:[0,0,1] neg_hi:[0,0,1]
	v_pk_fma_f32 v[42:43], v[34:35], v[12:13], v[50:51] op_sel_hi:[0,1,1] neg_lo:[0,0,1] neg_hi:[0,0,1]
	v_cvt_pk_bf16_f32 v28, v36, v37
	v_cvt_pk_bf16_f32 v29, v38, v39
	v_cvt_pk_bf16_f32 v30, v40, v41
	v_cvt_pk_bf16_f32 v31, v42, v43
	global_store_dwordx4 v[10:11], v[28:31], off
	v_lshlrev_b32_e32 v44, 16, v208
	v_and_b32_e32 v45, 0xffff0000, v208
	v_lshlrev_b32_e32 v46, 16, v209
	v_and_b32_e32 v47, 0xffff0000, v209
	v_lshlrev_b32_e32 v48, 16, v210
	v_and_b32_e32 v49, 0xffff0000, v210
	v_lshlrev_b32_e32 v50, 16, v211
	v_and_b32_e32 v51, 0xffff0000, v211
	v_pk_add_f32 v[14:15], v[14:15], v[44:45] neg_lo:[0,1] neg_hi:[0,1]
	v_pk_add_f32 v[16:17], v[16:17], v[46:47] neg_lo:[0,1] neg_hi:[0,1]
	v_pk_add_f32 v[18:19], v[18:19], v[48:49] neg_lo:[0,1] neg_hi:[0,1]
	v_pk_add_f32 v[12:13], v[12:13], v[50:51] neg_lo:[0,1] neg_hi:[0,1]
	v_lshl_add_u64 v[10:11], v[10:11], 0, s[26:27]
	v_lshlrev_b32_e32 v44, 16, v218
	v_and_b32_e32 v45, 0xffff0000, v218
	v_lshlrev_b32_e32 v46, 16, v219
	v_and_b32_e32 v47, 0xffff0000, v219
	v_lshlrev_b32_e32 v48, 16, v220
	v_and_b32_e32 v49, 0xffff0000, v220
	v_lshlrev_b32_e32 v50, 16, v221
	v_and_b32_e32 v51, 0xffff0000, v221
	v_pk_add_f32 v[14:15], v[14:15], v[44:45]
	v_pk_add_f32 v[16:17], v[16:17], v[46:47]
	v_pk_add_f32 v[18:19], v[18:19], v[48:49]
	v_pk_add_f32 v[12:13], v[12:13], v[50:51]
	v_pk_fma_f32 v[36:37], v[34:35], v[14:15], v[44:45] op_sel_hi:[0,1,1] neg_lo:[0,0,1] neg_hi:[0,0,1]
	v_pk_fma_f32 v[38:39], v[34:35], v[16:17], v[46:47] op_sel_hi:[0,1,1] neg_lo:[0,0,1] neg_hi:[0,0,1]
	v_pk_fma_f32 v[40:41], v[34:35], v[18:19], v[48:49] op_sel_hi:[0,1,1] neg_lo:[0,0,1] neg_hi:[0,0,1]
	v_pk_fma_f32 v[42:43], v[34:35], v[12:13], v[50:51] op_sel_hi:[0,1,1] neg_lo:[0,0,1] neg_hi:[0,0,1]
	v_cvt_pk_bf16_f32 v28, v36, v37
	v_cvt_pk_bf16_f32 v29, v38, v39
	v_cvt_pk_bf16_f32 v30, v40, v41
	v_cvt_pk_bf16_f32 v31, v42, v43
	global_store_dwordx4 v[10:11], v[28:31], off
	v_lshlrev_b32_e32 v44, 16, v214
	v_and_b32_e32 v45, 0xffff0000, v214
	v_lshlrev_b32_e32 v46, 16, v215
	v_and_b32_e32 v47, 0xffff0000, v215
	v_lshlrev_b32_e32 v48, 16, v216
	v_and_b32_e32 v49, 0xffff0000, v216
	v_lshlrev_b32_e32 v50, 16, v217
	v_and_b32_e32 v51, 0xffff0000, v217
	v_pk_add_f32 v[14:15], v[14:15], v[44:45] neg_lo:[0,1] neg_hi:[0,1]
	v_pk_add_f32 v[16:17], v[16:17], v[46:47] neg_lo:[0,1] neg_hi:[0,1]
	v_pk_add_f32 v[18:19], v[18:19], v[48:49] neg_lo:[0,1] neg_hi:[0,1]
	v_pk_add_f32 v[12:13], v[12:13], v[50:51] neg_lo:[0,1] neg_hi:[0,1]
	v_lshl_add_u64 v[10:11], v[10:11], 0, s[26:27]
	v_lshlrev_b32_e32 v44, 16, v222
	v_and_b32_e32 v45, 0xffff0000, v222
	v_lshlrev_b32_e32 v46, 16, v223
	v_and_b32_e32 v47, 0xffff0000, v223
	v_lshlrev_b32_e32 v48, 16, v224
	v_and_b32_e32 v49, 0xffff0000, v224
	v_lshlrev_b32_e32 v50, 16, v225
	v_and_b32_e32 v51, 0xffff0000, v225
	v_pk_add_f32 v[14:15], v[14:15], v[44:45]
	v_pk_add_f32 v[16:17], v[16:17], v[46:47]
	v_pk_add_f32 v[18:19], v[18:19], v[48:49]
	v_pk_add_f32 v[12:13], v[12:13], v[50:51]
	v_pk_fma_f32 v[36:37], v[34:35], v[14:15], v[44:45] op_sel_hi:[0,1,1] neg_lo:[0,0,1] neg_hi:[0,0,1]
	v_pk_fma_f32 v[38:39], v[34:35], v[16:17], v[46:47] op_sel_hi:[0,1,1] neg_lo:[0,0,1] neg_hi:[0,0,1]
	v_pk_fma_f32 v[40:41], v[34:35], v[18:19], v[48:49] op_sel_hi:[0,1,1] neg_lo:[0,0,1] neg_hi:[0,0,1]
	v_pk_fma_f32 v[42:43], v[34:35], v[12:13], v[50:51] op_sel_hi:[0,1,1] neg_lo:[0,0,1] neg_hi:[0,0,1]
	v_cvt_pk_bf16_f32 v28, v36, v37
	v_cvt_pk_bf16_f32 v29, v38, v39
	v_cvt_pk_bf16_f32 v30, v40, v41
	v_cvt_pk_bf16_f32 v31, v42, v43
	global_store_dwordx4 v[10:11], v[28:31], off
	v_lshlrev_b32_e32 v44, 16, v218
	v_and_b32_e32 v45, 0xffff0000, v218
	v_lshlrev_b32_e32 v46, 16, v219
	v_and_b32_e32 v47, 0xffff0000, v219
	v_lshlrev_b32_e32 v48, 16, v220
	v_and_b32_e32 v49, 0xffff0000, v220
	v_lshlrev_b32_e32 v50, 16, v221
	v_and_b32_e32 v51, 0xffff0000, v221
	v_pk_add_f32 v[14:15], v[14:15], v[44:45] neg_lo:[0,1] neg_hi:[0,1]
	v_pk_add_f32 v[16:17], v[16:17], v[46:47] neg_lo:[0,1] neg_hi:[0,1]
	v_pk_add_f32 v[18:19], v[18:19], v[48:49] neg_lo:[0,1] neg_hi:[0,1]
	v_pk_add_f32 v[12:13], v[12:13], v[50:51] neg_lo:[0,1] neg_hi:[0,1]
	v_lshl_add_u64 v[10:11], v[10:11], 0, s[26:27]
	v_lshlrev_b32_e32 v44, 16, v226
	v_and_b32_e32 v45, 0xffff0000, v226
	v_lshlrev_b32_e32 v46, 16, v227
	v_and_b32_e32 v47, 0xffff0000, v227
	v_lshlrev_b32_e32 v48, 16, v228
	v_and_b32_e32 v49, 0xffff0000, v228
	v_lshlrev_b32_e32 v50, 16, v229
	v_and_b32_e32 v51, 0xffff0000, v229
	v_pk_add_f32 v[14:15], v[14:15], v[44:45]
	v_pk_add_f32 v[16:17], v[16:17], v[46:47]
	v_pk_add_f32 v[18:19], v[18:19], v[48:49]
	v_pk_add_f32 v[12:13], v[12:13], v[50:51]
	v_pk_fma_f32 v[36:37], v[34:35], v[14:15], v[44:45] op_sel_hi:[0,1,1] neg_lo:[0,0,1] neg_hi:[0,0,1]
	v_pk_fma_f32 v[38:39], v[34:35], v[16:17], v[46:47] op_sel_hi:[0,1,1] neg_lo:[0,0,1] neg_hi:[0,0,1]
	v_pk_fma_f32 v[40:41], v[34:35], v[18:19], v[48:49] op_sel_hi:[0,1,1] neg_lo:[0,0,1] neg_hi:[0,0,1]
	v_pk_fma_f32 v[42:43], v[34:35], v[12:13], v[50:51] op_sel_hi:[0,1,1] neg_lo:[0,0,1] neg_hi:[0,0,1]
	v_cvt_pk_bf16_f32 v28, v36, v37
	v_cvt_pk_bf16_f32 v29, v38, v39
; __device__ __forceinline__ unsigned pk2(float lo, float hi) { f32x2 v = {lo, hi}; bf16x2_t b = __builtin_convertvector(v, bf16x2_t); return __builtin_bit_cast(unsigned, b); }
; __device__ __forceinline__ void pool_window(const bf16_t* __restrict__ U  , bf16_t* __restrict__ A3, const int gtid, const int nthr) {
;     ...
;         for (int i = 0; i < 32; ++i) {
;             const int t = t0 + i, s = s0 + i;
;             const u32x4 uu = *(const u32x4*)(U + (size_t)t * LDU + c);
;             float cu[8] = {bflo(uu.x), bfhi(uu.x), bflo(uu.y), bfhi(uu.y), bflo(uu.z), bfhi(uu.z), bflo(uu.w), bfhi(uu.w)};
;             const float rc = 1.0f / (float)((s + 1) < w ? (s + 1) : w);
;             float o[8];
; #pragma unroll
;             for (int e = 0; e < 8; ++e) { sum[e] += cu[e]; o[e] = sum[e] * rc - cu[e]; }
;             u32x4 ww; ww.x = pk2(o[0], o[1]); ww.y = pk2(o[2], o[3]); ww.z = pk2(o[4], o[5]); ww.w = pk2(o[6], o[7]);
;             *(u32x4*)(A3 + (size_t)t * DM + c) = ww;
;             if (s + 1 >= w) { const u32x4 ud = *(const u32x4*)(U + (size_t)(t - w + 1) * LDU + c);
;                 sum[0] -= bflo(ud.x); sum[1] -= bfhi(ud.x); sum[2] -= bflo(ud.y); sum[3] -= bfhi(ud.y); sum[4] -= bflo(ud.z); sum[5] -= bfhi(ud.z); sum[6] -= bflo(ud.w); sum[7] -= bfhi(ud.w); }
	v_cvt_pk_bf16_f32 v30, v40, v41
	v_cvt_pk_bf16_f32 v31, v42, v43
	global_store_dwordx4 v[10:11], v[28:31], off
	v_lshlrev_b32_e32 v44, 16, v222
	v_and_b32_e32 v45, 0xffff0000, v222
	v_lshlrev_b32_e32 v46, 16, v223
	v_and_b32_e32 v47, 0xffff0000, v223
	v_lshlrev_b32_e32 v48, 16, v224
	v_and_b32_e32 v49, 0xffff0000, v224
	v_lshlrev_b32_e32 v50, 16, v225
	v_and_b32_e32 v51, 0xffff0000, v225
	v_pk_add_f32 v[14:15], v[14:15], v[44:45] neg_lo:[0,1] neg_hi:[0,1]
	v_pk_add_f32 v[16:17], v[16:17], v[46:47] neg_lo:[0,1] neg_hi:[0,1]
	v_pk_add_f32 v[18:19], v[18:19], v[48:49] neg_lo:[0,1] neg_hi:[0,1]
	v_pk_add_f32 v[12:13], v[12:13], v[50:51] neg_lo:[0,1] neg_hi:[0,1]
	v_lshl_add_u64 v[10:11], v[10:11], 0, s[26:27]
	v_lshlrev_b32_e32 v44, 16, v230
	v_and_b32_e32 v45, 0xffff0000, v230
	v_lshlrev_b32_e32 v46, 16, v231
	v_and_b32_e32 v47, 0xffff0000, v231
	v_lshlrev_b32_e32 v48, 16, v232
	v_and_b32_e32 v49, 0xffff0000, v232
	v_lshlrev_b32_e32 v50, 16, v233
	v_and_b32_e32 v51, 0xffff0000, v233
	v_pk_add_f32 v[14:15], v[14:15], v[44:45]
	v_pk_add_f32 v[16:17], v[16:17], v[46:47]
	v_pk_add_f32 v[18:19], v[18:19], v[48:49]
	v_pk_add_f32 v[12:13], v[12:13], v[50:51]
	v_pk_fma_f32 v[36:37], v[34:35], v[14:15], v[44:45] op_sel_hi:[0,1,1] neg_lo:[0,0,1] neg_hi:[0,0,1]
	v_pk_fma_f32 v[38:39], v[34:35], v[16:17], v[46:47] op_sel_hi:[0,1,1] neg_lo:[0,0,1] neg_hi:[0,0,1]
	v_pk_fma_f32 v[40:41], v[34:35], v[18:19], v[48:49] op_sel_hi:[0,1,1] neg_lo:[0,0,1] neg_hi:[0,0,1]
	v_pk_fma_f32 v[42:43], v[34:35], v[12:13], v[50:51] op_sel_hi:[0,1,1] neg_lo:[0,0,1] neg_hi:[0,0,1]
	v_cvt_pk_bf16_f32 v28, v36, v37
	v_cvt_pk_bf16_f32 v29, v38, v39
	v_cvt_pk_bf16_f32 v30, v40, v41
	v_cvt_pk_bf16_f32 v31, v42, v43
	global_store_dwordx4 v[10:11], v[28:31], off
	v_lshlrev_b32_e32 v44, 16, v226
	v_and_b32_e32 v45, 0xffff0000, v226
	v_lshlrev_b32_e32 v46, 16, v227
	v_and_b32_e32 v47, 0xffff0000, v227
	v_lshlrev_b32_e32 v48, 16, v228
	v_and_b32_e32 v49, 0xffff0000, v228
	v_lshlrev_b32_e32 v50, 16, v229
	v_and_b32_e32 v51, 0xffff0000, v229
	v_pk_add_f32 v[14:15], v[14:15], v[44:45] neg_lo:[0,1] neg_hi:[0,1]
	v_pk_add_f32 v[16:17], v[16:17], v[46:47] neg_lo:[0,1] neg_hi:[0,1]
	v_pk_add_f32 v[18:19], v[18:19], v[48:49] neg_lo:[0,1] neg_hi:[0,1]
	v_pk_add_f32 v[12:13], v[12:13], v[50:51] neg_lo:[0,1] neg_hi:[0,1]
	v_lshl_add_u64 v[10:11], v[10:11], 0, s[26:27]
	v_lshlrev_b32_e32 v44, 16, v234
	v_and_b32_e32 v45, 0xffff0000, v234
	v_lshlrev_b32_e32 v46, 16, v235
	v_and_b32_e32 v47, 0xffff0000, v235
	v_lshlrev_b32_e32 v48, 16, v236
	v_and_b32_e32 v49, 0xffff0000, v236
	v_lshlrev_b32_e32 v50, 16, v237
	v_and_b32_e32 v51, 0xffff0000, v237
	v_pk_add_f32 v[14:15], v[14:15], v[44:45]
	v_pk_add_f32 v[16:17], v[16:17], v[46:47]
	v_pk_add_f32 v[18:19], v[18:19], v[48:49]
	v_pk_add_f32 v[12:13], v[12:13], v[50:51]
	v_pk_fma_f32 v[36:37], v[34:35], v[14:15], v[44:45] op_sel_hi:[0,1,1] neg_lo:[0,0,1] neg_hi:[0,0,1]
	v_pk_fma_f32 v[38:39], v[34:35], v[16:17], v[46:47] op_sel_hi:[0,1,1] neg_lo:[0,0,1] neg_hi:[0,0,1]
	v_pk_fma_f32 v[40:41], v[34:35], v[18:19], v[48:49] op_sel_hi:[0,1,1] neg_lo:[0,0,1] neg_hi:[0,0,1]
	v_pk_fma_f32 v[42:43], v[34:35], v[12:13], v[50:51] op_sel_hi:[0,1,1] neg_lo:[0,0,1] neg_hi:[0,0,1]
	v_cvt_pk_bf16_f32 v28, v36, v37
	v_cvt_pk_bf16_f32 v29, v38, v39
	v_cvt_pk_bf16_f32 v30, v40, v41
	v_cvt_pk_bf16_f32 v31, v42, v43
	global_store_dwordx4 v[10:11], v[28:31], off
	v_lshlrev_b32_e32 v44, 16, v230
	v_and_b32_e32 v45, 0xffff0000, v230
	v_lshlrev_b32_e32 v46, 16, v231
	v_and_b32_e32 v47, 0xffff0000, v231
	v_lshlrev_b32_e32 v48, 16, v232
	v_and_b32_e32 v49, 0xffff0000, v232
	v_lshlrev_b32_e32 v50, 16, v233
	v_and_b32_e32 v51, 0xffff0000, v233
	v_pk_add_f32 v[14:15], v[14:15], v[44:45] neg_lo:[0,1] neg_hi:[0,1]
	v_pk_add_f32 v[16:17], v[16:17], v[46:47] neg_lo:[0,1] neg_hi:[0,1]
	v_pk_add_f32 v[18:19], v[18:19], v[48:49] neg_lo:[0,1] neg_hi:[0,1]
	v_pk_add_f32 v[12:13], v[12:13], v[50:51] neg_lo:[0,1] neg_hi:[0,1]
	v_lshl_add_u64 v[10:11], v[10:11], 0, s[26:27]
	v_lshlrev_b32_e32 v44, 16, v238
	v_and_b32_e32 v45, 0xffff0000, v238
	v_lshlrev_b32_e32 v46, 16, v239
	v_and_b32_e32 v47, 0xffff0000, v239
	v_lshlrev_b32_e32 v48, 16, v240
	v_and_b32_e32 v49, 0xffff0000, v240
	v_lshlrev_b32_e32 v50, 16, v241
	v_and_b32_e32 v51, 0xffff0000, v241
	v_pk_add_f32 v[14:15], v[14:15], v[44:45]
	v_pk_add_f32 v[16:17], v[16:17], v[46:47]
	v_pk_add_f32 v[18:19], v[18:19], v[48:49]
	v_pk_add_f32 v[12:13], v[12:13], v[50:51]
	v_pk_fma_f32 v[36:37], v[34:35], v[14:15], v[44:45] op_sel_hi:[0,1,1] neg_lo:[0,0,1] neg_hi:[0,0,1]
	v_pk_fma_f32 v[38:39], v[34:35], v[16:17], v[46:47] op_sel_hi:[0,1,1] neg_lo:[0,0,1] neg_hi:[0,0,1]
	v_pk_fma_f32 v[40:41], v[34:35], v[18:19], v[48:49] op_sel_hi:[0,1,1] neg_lo:[0,0,1] neg_hi:[0,0,1]
	v_pk_fma_f32 v[42:43], v[34:35], v[12:13], v[50:51] op_sel_hi:[0,1,1] neg_lo:[0,0,1] neg_hi:[0,0,1]
	v_cvt_pk_bf16_f32 v28, v36, v37
	v_cvt_pk_bf16_f32 v29, v38, v39
	v_cvt_pk_bf16_f32 v30, v40, v41
	v_cvt_pk_bf16_f32 v31, v42, v43
	global_store_dwordx4 v[10:11], v[28:31], off
	v_lshlrev_b32_e32 v44, 16, v234
	v_and_b32_e32 v45, 0xffff0000, v234
	v_lshlrev_b32_e32 v46, 16, v235
	v_and_b32_e32 v47, 0xffff0000, v235
	v_lshlrev_b32_e32 v48, 16, v236
	v_and_b32_e32 v49, 0xffff0000, v236
	v_lshlrev_b32_e32 v50, 16, v237
	v_and_b32_e32 v51, 0xffff0000, v237
	v_pk_add_f32 v[14:15], v[14:15], v[44:45] neg_lo:[0,1] neg_hi:[0,1]
	v_pk_add_f32 v[16:17], v[16:17], v[46:47] neg_lo:[0,1] neg_hi:[0,1]
	v_pk_add_f32 v[18:19], v[18:19], v[48:49] neg_lo:[0,1] neg_hi:[0,1]
	v_pk_add_f32 v[12:13], v[12:13], v[50:51] neg_lo:[0,1] neg_hi:[0,1]
	v_lshl_add_u64 v[10:11], v[10:11], 0, s[26:27]
; __device__ __forceinline__ unsigned pk2(float lo, float hi) { f32x2 v = {lo, hi}; bf16x2_t b = __builtin_convertvector(v, bf16x2_t); return __builtin_bit_cast(unsigned, b); }
; __device__ __forceinline__ void pool_window(const bf16_t* __restrict__ U  , bf16_t* __restrict__ A3, const int gtid, const int nthr) {
;     ...
;         for (int i = 0; i < 32; ++i) {
;             const int t = t0 + i, s = s0 + i;
;             const u32x4 uu = *(const u32x4*)(U + (size_t)t * LDU + c);
;             float cu[8] = {bflo(uu.x), bfhi(uu.x), bflo(uu.y), bfhi(uu.y), bflo(uu.z), bfhi(uu.z), bflo(uu.w), bfhi(uu.w)};
;             const float rc = 1.0f / (float)((s + 1) < w ? (s + 1) : w);
;             float o[8];
; #pragma unroll
;             for (int e = 0; e < 8; ++e) { sum[e] += cu[e]; o[e] = sum[e] * rc - cu[e]; }
;             u32x4 ww; ww.x = pk2(o[0], o[1]); ww.y = pk2(o[2], o[3]); ww.z = pk2(o[4], o[5]); ww.w = pk2(o[6], o[7]);
;             *(u32x4*)(A3 + (size_t)t * DM + c) = ww;
;             if (s + 1 >= w) { const u32x4 ud = *(const u32x4*)(U + (size_t)(t - w + 1) * LDU + c);
;                 sum[0] -= bflo(ud.x); sum[1] -= bfhi(ud.x); sum[2] -= bflo(ud.y); sum[3] -= bfhi(ud.y); sum[4] -= bflo(ud.z); sum[5] -= bfhi(ud.z); sum[6] -= bflo(ud.w); sum[7] -= bfhi(ud.w); }
	v_lshlrev_b32_e32 v44, 16, v242
	v_and_b32_e32 v45, 0xffff0000, v242
	v_lshlrev_b32_e32 v46, 16, v243
	v_and_b32_e32 v47, 0xffff0000, v243
	v_lshlrev_b32_e32 v48, 16, v244
	v_and_b32_e32 v49, 0xffff0000, v244
	v_lshlrev_b32_e32 v50, 16, v245
	v_and_b32_e32 v51, 0xffff0000, v245
	v_pk_add_f32 v[14:15], v[14:15], v[44:45]
	v_pk_add_f32 v[16:17], v[16:17], v[46:47]
	v_pk_add_f32 v[18:19], v[18:19], v[48:49]
	v_pk_add_f32 v[12:13], v[12:13], v[50:51]
	v_pk_fma_f32 v[36:37], v[34:35], v[14:15], v[44:45] op_sel_hi:[0,1,1] neg_lo:[0,0,1] neg_hi:[0,0,1]
	v_pk_fma_f32 v[38:39], v[34:35], v[16:17], v[46:47] op_sel_hi:[0,1,1] neg_lo:[0,0,1] neg_hi:[0,0,1]
	v_pk_fma_f32 v[40:41], v[34:35], v[18:19], v[48:49] op_sel_hi:[0,1,1] neg_lo:[0,0,1] neg_hi:[0,0,1]
	v_pk_fma_f32 v[42:43], v[34:35], v[12:13], v[50:51] op_sel_hi:[0,1,1] neg_lo:[0,0,1] neg_hi:[0,0,1]
	v_cvt_pk_bf16_f32 v28, v36, v37
	v_cvt_pk_bf16_f32 v29, v38, v39
	v_cvt_pk_bf16_f32 v30, v40, v41
	v_cvt_pk_bf16_f32 v31, v42, v43
	global_store_dwordx4 v[10:11], v[28:31], off
	v_lshlrev_b32_e32 v44, 16, v238
	v_and_b32_e32 v45, 0xffff0000, v238
	v_lshlrev_b32_e32 v46, 16, v239
	v_and_b32_e32 v47, 0xffff0000, v239
	v_lshlrev_b32_e32 v48, 16, v240
	v_and_b32_e32 v49, 0xffff0000, v240
	v_lshlrev_b32_e32 v50, 16, v241
	v_and_b32_e32 v51, 0xffff0000, v241
	v_pk_add_f32 v[14:15], v[14:15], v[44:45] neg_lo:[0,1] neg_hi:[0,1]
	v_pk_add_f32 v[16:17], v[16:17], v[46:47] neg_lo:[0,1] neg_hi:[0,1]
	v_pk_add_f32 v[18:19], v[18:19], v[48:49] neg_lo:[0,1] neg_hi:[0,1]
	v_pk_add_f32 v[12:13], v[12:13], v[50:51] neg_lo:[0,1] neg_hi:[0,1]
	v_lshl_add_u64 v[10:11], v[10:11], 0, s[26:27]
	v_lshlrev_b32_e32 v44, 16, v246
	v_and_b32_e32 v45, 0xffff0000, v246
	v_lshlrev_b32_e32 v46, 16, v247
	v_and_b32_e32 v47, 0xffff0000, v247
	v_lshlrev_b32_e32 v48, 16, v248
	v_and_b32_e32 v49, 0xffff0000, v248
	v_lshlrev_b32_e32 v50, 16, v249
	v_and_b32_e32 v51, 0xffff0000, v249
	v_pk_add_f32 v[14:15], v[14:15], v[44:45]
	v_pk_add_f32 v[16:17], v[16:17], v[46:47]
	v_pk_add_f32 v[18:19], v[18:19], v[48:49]
	v_pk_add_f32 v[12:13], v[12:13], v[50:51]
	v_pk_fma_f32 v[36:37], v[34:35], v[14:15], v[44:45] op_sel_hi:[0,1,1] neg_lo:[0,0,1] neg_hi:[0,0,1]
	v_pk_fma_f32 v[38:39], v[34:35], v[16:17], v[46:47] op_sel_hi:[0,1,1] neg_lo:[0,0,1] neg_hi:[0,0,1]
	v_pk_fma_f32 v[40:41], v[34:35], v[18:19], v[48:49] op_sel_hi:[0,1,1] neg_lo:[0,0,1] neg_hi:[0,0,1]
	v_pk_fma_f32 v[42:43], v[34:35], v[12:13], v[50:51] op_sel_hi:[0,1,1] neg_lo:[0,0,1] neg_hi:[0,0,1]
	v_cvt_pk_bf16_f32 v28, v36, v37
	v_cvt_pk_bf16_f32 v29, v38, v39
	v_cvt_pk_bf16_f32 v30, v40, v41
	v_cvt_pk_bf16_f32 v31, v42, v43
	global_store_dwordx4 v[10:11], v[28:31], off
	v_lshlrev_b32_e32 v44, 16, v242
	v_and_b32_e32 v45, 0xffff0000, v242
	v_lshlrev_b32_e32 v46, 16, v243
	v_and_b32_e32 v47, 0xffff0000, v243
	v_lshlrev_b32_e32 v48, 16, v244
	v_and_b32_e32 v49, 0xffff0000, v244
	v_lshlrev_b32_e32 v50, 16, v245
	v_and_b32_e32 v51, 0xffff0000, v245
	v_pk_add_f32 v[14:15], v[14:15], v[44:45] neg_lo:[0,1] neg_hi:[0,1]
	v_pk_add_f32 v[16:17], v[16:17], v[46:47] neg_lo:[0,1] neg_hi:[0,1]
	v_pk_add_f32 v[18:19], v[18:19], v[48:49] neg_lo:[0,1] neg_hi:[0,1]
	v_pk_add_f32 v[12:13], v[12:13], v[50:51] neg_lo:[0,1] neg_hi:[0,1]
	v_lshl_add_u64 v[10:11], v[10:11], 0, s[26:27]
	v_lshlrev_b32_e32 v44, 16, v250
	v_and_b32_e32 v45, 0xffff0000, v250
	v_lshlrev_b32_e32 v46, 16, v251
	v_and_b32_e32 v47, 0xffff0000, v251
	v_lshlrev_b32_e32 v48, 16, v252
	v_and_b32_e32 v49, 0xffff0000, v252
	v_lshlrev_b32_e32 v50, 16, v253
	v_and_b32_e32 v51, 0xffff0000, v253
	v_pk_add_f32 v[14:15], v[14:15], v[44:45]
	v_pk_add_f32 v[16:17], v[16:17], v[46:47]
	v_pk_add_f32 v[18:19], v[18:19], v[48:49]
	v_pk_add_f32 v[12:13], v[12:13], v[50:51]
	v_pk_fma_f32 v[36:37], v[34:35], v[14:15], v[44:45] op_sel_hi:[0,1,1] neg_lo:[0,0,1] neg_hi:[0,0,1]
	v_pk_fma_f32 v[38:39], v[34:35], v[16:17], v[46:47] op_sel_hi:[0,1,1] neg_lo:[0,0,1] neg_hi:[0,0,1]
	v_pk_fma_f32 v[40:41], v[34:35], v[18:19], v[48:49] op_sel_hi:[0,1,1] neg_lo:[0,0,1] neg_hi:[0,0,1]
	v_pk_fma_f32 v[42:43], v[34:35], v[12:13], v[50:51] op_sel_hi:[0,1,1] neg_lo:[0,0,1] neg_hi:[0,0,1]
	v_cvt_pk_bf16_f32 v28, v36, v37
	v_cvt_pk_bf16_f32 v29, v38, v39
	v_cvt_pk_bf16_f32 v30, v40, v41
	v_cvt_pk_bf16_f32 v31, v42, v43
	global_store_dwordx4 v[10:11], v[28:31], off
	v_lshlrev_b32_e32 v44, 16, v246
	v_and_b32_e32 v45, 0xffff0000, v246
	v_lshlrev_b32_e32 v46, 16, v247
	v_and_b32_e32 v47, 0xffff0000, v247
	v_lshlrev_b32_e32 v48, 16, v248
	v_and_b32_e32 v49, 0xffff0000, v248
	v_lshlrev_b32_e32 v50, 16, v249
	v_and_b32_e32 v51, 0xffff0000, v249
	v_pk_add_f32 v[14:15], v[14:15], v[44:45] neg_lo:[0,1] neg_hi:[0,1]
	v_pk_add_f32 v[16:17], v[16:17], v[46:47] neg_lo:[0,1] neg_hi:[0,1]
	v_pk_add_f32 v[18:19], v[18:19], v[48:49] neg_lo:[0,1] neg_hi:[0,1]
	v_pk_add_f32 v[12:13], v[12:13], v[50:51] neg_lo:[0,1] neg_hi:[0,1]
	s_branch .LBB0_1331
; __device__ __forceinline__ unsigned pk2(float lo, float hi) { f32x2 v = {lo, hi}; bf16x2_t b = __builtin_convertvector(v, bf16x2_t); return __builtin_bit_cast(unsigned, b); }
; __device__ __forceinline__ void pool_window(const bf16_t* __restrict__ U  , bf16_t* __restrict__ A3, const int gtid, const int nthr) {
;     ...
;             for (int k = 1; k < w; ++k) { const u32x4 uu = *(const u32x4*)(U + (size_t)(t0 - k) * LDU + c);
;                 sum[0] += bflo(uu.x); sum[1] += bfhi(uu.x); sum[2] += bflo(uu.y); sum[3] += bfhi(uu.y); sum[4] += bflo(uu.z); sum[5] += bfhi(uu.z); sum[6] += bflo(uu.w); sum[7] += bfhi(uu.w); }
;         }
; #pragma unroll 8
;         for (int i = 0; i < 32; ++i) {
;             const int t = t0 + i, s = s0 + i;
;             const u32x4 uu = *(const u32x4*)(U + (size_t)t * LDU + c);
;             float cu[8] = {bflo(uu.x), bfhi(uu.x), bflo(uu.y), bfhi(uu.y), bflo(uu.z), bfhi(uu.z), bflo(uu.w), bfhi(uu.w)};
;             const float rc = 1.0f / (float)((s + 1) < w ? (s + 1) : w);
;             float o[8];
; #pragma unroll
;             for (int e = 0; e < 8; ++e) { sum[e] += cu[e]; o[e] = sum[e] * rc - cu[e]; }
;             u32x4 ww; ww.x = pk2(o[0], o[1]); ww.y = pk2(o[2], o[3]); ww.z = pk2(o[4], o[5]); ww.w = pk2(o[6], o[7]);
;             *(u32x4*)(A3 + (size_t)t * DM + c) = ww;
;             if (s + 1 >= w) { const u32x4 ud = *(const u32x4*)(U + (size_t)(t - w + 1) * LDU + c);
;                 sum[0] -= bflo(ud.x); sum[1] -= bfhi(ud.x); sum[2] -= bflo(ud.y); sum[3] -= bfhi(ud.y); sum[4] -= bflo(ud.z); sum[5] -= bfhi(ud.z); sum[6] -= bflo(ud.w); sum[7] -= bfhi(ud.w); }
.Lpw_w4:
	v_mov_b32_e32 v34, 0x3e800000
	s_waitcnt vmcnt(0)
	v_lshlrev_b32_e32 v44, 16, v120
	v_and_b32_e32 v45, 0xffff0000, v120
	v_lshlrev_b32_e32 v46, 16, v121
	v_and_b32_e32 v47, 0xffff0000, v121
	v_lshlrev_b32_e32 v48, 16, v122
	v_and_b32_e32 v49, 0xffff0000, v122
	v_lshlrev_b32_e32 v50, 16, v123
	v_and_b32_e32 v51, 0xffff0000, v123
	v_pk_add_f32 v[14:15], v[14:15], v[44:45]
	v_pk_add_f32 v[16:17], v[16:17], v[46:47]
	v_pk_add_f32 v[18:19], v[18:19], v[48:49]
	v_pk_add_f32 v[12:13], v[12:13], v[50:51]
	v_lshlrev_b32_e32 v44, 16, v116
	v_and_b32_e32 v45, 0xffff0000, v116
	v_lshlrev_b32_e32 v46, 16, v117
	v_and_b32_e32 v47, 0xffff0000, v117
	v_lshlrev_b32_e32 v48, 16, v118
	v_and_b32_e32 v49, 0xffff0000, v118
	v_lshlrev_b32_e32 v50, 16, v119
	v_and_b32_e32 v51, 0xffff0000, v119
	v_pk_add_f32 v[14:15], v[14:15], v[44:45]
	v_pk_add_f32 v[16:17], v[16:17], v[46:47]
	v_pk_add_f32 v[18:19], v[18:19], v[48:49]
	v_pk_add_f32 v[12:13], v[12:13], v[50:51]
	v_lshlrev_b32_e32 v44, 16, v112
	v_and_b32_e32 v45, 0xffff0000, v112
	v_lshlrev_b32_e32 v46, 16, v113
	v_and_b32_e32 v47, 0xffff0000, v113
	v_lshlrev_b32_e32 v48, 16, v114
	v_and_b32_e32 v49, 0xffff0000, v114
	v_lshlrev_b32_e32 v50, 16, v115
	v_and_b32_e32 v51, 0xffff0000, v115
	v_pk_add_f32 v[14:15], v[14:15], v[44:45]
	v_pk_add_f32 v[16:17], v[16:17], v[46:47]
	v_pk_add_f32 v[18:19], v[18:19], v[48:49]
	v_pk_add_f32 v[12:13], v[12:13], v[50:51]
	v_lshlrev_b32_e32 v44, 16, v124
	v_and_b32_e32 v45, 0xffff0000, v124
	v_lshlrev_b32_e32 v46, 16, v125
	v_and_b32_e32 v47, 0xffff0000, v125
	v_lshlrev_b32_e32 v48, 16, v126
	v_and_b32_e32 v49, 0xffff0000, v126
	v_lshlrev_b32_e32 v50, 16, v127
	v_and_b32_e32 v51, 0xffff0000, v127
	v_pk_add_f32 v[14:15], v[14:15], v[44:45]
	v_pk_add_f32 v[16:17], v[16:17], v[46:47]
	v_pk_add_f32 v[18:19], v[18:19], v[48:49]
	v_pk_add_f32 v[12:13], v[12:13], v[50:51]
	v_pk_fma_f32 v[36:37], v[34:35], v[14:15], v[44:45] op_sel_hi:[0,1,1] neg_lo:[0,0,1] neg_hi:[0,0,1]
	v_pk_fma_f32 v[38:39], v[34:35], v[16:17], v[46:47] op_sel_hi:[0,1,1] neg_lo:[0,0,1] neg_hi:[0,0,1]
	v_pk_fma_f32 v[40:41], v[34:35], v[18:19], v[48:49] op_sel_hi:[0,1,1] neg_lo:[0,0,1] neg_hi:[0,0,1]
	v_pk_fma_f32 v[42:43], v[34:35], v[12:13], v[50:51] op_sel_hi:[0,1,1] neg_lo:[0,0,1] neg_hi:[0,0,1]
	v_cvt_pk_bf16_f32 v28, v36, v37
	v_cvt_pk_bf16_f32 v29, v38, v39
	v_cvt_pk_bf16_f32 v30, v40, v41
	v_cvt_pk_bf16_f32 v31, v42, v43
	global_store_dwordx4 v[10:11], v[28:31], off
	v_lshlrev_b32_e32 v44, 16, v112
	v_and_b32_e32 v45, 0xffff0000, v112
	v_lshlrev_b32_e32 v46, 16, v113
	v_and_b32_e32 v47, 0xffff0000, v113
	v_lshlrev_b32_e32 v48, 16, v114
	v_and_b32_e32 v49, 0xffff0000, v114
	v_lshlrev_b32_e32 v50, 16, v115
	v_and_b32_e32 v51, 0xffff0000, v115
	v_pk_add_f32 v[14:15], v[14:15], v[44:45] neg_lo:[0,1] neg_hi:[0,1]
	v_pk_add_f32 v[16:17], v[16:17], v[46:47] neg_lo:[0,1] neg_hi:[0,1]
	v_pk_add_f32 v[18:19], v[18:19], v[48:49] neg_lo:[0,1] neg_hi:[0,1]
	v_pk_add_f32 v[12:13], v[12:13], v[50:51] neg_lo:[0,1] neg_hi:[0,1]
	v_lshl_add_u64 v[10:11], v[10:11], 0, s[26:27]
	v_lshlrev_b32_e32 v44, 16, v128
	v_and_b32_e32 v45, 0xffff0000, v128
	v_lshlrev_b32_e32 v46, 16, v129
	v_and_b32_e32 v47, 0xffff0000, v129
	v_lshlrev_b32_e32 v48, 16, v130
	v_and_b32_e32 v49, 0xffff0000, v130
	v_lshlrev_b32_e32 v50, 16, v131
	v_and_b32_e32 v51, 0xffff0000, v131
	v_pk_add_f32 v[14:15], v[14:15], v[44:45]
	v_pk_add_f32 v[16:17], v[16:17], v[46:47]
	v_pk_add_f32 v[18:19], v[18:19], v[48:49]
	v_pk_add_f32 v[12:13], v[12:13], v[50:51]
	v_pk_fma_f32 v[36:37], v[34:35], v[14:15], v[44:45] op_sel_hi:[0,1,1] neg_lo:[0,0,1] neg_hi:[0,0,1]
	v_pk_fma_f32 v[38:39], v[34:35], v[16:17], v[46:47] op_sel_hi:[0,1,1] neg_lo:[0,0,1] neg_hi:[0,0,1]
	v_pk_fma_f32 v[40:41], v[34:35], v[18:19], v[48:49] op_sel_hi:[0,1,1] neg_lo:[0,0,1] neg_hi:[0,0,1]
	v_pk_fma_f32 v[42:43], v[34:35], v[12:13], v[50:51] op_sel_hi:[0,1,1] neg_lo:[0,0,1] neg_hi:[0,0,1]
	v_cvt_pk_bf16_f32 v28, v36, v37
	v_cvt_pk_bf16_f32 v29, v38, v39
	v_cvt_pk_bf16_f32 v30, v40, v41
	v_cvt_pk_bf16_f32 v31, v42, v43
	global_store_dwordx4 v[10:11], v[28:31], off
	v_lshlrev_b32_e32 v44, 16, v116
	v_and_b32_e32 v45, 0xffff0000, v116
	v_lshlrev_b32_e32 v46, 16, v117
	v_and_b32_e32 v47, 0xffff0000, v117
	v_lshlrev_b32_e32 v48, 16, v118
	v_and_b32_e32 v49, 0xffff0000, v118
	v_lshlrev_b32_e32 v50, 16, v119
	v_and_b32_e32 v51, 0xffff0000, v119
	v_pk_add_f32 v[14:15], v[14:15], v[44:45] neg_lo:[0,1] neg_hi:[0,1]
	v_pk_add_f32 v[16:17], v[16:17], v[46:47] neg_lo:[0,1] neg_hi:[0,1]
	v_pk_add_f32 v[18:19], v[18:19], v[48:49] neg_lo:[0,1] neg_hi:[0,1]
	v_pk_add_f32 v[12:13], v[12:13], v[50:51] neg_lo:[0,1] neg_hi:[0,1]
	v_lshl_add_u64 v[10:11], v[10:11], 0, s[26:27]
	v_lshlrev_b32_e32 v44, 16, v132
	v_and_b32_e32 v45, 0xffff0000, v132
	v_lshlrev_b32_e32 v46, 16, v133
	v_and_b32_e32 v47, 0xffff0000, v133
	v_lshlrev_b32_e32 v48, 16, v134
	v_and_b32_e32 v49, 0xffff0000, v134
	v_lshlrev_b32_e32 v50, 16, v135
	v_and_b32_e32 v51, 0xffff0000, v135
	v_pk_add_f32 v[14:15], v[14:15], v[44:45]
	v_pk_add_f32 v[16:17], v[16:17], v[46:47]
	v_pk_add_f32 v[18:19], v[18:19], v[48:49]
	v_pk_add_f32 v[12:13], v[12:13], v[50:51]
	v_pk_fma_f32 v[36:37], v[34:35], v[14:15], v[44:45] op_sel_hi:[0,1,1] neg_lo:[0,0,1] neg_hi:[0,0,1]
	v_pk_fma_f32 v[38:39], v[34:35], v[16:17], v[46:47] op_sel_hi:[0,1,1] neg_lo:[0,0,1] neg_hi:[0,0,1]
	v_pk_fma_f32 v[40:41], v[34:35], v[18:19], v[48:49] op_sel_hi:[0,1,1] neg_lo:[0,0,1] neg_hi:[0,0,1]
	v_pk_fma_f32 v[42:43], v[34:35], v[12:13], v[50:51] op_sel_hi:[0,1,1] neg_lo:[0,0,1] neg_hi:[0,0,1]
	v_cvt_pk_bf16_f32 v28, v36, v37
	v_cvt_pk_bf16_f32 v29, v38, v39
	v_cvt_pk_bf16_f32 v30, v40, v41
; __device__ __forceinline__ unsigned pk2(float lo, float hi) { f32x2 v = {lo, hi}; bf16x2_t b = __builtin_convertvector(v, bf16x2_t); return __builtin_bit_cast(unsigned, b); }
; __device__ __forceinline__ void pool_window(const bf16_t* __restrict__ U  , bf16_t* __restrict__ A3, const int gtid, const int nthr) {
;     ...
;         for (int i = 0; i < 32; ++i) {
;             const int t = t0 + i, s = s0 + i;
;             const u32x4 uu = *(const u32x4*)(U + (size_t)t * LDU + c);
;             float cu[8] = {bflo(uu.x), bfhi(uu.x), bflo(uu.y), bfhi(uu.y), bflo(uu.z), bfhi(uu.z), bflo(uu.w), bfhi(uu.w)};
;             const float rc = 1.0f / (float)((s + 1) < w ? (s + 1) : w);
;             float o[8];
; #pragma unroll
;             for (int e = 0; e < 8; ++e) { sum[e] += cu[e]; o[e] = sum[e] * rc - cu[e]; }
;             u32x4 ww; ww.x = pk2(o[0], o[1]); ww.y = pk2(o[2], o[3]); ww.z = pk2(o[4], o[5]); ww.w = pk2(o[6], o[7]);
;             *(u32x4*)(A3 + (size_t)t * DM + c) = ww;
;             if (s + 1 >= w) { const u32x4 ud = *(const u32x4*)(U + (size_t)(t - w + 1) * LDU + c);
;                 sum[0] -= bflo(ud.x); sum[1] -= bfhi(ud.x); sum[2] -= bflo(ud.y); sum[3] -= bfhi(ud.y); sum[4] -= bflo(ud.z); sum[5] -= bfhi(ud.z); sum[6] -= bflo(ud.w); sum[7] -= bfhi(ud.w); }
	v_cvt_pk_bf16_f32 v31, v42, v43
	global_store_dwordx4 v[10:11], v[28:31], off
	v_lshlrev_b32_e32 v44, 16, v120
	v_and_b32_e32 v45, 0xffff0000, v120
	v_lshlrev_b32_e32 v46, 16, v121
	v_and_b32_e32 v47, 0xffff0000, v121
	v_lshlrev_b32_e32 v48, 16, v122
	v_and_b32_e32 v49, 0xffff0000, v122
	v_lshlrev_b32_e32 v50, 16, v123
	v_and_b32_e32 v51, 0xffff0000, v123
	v_pk_add_f32 v[14:15], v[14:15], v[44:45] neg_lo:[0,1] neg_hi:[0,1]
	v_pk_add_f32 v[16:17], v[16:17], v[46:47] neg_lo:[0,1] neg_hi:[0,1]
	v_pk_add_f32 v[18:19], v[18:19], v[48:49] neg_lo:[0,1] neg_hi:[0,1]
	v_pk_add_f32 v[12:13], v[12:13], v[50:51] neg_lo:[0,1] neg_hi:[0,1]
	v_lshl_add_u64 v[10:11], v[10:11], 0, s[26:27]
	v_lshlrev_b32_e32 v44, 16, v136
	v_and_b32_e32 v45, 0xffff0000, v136
	v_lshlrev_b32_e32 v46, 16, v137
	v_and_b32_e32 v47, 0xffff0000, v137
	v_lshlrev_b32_e32 v48, 16, v138
	v_and_b32_e32 v49, 0xffff0000, v138
	v_lshlrev_b32_e32 v50, 16, v139
	v_and_b32_e32 v51, 0xffff0000, v139
	v_pk_add_f32 v[14:15], v[14:15], v[44:45]
	v_pk_add_f32 v[16:17], v[16:17], v[46:47]
	v_pk_add_f32 v[18:19], v[18:19], v[48:49]
	v_pk_add_f32 v[12:13], v[12:13], v[50:51]
	v_pk_fma_f32 v[36:37], v[34:35], v[14:15], v[44:45] op_sel_hi:[0,1,1] neg_lo:[0,0,1] neg_hi:[0,0,1]
	v_pk_fma_f32 v[38:39], v[34:35], v[16:17], v[46:47] op_sel_hi:[0,1,1] neg_lo:[0,0,1] neg_hi:[0,0,1]
	v_pk_fma_f32 v[40:41], v[34:35], v[18:19], v[48:49] op_sel_hi:[0,1,1] neg_lo:[0,0,1] neg_hi:[0,0,1]
	v_pk_fma_f32 v[42:43], v[34:35], v[12:13], v[50:51] op_sel_hi:[0,1,1] neg_lo:[0,0,1] neg_hi:[0,0,1]
	v_cvt_pk_bf16_f32 v28, v36, v37
	v_cvt_pk_bf16_f32 v29, v38, v39
	v_cvt_pk_bf16_f32 v30, v40, v41
	v_cvt_pk_bf16_f32 v31, v42, v43
	global_store_dwordx4 v[10:11], v[28:31], off
	v_lshlrev_b32_e32 v44, 16, v124
	v_and_b32_e32 v45, 0xffff0000, v124
	v_lshlrev_b32_e32 v46, 16, v125
	v_and_b32_e32 v47, 0xffff0000, v125
	v_lshlrev_b32_e32 v48, 16, v126
	v_and_b32_e32 v49, 0xffff0000, v126
	v_lshlrev_b32_e32 v50, 16, v127
	v_and_b32_e32 v51, 0xffff0000, v127
	v_pk_add_f32 v[14:15], v[14:15], v[44:45] neg_lo:[0,1] neg_hi:[0,1]
	v_pk_add_f32 v[16:17], v[16:17], v[46:47] neg_lo:[0,1] neg_hi:[0,1]
	v_pk_add_f32 v[18:19], v[18:19], v[48:49] neg_lo:[0,1] neg_hi:[0,1]
	v_pk_add_f32 v[12:13], v[12:13], v[50:51] neg_lo:[0,1] neg_hi:[0,1]
	v_lshl_add_u64 v[10:11], v[10:11], 0, s[26:27]
	v_lshlrev_b32_e32 v44, 16, v140
	v_and_b32_e32 v45, 0xffff0000, v140
	v_lshlrev_b32_e32 v46, 16, v141
	v_and_b32_e32 v47, 0xffff0000, v141
	v_lshlrev_b32_e32 v48, 16, v142
	v_and_b32_e32 v49, 0xffff0000, v142
	v_lshlrev_b32_e32 v50, 16, v143
	v_and_b32_e32 v51, 0xffff0000, v143
	v_pk_add_f32 v[14:15], v[14:15], v[44:45]
	v_pk_add_f32 v[16:17], v[16:17], v[46:47]
	v_pk_add_f32 v[18:19], v[18:19], v[48:49]
	v_pk_add_f32 v[12:13], v[12:13], v[50:51]
	v_pk_fma_f32 v[36:37], v[34:35], v[14:15], v[44:45] op_sel_hi:[0,1,1] neg_lo:[0,0,1] neg_hi:[0,0,1]
	v_pk_fma_f32 v[38:39], v[34:35], v[16:17], v[46:47] op_sel_hi:[0,1,1] neg_lo:[0,0,1] neg_hi:[0,0,1]
	v_pk_fma_f32 v[40:41], v[34:35], v[18:19], v[48:49] op_sel_hi:[0,1,1] neg_lo:[0,0,1] neg_hi:[0,0,1]
	v_pk_fma_f32 v[42:43], v[34:35], v[12:13], v[50:51] op_sel_hi:[0,1,1] neg_lo:[0,0,1] neg_hi:[0,0,1]
	v_cvt_pk_bf16_f32 v28, v36, v37
	v_cvt_pk_bf16_f32 v29, v38, v39
	v_cvt_pk_bf16_f32 v30, v40, v41
	v_cvt_pk_bf16_f32 v31, v42, v43
	global_store_dwordx4 v[10:11], v[28:31], off
	v_lshlrev_b32_e32 v44, 16, v128
	v_and_b32_e32 v45, 0xffff0000, v128
	v_lshlrev_b32_e32 v46, 16, v129
	v_and_b32_e32 v47, 0xffff0000, v129
	v_lshlrev_b32_e32 v48, 16, v130
	v_and_b32_e32 v49, 0xffff0000, v130
	v_lshlrev_b32_e32 v50, 16, v131
	v_and_b32_e32 v51, 0xffff0000, v131
	v_pk_add_f32 v[14:15], v[14:15], v[44:45] neg_lo:[0,1] neg_hi:[0,1]
	v_pk_add_f32 v[16:17], v[16:17], v[46:47] neg_lo:[0,1] neg_hi:[0,1]
	v_pk_add_f32 v[18:19], v[18:19], v[48:49] neg_lo:[0,1] neg_hi:[0,1]
	v_pk_add_f32 v[12:13], v[12:13], v[50:51] neg_lo:[0,1] neg_hi:[0,1]
	v_lshl_add_u64 v[10:11], v[10:11], 0, s[26:27]
	v_lshlrev_b32_e32 v44, 16, v144
	v_and_b32_e32 v45, 0xffff0000, v144
	v_lshlrev_b32_e32 v46, 16, v145
	v_and_b32_e32 v47, 0xffff0000, v145
	v_lshlrev_b32_e32 v48, 16, v146
	v_and_b32_e32 v49, 0xffff0000, v146
	v_lshlrev_b32_e32 v50, 16, v147
	v_and_b32_e32 v51, 0xffff0000, v147
	v_pk_add_f32 v[14:15], v[14:15], v[44:45]
	v_pk_add_f32 v[16:17], v[16:17], v[46:47]
	v_pk_add_f32 v[18:19], v[18:19], v[48:49]
	v_pk_add_f32 v[12:13], v[12:13], v[50:51]
	v_pk_fma_f32 v[36:37], v[34:35], v[14:15], v[44:45] op_sel_hi:[0,1,1] neg_lo:[0,0,1] neg_hi:[0,0,1]
	v_pk_fma_f32 v[38:39], v[34:35], v[16:17], v[46:47] op_sel_hi:[0,1,1] neg_lo:[0,0,1] neg_hi:[0,0,1]
	v_pk_fma_f32 v[40:41], v[34:35], v[18:19], v[48:49] op_sel_hi:[0,1,1] neg_lo:[0,0,1] neg_hi:[0,0,1]
	v_pk_fma_f32 v[42:43], v[34:35], v[12:13], v[50:51] op_sel_hi:[0,1,1] neg_lo:[0,0,1] neg_hi:[0,0,1]
	v_cvt_pk_bf16_f32 v28, v36, v37
	v_cvt_pk_bf16_f32 v29, v38, v39
	v_cvt_pk_bf16_f32 v30, v40, v41
	v_cvt_pk_bf16_f32 v31, v42, v43
	global_store_dwordx4 v[10:11], v[28:31], off
	v_lshlrev_b32_e32 v44, 16, v132
	v_and_b32_e32 v45, 0xffff0000, v132
	v_lshlrev_b32_e32 v46, 16, v133
	v_and_b32_e32 v47, 0xffff0000, v133
	v_lshlrev_b32_e32 v48, 16, v134
	v_and_b32_e32 v49, 0xffff0000, v134
	v_lshlrev_b32_e32 v50, 16, v135
	v_and_b32_e32 v51, 0xffff0000, v135
	v_pk_add_f32 v[14:15], v[14:15], v[44:45] neg_lo:[0,1] neg_hi:[0,1]
	v_pk_add_f32 v[16:17], v[16:17], v[46:47] neg_lo:[0,1] neg_hi:[0,1]
	v_pk_add_f32 v[18:19], v[18:19], v[48:49] neg_lo:[0,1] neg_hi:[0,1]
	v_pk_add_f32 v[12:13], v[12:13], v[50:51] neg_lo:[0,1] neg_hi:[0,1]
	v_lshl_add_u64 v[10:11], v[10:11], 0, s[26:27]
	v_lshlrev_b32_e32 v44, 16, v148
; __device__ __forceinline__ unsigned pk2(float lo, float hi) { f32x2 v = {lo, hi}; bf16x2_t b = __builtin_convertvector(v, bf16x2_t); return __builtin_bit_cast(unsigned, b); }
; __device__ __forceinline__ void pool_window(const bf16_t* __restrict__ U  , bf16_t* __restrict__ A3, const int gtid, const int nthr) {
;     ...
;         for (int i = 0; i < 32; ++i) {
;             const int t = t0 + i, s = s0 + i;
;             const u32x4 uu = *(const u32x4*)(U + (size_t)t * LDU + c);
;             float cu[8] = {bflo(uu.x), bfhi(uu.x), bflo(uu.y), bfhi(uu.y), bflo(uu.z), bfhi(uu.z), bflo(uu.w), bfhi(uu.w)};
;             const float rc = 1.0f / (float)((s + 1) < w ? (s + 1) : w);
;             float o[8];
; #pragma unroll
;             for (int e = 0; e < 8; ++e) { sum[e] += cu[e]; o[e] = sum[e] * rc - cu[e]; }
;             u32x4 ww; ww.x = pk2(o[0], o[1]); ww.y = pk2(o[2], o[3]); ww.z = pk2(o[4], o[5]); ww.w = pk2(o[6], o[7]);
;             *(u32x4*)(A3 + (size_t)t * DM + c) = ww;
;             if (s + 1 >= w) { const u32x4 ud = *(const u32x4*)(U + (size_t)(t - w + 1) * LDU + c);
;                 sum[0] -= bflo(ud.x); sum[1] -= bfhi(ud.x); sum[2] -= bflo(ud.y); sum[3] -= bfhi(ud.y); sum[4] -= bflo(ud.z); sum[5] -= bfhi(ud.z); sum[6] -= bflo(ud.w); sum[7] -= bfhi(ud.w); }
	v_and_b32_e32 v45, 0xffff0000, v148
	v_lshlrev_b32_e32 v46, 16, v149
	v_and_b32_e32 v47, 0xffff0000, v149
	v_lshlrev_b32_e32 v48, 16, v150
	v_and_b32_e32 v49, 0xffff0000, v150
	v_lshlrev_b32_e32 v50, 16, v151
	v_and_b32_e32 v51, 0xffff0000, v151
	v_pk_add_f32 v[14:15], v[14:15], v[44:45]
	v_pk_add_f32 v[16:17], v[16:17], v[46:47]
	v_pk_add_f32 v[18:19], v[18:19], v[48:49]
	v_pk_add_f32 v[12:13], v[12:13], v[50:51]
	v_pk_fma_f32 v[36:37], v[34:35], v[14:15], v[44:45] op_sel_hi:[0,1,1] neg_lo:[0,0,1] neg_hi:[0,0,1]
	v_pk_fma_f32 v[38:39], v[34:35], v[16:17], v[46:47] op_sel_hi:[0,1,1] neg_lo:[0,0,1] neg_hi:[0,0,1]
	v_pk_fma_f32 v[40:41], v[34:35], v[18:19], v[48:49] op_sel_hi:[0,1,1] neg_lo:[0,0,1] neg_hi:[0,0,1]
	v_pk_fma_f32 v[42:43], v[34:35], v[12:13], v[50:51] op_sel_hi:[0,1,1] neg_lo:[0,0,1] neg_hi:[0,0,1]
	v_cvt_pk_bf16_f32 v28, v36, v37
	v_cvt_pk_bf16_f32 v29, v38, v39
	v_cvt_pk_bf16_f32 v30, v40, v41
	v_cvt_pk_bf16_f32 v31, v42, v43
	global_store_dwordx4 v[10:11], v[28:31], off
	v_lshlrev_b32_e32 v44, 16, v136
	v_and_b32_e32 v45, 0xffff0000, v136
	v_lshlrev_b32_e32 v46, 16, v137
	v_and_b32_e32 v47, 0xffff0000, v137
	v_lshlrev_b32_e32 v48, 16, v138
	v_and_b32_e32 v49, 0xffff0000, v138
	v_lshlrev_b32_e32 v50, 16, v139
	v_and_b32_e32 v51, 0xffff0000, v139
	v_pk_add_f32 v[14:15], v[14:15], v[44:45] neg_lo:[0,1] neg_hi:[0,1]
	v_pk_add_f32 v[16:17], v[16:17], v[46:47] neg_lo:[0,1] neg_hi:[0,1]
	v_pk_add_f32 v[18:19], v[18:19], v[48:49] neg_lo:[0,1] neg_hi:[0,1]
	v_pk_add_f32 v[12:13], v[12:13], v[50:51] neg_lo:[0,1] neg_hi:[0,1]
	v_lshl_add_u64 v[10:11], v[10:11], 0, s[26:27]
	v_lshlrev_b32_e32 v44, 16, v152
	v_and_b32_e32 v45, 0xffff0000, v152
	v_lshlrev_b32_e32 v46, 16, v153
	v_and_b32_e32 v47, 0xffff0000, v153
	v_lshlrev_b32_e32 v48, 16, v154
	v_and_b32_e32 v49, 0xffff0000, v154
	v_lshlrev_b32_e32 v50, 16, v155
	v_and_b32_e32 v51, 0xffff0000, v155
	v_pk_add_f32 v[14:15], v[14:15], v[44:45]
	v_pk_add_f32 v[16:17], v[16:17], v[46:47]
	v_pk_add_f32 v[18:19], v[18:19], v[48:49]
	v_pk_add_f32 v[12:13], v[12:13], v[50:51]
	v_pk_fma_f32 v[36:37], v[34:35], v[14:15], v[44:45] op_sel_hi:[0,1,1] neg_lo:[0,0,1] neg_hi:[0,0,1]
	v_pk_fma_f32 v[38:39], v[34:35], v[16:17], v[46:47] op_sel_hi:[0,1,1] neg_lo:[0,0,1] neg_hi:[0,0,1]
	v_pk_fma_f32 v[40:41], v[34:35], v[18:19], v[48:49] op_sel_hi:[0,1,1] neg_lo:[0,0,1] neg_hi:[0,0,1]
	v_pk_fma_f32 v[42:43], v[34:35], v[12:13], v[50:51] op_sel_hi:[0,1,1] neg_lo:[0,0,1] neg_hi:[0,0,1]
	v_cvt_pk_bf16_f32 v28, v36, v37
	v_cvt_pk_bf16_f32 v29, v38, v39
	v_cvt_pk_bf16_f32 v30, v40, v41
	v_cvt_pk_bf16_f32 v31, v42, v43
	global_store_dwordx4 v[10:11], v[28:31], off
	v_lshlrev_b32_e32 v44, 16, v140
	v_and_b32_e32 v45, 0xffff0000, v140
	v_lshlrev_b32_e32 v46, 16, v141
	v_and_b32_e32 v47, 0xffff0000, v141
	v_lshlrev_b32_e32 v48, 16, v142
	v_and_b32_e32 v49, 0xffff0000, v142
	v_lshlrev_b32_e32 v50, 16, v143
	v_and_b32_e32 v51, 0xffff0000, v143
	v_pk_add_f32 v[14:15], v[14:15], v[44:45] neg_lo:[0,1] neg_hi:[0,1]
	v_pk_add_f32 v[16:17], v[16:17], v[46:47] neg_lo:[0,1] neg_hi:[0,1]
	v_pk_add_f32 v[18:19], v[18:19], v[48:49] neg_lo:[0,1] neg_hi:[0,1]
	v_pk_add_f32 v[12:13], v[12:13], v[50:51] neg_lo:[0,1] neg_hi:[0,1]
	v_lshl_add_u64 v[10:11], v[10:11], 0, s[26:27]
	v_lshlrev_b32_e32 v44, 16, v156
	v_and_b32_e32 v45, 0xffff0000, v156
	v_lshlrev_b32_e32 v46, 16, v157
	v_and_b32_e32 v47, 0xffff0000, v157
	v_lshlrev_b32_e32 v48, 16, v158
	v_and_b32_e32 v49, 0xffff0000, v158
	v_lshlrev_b32_e32 v50, 16, v159
	v_and_b32_e32 v51, 0xffff0000, v159
	v_pk_add_f32 v[14:15], v[14:15], v[44:45]
	v_pk_add_f32 v[16:17], v[16:17], v[46:47]
	v_pk_add_f32 v[18:19], v[18:19], v[48:49]
	v_pk_add_f32 v[12:13], v[12:13], v[50:51]
	v_pk_fma_f32 v[36:37], v[34:35], v[14:15], v[44:45] op_sel_hi:[0,1,1] neg_lo:[0,0,1] neg_hi:[0,0,1]
	v_pk_fma_f32 v[38:39], v[34:35], v[16:17], v[46:47] op_sel_hi:[0,1,1] neg_lo:[0,0,1] neg_hi:[0,0,1]
	v_pk_fma_f32 v[40:41], v[34:35], v[18:19], v[48:49] op_sel_hi:[0,1,1] neg_lo:[0,0,1] neg_hi:[0,0,1]
	v_pk_fma_f32 v[42:43], v[34:35], v[12:13], v[50:51] op_sel_hi:[0,1,1] neg_lo:[0,0,1] neg_hi:[0,0,1]
	v_cvt_pk_bf16_f32 v28, v36, v37
	v_cvt_pk_bf16_f32 v29, v38, v39
	v_cvt_pk_bf16_f32 v30, v40, v41
	v_cvt_pk_bf16_f32 v31, v42, v43
	global_store_dwordx4 v[10:11], v[28:31], off
	v_lshlrev_b32_e32 v44, 16, v144
	v_and_b32_e32 v45, 0xffff0000, v144
	v_lshlrev_b32_e32 v46, 16, v145
	v_and_b32_e32 v47, 0xffff0000, v145
	v_lshlrev_b32_e32 v48, 16, v146
	v_and_b32_e32 v49, 0xffff0000, v146
	v_lshlrev_b32_e32 v50, 16, v147
	v_and_b32_e32 v51, 0xffff0000, v147
	v_pk_add_f32 v[14:15], v[14:15], v[44:45] neg_lo:[0,1] neg_hi:[0,1]
	v_pk_add_f32 v[16:17], v[16:17], v[46:47] neg_lo:[0,1] neg_hi:[0,1]
	v_pk_add_f32 v[18:19], v[18:19], v[48:49] neg_lo:[0,1] neg_hi:[0,1]
	v_pk_add_f32 v[12:13], v[12:13], v[50:51] neg_lo:[0,1] neg_hi:[0,1]
	v_lshl_add_u64 v[10:11], v[10:11], 0, s[26:27]
	v_lshlrev_b32_e32 v44, 16, v160
	v_and_b32_e32 v45, 0xffff0000, v160
	v_lshlrev_b32_e32 v46, 16, v161
	v_and_b32_e32 v47, 0xffff0000, v161
	v_lshlrev_b32_e32 v48, 16, v162
	v_and_b32_e32 v49, 0xffff0000, v162
	v_lshlrev_b32_e32 v50, 16, v163
	v_and_b32_e32 v51, 0xffff0000, v163
	v_pk_add_f32 v[14:15], v[14:15], v[44:45]
	v_pk_add_f32 v[16:17], v[16:17], v[46:47]
	v_pk_add_f32 v[18:19], v[18:19], v[48:49]
	v_pk_add_f32 v[12:13], v[12:13], v[50:51]
	v_pk_fma_f32 v[36:37], v[34:35], v[14:15], v[44:45] op_sel_hi:[0,1,1] neg_lo:[0,0,1] neg_hi:[0,0,1]
	v_pk_fma_f32 v[38:39], v[34:35], v[16:17], v[46:47] op_sel_hi:[0,1,1] neg_lo:[0,0,1] neg_hi:[0,0,1]
	v_pk_fma_f32 v[40:41], v[34:35], v[18:19], v[48:49] op_sel_hi:[0,1,1] neg_lo:[0,0,1] neg_hi:[0,0,1]
; __device__ __forceinline__ unsigned pk2(float lo, float hi) { f32x2 v = {lo, hi}; bf16x2_t b = __builtin_convertvector(v, bf16x2_t); return __builtin_bit_cast(unsigned, b); }
; __device__ __forceinline__ void pool_window(const bf16_t* __restrict__ U  , bf16_t* __restrict__ A3, const int gtid, const int nthr) {
;     ...
;         for (int i = 0; i < 32; ++i) {
;             const int t = t0 + i, s = s0 + i;
;             const u32x4 uu = *(const u32x4*)(U + (size_t)t * LDU + c);
;             float cu[8] = {bflo(uu.x), bfhi(uu.x), bflo(uu.y), bfhi(uu.y), bflo(uu.z), bfhi(uu.z), bflo(uu.w), bfhi(uu.w)};
;             const float rc = 1.0f / (float)((s + 1) < w ? (s + 1) : w);
;             float o[8];
; #pragma unroll
;             for (int e = 0; e < 8; ++e) { sum[e] += cu[e]; o[e] = sum[e] * rc - cu[e]; }
;             u32x4 ww; ww.x = pk2(o[0], o[1]); ww.y = pk2(o[2], o[3]); ww.z = pk2(o[4], o[5]); ww.w = pk2(o[6], o[7]);
;             *(u32x4*)(A3 + (size_t)t * DM + c) = ww;
;             if (s + 1 >= w) { const u32x4 ud = *(const u32x4*)(U + (size_t)(t - w + 1) * LDU + c);
;                 sum[0] -= bflo(ud.x); sum[1] -= bfhi(ud.x); sum[2] -= bflo(ud.y); sum[3] -= bfhi(ud.y); sum[4] -= bflo(ud.z); sum[5] -= bfhi(ud.z); sum[6] -= bflo(ud.w); sum[7] -= bfhi(ud.w); }
	v_pk_fma_f32 v[42:43], v[34:35], v[12:13], v[50:51] op_sel_hi:[0,1,1] neg_lo:[0,0,1] neg_hi:[0,0,1]
	v_cvt_pk_bf16_f32 v28, v36, v37
	v_cvt_pk_bf16_f32 v29, v38, v39
	v_cvt_pk_bf16_f32 v30, v40, v41
	v_cvt_pk_bf16_f32 v31, v42, v43
	global_store_dwordx4 v[10:11], v[28:31], off
	v_lshlrev_b32_e32 v44, 16, v148
	v_and_b32_e32 v45, 0xffff0000, v148
	v_lshlrev_b32_e32 v46, 16, v149
	v_and_b32_e32 v47, 0xffff0000, v149
	v_lshlrev_b32_e32 v48, 16, v150
	v_and_b32_e32 v49, 0xffff0000, v150
	v_lshlrev_b32_e32 v50, 16, v151
	v_and_b32_e32 v51, 0xffff0000, v151
	v_pk_add_f32 v[14:15], v[14:15], v[44:45] neg_lo:[0,1] neg_hi:[0,1]
	v_pk_add_f32 v[16:17], v[16:17], v[46:47] neg_lo:[0,1] neg_hi:[0,1]
	v_pk_add_f32 v[18:19], v[18:19], v[48:49] neg_lo:[0,1] neg_hi:[0,1]
	v_pk_add_f32 v[12:13], v[12:13], v[50:51] neg_lo:[0,1] neg_hi:[0,1]
	v_lshl_add_u64 v[10:11], v[10:11], 0, s[26:27]
	v_lshlrev_b32_e32 v44, 16, v164
	v_and_b32_e32 v45, 0xffff0000, v164
	v_lshlrev_b32_e32 v46, 16, v165
	v_and_b32_e32 v47, 0xffff0000, v165
	v_lshlrev_b32_e32 v48, 16, v166
	v_and_b32_e32 v49, 0xffff0000, v166
	v_lshlrev_b32_e32 v50, 16, v167
	v_and_b32_e32 v51, 0xffff0000, v167
	v_pk_add_f32 v[14:15], v[14:15], v[44:45]
	v_pk_add_f32 v[16:17], v[16:17], v[46:47]
	v_pk_add_f32 v[18:19], v[18:19], v[48:49]
	v_pk_add_f32 v[12:13], v[12:13], v[50:51]
	v_pk_fma_f32 v[36:37], v[34:35], v[14:15], v[44:45] op_sel_hi:[0,1,1] neg_lo:[0,0,1] neg_hi:[0,0,1]
	v_pk_fma_f32 v[38:39], v[34:35], v[16:17], v[46:47] op_sel_hi:[0,1,1] neg_lo:[0,0,1] neg_hi:[0,0,1]
	v_pk_fma_f32 v[40:41], v[34:35], v[18:19], v[48:49] op_sel_hi:[0,1,1] neg_lo:[0,0,1] neg_hi:[0,0,1]
	v_pk_fma_f32 v[42:43], v[34:35], v[12:13], v[50:51] op_sel_hi:[0,1,1] neg_lo:[0,0,1] neg_hi:[0,0,1]
	v_cvt_pk_bf16_f32 v28, v36, v37
	v_cvt_pk_bf16_f32 v29, v38, v39
	v_cvt_pk_bf16_f32 v30, v40, v41
	v_cvt_pk_bf16_f32 v31, v42, v43
	global_store_dwordx4 v[10:11], v[28:31], off
	v_lshlrev_b32_e32 v44, 16, v152
	v_and_b32_e32 v45, 0xffff0000, v152
	v_lshlrev_b32_e32 v46, 16, v153
	v_and_b32_e32 v47, 0xffff0000, v153
	v_lshlrev_b32_e32 v48, 16, v154
	v_and_b32_e32 v49, 0xffff0000, v154
	v_lshlrev_b32_e32 v50, 16, v155
	v_and_b32_e32 v51, 0xffff0000, v155
	v_pk_add_f32 v[14:15], v[14:15], v[44:45] neg_lo:[0,1] neg_hi:[0,1]
	v_pk_add_f32 v[16:17], v[16:17], v[46:47] neg_lo:[0,1] neg_hi:[0,1]
	v_pk_add_f32 v[18:19], v[18:19], v[48:49] neg_lo:[0,1] neg_hi:[0,1]
	v_pk_add_f32 v[12:13], v[12:13], v[50:51] neg_lo:[0,1] neg_hi:[0,1]
	v_lshl_add_u64 v[10:11], v[10:11], 0, s[26:27]
	v_lshlrev_b32_e32 v44, 16, v168
	v_and_b32_e32 v45, 0xffff0000, v168
	v_lshlrev_b32_e32 v46, 16, v169
	v_and_b32_e32 v47, 0xffff0000, v169
	v_lshlrev_b32_e32 v48, 16, v170
	v_and_b32_e32 v49, 0xffff0000, v170
	v_lshlrev_b32_e32 v50, 16, v171
	v_and_b32_e32 v51, 0xffff0000, v171
	v_pk_add_f32 v[14:15], v[14:15], v[44:45]
	v_pk_add_f32 v[16:17], v[16:17], v[46:47]
	v_pk_add_f32 v[18:19], v[18:19], v[48:49]
	v_pk_add_f32 v[12:13], v[12:13], v[50:51]
	v_pk_fma_f32 v[36:37], v[34:35], v[14:15], v[44:45] op_sel_hi:[0,1,1] neg_lo:[0,0,1] neg_hi:[0,0,1]
	v_pk_fma_f32 v[38:39], v[34:35], v[16:17], v[46:47] op_sel_hi:[0,1,1] neg_lo:[0,0,1] neg_hi:[0,0,1]
	v_pk_fma_f32 v[40:41], v[34:35], v[18:19], v[48:49] op_sel_hi:[0,1,1] neg_lo:[0,0,1] neg_hi:[0,0,1]
	v_pk_fma_f32 v[42:43], v[34:35], v[12:13], v[50:51] op_sel_hi:[0,1,1] neg_lo:[0,0,1] neg_hi:[0,0,1]
	v_cvt_pk_bf16_f32 v28, v36, v37
	v_cvt_pk_bf16_f32 v29, v38, v39
	v_cvt_pk_bf16_f32 v30, v40, v41
	v_cvt_pk_bf16_f32 v31, v42, v43
	global_store_dwordx4 v[10:11], v[28:31], off
	v_lshlrev_b32_e32 v44, 16, v156
	v_and_b32_e32 v45, 0xffff0000, v156
	v_lshlrev_b32_e32 v46, 16, v157
	v_and_b32_e32 v47, 0xffff0000, v157
	v_lshlrev_b32_e32 v48, 16, v158
	v_and_b32_e32 v49, 0xffff0000, v158
	v_lshlrev_b32_e32 v50, 16, v159
	v_and_b32_e32 v51, 0xffff0000, v159
	v_pk_add_f32 v[14:15], v[14:15], v[44:45] neg_lo:[0,1] neg_hi:[0,1]
	v_pk_add_f32 v[16:17], v[16:17], v[46:47] neg_lo:[0,1] neg_hi:[0,1]
	v_pk_add_f32 v[18:19], v[18:19], v[48:49] neg_lo:[0,1] neg_hi:[0,1]
	v_pk_add_f32 v[12:13], v[12:13], v[50:51] neg_lo:[0,1] neg_hi:[0,1]
	v_lshl_add_u64 v[10:11], v[10:11], 0, s[26:27]
	v_lshlrev_b32_e32 v44, 16, v172
	v_and_b32_e32 v45, 0xffff0000, v172
	v_lshlrev_b32_e32 v46, 16, v173
	v_and_b32_e32 v47, 0xffff0000, v173
	v_lshlrev_b32_e32 v48, 16, v174
	v_and_b32_e32 v49, 0xffff0000, v174
	v_lshlrev_b32_e32 v50, 16, v175
	v_and_b32_e32 v51, 0xffff0000, v175
	v_pk_add_f32 v[14:15], v[14:15], v[44:45]
	v_pk_add_f32 v[16:17], v[16:17], v[46:47]
	v_pk_add_f32 v[18:19], v[18:19], v[48:49]
	v_pk_add_f32 v[12:13], v[12:13], v[50:51]
	v_pk_fma_f32 v[36:37], v[34:35], v[14:15], v[44:45] op_sel_hi:[0,1,1] neg_lo:[0,0,1] neg_hi:[0,0,1]
	v_pk_fma_f32 v[38:39], v[34:35], v[16:17], v[46:47] op_sel_hi:[0,1,1] neg_lo:[0,0,1] neg_hi:[0,0,1]
	v_pk_fma_f32 v[40:41], v[34:35], v[18:19], v[48:49] op_sel_hi:[0,1,1] neg_lo:[0,0,1] neg_hi:[0,0,1]
	v_pk_fma_f32 v[42:43], v[34:35], v[12:13], v[50:51] op_sel_hi:[0,1,1] neg_lo:[0,0,1] neg_hi:[0,0,1]
	v_cvt_pk_bf16_f32 v28, v36, v37
	v_cvt_pk_bf16_f32 v29, v38, v39
	v_cvt_pk_bf16_f32 v30, v40, v41
	v_cvt_pk_bf16_f32 v31, v42, v43
	global_store_dwordx4 v[10:11], v[28:31], off
	v_lshlrev_b32_e32 v44, 16, v160
	v_and_b32_e32 v45, 0xffff0000, v160
	v_lshlrev_b32_e32 v46, 16, v161
	v_and_b32_e32 v47, 0xffff0000, v161
	v_lshlrev_b32_e32 v48, 16, v162
	v_and_b32_e32 v49, 0xffff0000, v162
	v_lshlrev_b32_e32 v50, 16, v163
	v_and_b32_e32 v51, 0xffff0000, v163
	v_pk_add_f32 v[14:15], v[14:15], v[44:45] neg_lo:[0,1] neg_hi:[0,1]
	v_pk_add_f32 v[16:17], v[16:17], v[46:47] neg_lo:[0,1] neg_hi:[0,1]
; __device__ __forceinline__ unsigned pk2(float lo, float hi) { f32x2 v = {lo, hi}; bf16x2_t b = __builtin_convertvector(v, bf16x2_t); return __builtin_bit_cast(unsigned, b); }
; __device__ __forceinline__ void pool_window(const bf16_t* __restrict__ U  , bf16_t* __restrict__ A3, const int gtid, const int nthr) {
;     ...
;         for (int i = 0; i < 32; ++i) {
;             const int t = t0 + i, s = s0 + i;
;             const u32x4 uu = *(const u32x4*)(U + (size_t)t * LDU + c);
;             float cu[8] = {bflo(uu.x), bfhi(uu.x), bflo(uu.y), bfhi(uu.y), bflo(uu.z), bfhi(uu.z), bflo(uu.w), bfhi(uu.w)};
;             const float rc = 1.0f / (float)((s + 1) < w ? (s + 1) : w);
;             float o[8];
; #pragma unroll
;             for (int e = 0; e < 8; ++e) { sum[e] += cu[e]; o[e] = sum[e] * rc - cu[e]; }
;             u32x4 ww; ww.x = pk2(o[0], o[1]); ww.y = pk2(o[2], o[3]); ww.z = pk2(o[4], o[5]); ww.w = pk2(o[6], o[7]);
;             *(u32x4*)(A3 + (size_t)t * DM + c) = ww;
;             if (s + 1 >= w) { const u32x4 ud = *(const u32x4*)(U + (size_t)(t - w + 1) * LDU + c);
;                 sum[0] -= bflo(ud.x); sum[1] -= bfhi(ud.x); sum[2] -= bflo(ud.y); sum[3] -= bfhi(ud.y); sum[4] -= bflo(ud.z); sum[5] -= bfhi(ud.z); sum[6] -= bflo(ud.w); sum[7] -= bfhi(ud.w); }
	v_pk_add_f32 v[18:19], v[18:19], v[48:49] neg_lo:[0,1] neg_hi:[0,1]
	v_pk_add_f32 v[12:13], v[12:13], v[50:51] neg_lo:[0,1] neg_hi:[0,1]
	v_lshl_add_u64 v[10:11], v[10:11], 0, s[26:27]
	v_lshlrev_b32_e32 v44, 16, v176
	v_and_b32_e32 v45, 0xffff0000, v176
	v_lshlrev_b32_e32 v46, 16, v177
	v_and_b32_e32 v47, 0xffff0000, v177
	v_lshlrev_b32_e32 v48, 16, v178
	v_and_b32_e32 v49, 0xffff0000, v178
	v_lshlrev_b32_e32 v50, 16, v179
	v_and_b32_e32 v51, 0xffff0000, v179
	v_pk_add_f32 v[14:15], v[14:15], v[44:45]
	v_pk_add_f32 v[16:17], v[16:17], v[46:47]
	v_pk_add_f32 v[18:19], v[18:19], v[48:49]
	v_pk_add_f32 v[12:13], v[12:13], v[50:51]
	v_pk_fma_f32 v[36:37], v[34:35], v[14:15], v[44:45] op_sel_hi:[0,1,1] neg_lo:[0,0,1] neg_hi:[0,0,1]
	v_pk_fma_f32 v[38:39], v[34:35], v[16:17], v[46:47] op_sel_hi:[0,1,1] neg_lo:[0,0,1] neg_hi:[0,0,1]
	v_pk_fma_f32 v[40:41], v[34:35], v[18:19], v[48:49] op_sel_hi:[0,1,1] neg_lo:[0,0,1] neg_hi:[0,0,1]
	v_pk_fma_f32 v[42:43], v[34:35], v[12:13], v[50:51] op_sel_hi:[0,1,1] neg_lo:[0,0,1] neg_hi:[0,0,1]
	v_cvt_pk_bf16_f32 v28, v36, v37
	v_cvt_pk_bf16_f32 v29, v38, v39
	v_cvt_pk_bf16_f32 v30, v40, v41
	v_cvt_pk_bf16_f32 v31, v42, v43
	global_store_dwordx4 v[10:11], v[28:31], off
	v_lshlrev_b32_e32 v44, 16, v164
	v_and_b32_e32 v45, 0xffff0000, v164
	v_lshlrev_b32_e32 v46, 16, v165
	v_and_b32_e32 v47, 0xffff0000, v165
	v_lshlrev_b32_e32 v48, 16, v166
	v_and_b32_e32 v49, 0xffff0000, v166
	v_lshlrev_b32_e32 v50, 16, v167
	v_and_b32_e32 v51, 0xffff0000, v167
	v_pk_add_f32 v[14:15], v[14:15], v[44:45] neg_lo:[0,1] neg_hi:[0,1]
	v_pk_add_f32 v[16:17], v[16:17], v[46:47] neg_lo:[0,1] neg_hi:[0,1]
	v_pk_add_f32 v[18:19], v[18:19], v[48:49] neg_lo:[0,1] neg_hi:[0,1]
	v_pk_add_f32 v[12:13], v[12:13], v[50:51] neg_lo:[0,1] neg_hi:[0,1]
	v_lshl_add_u64 v[10:11], v[10:11], 0, s[26:27]
	v_lshlrev_b32_e32 v44, 16, v180
	v_and_b32_e32 v45, 0xffff0000, v180
	v_lshlrev_b32_e32 v46, 16, v181
	v_and_b32_e32 v47, 0xffff0000, v181
	v_lshlrev_b32_e32 v48, 16, v182
	v_and_b32_e32 v49, 0xffff0000, v182
	v_lshlrev_b32_e32 v50, 16, v183
	v_and_b32_e32 v51, 0xffff0000, v183
	v_pk_add_f32 v[14:15], v[14:15], v[44:45]
	v_pk_add_f32 v[16:17], v[16:17], v[46:47]
	v_pk_add_f32 v[18:19], v[18:19], v[48:49]
	v_pk_add_f32 v[12:13], v[12:13], v[50:51]
	v_pk_fma_f32 v[36:37], v[34:35], v[14:15], v[44:45] op_sel_hi:[0,1,1] neg_lo:[0,0,1] neg_hi:[0,0,1]
	v_pk_fma_f32 v[38:39], v[34:35], v[16:17], v[46:47] op_sel_hi:[0,1,1] neg_lo:[0,0,1] neg_hi:[0,0,1]
	v_pk_fma_f32 v[40:41], v[34:35], v[18:19], v[48:49] op_sel_hi:[0,1,1] neg_lo:[0,0,1] neg_hi:[0,0,1]
	v_pk_fma_f32 v[42:43], v[34:35], v[12:13], v[50:51] op_sel_hi:[0,1,1] neg_lo:[0,0,1] neg_hi:[0,0,1]
	v_cvt_pk_bf16_f32 v28, v36, v37
	v_cvt_pk_bf16_f32 v29, v38, v39
	v_cvt_pk_bf16_f32 v30, v40, v41
	v_cvt_pk_bf16_f32 v31, v42, v43
	global_store_dwordx4 v[10:11], v[28:31], off
	v_lshlrev_b32_e32 v44, 16, v168
	v_and_b32_e32 v45, 0xffff0000, v168
	v_lshlrev_b32_e32 v46, 16, v169
	v_and_b32_e32 v47, 0xffff0000, v169
	v_lshlrev_b32_e32 v48, 16, v170
	v_and_b32_e32 v49, 0xffff0000, v170
	v_lshlrev_b32_e32 v50, 16, v171
	v_and_b32_e32 v51, 0xffff0000, v171
	v_pk_add_f32 v[14:15], v[14:15], v[44:45] neg_lo:[0,1] neg_hi:[0,1]
	v_pk_add_f32 v[16:17], v[16:17], v[46:47] neg_lo:[0,1] neg_hi:[0,1]
	v_pk_add_f32 v[18:19], v[18:19], v[48:49] neg_lo:[0,1] neg_hi:[0,1]
	v_pk_add_f32 v[12:13], v[12:13], v[50:51] neg_lo:[0,1] neg_hi:[0,1]
	v_lshl_add_u64 v[10:11], v[10:11], 0, s[26:27]
	v_lshlrev_b32_e32 v44, 16, v184
	v_and_b32_e32 v45, 0xffff0000, v184
	v_lshlrev_b32_e32 v46, 16, v185
	v_and_b32_e32 v47, 0xffff0000, v185
	v_lshlrev_b32_e32 v48, 16, v186
	v_and_b32_e32 v49, 0xffff0000, v186
	v_lshlrev_b32_e32 v50, 16, v187
	v_and_b32_e32 v51, 0xffff0000, v187
	v_pk_add_f32 v[14:15], v[14:15], v[44:45]
	v_pk_add_f32 v[16:17], v[16:17], v[46:47]
	v_pk_add_f32 v[18:19], v[18:19], v[48:49]
	v_pk_add_f32 v[12:13], v[12:13], v[50:51]
	v_pk_fma_f32 v[36:37], v[34:35], v[14:15], v[44:45] op_sel_hi:[0,1,1] neg_lo:[0,0,1] neg_hi:[0,0,1]
	v_pk_fma_f32 v[38:39], v[34:35], v[16:17], v[46:47] op_sel_hi:[0,1,1] neg_lo:[0,0,1] neg_hi:[0,0,1]
	v_pk_fma_f32 v[40:41], v[34:35], v[18:19], v[48:49] op_sel_hi:[0,1,1] neg_lo:[0,0,1] neg_hi:[0,0,1]
	v_pk_fma_f32 v[42:43], v[34:35], v[12:13], v[50:51] op_sel_hi:[0,1,1] neg_lo:[0,0,1] neg_hi:[0,0,1]
	v_cvt_pk_bf16_f32 v28, v36, v37
	v_cvt_pk_bf16_f32 v29, v38, v39
	v_cvt_pk_bf16_f32 v30, v40, v41
	v_cvt_pk_bf16_f32 v31, v42, v43
	global_store_dwordx4 v[10:11], v[28:31], off
	v_lshlrev_b32_e32 v44, 16, v172
	v_and_b32_e32 v45, 0xffff0000, v172
	v_lshlrev_b32_e32 v46, 16, v173
	v_and_b32_e32 v47, 0xffff0000, v173
	v_lshlrev_b32_e32 v48, 16, v174
	v_and_b32_e32 v49, 0xffff0000, v174
	v_lshlrev_b32_e32 v50, 16, v175
	v_and_b32_e32 v51, 0xffff0000, v175
	v_pk_add_f32 v[14:15], v[14:15], v[44:45] neg_lo:[0,1] neg_hi:[0,1]
	v_pk_add_f32 v[16:17], v[16:17], v[46:47] neg_lo:[0,1] neg_hi:[0,1]
	v_pk_add_f32 v[18:19], v[18:19], v[48:49] neg_lo:[0,1] neg_hi:[0,1]
	v_pk_add_f32 v[12:13], v[12:13], v[50:51] neg_lo:[0,1] neg_hi:[0,1]
	v_lshl_add_u64 v[10:11], v[10:11], 0, s[26:27]
	v_lshlrev_b32_e32 v44, 16, v188
	v_and_b32_e32 v45, 0xffff0000, v188
	v_lshlrev_b32_e32 v46, 16, v189
	v_and_b32_e32 v47, 0xffff0000, v189
	v_lshlrev_b32_e32 v48, 16, v190
	v_and_b32_e32 v49, 0xffff0000, v190
	v_lshlrev_b32_e32 v50, 16, v191
	v_and_b32_e32 v51, 0xffff0000, v191
	v_pk_add_f32 v[14:15], v[14:15], v[44:45]
	v_pk_add_f32 v[16:17], v[16:17], v[46:47]
	v_pk_add_f32 v[18:19], v[18:19], v[48:49]
	v_pk_add_f32 v[12:13], v[12:13], v[50:51]
	v_pk_fma_f32 v[36:37], v[34:35], v[14:15], v[44:45] op_sel_hi:[0,1,1] neg_lo:[0,0,1] neg_hi:[0,0,1]
; __device__ __forceinline__ unsigned pk2(float lo, float hi) { f32x2 v = {lo, hi}; bf16x2_t b = __builtin_convertvector(v, bf16x2_t); return __builtin_bit_cast(unsigned, b); }
; __device__ __forceinline__ void pool_window(const bf16_t* __restrict__ U  , bf16_t* __restrict__ A3, const int gtid, const int nthr) {
;     ...
;         for (int i = 0; i < 32; ++i) {
;             const int t = t0 + i, s = s0 + i;
;             const u32x4 uu = *(const u32x4*)(U + (size_t)t * LDU + c);
;             float cu[8] = {bflo(uu.x), bfhi(uu.x), bflo(uu.y), bfhi(uu.y), bflo(uu.z), bfhi(uu.z), bflo(uu.w), bfhi(uu.w)};
;             const float rc = 1.0f / (float)((s + 1) < w ? (s + 1) : w);
;             float o[8];
; #pragma unroll
;             for (int e = 0; e < 8; ++e) { sum[e] += cu[e]; o[e] = sum[e] * rc - cu[e]; }
;             u32x4 ww; ww.x = pk2(o[0], o[1]); ww.y = pk2(o[2], o[3]); ww.z = pk2(o[4], o[5]); ww.w = pk2(o[6], o[7]);
;             *(u32x4*)(A3 + (size_t)t * DM + c) = ww;
;             if (s + 1 >= w) { const u32x4 ud = *(const u32x4*)(U + (size_t)(t - w + 1) * LDU + c);
;                 sum[0] -= bflo(ud.x); sum[1] -= bfhi(ud.x); sum[2] -= bflo(ud.y); sum[3] -= bfhi(ud.y); sum[4] -= bflo(ud.z); sum[5] -= bfhi(ud.z); sum[6] -= bflo(ud.w); sum[7] -= bfhi(ud.w); }
	v_pk_fma_f32 v[38:39], v[34:35], v[16:17], v[46:47] op_sel_hi:[0,1,1] neg_lo:[0,0,1] neg_hi:[0,0,1]
	v_pk_fma_f32 v[40:41], v[34:35], v[18:19], v[48:49] op_sel_hi:[0,1,1] neg_lo:[0,0,1] neg_hi:[0,0,1]
	v_pk_fma_f32 v[42:43], v[34:35], v[12:13], v[50:51] op_sel_hi:[0,1,1] neg_lo:[0,0,1] neg_hi:[0,0,1]
	v_cvt_pk_bf16_f32 v28, v36, v37
	v_cvt_pk_bf16_f32 v29, v38, v39
	v_cvt_pk_bf16_f32 v30, v40, v41
	v_cvt_pk_bf16_f32 v31, v42, v43
	global_store_dwordx4 v[10:11], v[28:31], off
	v_lshlrev_b32_e32 v44, 16, v176
	v_and_b32_e32 v45, 0xffff0000, v176
	v_lshlrev_b32_e32 v46, 16, v177
	v_and_b32_e32 v47, 0xffff0000, v177
	v_lshlrev_b32_e32 v48, 16, v178
	v_and_b32_e32 v49, 0xffff0000, v178
	v_lshlrev_b32_e32 v50, 16, v179
	v_and_b32_e32 v51, 0xffff0000, v179
	v_pk_add_f32 v[14:15], v[14:15], v[44:45] neg_lo:[0,1] neg_hi:[0,1]
	v_pk_add_f32 v[16:17], v[16:17], v[46:47] neg_lo:[0,1] neg_hi:[0,1]
	v_pk_add_f32 v[18:19], v[18:19], v[48:49] neg_lo:[0,1] neg_hi:[0,1]
	v_pk_add_f32 v[12:13], v[12:13], v[50:51] neg_lo:[0,1] neg_hi:[0,1]
	v_lshl_add_u64 v[10:11], v[10:11], 0, s[26:27]
	v_lshlrev_b32_e32 v44, 16, v192
	v_and_b32_e32 v45, 0xffff0000, v192
	v_lshlrev_b32_e32 v46, 16, v193
	v_and_b32_e32 v47, 0xffff0000, v193
	v_lshlrev_b32_e32 v48, 16, v194
	v_and_b32_e32 v49, 0xffff0000, v194
	v_lshlrev_b32_e32 v50, 16, v195
	v_and_b32_e32 v51, 0xffff0000, v195
	v_pk_add_f32 v[14:15], v[14:15], v[44:45]
	v_pk_add_f32 v[16:17], v[16:17], v[46:47]
	v_pk_add_f32 v[18:19], v[18:19], v[48:49]
	v_pk_add_f32 v[12:13], v[12:13], v[50:51]
	v_pk_fma_f32 v[36:37], v[34:35], v[14:15], v[44:45] op_sel_hi:[0,1,1] neg_lo:[0,0,1] neg_hi:[0,0,1]
	v_pk_fma_f32 v[38:39], v[34:35], v[16:17], v[46:47] op_sel_hi:[0,1,1] neg_lo:[0,0,1] neg_hi:[0,0,1]
	v_pk_fma_f32 v[40:41], v[34:35], v[18:19], v[48:49] op_sel_hi:[0,1,1] neg_lo:[0,0,1] neg_hi:[0,0,1]
	v_pk_fma_f32 v[42:43], v[34:35], v[12:13], v[50:51] op_sel_hi:[0,1,1] neg_lo:[0,0,1] neg_hi:[0,0,1]
	v_cvt_pk_bf16_f32 v28, v36, v37
	v_cvt_pk_bf16_f32 v29, v38, v39
	v_cvt_pk_bf16_f32 v30, v40, v41
	v_cvt_pk_bf16_f32 v31, v42, v43
	global_store_dwordx4 v[10:11], v[28:31], off
	v_lshlrev_b32_e32 v44, 16, v180
	v_and_b32_e32 v45, 0xffff0000, v180
	v_lshlrev_b32_e32 v46, 16, v181
	v_and_b32_e32 v47, 0xffff0000, v181
	v_lshlrev_b32_e32 v48, 16, v182
	v_and_b32_e32 v49, 0xffff0000, v182
	v_lshlrev_b32_e32 v50, 16, v183
	v_and_b32_e32 v51, 0xffff0000, v183
	v_pk_add_f32 v[14:15], v[14:15], v[44:45] neg_lo:[0,1] neg_hi:[0,1]
	v_pk_add_f32 v[16:17], v[16:17], v[46:47] neg_lo:[0,1] neg_hi:[0,1]
	v_pk_add_f32 v[18:19], v[18:19], v[48:49] neg_lo:[0,1] neg_hi:[0,1]
	v_pk_add_f32 v[12:13], v[12:13], v[50:51] neg_lo:[0,1] neg_hi:[0,1]
	v_lshl_add_u64 v[10:11], v[10:11], 0, s[26:27]
	v_lshlrev_b32_e32 v44, 16, v196
	v_and_b32_e32 v45, 0xffff0000, v196
	v_lshlrev_b32_e32 v46, 16, v197
	v_and_b32_e32 v47, 0xffff0000, v197
	v_lshlrev_b32_e32 v48, 16, v198
	v_and_b32_e32 v49, 0xffff0000, v198
	v_lshlrev_b32_e32 v50, 16, v199
	v_and_b32_e32 v51, 0xffff0000, v199
	v_pk_add_f32 v[14:15], v[14:15], v[44:45]
	v_pk_add_f32 v[16:17], v[16:17], v[46:47]
	v_pk_add_f32 v[18:19], v[18:19], v[48:49]
	v_pk_add_f32 v[12:13], v[12:13], v[50:51]
	v_pk_fma_f32 v[36:37], v[34:35], v[14:15], v[44:45] op_sel_hi:[0,1,1] neg_lo:[0,0,1] neg_hi:[0,0,1]
	v_pk_fma_f32 v[38:39], v[34:35], v[16:17], v[46:47] op_sel_hi:[0,1,1] neg_lo:[0,0,1] neg_hi:[0,0,1]
	v_pk_fma_f32 v[40:41], v[34:35], v[18:19], v[48:49] op_sel_hi:[0,1,1] neg_lo:[0,0,1] neg_hi:[0,0,1]
	v_pk_fma_f32 v[42:43], v[34:35], v[12:13], v[50:51] op_sel_hi:[0,1,1] neg_lo:[0,0,1] neg_hi:[0,0,1]
	v_cvt_pk_bf16_f32 v28, v36, v37
	v_cvt_pk_bf16_f32 v29, v38, v39
	v_cvt_pk_bf16_f32 v30, v40, v41
	v_cvt_pk_bf16_f32 v31, v42, v43
	global_store_dwordx4 v[10:11], v[28:31], off
	v_lshlrev_b32_e32 v44, 16, v184
	v_and_b32_e32 v45, 0xffff0000, v184
	v_lshlrev_b32_e32 v46, 16, v185
	v_and_b32_e32 v47, 0xffff0000, v185
	v_lshlrev_b32_e32 v48, 16, v186
	v_and_b32_e32 v49, 0xffff0000, v186
	v_lshlrev_b32_e32 v50, 16, v187
	v_and_b32_e32 v51, 0xffff0000, v187
	v_pk_add_f32 v[14:15], v[14:15], v[44:45] neg_lo:[0,1] neg_hi:[0,1]
	v_pk_add_f32 v[16:17], v[16:17], v[46:47] neg_lo:[0,1] neg_hi:[0,1]
	v_pk_add_f32 v[18:19], v[18:19], v[48:49] neg_lo:[0,1] neg_hi:[0,1]
	v_pk_add_f32 v[12:13], v[12:13], v[50:51] neg_lo:[0,1] neg_hi:[0,1]
	v_lshl_add_u64 v[10:11], v[10:11], 0, s[26:27]
	v_lshlrev_b32_e32 v44, 16, v200
	v_and_b32_e32 v45, 0xffff0000, v200
	v_lshlrev_b32_e32 v46, 16, v201
	v_and_b32_e32 v47, 0xffff0000, v201
	v_lshlrev_b32_e32 v48, 16, v202
	v_and_b32_e32 v49, 0xffff0000, v202
	v_lshlrev_b32_e32 v50, 16, v203
	v_and_b32_e32 v51, 0xffff0000, v203
	v_pk_add_f32 v[14:15], v[14:15], v[44:45]
	v_pk_add_f32 v[16:17], v[16:17], v[46:47]
	v_pk_add_f32 v[18:19], v[18:19], v[48:49]
	v_pk_add_f32 v[12:13], v[12:13], v[50:51]
	v_pk_fma_f32 v[36:37], v[34:35], v[14:15], v[44:45] op_sel_hi:[0,1,1] neg_lo:[0,0,1] neg_hi:[0,0,1]
	v_pk_fma_f32 v[38:39], v[34:35], v[16:17], v[46:47] op_sel_hi:[0,1,1] neg_lo:[0,0,1] neg_hi:[0,0,1]
	v_pk_fma_f32 v[40:41], v[34:35], v[18:19], v[48:49] op_sel_hi:[0,1,1] neg_lo:[0,0,1] neg_hi:[0,0,1]
	v_pk_fma_f32 v[42:43], v[34:35], v[12:13], v[50:51] op_sel_hi:[0,1,1] neg_lo:[0,0,1] neg_hi:[0,0,1]
	v_cvt_pk_bf16_f32 v28, v36, v37
	v_cvt_pk_bf16_f32 v29, v38, v39
	v_cvt_pk_bf16_f32 v30, v40, v41
	v_cvt_pk_bf16_f32 v31, v42, v43
	global_store_dwordx4 v[10:11], v[28:31], off
	v_lshlrev_b32_e32 v44, 16, v188
	v_and_b32_e32 v45, 0xffff0000, v188
	v_lshlrev_b32_e32 v46, 16, v189
	v_and_b32_e32 v47, 0xffff0000, v189
	v_lshlrev_b32_e32 v48, 16, v190
	v_and_b32_e32 v49, 0xffff0000, v190
	v_lshlrev_b32_e32 v50, 16, v191
; __device__ __forceinline__ unsigned pk2(float lo, float hi) { f32x2 v = {lo, hi}; bf16x2_t b = __builtin_convertvector(v, bf16x2_t); return __builtin_bit_cast(unsigned, b); }
; __device__ __forceinline__ void pool_window(const bf16_t* __restrict__ U  , bf16_t* __restrict__ A3, const int gtid, const int nthr) {
;     ...
;         for (int i = 0; i < 32; ++i) {
;             const int t = t0 + i, s = s0 + i;
;             const u32x4 uu = *(const u32x4*)(U + (size_t)t * LDU + c);
;             float cu[8] = {bflo(uu.x), bfhi(uu.x), bflo(uu.y), bfhi(uu.y), bflo(uu.z), bfhi(uu.z), bflo(uu.w), bfhi(uu.w)};
;             const float rc = 1.0f / (float)((s + 1) < w ? (s + 1) : w);
;             float o[8];
; #pragma unroll
;             for (int e = 0; e < 8; ++e) { sum[e] += cu[e]; o[e] = sum[e] * rc - cu[e]; }
;             u32x4 ww; ww.x = pk2(o[0], o[1]); ww.y = pk2(o[2], o[3]); ww.z = pk2(o[4], o[5]); ww.w = pk2(o[6], o[7]);
;             *(u32x4*)(A3 + (size_t)t * DM + c) = ww;
;             if (s + 1 >= w) { const u32x4 ud = *(const u32x4*)(U + (size_t)(t - w + 1) * LDU + c);
;                 sum[0] -= bflo(ud.x); sum[1] -= bfhi(ud.x); sum[2] -= bflo(ud.y); sum[3] -= bfhi(ud.y); sum[4] -= bflo(ud.z); sum[5] -= bfhi(ud.z); sum[6] -= bflo(ud.w); sum[7] -= bfhi(ud.w); }
	v_and_b32_e32 v51, 0xffff0000, v191
	v_pk_add_f32 v[14:15], v[14:15], v[44:45] neg_lo:[0,1] neg_hi:[0,1]
	v_pk_add_f32 v[16:17], v[16:17], v[46:47] neg_lo:[0,1] neg_hi:[0,1]
	v_pk_add_f32 v[18:19], v[18:19], v[48:49] neg_lo:[0,1] neg_hi:[0,1]
	v_pk_add_f32 v[12:13], v[12:13], v[50:51] neg_lo:[0,1] neg_hi:[0,1]
	v_lshl_add_u64 v[10:11], v[10:11], 0, s[26:27]
	v_lshlrev_b32_e32 v44, 16, v204
	v_and_b32_e32 v45, 0xffff0000, v204
	v_lshlrev_b32_e32 v46, 16, v205
	v_and_b32_e32 v47, 0xffff0000, v205
	v_lshlrev_b32_e32 v48, 16, v206
	v_and_b32_e32 v49, 0xffff0000, v206
	v_lshlrev_b32_e32 v50, 16, v207
	v_and_b32_e32 v51, 0xffff0000, v207
	v_pk_add_f32 v[14:15], v[14:15], v[44:45]
	v_pk_add_f32 v[16:17], v[16:17], v[46:47]
	v_pk_add_f32 v[18:19], v[18:19], v[48:49]
	v_pk_add_f32 v[12:13], v[12:13], v[50:51]
	v_pk_fma_f32 v[36:37], v[34:35], v[14:15], v[44:45] op_sel_hi:[0,1,1] neg_lo:[0,0,1] neg_hi:[0,0,1]
	v_pk_fma_f32 v[38:39], v[34:35], v[16:17], v[46:47] op_sel_hi:[0,1,1] neg_lo:[0,0,1] neg_hi:[0,0,1]
	v_pk_fma_f32 v[40:41], v[34:35], v[18:19], v[48:49] op_sel_hi:[0,1,1] neg_lo:[0,0,1] neg_hi:[0,0,1]
	v_pk_fma_f32 v[42:43], v[34:35], v[12:13], v[50:51] op_sel_hi:[0,1,1] neg_lo:[0,0,1] neg_hi:[0,0,1]
	v_cvt_pk_bf16_f32 v28, v36, v37
	v_cvt_pk_bf16_f32 v29, v38, v39
	v_cvt_pk_bf16_f32 v30, v40, v41
	v_cvt_pk_bf16_f32 v31, v42, v43
	global_store_dwordx4 v[10:11], v[28:31], off
	v_lshlrev_b32_e32 v44, 16, v192
	v_and_b32_e32 v45, 0xffff0000, v192
	v_lshlrev_b32_e32 v46, 16, v193
	v_and_b32_e32 v47, 0xffff0000, v193
	v_lshlrev_b32_e32 v48, 16, v194
	v_and_b32_e32 v49, 0xffff0000, v194
	v_lshlrev_b32_e32 v50, 16, v195
	v_and_b32_e32 v51, 0xffff0000, v195
	v_pk_add_f32 v[14:15], v[14:15], v[44:45] neg_lo:[0,1] neg_hi:[0,1]
	v_pk_add_f32 v[16:17], v[16:17], v[46:47] neg_lo:[0,1] neg_hi:[0,1]
	v_pk_add_f32 v[18:19], v[18:19], v[48:49] neg_lo:[0,1] neg_hi:[0,1]
	v_pk_add_f32 v[12:13], v[12:13], v[50:51] neg_lo:[0,1] neg_hi:[0,1]
	v_lshl_add_u64 v[10:11], v[10:11], 0, s[26:27]
	v_lshlrev_b32_e32 v44, 16, v208
	v_and_b32_e32 v45, 0xffff0000, v208
	v_lshlrev_b32_e32 v46, 16, v209
	v_and_b32_e32 v47, 0xffff0000, v209
	v_lshlrev_b32_e32 v48, 16, v210
	v_and_b32_e32 v49, 0xffff0000, v210
	v_lshlrev_b32_e32 v50, 16, v211
	v_and_b32_e32 v51, 0xffff0000, v211
	v_pk_add_f32 v[14:15], v[14:15], v[44:45]
	v_pk_add_f32 v[16:17], v[16:17], v[46:47]
	v_pk_add_f32 v[18:19], v[18:19], v[48:49]
	v_pk_add_f32 v[12:13], v[12:13], v[50:51]
	v_pk_fma_f32 v[36:37], v[34:35], v[14:15], v[44:45] op_sel_hi:[0,1,1] neg_lo:[0,0,1] neg_hi:[0,0,1]
	v_pk_fma_f32 v[38:39], v[34:35], v[16:17], v[46:47] op_sel_hi:[0,1,1] neg_lo:[0,0,1] neg_hi:[0,0,1]
	v_pk_fma_f32 v[40:41], v[34:35], v[18:19], v[48:49] op_sel_hi:[0,1,1] neg_lo:[0,0,1] neg_hi:[0,0,1]
	v_pk_fma_f32 v[42:43], v[34:35], v[12:13], v[50:51] op_sel_hi:[0,1,1] neg_lo:[0,0,1] neg_hi:[0,0,1]
	v_cvt_pk_bf16_f32 v28, v36, v37
	v_cvt_pk_bf16_f32 v29, v38, v39
	v_cvt_pk_bf16_f32 v30, v40, v41
	v_cvt_pk_bf16_f32 v31, v42, v43
	global_store_dwordx4 v[10:11], v[28:31], off
	v_lshlrev_b32_e32 v44, 16, v196
	v_and_b32_e32 v45, 0xffff0000, v196
	v_lshlrev_b32_e32 v46, 16, v197
	v_and_b32_e32 v47, 0xffff0000, v197
	v_lshlrev_b32_e32 v48, 16, v198
	v_and_b32_e32 v49, 0xffff0000, v198
	v_lshlrev_b32_e32 v50, 16, v199
	v_and_b32_e32 v51, 0xffff0000, v199
	v_pk_add_f32 v[14:15], v[14:15], v[44:45] neg_lo:[0,1] neg_hi:[0,1]
	v_pk_add_f32 v[16:17], v[16:17], v[46:47] neg_lo:[0,1] neg_hi:[0,1]
	v_pk_add_f32 v[18:19], v[18:19], v[48:49] neg_lo:[0,1] neg_hi:[0,1]
	v_pk_add_f32 v[12:13], v[12:13], v[50:51] neg_lo:[0,1] neg_hi:[0,1]
	v_lshl_add_u64 v[10:11], v[10:11], 0, s[26:27]
	v_lshlrev_b32_e32 v44, 16, v214
	v_and_b32_e32 v45, 0xffff0000, v214
	v_lshlrev_b32_e32 v46, 16, v215
	v_and_b32_e32 v47, 0xffff0000, v215
	v_lshlrev_b32_e32 v48, 16, v216
	v_and_b32_e32 v49, 0xffff0000, v216
	v_lshlrev_b32_e32 v50, 16, v217
	v_and_b32_e32 v51, 0xffff0000, v217
	v_pk_add_f32 v[14:15], v[14:15], v[44:45]
	v_pk_add_f32 v[16:17], v[16:17], v[46:47]
	v_pk_add_f32 v[18:19], v[18:19], v[48:49]
	v_pk_add_f32 v[12:13], v[12:13], v[50:51]
	v_pk_fma_f32 v[36:37], v[34:35], v[14:15], v[44:45] op_sel_hi:[0,1,1] neg_lo:[0,0,1] neg_hi:[0,0,1]
	v_pk_fma_f32 v[38:39], v[34:35], v[16:17], v[46:47] op_sel_hi:[0,1,1] neg_lo:[0,0,1] neg_hi:[0,0,1]
	v_pk_fma_f32 v[40:41], v[34:35], v[18:19], v[48:49] op_sel_hi:[0,1,1] neg_lo:[0,0,1] neg_hi:[0,0,1]
	v_pk_fma_f32 v[42:43], v[34:35], v[12:13], v[50:51] op_sel_hi:[0,1,1] neg_lo:[0,0,1] neg_hi:[0,0,1]
	v_cvt_pk_bf16_f32 v28, v36, v37
	v_cvt_pk_bf16_f32 v29, v38, v39
	v_cvt_pk_bf16_f32 v30, v40, v41
	v_cvt_pk_bf16_f32 v31, v42, v43
	global_store_dwordx4 v[10:11], v[28:31], off
	v_lshlrev_b32_e32 v44, 16, v200
	v_and_b32_e32 v45, 0xffff0000, v200
	v_lshlrev_b32_e32 v46, 16, v201
	v_and_b32_e32 v47, 0xffff0000, v201
	v_lshlrev_b32_e32 v48, 16, v202
	v_and_b32_e32 v49, 0xffff0000, v202
	v_lshlrev_b32_e32 v50, 16, v203
	v_and_b32_e32 v51, 0xffff0000, v203
	v_pk_add_f32 v[14:15], v[14:15], v[44:45] neg_lo:[0,1] neg_hi:[0,1]
	v_pk_add_f32 v[16:17], v[16:17], v[46:47] neg_lo:[0,1] neg_hi:[0,1]
	v_pk_add_f32 v[18:19], v[18:19], v[48:49] neg_lo:[0,1] neg_hi:[0,1]
	v_pk_add_f32 v[12:13], v[12:13], v[50:51] neg_lo:[0,1] neg_hi:[0,1]
	v_lshl_add_u64 v[10:11], v[10:11], 0, s[26:27]
	v_lshlrev_b32_e32 v44, 16, v218
	v_and_b32_e32 v45, 0xffff0000, v218
	v_lshlrev_b32_e32 v46, 16, v219
	v_and_b32_e32 v47, 0xffff0000, v219
	v_lshlrev_b32_e32 v48, 16, v220
	v_and_b32_e32 v49, 0xffff0000, v220
	v_lshlrev_b32_e32 v50, 16, v221
	v_and_b32_e32 v51, 0xffff0000, v221
	v_pk_add_f32 v[14:15], v[14:15], v[44:45]
	v_pk_add_f32 v[16:17], v[16:17], v[46:47]
; __device__ __forceinline__ unsigned pk2(float lo, float hi) { f32x2 v = {lo, hi}; bf16x2_t b = __builtin_convertvector(v, bf16x2_t); return __builtin_bit_cast(unsigned, b); }
; __device__ __forceinline__ void pool_window(const bf16_t* __restrict__ U  , bf16_t* __restrict__ A3, const int gtid, const int nthr) {
;     ...
;         for (int i = 0; i < 32; ++i) {
;             const int t = t0 + i, s = s0 + i;
;             const u32x4 uu = *(const u32x4*)(U + (size_t)t * LDU + c);
;             float cu[8] = {bflo(uu.x), bfhi(uu.x), bflo(uu.y), bfhi(uu.y), bflo(uu.z), bfhi(uu.z), bflo(uu.w), bfhi(uu.w)};
;             const float rc = 1.0f / (float)((s + 1) < w ? (s + 1) : w);
;             float o[8];
; #pragma unroll
;             for (int e = 0; e < 8; ++e) { sum[e] += cu[e]; o[e] = sum[e] * rc - cu[e]; }
;             u32x4 ww; ww.x = pk2(o[0], o[1]); ww.y = pk2(o[2], o[3]); ww.z = pk2(o[4], o[5]); ww.w = pk2(o[6], o[7]);
;             *(u32x4*)(A3 + (size_t)t * DM + c) = ww;
;             if (s + 1 >= w) { const u32x4 ud = *(const u32x4*)(U + (size_t)(t - w + 1) * LDU + c);
;                 sum[0] -= bflo(ud.x); sum[1] -= bfhi(ud.x); sum[2] -= bflo(ud.y); sum[3] -= bfhi(ud.y); sum[4] -= bflo(ud.z); sum[5] -= bfhi(ud.z); sum[6] -= bflo(ud.w); sum[7] -= bfhi(ud.w); }
	v_pk_add_f32 v[18:19], v[18:19], v[48:49]
	v_pk_add_f32 v[12:13], v[12:13], v[50:51]
	v_pk_fma_f32 v[36:37], v[34:35], v[14:15], v[44:45] op_sel_hi:[0,1,1] neg_lo:[0,0,1] neg_hi:[0,0,1]
	v_pk_fma_f32 v[38:39], v[34:35], v[16:17], v[46:47] op_sel_hi:[0,1,1] neg_lo:[0,0,1] neg_hi:[0,0,1]
	v_pk_fma_f32 v[40:41], v[34:35], v[18:19], v[48:49] op_sel_hi:[0,1,1] neg_lo:[0,0,1] neg_hi:[0,0,1]
	v_pk_fma_f32 v[42:43], v[34:35], v[12:13], v[50:51] op_sel_hi:[0,1,1] neg_lo:[0,0,1] neg_hi:[0,0,1]
	v_cvt_pk_bf16_f32 v28, v36, v37
	v_cvt_pk_bf16_f32 v29, v38, v39
	v_cvt_pk_bf16_f32 v30, v40, v41
	v_cvt_pk_bf16_f32 v31, v42, v43
	global_store_dwordx4 v[10:11], v[28:31], off
	v_lshlrev_b32_e32 v44, 16, v204
	v_and_b32_e32 v45, 0xffff0000, v204
	v_lshlrev_b32_e32 v46, 16, v205
	v_and_b32_e32 v47, 0xffff0000, v205
	v_lshlrev_b32_e32 v48, 16, v206
	v_and_b32_e32 v49, 0xffff0000, v206
	v_lshlrev_b32_e32 v50, 16, v207
	v_and_b32_e32 v51, 0xffff0000, v207
	v_pk_add_f32 v[14:15], v[14:15], v[44:45] neg_lo:[0,1] neg_hi:[0,1]
	v_pk_add_f32 v[16:17], v[16:17], v[46:47] neg_lo:[0,1] neg_hi:[0,1]
	v_pk_add_f32 v[18:19], v[18:19], v[48:49] neg_lo:[0,1] neg_hi:[0,1]
	v_pk_add_f32 v[12:13], v[12:13], v[50:51] neg_lo:[0,1] neg_hi:[0,1]
	v_lshl_add_u64 v[10:11], v[10:11], 0, s[26:27]
	v_lshlrev_b32_e32 v44, 16, v222
	v_and_b32_e32 v45, 0xffff0000, v222
	v_lshlrev_b32_e32 v46, 16, v223
	v_and_b32_e32 v47, 0xffff0000, v223
	v_lshlrev_b32_e32 v48, 16, v224
	v_and_b32_e32 v49, 0xffff0000, v224
	v_lshlrev_b32_e32 v50, 16, v225
	v_and_b32_e32 v51, 0xffff0000, v225
	v_pk_add_f32 v[14:15], v[14:15], v[44:45]
	v_pk_add_f32 v[16:17], v[16:17], v[46:47]
	v_pk_add_f32 v[18:19], v[18:19], v[48:49]
	v_pk_add_f32 v[12:13], v[12:13], v[50:51]
	v_pk_fma_f32 v[36:37], v[34:35], v[14:15], v[44:45] op_sel_hi:[0,1,1] neg_lo:[0,0,1] neg_hi:[0,0,1]
	v_pk_fma_f32 v[38:39], v[34:35], v[16:17], v[46:47] op_sel_hi:[0,1,1] neg_lo:[0,0,1] neg_hi:[0,0,1]
	v_pk_fma_f32 v[40:41], v[34:35], v[18:19], v[48:49] op_sel_hi:[0,1,1] neg_lo:[0,0,1] neg_hi:[0,0,1]
	v_pk_fma_f32 v[42:43], v[34:35], v[12:13], v[50:51] op_sel_hi:[0,1,1] neg_lo:[0,0,1] neg_hi:[0,0,1]
	v_cvt_pk_bf16_f32 v28, v36, v37
	v_cvt_pk_bf16_f32 v29, v38, v39
	v_cvt_pk_bf16_f32 v30, v40, v41
	v_cvt_pk_bf16_f32 v31, v42, v43
	global_store_dwordx4 v[10:11], v[28:31], off
	v_lshlrev_b32_e32 v44, 16, v208
	v_and_b32_e32 v45, 0xffff0000, v208
	v_lshlrev_b32_e32 v46, 16, v209
	v_and_b32_e32 v47, 0xffff0000, v209
	v_lshlrev_b32_e32 v48, 16, v210
	v_and_b32_e32 v49, 0xffff0000, v210
	v_lshlrev_b32_e32 v50, 16, v211
	v_and_b32_e32 v51, 0xffff0000, v211
	v_pk_add_f32 v[14:15], v[14:15], v[44:45] neg_lo:[0,1] neg_hi:[0,1]
	v_pk_add_f32 v[16:17], v[16:17], v[46:47] neg_lo:[0,1] neg_hi:[0,1]
	v_pk_add_f32 v[18:19], v[18:19], v[48:49] neg_lo:[0,1] neg_hi:[0,1]
	v_pk_add_f32 v[12:13], v[12:13], v[50:51] neg_lo:[0,1] neg_hi:[0,1]
	v_lshl_add_u64 v[10:11], v[10:11], 0, s[26:27]
	v_lshlrev_b32_e32 v44, 16, v226
	v_and_b32_e32 v45, 0xffff0000, v226
	v_lshlrev_b32_e32 v46, 16, v227
	v_and_b32_e32 v47, 0xffff0000, v227
	v_lshlrev_b32_e32 v48, 16, v228
	v_and_b32_e32 v49, 0xffff0000, v228
	v_lshlrev_b32_e32 v50, 16, v229
	v_and_b32_e32 v51, 0xffff0000, v229
	v_pk_add_f32 v[14:15], v[14:15], v[44:45]
	v_pk_add_f32 v[16:17], v[16:17], v[46:47]
	v_pk_add_f32 v[18:19], v[18:19], v[48:49]
	v_pk_add_f32 v[12:13], v[12:13], v[50:51]
	v_pk_fma_f32 v[36:37], v[34:35], v[14:15], v[44:45] op_sel_hi:[0,1,1] neg_lo:[0,0,1] neg_hi:[0,0,1]
	v_pk_fma_f32 v[38:39], v[34:35], v[16:17], v[46:47] op_sel_hi:[0,1,1] neg_lo:[0,0,1] neg_hi:[0,0,1]
	v_pk_fma_f32 v[40:41], v[34:35], v[18:19], v[48:49] op_sel_hi:[0,1,1] neg_lo:[0,0,1] neg_hi:[0,0,1]
	v_pk_fma_f32 v[42:43], v[34:35], v[12:13], v[50:51] op_sel_hi:[0,1,1] neg_lo:[0,0,1] neg_hi:[0,0,1]
	v_cvt_pk_bf16_f32 v28, v36, v37
	v_cvt_pk_bf16_f32 v29, v38, v39
	v_cvt_pk_bf16_f32 v30, v40, v41
	v_cvt_pk_bf16_f32 v31, v42, v43
	global_store_dwordx4 v[10:11], v[28:31], off
	v_lshlrev_b32_e32 v44, 16, v214
	v_and_b32_e32 v45, 0xffff0000, v214
	v_lshlrev_b32_e32 v46, 16, v215
	v_and_b32_e32 v47, 0xffff0000, v215
	v_lshlrev_b32_e32 v48, 16, v216
	v_and_b32_e32 v49, 0xffff0000, v216
	v_lshlrev_b32_e32 v50, 16, v217
	v_and_b32_e32 v51, 0xffff0000, v217
	v_pk_add_f32 v[14:15], v[14:15], v[44:45] neg_lo:[0,1] neg_hi:[0,1]
	v_pk_add_f32 v[16:17], v[16:17], v[46:47] neg_lo:[0,1] neg_hi:[0,1]
	v_pk_add_f32 v[18:19], v[18:19], v[48:49] neg_lo:[0,1] neg_hi:[0,1]
	v_pk_add_f32 v[12:13], v[12:13], v[50:51] neg_lo:[0,1] neg_hi:[0,1]
	v_lshl_add_u64 v[10:11], v[10:11], 0, s[26:27]
	v_lshlrev_b32_e32 v44, 16, v230
	v_and_b32_e32 v45, 0xffff0000, v230
	v_lshlrev_b32_e32 v46, 16, v231
	v_and_b32_e32 v47, 0xffff0000, v231
	v_lshlrev_b32_e32 v48, 16, v232
	v_and_b32_e32 v49, 0xffff0000, v232
	v_lshlrev_b32_e32 v50, 16, v233
	v_and_b32_e32 v51, 0xffff0000, v233
	v_pk_add_f32 v[14:15], v[14:15], v[44:45]
	v_pk_add_f32 v[16:17], v[16:17], v[46:47]
	v_pk_add_f32 v[18:19], v[18:19], v[48:49]
	v_pk_add_f32 v[12:13], v[12:13], v[50:51]
	v_pk_fma_f32 v[36:37], v[34:35], v[14:15], v[44:45] op_sel_hi:[0,1,1] neg_lo:[0,0,1] neg_hi:[0,0,1]
	v_pk_fma_f32 v[38:39], v[34:35], v[16:17], v[46:47] op_sel_hi:[0,1,1] neg_lo:[0,0,1] neg_hi:[0,0,1]
	v_pk_fma_f32 v[40:41], v[34:35], v[18:19], v[48:49] op_sel_hi:[0,1,1] neg_lo:[0,0,1] neg_hi:[0,0,1]
	v_pk_fma_f32 v[42:43], v[34:35], v[12:13], v[50:51] op_sel_hi:[0,1,1] neg_lo:[0,0,1] neg_hi:[0,0,1]
	v_cvt_pk_bf16_f32 v28, v36, v37
	v_cvt_pk_bf16_f32 v29, v38, v39
	v_cvt_pk_bf16_f32 v30, v40, v41
	v_cvt_pk_bf16_f32 v31, v42, v43
	global_store_dwordx4 v[10:11], v[28:31], off
	v_lshlrev_b32_e32 v44, 16, v218
	v_and_b32_e32 v45, 0xffff0000, v218
; __device__ __forceinline__ unsigned pk2(float lo, float hi) { f32x2 v = {lo, hi}; bf16x2_t b = __builtin_convertvector(v, bf16x2_t); return __builtin_bit_cast(unsigned, b); }
; __device__ __forceinline__ void pool_window(const bf16_t* __restrict__ U  , bf16_t* __restrict__ A3, const int gtid, const int nthr) {
;     ...
;         for (int i = 0; i < 32; ++i) {
;             const int t = t0 + i, s = s0 + i;
;             const u32x4 uu = *(const u32x4*)(U + (size_t)t * LDU + c);
;             float cu[8] = {bflo(uu.x), bfhi(uu.x), bflo(uu.y), bfhi(uu.y), bflo(uu.z), bfhi(uu.z), bflo(uu.w), bfhi(uu.w)};
;             const float rc = 1.0f / (float)((s + 1) < w ? (s + 1) : w);
;             float o[8];
; #pragma unroll
;             for (int e = 0; e < 8; ++e) { sum[e] += cu[e]; o[e] = sum[e] * rc - cu[e]; }
;             u32x4 ww; ww.x = pk2(o[0], o[1]); ww.y = pk2(o[2], o[3]); ww.z = pk2(o[4], o[5]); ww.w = pk2(o[6], o[7]);
;             *(u32x4*)(A3 + (size_t)t * DM + c) = ww;
;             if (s + 1 >= w) { const u32x4 ud = *(const u32x4*)(U + (size_t)(t - w + 1) * LDU + c);
;                 sum[0] -= bflo(ud.x); sum[1] -= bfhi(ud.x); sum[2] -= bflo(ud.y); sum[3] -= bfhi(ud.y); sum[4] -= bflo(ud.z); sum[5] -= bfhi(ud.z); sum[6] -= bflo(ud.w); sum[7] -= bfhi(ud.w); }
	v_lshlrev_b32_e32 v46, 16, v219
	v_and_b32_e32 v47, 0xffff0000, v219
	v_lshlrev_b32_e32 v48, 16, v220
	v_and_b32_e32 v49, 0xffff0000, v220
	v_lshlrev_b32_e32 v50, 16, v221
	v_and_b32_e32 v51, 0xffff0000, v221
	v_pk_add_f32 v[14:15], v[14:15], v[44:45] neg_lo:[0,1] neg_hi:[0,1]
	v_pk_add_f32 v[16:17], v[16:17], v[46:47] neg_lo:[0,1] neg_hi:[0,1]
	v_pk_add_f32 v[18:19], v[18:19], v[48:49] neg_lo:[0,1] neg_hi:[0,1]
	v_pk_add_f32 v[12:13], v[12:13], v[50:51] neg_lo:[0,1] neg_hi:[0,1]
	v_lshl_add_u64 v[10:11], v[10:11], 0, s[26:27]
	v_lshlrev_b32_e32 v44, 16, v234
	v_and_b32_e32 v45, 0xffff0000, v234
	v_lshlrev_b32_e32 v46, 16, v235
	v_and_b32_e32 v47, 0xffff0000, v235
	v_lshlrev_b32_e32 v48, 16, v236
	v_and_b32_e32 v49, 0xffff0000, v236
	v_lshlrev_b32_e32 v50, 16, v237
	v_and_b32_e32 v51, 0xffff0000, v237
	v_pk_add_f32 v[14:15], v[14:15], v[44:45]
	v_pk_add_f32 v[16:17], v[16:17], v[46:47]
	v_pk_add_f32 v[18:19], v[18:19], v[48:49]
	v_pk_add_f32 v[12:13], v[12:13], v[50:51]
	v_pk_fma_f32 v[36:37], v[34:35], v[14:15], v[44:45] op_sel_hi:[0,1,1] neg_lo:[0,0,1] neg_hi:[0,0,1]
	v_pk_fma_f32 v[38:39], v[34:35], v[16:17], v[46:47] op_sel_hi:[0,1,1] neg_lo:[0,0,1] neg_hi:[0,0,1]
	v_pk_fma_f32 v[40:41], v[34:35], v[18:19], v[48:49] op_sel_hi:[0,1,1] neg_lo:[0,0,1] neg_hi:[0,0,1]
	v_pk_fma_f32 v[42:43], v[34:35], v[12:13], v[50:51] op_sel_hi:[0,1,1] neg_lo:[0,0,1] neg_hi:[0,0,1]
	v_cvt_pk_bf16_f32 v28, v36, v37
	v_cvt_pk_bf16_f32 v29, v38, v39
	v_cvt_pk_bf16_f32 v30, v40, v41
	v_cvt_pk_bf16_f32 v31, v42, v43
	global_store_dwordx4 v[10:11], v[28:31], off
	v_lshlrev_b32_e32 v44, 16, v222
	v_and_b32_e32 v45, 0xffff0000, v222
	v_lshlrev_b32_e32 v46, 16, v223
	v_and_b32_e32 v47, 0xffff0000, v223
	v_lshlrev_b32_e32 v48, 16, v224
	v_and_b32_e32 v49, 0xffff0000, v224
	v_lshlrev_b32_e32 v50, 16, v225
	v_and_b32_e32 v51, 0xffff0000, v225
	v_pk_add_f32 v[14:15], v[14:15], v[44:45] neg_lo:[0,1] neg_hi:[0,1]
	v_pk_add_f32 v[16:17], v[16:17], v[46:47] neg_lo:[0,1] neg_hi:[0,1]
	v_pk_add_f32 v[18:19], v[18:19], v[48:49] neg_lo:[0,1] neg_hi:[0,1]
	v_pk_add_f32 v[12:13], v[12:13], v[50:51] neg_lo:[0,1] neg_hi:[0,1]
	v_lshl_add_u64 v[10:11], v[10:11], 0, s[26:27]
	v_lshlrev_b32_e32 v44, 16, v238
	v_and_b32_e32 v45, 0xffff0000, v238
	v_lshlrev_b32_e32 v46, 16, v239
	v_and_b32_e32 v47, 0xffff0000, v239
	v_lshlrev_b32_e32 v48, 16, v240
	v_and_b32_e32 v49, 0xffff0000, v240
	v_lshlrev_b32_e32 v50, 16, v241
	v_and_b32_e32 v51, 0xffff0000, v241
	v_pk_add_f32 v[14:15], v[14:15], v[44:45]
	v_pk_add_f32 v[16:17], v[16:17], v[46:47]
	v_pk_add_f32 v[18:19], v[18:19], v[48:49]
	v_pk_add_f32 v[12:13], v[12:13], v[50:51]
	v_pk_fma_f32 v[36:37], v[34:35], v[14:15], v[44:45] op_sel_hi:[0,1,1] neg_lo:[0,0,1] neg_hi:[0,0,1]
	v_pk_fma_f32 v[38:39], v[34:35], v[16:17], v[46:47] op_sel_hi:[0,1,1] neg_lo:[0,0,1] neg_hi:[0,0,1]
	v_pk_fma_f32 v[40:41], v[34:35], v[18:19], v[48:49] op_sel_hi:[0,1,1] neg_lo:[0,0,1] neg_hi:[0,0,1]
	v_pk_fma_f32 v[42:43], v[34:35], v[12:13], v[50:51] op_sel_hi:[0,1,1] neg_lo:[0,0,1] neg_hi:[0,0,1]
	v_cvt_pk_bf16_f32 v28, v36, v37
	v_cvt_pk_bf16_f32 v29, v38, v39
	v_cvt_pk_bf16_f32 v30, v40, v41
	v_cvt_pk_bf16_f32 v31, v42, v43
	global_store_dwordx4 v[10:11], v[28:31], off
	v_lshlrev_b32_e32 v44, 16, v226
	v_and_b32_e32 v45, 0xffff0000, v226
	v_lshlrev_b32_e32 v46, 16, v227
	v_and_b32_e32 v47, 0xffff0000, v227
	v_lshlrev_b32_e32 v48, 16, v228
	v_and_b32_e32 v49, 0xffff0000, v228
	v_lshlrev_b32_e32 v50, 16, v229
	v_and_b32_e32 v51, 0xffff0000, v229
	v_pk_add_f32 v[14:15], v[14:15], v[44:45] neg_lo:[0,1] neg_hi:[0,1]
	v_pk_add_f32 v[16:17], v[16:17], v[46:47] neg_lo:[0,1] neg_hi:[0,1]
	v_pk_add_f32 v[18:19], v[18:19], v[48:49] neg_lo:[0,1] neg_hi:[0,1]
	v_pk_add_f32 v[12:13], v[12:13], v[50:51] neg_lo:[0,1] neg_hi:[0,1]
	v_lshl_add_u64 v[10:11], v[10:11], 0, s[26:27]
	v_lshlrev_b32_e32 v44, 16, v242
	v_and_b32_e32 v45, 0xffff0000, v242
	v_lshlrev_b32_e32 v46, 16, v243
	v_and_b32_e32 v47, 0xffff0000, v243
	v_lshlrev_b32_e32 v48, 16, v244
	v_and_b32_e32 v49, 0xffff0000, v244
	v_lshlrev_b32_e32 v50, 16, v245
	v_and_b32_e32 v51, 0xffff0000, v245
	v_pk_add_f32 v[14:15], v[14:15], v[44:45]
	v_pk_add_f32 v[16:17], v[16:17], v[46:47]
	v_pk_add_f32 v[18:19], v[18:19], v[48:49]
	v_pk_add_f32 v[12:13], v[12:13], v[50:51]
	v_pk_fma_f32 v[36:37], v[34:35], v[14:15], v[44:45] op_sel_hi:[0,1,1] neg_lo:[0,0,1] neg_hi:[0,0,1]
	v_pk_fma_f32 v[38:39], v[34:35], v[16:17], v[46:47] op_sel_hi:[0,1,1] neg_lo:[0,0,1] neg_hi:[0,0,1]
	v_pk_fma_f32 v[40:41], v[34:35], v[18:19], v[48:49] op_sel_hi:[0,1,1] neg_lo:[0,0,1] neg_hi:[0,0,1]
	v_pk_fma_f32 v[42:43], v[34:35], v[12:13], v[50:51] op_sel_hi:[0,1,1] neg_lo:[0,0,1] neg_hi:[0,0,1]
	v_cvt_pk_bf16_f32 v28, v36, v37
	v_cvt_pk_bf16_f32 v29, v38, v39
	v_cvt_pk_bf16_f32 v30, v40, v41
	v_cvt_pk_bf16_f32 v31, v42, v43
	global_store_dwordx4 v[10:11], v[28:31], off
	v_lshlrev_b32_e32 v44, 16, v230
	v_and_b32_e32 v45, 0xffff0000, v230
	v_lshlrev_b32_e32 v46, 16, v231
	v_and_b32_e32 v47, 0xffff0000, v231
	v_lshlrev_b32_e32 v48, 16, v232
	v_and_b32_e32 v49, 0xffff0000, v232
	v_lshlrev_b32_e32 v50, 16, v233
	v_and_b32_e32 v51, 0xffff0000, v233
	v_pk_add_f32 v[14:15], v[14:15], v[44:45] neg_lo:[0,1] neg_hi:[0,1]
	v_pk_add_f32 v[16:17], v[16:17], v[46:47] neg_lo:[0,1] neg_hi:[0,1]
	v_pk_add_f32 v[18:19], v[18:19], v[48:49] neg_lo:[0,1] neg_hi:[0,1]
	v_pk_add_f32 v[12:13], v[12:13], v[50:51] neg_lo:[0,1] neg_hi:[0,1]
	v_lshl_add_u64 v[10:11], v[10:11], 0, s[26:27]
	v_lshlrev_b32_e32 v44, 16, v246
	v_and_b32_e32 v45, 0xffff0000, v246
	v_lshlrev_b32_e32 v46, 16, v247
	v_and_b32_e32 v47, 0xffff0000, v247
	v_lshlrev_b32_e32 v48, 16, v248
	v_and_b32_e32 v49, 0xffff0000, v248
; __device__ __forceinline__ unsigned pk2(float lo, float hi) { f32x2 v = {lo, hi}; bf16x2_t b = __builtin_convertvector(v, bf16x2_t); return __builtin_bit_cast(unsigned, b); }
; __device__ __forceinline__ void pool_window(const bf16_t* __restrict__ U  , bf16_t* __restrict__ A3, const int gtid, const int nthr) {
;     ...
;             for (int k = 1; k < w; ++k) { const u32x4 uu = *(const u32x4*)(U + (size_t)(t0 - k) * LDU + c);
;                 sum[0] += bflo(uu.x); sum[1] += bfhi(uu.x); sum[2] += bflo(uu.y); sum[3] += bfhi(uu.y); sum[4] += bflo(uu.z); sum[5] += bfhi(uu.z); sum[6] += bflo(uu.w); sum[7] += bfhi(uu.w); }
;     ...
;         for (int i = 0; i < 32; ++i) {
;             const int t = t0 + i, s = s0 + i;
;             const u32x4 uu = *(const u32x4*)(U + (size_t)t * LDU + c);
;             float cu[8] = {bflo(uu.x), bfhi(uu.x), bflo(uu.y), bfhi(uu.y), bflo(uu.z), bfhi(uu.z), bflo(uu.w), bfhi(uu.w)};
;             const float rc = 1.0f / (float)((s + 1) < w ? (s + 1) : w);
;             float o[8];
; #pragma unroll
;             for (int e = 0; e < 8; ++e) { sum[e] += cu[e]; o[e] = sum[e] * rc - cu[e]; }
;             u32x4 ww; ww.x = pk2(o[0], o[1]); ww.y = pk2(o[2], o[3]); ww.z = pk2(o[4], o[5]); ww.w = pk2(o[6], o[7]);
;             *(u32x4*)(A3 + (size_t)t * DM + c) = ww;
;             if (s + 1 >= w) { const u32x4 ud = *(const u32x4*)(U + (size_t)(t - w + 1) * LDU + c);
;                 sum[0] -= bflo(ud.x); sum[1] -= bfhi(ud.x); sum[2] -= bflo(ud.y); sum[3] -= bfhi(ud.y); sum[4] -= bflo(ud.z); sum[5] -= bfhi(ud.z); sum[6] -= bflo(ud.w); sum[7] -= bfhi(ud.w); }
	v_lshlrev_b32_e32 v50, 16, v249
	v_and_b32_e32 v51, 0xffff0000, v249
	v_pk_add_f32 v[14:15], v[14:15], v[44:45]
	v_pk_add_f32 v[16:17], v[16:17], v[46:47]
	v_pk_add_f32 v[18:19], v[18:19], v[48:49]
	v_pk_add_f32 v[12:13], v[12:13], v[50:51]
	v_pk_fma_f32 v[36:37], v[34:35], v[14:15], v[44:45] op_sel_hi:[0,1,1] neg_lo:[0,0,1] neg_hi:[0,0,1]
	v_pk_fma_f32 v[38:39], v[34:35], v[16:17], v[46:47] op_sel_hi:[0,1,1] neg_lo:[0,0,1] neg_hi:[0,0,1]
	v_pk_fma_f32 v[40:41], v[34:35], v[18:19], v[48:49] op_sel_hi:[0,1,1] neg_lo:[0,0,1] neg_hi:[0,0,1]
	v_pk_fma_f32 v[42:43], v[34:35], v[12:13], v[50:51] op_sel_hi:[0,1,1] neg_lo:[0,0,1] neg_hi:[0,0,1]
	v_cvt_pk_bf16_f32 v28, v36, v37
	v_cvt_pk_bf16_f32 v29, v38, v39
	v_cvt_pk_bf16_f32 v30, v40, v41
	v_cvt_pk_bf16_f32 v31, v42, v43
	global_store_dwordx4 v[10:11], v[28:31], off
	v_lshlrev_b32_e32 v44, 16, v234
	v_and_b32_e32 v45, 0xffff0000, v234
	v_lshlrev_b32_e32 v46, 16, v235
	v_and_b32_e32 v47, 0xffff0000, v235
	v_lshlrev_b32_e32 v48, 16, v236
	v_and_b32_e32 v49, 0xffff0000, v236
	v_lshlrev_b32_e32 v50, 16, v237
	v_and_b32_e32 v51, 0xffff0000, v237
	v_pk_add_f32 v[14:15], v[14:15], v[44:45] neg_lo:[0,1] neg_hi:[0,1]
	v_pk_add_f32 v[16:17], v[16:17], v[46:47] neg_lo:[0,1] neg_hi:[0,1]
	v_pk_add_f32 v[18:19], v[18:19], v[48:49] neg_lo:[0,1] neg_hi:[0,1]
	v_pk_add_f32 v[12:13], v[12:13], v[50:51] neg_lo:[0,1] neg_hi:[0,1]
	v_lshl_add_u64 v[10:11], v[10:11], 0, s[26:27]
	v_lshlrev_b32_e32 v44, 16, v250
	v_and_b32_e32 v45, 0xffff0000, v250
	v_lshlrev_b32_e32 v46, 16, v251
	v_and_b32_e32 v47, 0xffff0000, v251
	v_lshlrev_b32_e32 v48, 16, v252
	v_and_b32_e32 v49, 0xffff0000, v252
	v_lshlrev_b32_e32 v50, 16, v253
	v_and_b32_e32 v51, 0xffff0000, v253
	v_pk_add_f32 v[14:15], v[14:15], v[44:45]
	v_pk_add_f32 v[16:17], v[16:17], v[46:47]
	v_pk_add_f32 v[18:19], v[18:19], v[48:49]
	v_pk_add_f32 v[12:13], v[12:13], v[50:51]
	v_pk_fma_f32 v[36:37], v[34:35], v[14:15], v[44:45] op_sel_hi:[0,1,1] neg_lo:[0,0,1] neg_hi:[0,0,1]
	v_pk_fma_f32 v[38:39], v[34:35], v[16:17], v[46:47] op_sel_hi:[0,1,1] neg_lo:[0,0,1] neg_hi:[0,0,1]
	v_pk_fma_f32 v[40:41], v[34:35], v[18:19], v[48:49] op_sel_hi:[0,1,1] neg_lo:[0,0,1] neg_hi:[0,0,1]
	v_pk_fma_f32 v[42:43], v[34:35], v[12:13], v[50:51] op_sel_hi:[0,1,1] neg_lo:[0,0,1] neg_hi:[0,0,1]
	v_cvt_pk_bf16_f32 v28, v36, v37
	v_cvt_pk_bf16_f32 v29, v38, v39
	v_cvt_pk_bf16_f32 v30, v40, v41
	v_cvt_pk_bf16_f32 v31, v42, v43
	global_store_dwordx4 v[10:11], v[28:31], off
	v_lshlrev_b32_e32 v44, 16, v238
	v_and_b32_e32 v45, 0xffff0000, v238
	v_lshlrev_b32_e32 v46, 16, v239
	v_and_b32_e32 v47, 0xffff0000, v239
	v_lshlrev_b32_e32 v48, 16, v240
	v_and_b32_e32 v49, 0xffff0000, v240
	v_lshlrev_b32_e32 v50, 16, v241
	v_and_b32_e32 v51, 0xffff0000, v241
	v_pk_add_f32 v[14:15], v[14:15], v[44:45] neg_lo:[0,1] neg_hi:[0,1]
	v_pk_add_f32 v[16:17], v[16:17], v[46:47] neg_lo:[0,1] neg_hi:[0,1]
	v_pk_add_f32 v[18:19], v[18:19], v[48:49] neg_lo:[0,1] neg_hi:[0,1]
	v_pk_add_f32 v[12:13], v[12:13], v[50:51] neg_lo:[0,1] neg_hi:[0,1]
	s_branch .LBB0_1331
.Lpw_w8:
	v_mov_b32_e32 v34, 0x3e000000
	s_waitcnt vmcnt(0)
	v_lshlrev_b32_e32 v44, 16, v120
	v_and_b32_e32 v45, 0xffff0000, v120
	v_lshlrev_b32_e32 v46, 16, v121
	v_and_b32_e32 v47, 0xffff0000, v121
	v_lshlrev_b32_e32 v48, 16, v122
	v_and_b32_e32 v49, 0xffff0000, v122
	v_lshlrev_b32_e32 v50, 16, v123
	v_and_b32_e32 v51, 0xffff0000, v123
	v_pk_add_f32 v[14:15], v[14:15], v[44:45]
	v_pk_add_f32 v[16:17], v[16:17], v[46:47]
	v_pk_add_f32 v[18:19], v[18:19], v[48:49]
	v_pk_add_f32 v[12:13], v[12:13], v[50:51]
	v_lshlrev_b32_e32 v44, 16, v116
	v_and_b32_e32 v45, 0xffff0000, v116
	v_lshlrev_b32_e32 v46, 16, v117
	v_and_b32_e32 v47, 0xffff0000, v117
	v_lshlrev_b32_e32 v48, 16, v118
	v_and_b32_e32 v49, 0xffff0000, v118
	v_lshlrev_b32_e32 v50, 16, v119
	v_and_b32_e32 v51, 0xffff0000, v119
	v_pk_add_f32 v[14:15], v[14:15], v[44:45]
	v_pk_add_f32 v[16:17], v[16:17], v[46:47]
	v_pk_add_f32 v[18:19], v[18:19], v[48:49]
	v_pk_add_f32 v[12:13], v[12:13], v[50:51]
	v_lshlrev_b32_e32 v44, 16, v112
	v_and_b32_e32 v45, 0xffff0000, v112
	v_lshlrev_b32_e32 v46, 16, v113
	v_and_b32_e32 v47, 0xffff0000, v113
	v_lshlrev_b32_e32 v48, 16, v114
	v_and_b32_e32 v49, 0xffff0000, v114
	v_lshlrev_b32_e32 v50, 16, v115
	v_and_b32_e32 v51, 0xffff0000, v115
	v_pk_add_f32 v[14:15], v[14:15], v[44:45]
	v_pk_add_f32 v[16:17], v[16:17], v[46:47]
	v_pk_add_f32 v[18:19], v[18:19], v[48:49]
	v_pk_add_f32 v[12:13], v[12:13], v[50:51]
	v_lshlrev_b32_e32 v44, 16, v108
	v_and_b32_e32 v45, 0xffff0000, v108
	v_lshlrev_b32_e32 v46, 16, v109
	v_and_b32_e32 v47, 0xffff0000, v109
	v_lshlrev_b32_e32 v48, 16, v110
	v_and_b32_e32 v49, 0xffff0000, v110
	v_lshlrev_b32_e32 v50, 16, v111
	v_and_b32_e32 v51, 0xffff0000, v111
	v_pk_add_f32 v[14:15], v[14:15], v[44:45]
	v_pk_add_f32 v[16:17], v[16:17], v[46:47]
	v_pk_add_f32 v[18:19], v[18:19], v[48:49]
	v_pk_add_f32 v[12:13], v[12:13], v[50:51]
	v_lshlrev_b32_e32 v44, 16, v104
	v_and_b32_e32 v45, 0xffff0000, v104
	v_lshlrev_b32_e32 v46, 16, v105
	v_and_b32_e32 v47, 0xffff0000, v105
	v_lshlrev_b32_e32 v48, 16, v106
	v_and_b32_e32 v49, 0xffff0000, v106
	v_lshlrev_b32_e32 v50, 16, v107
	v_and_b32_e32 v51, 0xffff0000, v107
	v_pk_add_f32 v[14:15], v[14:15], v[44:45]
	v_pk_add_f32 v[16:17], v[16:17], v[46:47]
	v_pk_add_f32 v[18:19], v[18:19], v[48:49]
	v_pk_add_f32 v[12:13], v[12:13], v[50:51]
	v_lshlrev_b32_e32 v44, 16, v100
	v_and_b32_e32 v45, 0xffff0000, v100
	v_lshlrev_b32_e32 v46, 16, v101
	v_and_b32_e32 v47, 0xffff0000, v101
	v_lshlrev_b32_e32 v48, 16, v102
	v_and_b32_e32 v49, 0xffff0000, v102
	v_lshlrev_b32_e32 v50, 16, v103
	v_and_b32_e32 v51, 0xffff0000, v103
; __device__ __forceinline__ unsigned pk2(float lo, float hi) { f32x2 v = {lo, hi}; bf16x2_t b = __builtin_convertvector(v, bf16x2_t); return __builtin_bit_cast(unsigned, b); }
; __device__ __forceinline__ void pool_window(const bf16_t* __restrict__ U  , bf16_t* __restrict__ A3, const int gtid, const int nthr) {
;     ...
;             for (int k = 1; k < w; ++k) { const u32x4 uu = *(const u32x4*)(U + (size_t)(t0 - k) * LDU + c);
;                 sum[0] += bflo(uu.x); sum[1] += bfhi(uu.x); sum[2] += bflo(uu.y); sum[3] += bfhi(uu.y); sum[4] += bflo(uu.z); sum[5] += bfhi(uu.z); sum[6] += bflo(uu.w); sum[7] += bfhi(uu.w); }
;         }
; #pragma unroll 8
;         for (int i = 0; i < 32; ++i) {
;             const int t = t0 + i, s = s0 + i;
;             const u32x4 uu = *(const u32x4*)(U + (size_t)t * LDU + c);
;             float cu[8] = {bflo(uu.x), bfhi(uu.x), bflo(uu.y), bfhi(uu.y), bflo(uu.z), bfhi(uu.z), bflo(uu.w), bfhi(uu.w)};
;             const float rc = 1.0f / (float)((s + 1) < w ? (s + 1) : w);
;             float o[8];
; #pragma unroll
;             for (int e = 0; e < 8; ++e) { sum[e] += cu[e]; o[e] = sum[e] * rc - cu[e]; }
;             u32x4 ww; ww.x = pk2(o[0], o[1]); ww.y = pk2(o[2], o[3]); ww.z = pk2(o[4], o[5]); ww.w = pk2(o[6], o[7]);
;             *(u32x4*)(A3 + (size_t)t * DM + c) = ww;
;             if (s + 1 >= w) { const u32x4 ud = *(const u32x4*)(U + (size_t)(t - w + 1) * LDU + c);
;                 sum[0] -= bflo(ud.x); sum[1] -= bfhi(ud.x); sum[2] -= bflo(ud.y); sum[3] -= bfhi(ud.y); sum[4] -= bflo(ud.z); sum[5] -= bfhi(ud.z); sum[6] -= bflo(ud.w); sum[7] -= bfhi(ud.w); }
	v_pk_add_f32 v[14:15], v[14:15], v[44:45]
	v_pk_add_f32 v[16:17], v[16:17], v[46:47]
	v_pk_add_f32 v[18:19], v[18:19], v[48:49]
	v_pk_add_f32 v[12:13], v[12:13], v[50:51]
	v_lshlrev_b32_e32 v44, 16, v96
	v_and_b32_e32 v45, 0xffff0000, v96
	v_lshlrev_b32_e32 v46, 16, v97
	v_and_b32_e32 v47, 0xffff0000, v97
	v_lshlrev_b32_e32 v48, 16, v98
	v_and_b32_e32 v49, 0xffff0000, v98
	v_lshlrev_b32_e32 v50, 16, v99
	v_and_b32_e32 v51, 0xffff0000, v99
	v_pk_add_f32 v[14:15], v[14:15], v[44:45]
	v_pk_add_f32 v[16:17], v[16:17], v[46:47]
	v_pk_add_f32 v[18:19], v[18:19], v[48:49]
	v_pk_add_f32 v[12:13], v[12:13], v[50:51]
	v_lshlrev_b32_e32 v44, 16, v124
	v_and_b32_e32 v45, 0xffff0000, v124
	v_lshlrev_b32_e32 v46, 16, v125
	v_and_b32_e32 v47, 0xffff0000, v125
	v_lshlrev_b32_e32 v48, 16, v126
	v_and_b32_e32 v49, 0xffff0000, v126
	v_lshlrev_b32_e32 v50, 16, v127
	v_and_b32_e32 v51, 0xffff0000, v127
	v_pk_add_f32 v[14:15], v[14:15], v[44:45]
	v_pk_add_f32 v[16:17], v[16:17], v[46:47]
	v_pk_add_f32 v[18:19], v[18:19], v[48:49]
	v_pk_add_f32 v[12:13], v[12:13], v[50:51]
	v_pk_fma_f32 v[36:37], v[34:35], v[14:15], v[44:45] op_sel_hi:[0,1,1] neg_lo:[0,0,1] neg_hi:[0,0,1]
	v_pk_fma_f32 v[38:39], v[34:35], v[16:17], v[46:47] op_sel_hi:[0,1,1] neg_lo:[0,0,1] neg_hi:[0,0,1]
	v_pk_fma_f32 v[40:41], v[34:35], v[18:19], v[48:49] op_sel_hi:[0,1,1] neg_lo:[0,0,1] neg_hi:[0,0,1]
	v_pk_fma_f32 v[42:43], v[34:35], v[12:13], v[50:51] op_sel_hi:[0,1,1] neg_lo:[0,0,1] neg_hi:[0,0,1]
	v_cvt_pk_bf16_f32 v28, v36, v37
	v_cvt_pk_bf16_f32 v29, v38, v39
	v_cvt_pk_bf16_f32 v30, v40, v41
	v_cvt_pk_bf16_f32 v31, v42, v43
	global_store_dwordx4 v[10:11], v[28:31], off
	v_lshlrev_b32_e32 v44, 16, v96
	v_and_b32_e32 v45, 0xffff0000, v96
	v_lshlrev_b32_e32 v46, 16, v97
	v_and_b32_e32 v47, 0xffff0000, v97
	v_lshlrev_b32_e32 v48, 16, v98
	v_and_b32_e32 v49, 0xffff0000, v98
	v_lshlrev_b32_e32 v50, 16, v99
	v_and_b32_e32 v51, 0xffff0000, v99
	v_pk_add_f32 v[14:15], v[14:15], v[44:45] neg_lo:[0,1] neg_hi:[0,1]
	v_pk_add_f32 v[16:17], v[16:17], v[46:47] neg_lo:[0,1] neg_hi:[0,1]
	v_pk_add_f32 v[18:19], v[18:19], v[48:49] neg_lo:[0,1] neg_hi:[0,1]
	v_pk_add_f32 v[12:13], v[12:13], v[50:51] neg_lo:[0,1] neg_hi:[0,1]
	v_lshl_add_u64 v[10:11], v[10:11], 0, s[26:27]
	v_lshlrev_b32_e32 v44, 16, v128
	v_and_b32_e32 v45, 0xffff0000, v128
	v_lshlrev_b32_e32 v46, 16, v129
	v_and_b32_e32 v47, 0xffff0000, v129
	v_lshlrev_b32_e32 v48, 16, v130
	v_and_b32_e32 v49, 0xffff0000, v130
	v_lshlrev_b32_e32 v50, 16, v131
	v_and_b32_e32 v51, 0xffff0000, v131
	v_pk_add_f32 v[14:15], v[14:15], v[44:45]
	v_pk_add_f32 v[16:17], v[16:17], v[46:47]
	v_pk_add_f32 v[18:19], v[18:19], v[48:49]
	v_pk_add_f32 v[12:13], v[12:13], v[50:51]
	v_pk_fma_f32 v[36:37], v[34:35], v[14:15], v[44:45] op_sel_hi:[0,1,1] neg_lo:[0,0,1] neg_hi:[0,0,1]
	v_pk_fma_f32 v[38:39], v[34:35], v[16:17], v[46:47] op_sel_hi:[0,1,1] neg_lo:[0,0,1] neg_hi:[0,0,1]
	v_pk_fma_f32 v[40:41], v[34:35], v[18:19], v[48:49] op_sel_hi:[0,1,1] neg_lo:[0,0,1] neg_hi:[0,0,1]
	v_pk_fma_f32 v[42:43], v[34:35], v[12:13], v[50:51] op_sel_hi:[0,1,1] neg_lo:[0,0,1] neg_hi:[0,0,1]
	v_cvt_pk_bf16_f32 v28, v36, v37
	v_cvt_pk_bf16_f32 v29, v38, v39
	v_cvt_pk_bf16_f32 v30, v40, v41
	v_cvt_pk_bf16_f32 v31, v42, v43
	global_store_dwordx4 v[10:11], v[28:31], off
	v_lshlrev_b32_e32 v44, 16, v100
	v_and_b32_e32 v45, 0xffff0000, v100
	v_lshlrev_b32_e32 v46, 16, v101
	v_and_b32_e32 v47, 0xffff0000, v101
	v_lshlrev_b32_e32 v48, 16, v102
	v_and_b32_e32 v49, 0xffff0000, v102
	v_lshlrev_b32_e32 v50, 16, v103
	v_and_b32_e32 v51, 0xffff0000, v103
	v_pk_add_f32 v[14:15], v[14:15], v[44:45] neg_lo:[0,1] neg_hi:[0,1]
	v_pk_add_f32 v[16:17], v[16:17], v[46:47] neg_lo:[0,1] neg_hi:[0,1]
	v_pk_add_f32 v[18:19], v[18:19], v[48:49] neg_lo:[0,1] neg_hi:[0,1]
	v_pk_add_f32 v[12:13], v[12:13], v[50:51] neg_lo:[0,1] neg_hi:[0,1]
	v_lshl_add_u64 v[10:11], v[10:11], 0, s[26:27]
	v_lshlrev_b32_e32 v44, 16, v132
	v_and_b32_e32 v45, 0xffff0000, v132
	v_lshlrev_b32_e32 v46, 16, v133
	v_and_b32_e32 v47, 0xffff0000, v133
	v_lshlrev_b32_e32 v48, 16, v134
	v_and_b32_e32 v49, 0xffff0000, v134
	v_lshlrev_b32_e32 v50, 16, v135
	v_and_b32_e32 v51, 0xffff0000, v135
	v_pk_add_f32 v[14:15], v[14:15], v[44:45]
	v_pk_add_f32 v[16:17], v[16:17], v[46:47]
	v_pk_add_f32 v[18:19], v[18:19], v[48:49]
	v_pk_add_f32 v[12:13], v[12:13], v[50:51]
	v_pk_fma_f32 v[36:37], v[34:35], v[14:15], v[44:45] op_sel_hi:[0,1,1] neg_lo:[0,0,1] neg_hi:[0,0,1]
	v_pk_fma_f32 v[38:39], v[34:35], v[16:17], v[46:47] op_sel_hi:[0,1,1] neg_lo:[0,0,1] neg_hi:[0,0,1]
	v_pk_fma_f32 v[40:41], v[34:35], v[18:19], v[48:49] op_sel_hi:[0,1,1] neg_lo:[0,0,1] neg_hi:[0,0,1]
	v_pk_fma_f32 v[42:43], v[34:35], v[12:13], v[50:51] op_sel_hi:[0,1,1] neg_lo:[0,0,1] neg_hi:[0,0,1]
	v_cvt_pk_bf16_f32 v28, v36, v37
	v_cvt_pk_bf16_f32 v29, v38, v39
	v_cvt_pk_bf16_f32 v30, v40, v41
	v_cvt_pk_bf16_f32 v31, v42, v43
	global_store_dwordx4 v[10:11], v[28:31], off
	v_lshlrev_b32_e32 v44, 16, v104
	v_and_b32_e32 v45, 0xffff0000, v104
	v_lshlrev_b32_e32 v46, 16, v105
	v_and_b32_e32 v47, 0xffff0000, v105
	v_lshlrev_b32_e32 v48, 16, v106
	v_and_b32_e32 v49, 0xffff0000, v106
	v_lshlrev_b32_e32 v50, 16, v107
	v_and_b32_e32 v51, 0xffff0000, v107
	v_pk_add_f32 v[14:15], v[14:15], v[44:45] neg_lo:[0,1] neg_hi:[0,1]
	v_pk_add_f32 v[16:17], v[16:17], v[46:47] neg_lo:[0,1] neg_hi:[0,1]
	v_pk_add_f32 v[18:19], v[18:19], v[48:49] neg_lo:[0,1] neg_hi:[0,1]
	v_pk_add_f32 v[12:13], v[12:13], v[50:51] neg_lo:[0,1] neg_hi:[0,1]
	v_lshl_add_u64 v[10:11], v[10:11], 0, s[26:27]
	v_lshlrev_b32_e32 v44, 16, v136
	v_and_b32_e32 v45, 0xffff0000, v136
	v_lshlrev_b32_e32 v46, 16, v137
; __device__ __forceinline__ unsigned pk2(float lo, float hi) { f32x2 v = {lo, hi}; bf16x2_t b = __builtin_convertvector(v, bf16x2_t); return __builtin_bit_cast(unsigned, b); }
; __device__ __forceinline__ void pool_window(const bf16_t* __restrict__ U  , bf16_t* __restrict__ A3, const int gtid, const int nthr) {
;     ...
;         for (int i = 0; i < 32; ++i) {
;             const int t = t0 + i, s = s0 + i;
;             const u32x4 uu = *(const u32x4*)(U + (size_t)t * LDU + c);
;             float cu[8] = {bflo(uu.x), bfhi(uu.x), bflo(uu.y), bfhi(uu.y), bflo(uu.z), bfhi(uu.z), bflo(uu.w), bfhi(uu.w)};
;             const float rc = 1.0f / (float)((s + 1) < w ? (s + 1) : w);
;             float o[8];
; #pragma unroll
;             for (int e = 0; e < 8; ++e) { sum[e] += cu[e]; o[e] = sum[e] * rc - cu[e]; }
;             u32x4 ww; ww.x = pk2(o[0], o[1]); ww.y = pk2(o[2], o[3]); ww.z = pk2(o[4], o[5]); ww.w = pk2(o[6], o[7]);
;             *(u32x4*)(A3 + (size_t)t * DM + c) = ww;
;             if (s + 1 >= w) { const u32x4 ud = *(const u32x4*)(U + (size_t)(t - w + 1) * LDU + c);
;                 sum[0] -= bflo(ud.x); sum[1] -= bfhi(ud.x); sum[2] -= bflo(ud.y); sum[3] -= bfhi(ud.y); sum[4] -= bflo(ud.z); sum[5] -= bfhi(ud.z); sum[6] -= bflo(ud.w); sum[7] -= bfhi(ud.w); }
	v_and_b32_e32 v47, 0xffff0000, v137
	v_lshlrev_b32_e32 v48, 16, v138
	v_and_b32_e32 v49, 0xffff0000, v138
	v_lshlrev_b32_e32 v50, 16, v139
	v_and_b32_e32 v51, 0xffff0000, v139
	v_pk_add_f32 v[14:15], v[14:15], v[44:45]
	v_pk_add_f32 v[16:17], v[16:17], v[46:47]
	v_pk_add_f32 v[18:19], v[18:19], v[48:49]
	v_pk_add_f32 v[12:13], v[12:13], v[50:51]
	v_pk_fma_f32 v[36:37], v[34:35], v[14:15], v[44:45] op_sel_hi:[0,1,1] neg_lo:[0,0,1] neg_hi:[0,0,1]
	v_pk_fma_f32 v[38:39], v[34:35], v[16:17], v[46:47] op_sel_hi:[0,1,1] neg_lo:[0,0,1] neg_hi:[0,0,1]
	v_pk_fma_f32 v[40:41], v[34:35], v[18:19], v[48:49] op_sel_hi:[0,1,1] neg_lo:[0,0,1] neg_hi:[0,0,1]
	v_pk_fma_f32 v[42:43], v[34:35], v[12:13], v[50:51] op_sel_hi:[0,1,1] neg_lo:[0,0,1] neg_hi:[0,0,1]
	v_cvt_pk_bf16_f32 v28, v36, v37
	v_cvt_pk_bf16_f32 v29, v38, v39
	v_cvt_pk_bf16_f32 v30, v40, v41
	v_cvt_pk_bf16_f32 v31, v42, v43
	global_store_dwordx4 v[10:11], v[28:31], off
	v_lshlrev_b32_e32 v44, 16, v108
	v_and_b32_e32 v45, 0xffff0000, v108
	v_lshlrev_b32_e32 v46, 16, v109
	v_and_b32_e32 v47, 0xffff0000, v109
	v_lshlrev_b32_e32 v48, 16, v110
	v_and_b32_e32 v49, 0xffff0000, v110
	v_lshlrev_b32_e32 v50, 16, v111
	v_and_b32_e32 v51, 0xffff0000, v111
	v_pk_add_f32 v[14:15], v[14:15], v[44:45] neg_lo:[0,1] neg_hi:[0,1]
	v_pk_add_f32 v[16:17], v[16:17], v[46:47] neg_lo:[0,1] neg_hi:[0,1]
	v_pk_add_f32 v[18:19], v[18:19], v[48:49] neg_lo:[0,1] neg_hi:[0,1]
	v_pk_add_f32 v[12:13], v[12:13], v[50:51] neg_lo:[0,1] neg_hi:[0,1]
	v_lshl_add_u64 v[10:11], v[10:11], 0, s[26:27]
	v_lshlrev_b32_e32 v44, 16, v140
	v_and_b32_e32 v45, 0xffff0000, v140
	v_lshlrev_b32_e32 v46, 16, v141
	v_and_b32_e32 v47, 0xffff0000, v141
	v_lshlrev_b32_e32 v48, 16, v142
	v_and_b32_e32 v49, 0xffff0000, v142
	v_lshlrev_b32_e32 v50, 16, v143
	v_and_b32_e32 v51, 0xffff0000, v143
	v_pk_add_f32 v[14:15], v[14:15], v[44:45]
	v_pk_add_f32 v[16:17], v[16:17], v[46:47]
	v_pk_add_f32 v[18:19], v[18:19], v[48:49]
	v_pk_add_f32 v[12:13], v[12:13], v[50:51]
	v_pk_fma_f32 v[36:37], v[34:35], v[14:15], v[44:45] op_sel_hi:[0,1,1] neg_lo:[0,0,1] neg_hi:[0,0,1]
	v_pk_fma_f32 v[38:39], v[34:35], v[16:17], v[46:47] op_sel_hi:[0,1,1] neg_lo:[0,0,1] neg_hi:[0,0,1]
	v_pk_fma_f32 v[40:41], v[34:35], v[18:19], v[48:49] op_sel_hi:[0,1,1] neg_lo:[0,0,1] neg_hi:[0,0,1]
	v_pk_fma_f32 v[42:43], v[34:35], v[12:13], v[50:51] op_sel_hi:[0,1,1] neg_lo:[0,0,1] neg_hi:[0,0,1]
	v_cvt_pk_bf16_f32 v28, v36, v37
	v_cvt_pk_bf16_f32 v29, v38, v39
	v_cvt_pk_bf16_f32 v30, v40, v41
	v_cvt_pk_bf16_f32 v31, v42, v43
	global_store_dwordx4 v[10:11], v[28:31], off
	v_lshlrev_b32_e32 v44, 16, v112
	v_and_b32_e32 v45, 0xffff0000, v112
	v_lshlrev_b32_e32 v46, 16, v113
	v_and_b32_e32 v47, 0xffff0000, v113
	v_lshlrev_b32_e32 v48, 16, v114
	v_and_b32_e32 v49, 0xffff0000, v114
	v_lshlrev_b32_e32 v50, 16, v115
	v_and_b32_e32 v51, 0xffff0000, v115
	v_pk_add_f32 v[14:15], v[14:15], v[44:45] neg_lo:[0,1] neg_hi:[0,1]
	v_pk_add_f32 v[16:17], v[16:17], v[46:47] neg_lo:[0,1] neg_hi:[0,1]
	v_pk_add_f32 v[18:19], v[18:19], v[48:49] neg_lo:[0,1] neg_hi:[0,1]
	v_pk_add_f32 v[12:13], v[12:13], v[50:51] neg_lo:[0,1] neg_hi:[0,1]
	v_lshl_add_u64 v[10:11], v[10:11], 0, s[26:27]
	v_lshlrev_b32_e32 v44, 16, v144
	v_and_b32_e32 v45, 0xffff0000, v144
	v_lshlrev_b32_e32 v46, 16, v145
	v_and_b32_e32 v47, 0xffff0000, v145
	v_lshlrev_b32_e32 v48, 16, v146
	v_and_b32_e32 v49, 0xffff0000, v146
	v_lshlrev_b32_e32 v50, 16, v147
	v_and_b32_e32 v51, 0xffff0000, v147
	v_pk_add_f32 v[14:15], v[14:15], v[44:45]
	v_pk_add_f32 v[16:17], v[16:17], v[46:47]
	v_pk_add_f32 v[18:19], v[18:19], v[48:49]
	v_pk_add_f32 v[12:13], v[12:13], v[50:51]
	v_pk_fma_f32 v[36:37], v[34:35], v[14:15], v[44:45] op_sel_hi:[0,1,1] neg_lo:[0,0,1] neg_hi:[0,0,1]
	v_pk_fma_f32 v[38:39], v[34:35], v[16:17], v[46:47] op_sel_hi:[0,1,1] neg_lo:[0,0,1] neg_hi:[0,0,1]
	v_pk_fma_f32 v[40:41], v[34:35], v[18:19], v[48:49] op_sel_hi:[0,1,1] neg_lo:[0,0,1] neg_hi:[0,0,1]
	v_pk_fma_f32 v[42:43], v[34:35], v[12:13], v[50:51] op_sel_hi:[0,1,1] neg_lo:[0,0,1] neg_hi:[0,0,1]
	v_cvt_pk_bf16_f32 v28, v36, v37
	v_cvt_pk_bf16_f32 v29, v38, v39
	v_cvt_pk_bf16_f32 v30, v40, v41
	v_cvt_pk_bf16_f32 v31, v42, v43
	global_store_dwordx4 v[10:11], v[28:31], off
	v_lshlrev_b32_e32 v44, 16, v116
	v_and_b32_e32 v45, 0xffff0000, v116
	v_lshlrev_b32_e32 v46, 16, v117
	v_and_b32_e32 v47, 0xffff0000, v117
	v_lshlrev_b32_e32 v48, 16, v118
	v_and_b32_e32 v49, 0xffff0000, v118
	v_lshlrev_b32_e32 v50, 16, v119
	v_and_b32_e32 v51, 0xffff0000, v119
	v_pk_add_f32 v[14:15], v[14:15], v[44:45] neg_lo:[0,1] neg_hi:[0,1]
	v_pk_add_f32 v[16:17], v[16:17], v[46:47] neg_lo:[0,1] neg_hi:[0,1]
	v_pk_add_f32 v[18:19], v[18:19], v[48:49] neg_lo:[0,1] neg_hi:[0,1]
	v_pk_add_f32 v[12:13], v[12:13], v[50:51] neg_lo:[0,1] neg_hi:[0,1]
	v_lshl_add_u64 v[10:11], v[10:11], 0, s[26:27]
	v_lshlrev_b32_e32 v44, 16, v148
	v_and_b32_e32 v45, 0xffff0000, v148
	v_lshlrev_b32_e32 v46, 16, v149
	v_and_b32_e32 v47, 0xffff0000, v149
	v_lshlrev_b32_e32 v48, 16, v150
	v_and_b32_e32 v49, 0xffff0000, v150
	v_lshlrev_b32_e32 v50, 16, v151
	v_and_b32_e32 v51, 0xffff0000, v151
	v_pk_add_f32 v[14:15], v[14:15], v[44:45]
	v_pk_add_f32 v[16:17], v[16:17], v[46:47]
	v_pk_add_f32 v[18:19], v[18:19], v[48:49]
	v_pk_add_f32 v[12:13], v[12:13], v[50:51]
	v_pk_fma_f32 v[36:37], v[34:35], v[14:15], v[44:45] op_sel_hi:[0,1,1] neg_lo:[0,0,1] neg_hi:[0,0,1]
	v_pk_fma_f32 v[38:39], v[34:35], v[16:17], v[46:47] op_sel_hi:[0,1,1] neg_lo:[0,0,1] neg_hi:[0,0,1]
	v_pk_fma_f32 v[40:41], v[34:35], v[18:19], v[48:49] op_sel_hi:[0,1,1] neg_lo:[0,0,1] neg_hi:[0,0,1]
	v_pk_fma_f32 v[42:43], v[34:35], v[12:13], v[50:51] op_sel_hi:[0,1,1] neg_lo:[0,0,1] neg_hi:[0,0,1]
; __device__ __forceinline__ unsigned pk2(float lo, float hi) { f32x2 v = {lo, hi}; bf16x2_t b = __builtin_convertvector(v, bf16x2_t); return __builtin_bit_cast(unsigned, b); }
; __device__ __forceinline__ void pool_window(const bf16_t* __restrict__ U  , bf16_t* __restrict__ A3, const int gtid, const int nthr) {
;     ...
;         for (int i = 0; i < 32; ++i) {
;             const int t = t0 + i, s = s0 + i;
;             const u32x4 uu = *(const u32x4*)(U + (size_t)t * LDU + c);
;             float cu[8] = {bflo(uu.x), bfhi(uu.x), bflo(uu.y), bfhi(uu.y), bflo(uu.z), bfhi(uu.z), bflo(uu.w), bfhi(uu.w)};
;             const float rc = 1.0f / (float)((s + 1) < w ? (s + 1) : w);
;             float o[8];
; #pragma unroll
;             for (int e = 0; e < 8; ++e) { sum[e] += cu[e]; o[e] = sum[e] * rc - cu[e]; }
;             u32x4 ww; ww.x = pk2(o[0], o[1]); ww.y = pk2(o[2], o[3]); ww.z = pk2(o[4], o[5]); ww.w = pk2(o[6], o[7]);
;             *(u32x4*)(A3 + (size_t)t * DM + c) = ww;
;             if (s + 1 >= w) { const u32x4 ud = *(const u32x4*)(U + (size_t)(t - w + 1) * LDU + c);
;                 sum[0] -= bflo(ud.x); sum[1] -= bfhi(ud.x); sum[2] -= bflo(ud.y); sum[3] -= bfhi(ud.y); sum[4] -= bflo(ud.z); sum[5] -= bfhi(ud.z); sum[6] -= bflo(ud.w); sum[7] -= bfhi(ud.w); }
;         }
	v_cvt_pk_bf16_f32 v28, v36, v37
	v_cvt_pk_bf16_f32 v29, v38, v39
	v_cvt_pk_bf16_f32 v30, v40, v41
	v_cvt_pk_bf16_f32 v31, v42, v43
	global_store_dwordx4 v[10:11], v[28:31], off
	v_lshlrev_b32_e32 v44, 16, v120
	v_and_b32_e32 v45, 0xffff0000, v120
	v_lshlrev_b32_e32 v46, 16, v121
	v_and_b32_e32 v47, 0xffff0000, v121
	v_lshlrev_b32_e32 v48, 16, v122
	v_and_b32_e32 v49, 0xffff0000, v122
	v_lshlrev_b32_e32 v50, 16, v123
	v_and_b32_e32 v51, 0xffff0000, v123
	v_pk_add_f32 v[14:15], v[14:15], v[44:45] neg_lo:[0,1] neg_hi:[0,1]
	v_pk_add_f32 v[16:17], v[16:17], v[46:47] neg_lo:[0,1] neg_hi:[0,1]
	v_pk_add_f32 v[18:19], v[18:19], v[48:49] neg_lo:[0,1] neg_hi:[0,1]
	v_pk_add_f32 v[12:13], v[12:13], v[50:51] neg_lo:[0,1] neg_hi:[0,1]
	v_lshl_add_u64 v[10:11], v[10:11], 0, s[26:27]
	v_lshlrev_b32_e32 v44, 16, v152
	v_and_b32_e32 v45, 0xffff0000, v152
	v_lshlrev_b32_e32 v46, 16, v153
	v_and_b32_e32 v47, 0xffff0000, v153
	v_lshlrev_b32_e32 v48, 16, v154
	v_and_b32_e32 v49, 0xffff0000, v154
	v_lshlrev_b32_e32 v50, 16, v155
	v_and_b32_e32 v51, 0xffff0000, v155
	v_pk_add_f32 v[14:15], v[14:15], v[44:45]
	v_pk_add_f32 v[16:17], v[16:17], v[46:47]
	v_pk_add_f32 v[18:19], v[18:19], v[48:49]
	v_pk_add_f32 v[12:13], v[12:13], v[50:51]
	v_pk_fma_f32 v[36:37], v[34:35], v[14:15], v[44:45] op_sel_hi:[0,1,1] neg_lo:[0,0,1] neg_hi:[0,0,1]
	v_pk_fma_f32 v[38:39], v[34:35], v[16:17], v[46:47] op_sel_hi:[0,1,1] neg_lo:[0,0,1] neg_hi:[0,0,1]
	v_pk_fma_f32 v[40:41], v[34:35], v[18:19], v[48:49] op_sel_hi:[0,1,1] neg_lo:[0,0,1] neg_hi:[0,0,1]
	v_pk_fma_f32 v[42:43], v[34:35], v[12:13], v[50:51] op_sel_hi:[0,1,1] neg_lo:[0,0,1] neg_hi:[0,0,1]
	v_cvt_pk_bf16_f32 v28, v36, v37
	v_cvt_pk_bf16_f32 v29, v38, v39
	v_cvt_pk_bf16_f32 v30, v40, v41
	v_cvt_pk_bf16_f32 v31, v42, v43
	global_store_dwordx4 v[10:11], v[28:31], off
	v_lshlrev_b32_e32 v44, 16, v124
	v_and_b32_e32 v45, 0xffff0000, v124
	v_lshlrev_b32_e32 v46, 16, v125
	v_and_b32_e32 v47, 0xffff0000, v125
	v_lshlrev_b32_e32 v48, 16, v126
	v_and_b32_e32 v49, 0xffff0000, v126
	v_lshlrev_b32_e32 v50, 16, v127
	v_and_b32_e32 v51, 0xffff0000, v127
	v_pk_add_f32 v[14:15], v[14:15], v[44:45] neg_lo:[0,1] neg_hi:[0,1]
	v_pk_add_f32 v[16:17], v[16:17], v[46:47] neg_lo:[0,1] neg_hi:[0,1]
	v_pk_add_f32 v[18:19], v[18:19], v[48:49] neg_lo:[0,1] neg_hi:[0,1]
	v_pk_add_f32 v[12:13], v[12:13], v[50:51] neg_lo:[0,1] neg_hi:[0,1]
	v_lshl_add_u64 v[10:11], v[10:11], 0, s[26:27]
	v_lshlrev_b32_e32 v44, 16, v156
	v_and_b32_e32 v45, 0xffff0000, v156
	v_lshlrev_b32_e32 v46, 16, v157
	v_and_b32_e32 v47, 0xffff0000, v157
	v_lshlrev_b32_e32 v48, 16, v158
	v_and_b32_e32 v49, 0xffff0000, v158
	v_lshlrev_b32_e32 v50, 16, v159
	v_and_b32_e32 v51, 0xffff0000, v159
	v_pk_add_f32 v[14:15], v[14:15], v[44:45]
	v_pk_add_f32 v[16:17], v[16:17], v[46:47]
	v_pk_add_f32 v[18:19], v[18:19], v[48:49]
	v_pk_add_f32 v[12:13], v[12:13], v[50:51]
	v_pk_fma_f32 v[36:37], v[34:35], v[14:15], v[44:45] op_sel_hi:[0,1,1] neg_lo:[0,0,1] neg_hi:[0,0,1]
	v_pk_fma_f32 v[38:39], v[34:35], v[16:17], v[46:47] op_sel_hi:[0,1,1] neg_lo:[0,0,1] neg_hi:[0,0,1]
	v_pk_fma_f32 v[40:41], v[34:35], v[18:19], v[48:49] op_sel_hi:[0,1,1] neg_lo:[0,0,1] neg_hi:[0,0,1]
	v_pk_fma_f32 v[42:43], v[34:35], v[12:13], v[50:51] op_sel_hi:[0,1,1] neg_lo:[0,0,1] neg_hi:[0,0,1]
	v_cvt_pk_bf16_f32 v28, v36, v37
	v_cvt_pk_bf16_f32 v29, v38, v39
	v_cvt_pk_bf16_f32 v30, v40, v41
	v_cvt_pk_bf16_f32 v31, v42, v43
	global_store_dwordx4 v[10:11], v[28:31], off
	v_lshlrev_b32_e32 v44, 16, v128
	v_and_b32_e32 v45, 0xffff0000, v128
	v_lshlrev_b32_e32 v46, 16, v129
	v_and_b32_e32 v47, 0xffff0000, v129
	v_lshlrev_b32_e32 v48, 16, v130
	v_and_b32_e32 v49, 0xffff0000, v130
	v_lshlrev_b32_e32 v50, 16, v131
	v_and_b32_e32 v51, 0xffff0000, v131
	v_pk_add_f32 v[14:15], v[14:15], v[44:45] neg_lo:[0,1] neg_hi:[0,1]
	v_pk_add_f32 v[16:17], v[16:17], v[46:47] neg_lo:[0,1] neg_hi:[0,1]
	v_pk_add_f32 v[18:19], v[18:19], v[48:49] neg_lo:[0,1] neg_hi:[0,1]
	v_pk_add_f32 v[12:13], v[12:13], v[50:51] neg_lo:[0,1] neg_hi:[0,1]
	v_lshl_add_u64 v[10:11], v[10:11], 0, s[26:27]
	v_lshlrev_b32_e32 v44, 16, v160
	v_and_b32_e32 v45, 0xffff0000, v160
	v_lshlrev_b32_e32 v46, 16, v161
	v_and_b32_e32 v47, 0xffff0000, v161
	v_lshlrev_b32_e32 v48, 16, v162
	v_and_b32_e32 v49, 0xffff0000, v162
	v_lshlrev_b32_e32 v50, 16, v163
	v_and_b32_e32 v51, 0xffff0000, v163
	v_pk_add_f32 v[14:15], v[14:15], v[44:45]
	v_pk_add_f32 v[16:17], v[16:17], v[46:47]
	v_pk_add_f32 v[18:19], v[18:19], v[48:49]
	v_pk_add_f32 v[12:13], v[12:13], v[50:51]
	v_pk_fma_f32 v[36:37], v[34:35], v[14:15], v[44:45] op_sel_hi:[0,1,1] neg_lo:[0,0,1] neg_hi:[0,0,1]
	v_pk_fma_f32 v[38:39], v[34:35], v[16:17], v[46:47] op_sel_hi:[0,1,1] neg_lo:[0,0,1] neg_hi:[0,0,1]
	v_pk_fma_f32 v[40:41], v[34:35], v[18:19], v[48:49] op_sel_hi:[0,1,1] neg_lo:[0,0,1] neg_hi:[0,0,1]
	v_pk_fma_f32 v[42:43], v[34:35], v[12:13], v[50:51] op_sel_hi:[0,1,1] neg_lo:[0,0,1] neg_hi:[0,0,1]
	v_cvt_pk_bf16_f32 v28, v36, v37
	v_cvt_pk_bf16_f32 v29, v38, v39
	v_cvt_pk_bf16_f32 v30, v40, v41
	v_cvt_pk_bf16_f32 v31, v42, v43
	global_store_dwordx4 v[10:11], v[28:31], off
	v_lshlrev_b32_e32 v44, 16, v132
	v_and_b32_e32 v45, 0xffff0000, v132
	v_lshlrev_b32_e32 v46, 16, v133
	v_and_b32_e32 v47, 0xffff0000, v133
	v_lshlrev_b32_e32 v48, 16, v134
	v_and_b32_e32 v49, 0xffff0000, v134
	v_lshlrev_b32_e32 v50, 16, v135
	v_and_b32_e32 v51, 0xffff0000, v135
	v_pk_add_f32 v[14:15], v[14:15], v[44:45] neg_lo:[0,1] neg_hi:[0,1]
	v_pk_add_f32 v[16:17], v[16:17], v[46:47] neg_lo:[0,1] neg_hi:[0,1]
	v_pk_add_f32 v[18:19], v[18:19], v[48:49] neg_lo:[0,1] neg_hi:[0,1]
	v_pk_add_f32 v[12:13], v[12:13], v[50:51] neg_lo:[0,1] neg_hi:[0,1]
; __device__ __forceinline__ unsigned pk2(float lo, float hi) { f32x2 v = {lo, hi}; bf16x2_t b = __builtin_convertvector(v, bf16x2_t); return __builtin_bit_cast(unsigned, b); }
; __device__ __forceinline__ void pool_window(const bf16_t* __restrict__ U  , bf16_t* __restrict__ A3, const int gtid, const int nthr) {
;     ...
;         for (int i = 0; i < 32; ++i) {
;             const int t = t0 + i, s = s0 + i;
;             const u32x4 uu = *(const u32x4*)(U + (size_t)t * LDU + c);
;             float cu[8] = {bflo(uu.x), bfhi(uu.x), bflo(uu.y), bfhi(uu.y), bflo(uu.z), bfhi(uu.z), bflo(uu.w), bfhi(uu.w)};
;             const float rc = 1.0f / (float)((s + 1) < w ? (s + 1) : w);
;             float o[8];
; #pragma unroll
;             for (int e = 0; e < 8; ++e) { sum[e] += cu[e]; o[e] = sum[e] * rc - cu[e]; }
;             u32x4 ww; ww.x = pk2(o[0], o[1]); ww.y = pk2(o[2], o[3]); ww.z = pk2(o[4], o[5]); ww.w = pk2(o[6], o[7]);
;             *(u32x4*)(A3 + (size_t)t * DM + c) = ww;
;             if (s + 1 >= w) { const u32x4 ud = *(const u32x4*)(U + (size_t)(t - w + 1) * LDU + c);
;                 sum[0] -= bflo(ud.x); sum[1] -= bfhi(ud.x); sum[2] -= bflo(ud.y); sum[3] -= bfhi(ud.y); sum[4] -= bflo(ud.z); sum[5] -= bfhi(ud.z); sum[6] -= bflo(ud.w); sum[7] -= bfhi(ud.w); }
;         }
	v_lshl_add_u64 v[10:11], v[10:11], 0, s[26:27]
	v_lshlrev_b32_e32 v44, 16, v164
	v_and_b32_e32 v45, 0xffff0000, v164
	v_lshlrev_b32_e32 v46, 16, v165
	v_and_b32_e32 v47, 0xffff0000, v165
	v_lshlrev_b32_e32 v48, 16, v166
	v_and_b32_e32 v49, 0xffff0000, v166
	v_lshlrev_b32_e32 v50, 16, v167
	v_and_b32_e32 v51, 0xffff0000, v167
	v_pk_add_f32 v[14:15], v[14:15], v[44:45]
	v_pk_add_f32 v[16:17], v[16:17], v[46:47]
	v_pk_add_f32 v[18:19], v[18:19], v[48:49]
	v_pk_add_f32 v[12:13], v[12:13], v[50:51]
	v_pk_fma_f32 v[36:37], v[34:35], v[14:15], v[44:45] op_sel_hi:[0,1,1] neg_lo:[0,0,1] neg_hi:[0,0,1]
	v_pk_fma_f32 v[38:39], v[34:35], v[16:17], v[46:47] op_sel_hi:[0,1,1] neg_lo:[0,0,1] neg_hi:[0,0,1]
	v_pk_fma_f32 v[40:41], v[34:35], v[18:19], v[48:49] op_sel_hi:[0,1,1] neg_lo:[0,0,1] neg_hi:[0,0,1]
	v_pk_fma_f32 v[42:43], v[34:35], v[12:13], v[50:51] op_sel_hi:[0,1,1] neg_lo:[0,0,1] neg_hi:[0,0,1]
	v_cvt_pk_bf16_f32 v28, v36, v37
	v_cvt_pk_bf16_f32 v29, v38, v39
	v_cvt_pk_bf16_f32 v30, v40, v41
	v_cvt_pk_bf16_f32 v31, v42, v43
	global_store_dwordx4 v[10:11], v[28:31], off
	v_lshlrev_b32_e32 v44, 16, v136
	v_and_b32_e32 v45, 0xffff0000, v136
	v_lshlrev_b32_e32 v46, 16, v137
	v_and_b32_e32 v47, 0xffff0000, v137
	v_lshlrev_b32_e32 v48, 16, v138
	v_and_b32_e32 v49, 0xffff0000, v138
	v_lshlrev_b32_e32 v50, 16, v139
	v_and_b32_e32 v51, 0xffff0000, v139
	v_pk_add_f32 v[14:15], v[14:15], v[44:45] neg_lo:[0,1] neg_hi:[0,1]
	v_pk_add_f32 v[16:17], v[16:17], v[46:47] neg_lo:[0,1] neg_hi:[0,1]
	v_pk_add_f32 v[18:19], v[18:19], v[48:49] neg_lo:[0,1] neg_hi:[0,1]
	v_pk_add_f32 v[12:13], v[12:13], v[50:51] neg_lo:[0,1] neg_hi:[0,1]
	v_lshl_add_u64 v[10:11], v[10:11], 0, s[26:27]
	v_lshlrev_b32_e32 v44, 16, v168
	v_and_b32_e32 v45, 0xffff0000, v168
	v_lshlrev_b32_e32 v46, 16, v169
	v_and_b32_e32 v47, 0xffff0000, v169
	v_lshlrev_b32_e32 v48, 16, v170
	v_and_b32_e32 v49, 0xffff0000, v170
	v_lshlrev_b32_e32 v50, 16, v171
	v_and_b32_e32 v51, 0xffff0000, v171
	v_pk_add_f32 v[14:15], v[14:15], v[44:45]
	v_pk_add_f32 v[16:17], v[16:17], v[46:47]
	v_pk_add_f32 v[18:19], v[18:19], v[48:49]
	v_pk_add_f32 v[12:13], v[12:13], v[50:51]
	v_pk_fma_f32 v[36:37], v[34:35], v[14:15], v[44:45] op_sel_hi:[0,1,1] neg_lo:[0,0,1] neg_hi:[0,0,1]
	v_pk_fma_f32 v[38:39], v[34:35], v[16:17], v[46:47] op_sel_hi:[0,1,1] neg_lo:[0,0,1] neg_hi:[0,0,1]
	v_pk_fma_f32 v[40:41], v[34:35], v[18:19], v[48:49] op_sel_hi:[0,1,1] neg_lo:[0,0,1] neg_hi:[0,0,1]
	v_pk_fma_f32 v[42:43], v[34:35], v[12:13], v[50:51] op_sel_hi:[0,1,1] neg_lo:[0,0,1] neg_hi:[0,0,1]
	v_cvt_pk_bf16_f32 v28, v36, v37
	v_cvt_pk_bf16_f32 v29, v38, v39
	v_cvt_pk_bf16_f32 v30, v40, v41
	v_cvt_pk_bf16_f32 v31, v42, v43
	global_store_dwordx4 v[10:11], v[28:31], off
	v_lshlrev_b32_e32 v44, 16, v140
	v_and_b32_e32 v45, 0xffff0000, v140
	v_lshlrev_b32_e32 v46, 16, v141
	v_and_b32_e32 v47, 0xffff0000, v141
	v_lshlrev_b32_e32 v48, 16, v142
	v_and_b32_e32 v49, 0xffff0000, v142
	v_lshlrev_b32_e32 v50, 16, v143
	v_and_b32_e32 v51, 0xffff0000, v143
	v_pk_add_f32 v[14:15], v[14:15], v[44:45] neg_lo:[0,1] neg_hi:[0,1]
	v_pk_add_f32 v[16:17], v[16:17], v[46:47] neg_lo:[0,1] neg_hi:[0,1]
	v_pk_add_f32 v[18:19], v[18:19], v[48:49] neg_lo:[0,1] neg_hi:[0,1]
	v_pk_add_f32 v[12:13], v[12:13], v[50:51] neg_lo:[0,1] neg_hi:[0,1]
	v_lshl_add_u64 v[10:11], v[10:11], 0, s[26:27]
	v_lshlrev_b32_e32 v44, 16, v172
	v_and_b32_e32 v45, 0xffff0000, v172
	v_lshlrev_b32_e32 v46, 16, v173
	v_and_b32_e32 v47, 0xffff0000, v173
	v_lshlrev_b32_e32 v48, 16, v174
	v_and_b32_e32 v49, 0xffff0000, v174
	v_lshlrev_b32_e32 v50, 16, v175
	v_and_b32_e32 v51, 0xffff0000, v175
	v_pk_add_f32 v[14:15], v[14:15], v[44:45]
	v_pk_add_f32 v[16:17], v[16:17], v[46:47]
	v_pk_add_f32 v[18:19], v[18:19], v[48:49]
	v_pk_add_f32 v[12:13], v[12:13], v[50:51]
	v_pk_fma_f32 v[36:37], v[34:35], v[14:15], v[44:45] op_sel_hi:[0,1,1] neg_lo:[0,0,1] neg_hi:[0,0,1]
	v_pk_fma_f32 v[38:39], v[34:35], v[16:17], v[46:47] op_sel_hi:[0,1,1] neg_lo:[0,0,1] neg_hi:[0,0,1]
	v_pk_fma_f32 v[40:41], v[34:35], v[18:19], v[48:49] op_sel_hi:[0,1,1] neg_lo:[0,0,1] neg_hi:[0,0,1]
	v_pk_fma_f32 v[42:43], v[34:35], v[12:13], v[50:51] op_sel_hi:[0,1,1] neg_lo:[0,0,1] neg_hi:[0,0,1]
	v_cvt_pk_bf16_f32 v28, v36, v37
	v_cvt_pk_bf16_f32 v29, v38, v39
	v_cvt_pk_bf16_f32 v30, v40, v41
	v_cvt_pk_bf16_f32 v31, v42, v43
	global_store_dwordx4 v[10:11], v[28:31], off
	v_lshlrev_b32_e32 v44, 16, v144
	v_and_b32_e32 v45, 0xffff0000, v144
	v_lshlrev_b32_e32 v46, 16, v145
	v_and_b32_e32 v47, 0xffff0000, v145
	v_lshlrev_b32_e32 v48, 16, v146
	v_and_b32_e32 v49, 0xffff0000, v146
	v_lshlrev_b32_e32 v50, 16, v147
	v_and_b32_e32 v51, 0xffff0000, v147
	v_pk_add_f32 v[14:15], v[14:15], v[44:45] neg_lo:[0,1] neg_hi:[0,1]
	v_pk_add_f32 v[16:17], v[16:17], v[46:47] neg_lo:[0,1] neg_hi:[0,1]
	v_pk_add_f32 v[18:19], v[18:19], v[48:49] neg_lo:[0,1] neg_hi:[0,1]
	v_pk_add_f32 v[12:13], v[12:13], v[50:51] neg_lo:[0,1] neg_hi:[0,1]
	v_lshl_add_u64 v[10:11], v[10:11], 0, s[26:27]
	v_lshlrev_b32_e32 v44, 16, v176
	v_and_b32_e32 v45, 0xffff0000, v176
	v_lshlrev_b32_e32 v46, 16, v177
	v_and_b32_e32 v47, 0xffff0000, v177
	v_lshlrev_b32_e32 v48, 16, v178
	v_and_b32_e32 v49, 0xffff0000, v178
	v_lshlrev_b32_e32 v50, 16, v179
	v_and_b32_e32 v51, 0xffff0000, v179
	v_pk_add_f32 v[14:15], v[14:15], v[44:45]
	v_pk_add_f32 v[16:17], v[16:17], v[46:47]
	v_pk_add_f32 v[18:19], v[18:19], v[48:49]
	v_pk_add_f32 v[12:13], v[12:13], v[50:51]
	v_pk_fma_f32 v[36:37], v[34:35], v[14:15], v[44:45] op_sel_hi:[0,1,1] neg_lo:[0,0,1] neg_hi:[0,0,1]
	v_pk_fma_f32 v[38:39], v[34:35], v[16:17], v[46:47] op_sel_hi:[0,1,1] neg_lo:[0,0,1] neg_hi:[0,0,1]
; __device__ __forceinline__ unsigned pk2(float lo, float hi) { f32x2 v = {lo, hi}; bf16x2_t b = __builtin_convertvector(v, bf16x2_t); return __builtin_bit_cast(unsigned, b); }
; __device__ __forceinline__ void pool_window(const bf16_t* __restrict__ U  , bf16_t* __restrict__ A3, const int gtid, const int nthr) {
;     ...
;         for (int i = 0; i < 32; ++i) {
;             const int t = t0 + i, s = s0 + i;
;             const u32x4 uu = *(const u32x4*)(U + (size_t)t * LDU + c);
;             float cu[8] = {bflo(uu.x), bfhi(uu.x), bflo(uu.y), bfhi(uu.y), bflo(uu.z), bfhi(uu.z), bflo(uu.w), bfhi(uu.w)};
;             const float rc = 1.0f / (float)((s + 1) < w ? (s + 1) : w);
;             float o[8];
; #pragma unroll
;             for (int e = 0; e < 8; ++e) { sum[e] += cu[e]; o[e] = sum[e] * rc - cu[e]; }
;             u32x4 ww; ww.x = pk2(o[0], o[1]); ww.y = pk2(o[2], o[3]); ww.z = pk2(o[4], o[5]); ww.w = pk2(o[6], o[7]);
;             *(u32x4*)(A3 + (size_t)t * DM + c) = ww;
;             if (s + 1 >= w) { const u32x4 ud = *(const u32x4*)(U + (size_t)(t - w + 1) * LDU + c);
;                 sum[0] -= bflo(ud.x); sum[1] -= bfhi(ud.x); sum[2] -= bflo(ud.y); sum[3] -= bfhi(ud.y); sum[4] -= bflo(ud.z); sum[5] -= bfhi(ud.z); sum[6] -= bflo(ud.w); sum[7] -= bfhi(ud.w); }
;         }
	v_pk_fma_f32 v[40:41], v[34:35], v[18:19], v[48:49] op_sel_hi:[0,1,1] neg_lo:[0,0,1] neg_hi:[0,0,1]
	v_pk_fma_f32 v[42:43], v[34:35], v[12:13], v[50:51] op_sel_hi:[0,1,1] neg_lo:[0,0,1] neg_hi:[0,0,1]
	v_cvt_pk_bf16_f32 v28, v36, v37
	v_cvt_pk_bf16_f32 v29, v38, v39
	v_cvt_pk_bf16_f32 v30, v40, v41
	v_cvt_pk_bf16_f32 v31, v42, v43
	global_store_dwordx4 v[10:11], v[28:31], off
	v_lshlrev_b32_e32 v44, 16, v148
	v_and_b32_e32 v45, 0xffff0000, v148
	v_lshlrev_b32_e32 v46, 16, v149
	v_and_b32_e32 v47, 0xffff0000, v149
	v_lshlrev_b32_e32 v48, 16, v150
	v_and_b32_e32 v49, 0xffff0000, v150
	v_lshlrev_b32_e32 v50, 16, v151
	v_and_b32_e32 v51, 0xffff0000, v151
	v_pk_add_f32 v[14:15], v[14:15], v[44:45] neg_lo:[0,1] neg_hi:[0,1]
	v_pk_add_f32 v[16:17], v[16:17], v[46:47] neg_lo:[0,1] neg_hi:[0,1]
	v_pk_add_f32 v[18:19], v[18:19], v[48:49] neg_lo:[0,1] neg_hi:[0,1]
	v_pk_add_f32 v[12:13], v[12:13], v[50:51] neg_lo:[0,1] neg_hi:[0,1]
	v_lshl_add_u64 v[10:11], v[10:11], 0, s[26:27]
	v_lshlrev_b32_e32 v44, 16, v180
	v_and_b32_e32 v45, 0xffff0000, v180
	v_lshlrev_b32_e32 v46, 16, v181
	v_and_b32_e32 v47, 0xffff0000, v181
	v_lshlrev_b32_e32 v48, 16, v182
	v_and_b32_e32 v49, 0xffff0000, v182
	v_lshlrev_b32_e32 v50, 16, v183
	v_and_b32_e32 v51, 0xffff0000, v183
	v_pk_add_f32 v[14:15], v[14:15], v[44:45]
	v_pk_add_f32 v[16:17], v[16:17], v[46:47]
	v_pk_add_f32 v[18:19], v[18:19], v[48:49]
	v_pk_add_f32 v[12:13], v[12:13], v[50:51]
	v_pk_fma_f32 v[36:37], v[34:35], v[14:15], v[44:45] op_sel_hi:[0,1,1] neg_lo:[0,0,1] neg_hi:[0,0,1]
	v_pk_fma_f32 v[38:39], v[34:35], v[16:17], v[46:47] op_sel_hi:[0,1,1] neg_lo:[0,0,1] neg_hi:[0,0,1]
	v_pk_fma_f32 v[40:41], v[34:35], v[18:19], v[48:49] op_sel_hi:[0,1,1] neg_lo:[0,0,1] neg_hi:[0,0,1]
	v_pk_fma_f32 v[42:43], v[34:35], v[12:13], v[50:51] op_sel_hi:[0,1,1] neg_lo:[0,0,1] neg_hi:[0,0,1]
	v_cvt_pk_bf16_f32 v28, v36, v37
	v_cvt_pk_bf16_f32 v29, v38, v39
	v_cvt_pk_bf16_f32 v30, v40, v41
	v_cvt_pk_bf16_f32 v31, v42, v43
	global_store_dwordx4 v[10:11], v[28:31], off
	v_lshlrev_b32_e32 v44, 16, v152
	v_and_b32_e32 v45, 0xffff0000, v152
	v_lshlrev_b32_e32 v46, 16, v153
	v_and_b32_e32 v47, 0xffff0000, v153
	v_lshlrev_b32_e32 v48, 16, v154
	v_and_b32_e32 v49, 0xffff0000, v154
	v_lshlrev_b32_e32 v50, 16, v155
	v_and_b32_e32 v51, 0xffff0000, v155
	v_pk_add_f32 v[14:15], v[14:15], v[44:45] neg_lo:[0,1] neg_hi:[0,1]
	v_pk_add_f32 v[16:17], v[16:17], v[46:47] neg_lo:[0,1] neg_hi:[0,1]
	v_pk_add_f32 v[18:19], v[18:19], v[48:49] neg_lo:[0,1] neg_hi:[0,1]
	v_pk_add_f32 v[12:13], v[12:13], v[50:51] neg_lo:[0,1] neg_hi:[0,1]
	v_lshl_add_u64 v[10:11], v[10:11], 0, s[26:27]
	v_lshlrev_b32_e32 v44, 16, v184
	v_and_b32_e32 v45, 0xffff0000, v184
	v_lshlrev_b32_e32 v46, 16, v185
	v_and_b32_e32 v47, 0xffff0000, v185
	v_lshlrev_b32_e32 v48, 16, v186
	v_and_b32_e32 v49, 0xffff0000, v186
	v_lshlrev_b32_e32 v50, 16, v187
	v_and_b32_e32 v51, 0xffff0000, v187
	v_pk_add_f32 v[14:15], v[14:15], v[44:45]
	v_pk_add_f32 v[16:17], v[16:17], v[46:47]
	v_pk_add_f32 v[18:19], v[18:19], v[48:49]
	v_pk_add_f32 v[12:13], v[12:13], v[50:51]
	v_pk_fma_f32 v[36:37], v[34:35], v[14:15], v[44:45] op_sel_hi:[0,1,1] neg_lo:[0,0,1] neg_hi:[0,0,1]
	v_pk_fma_f32 v[38:39], v[34:35], v[16:17], v[46:47] op_sel_hi:[0,1,1] neg_lo:[0,0,1] neg_hi:[0,0,1]
	v_pk_fma_f32 v[40:41], v[34:35], v[18:19], v[48:49] op_sel_hi:[0,1,1] neg_lo:[0,0,1] neg_hi:[0,0,1]
	v_pk_fma_f32 v[42:43], v[34:35], v[12:13], v[50:51] op_sel_hi:[0,1,1] neg_lo:[0,0,1] neg_hi:[0,0,1]
	v_cvt_pk_bf16_f32 v28, v36, v37
	v_cvt_pk_bf16_f32 v29, v38, v39
	v_cvt_pk_bf16_f32 v30, v40, v41
	v_cvt_pk_bf16_f32 v31, v42, v43
	global_store_dwordx4 v[10:11], v[28:31], off
	v_lshlrev_b32_e32 v44, 16, v156
	v_and_b32_e32 v45, 0xffff0000, v156
	v_lshlrev_b32_e32 v46, 16, v157
	v_and_b32_e32 v47, 0xffff0000, v157
	v_lshlrev_b32_e32 v48, 16, v158
	v_and_b32_e32 v49, 0xffff0000, v158
	v_lshlrev_b32_e32 v50, 16, v159
	v_and_b32_e32 v51, 0xffff0000, v159
	v_pk_add_f32 v[14:15], v[14:15], v[44:45] neg_lo:[0,1] neg_hi:[0,1]
	v_pk_add_f32 v[16:17], v[16:17], v[46:47] neg_lo:[0,1] neg_hi:[0,1]
	v_pk_add_f32 v[18:19], v[18:19], v[48:49] neg_lo:[0,1] neg_hi:[0,1]
	v_pk_add_f32 v[12:13], v[12:13], v[50:51] neg_lo:[0,1] neg_hi:[0,1]
	v_lshl_add_u64 v[10:11], v[10:11], 0, s[26:27]
	v_lshlrev_b32_e32 v44, 16, v188
	v_and_b32_e32 v45, 0xffff0000, v188
	v_lshlrev_b32_e32 v46, 16, v189
	v_and_b32_e32 v47, 0xffff0000, v189
	v_lshlrev_b32_e32 v48, 16, v190
	v_and_b32_e32 v49, 0xffff0000, v190
	v_lshlrev_b32_e32 v50, 16, v191
	v_and_b32_e32 v51, 0xffff0000, v191
	v_pk_add_f32 v[14:15], v[14:15], v[44:45]
	v_pk_add_f32 v[16:17], v[16:17], v[46:47]
	v_pk_add_f32 v[18:19], v[18:19], v[48:49]
	v_pk_add_f32 v[12:13], v[12:13], v[50:51]
	v_pk_fma_f32 v[36:37], v[34:35], v[14:15], v[44:45] op_sel_hi:[0,1,1] neg_lo:[0,0,1] neg_hi:[0,0,1]
	v_pk_fma_f32 v[38:39], v[34:35], v[16:17], v[46:47] op_sel_hi:[0,1,1] neg_lo:[0,0,1] neg_hi:[0,0,1]
	v_pk_fma_f32 v[40:41], v[34:35], v[18:19], v[48:49] op_sel_hi:[0,1,1] neg_lo:[0,0,1] neg_hi:[0,0,1]
	v_pk_fma_f32 v[42:43], v[34:35], v[12:13], v[50:51] op_sel_hi:[0,1,1] neg_lo:[0,0,1] neg_hi:[0,0,1]
	v_cvt_pk_bf16_f32 v28, v36, v37
	v_cvt_pk_bf16_f32 v29, v38, v39
	v_cvt_pk_bf16_f32 v30, v40, v41
	v_cvt_pk_bf16_f32 v31, v42, v43
	global_store_dwordx4 v[10:11], v[28:31], off
	v_lshlrev_b32_e32 v44, 16, v160
	v_and_b32_e32 v45, 0xffff0000, v160
	v_lshlrev_b32_e32 v46, 16, v161
	v_and_b32_e32 v47, 0xffff0000, v161
	v_lshlrev_b32_e32 v48, 16, v162
	v_and_b32_e32 v49, 0xffff0000, v162
	v_lshlrev_b32_e32 v50, 16, v163
	v_and_b32_e32 v51, 0xffff0000, v163
	v_pk_add_f32 v[14:15], v[14:15], v[44:45] neg_lo:[0,1] neg_hi:[0,1]
; __device__ __forceinline__ unsigned pk2(float lo, float hi) { f32x2 v = {lo, hi}; bf16x2_t b = __builtin_convertvector(v, bf16x2_t); return __builtin_bit_cast(unsigned, b); }
; __device__ __forceinline__ void pool_window(const bf16_t* __restrict__ U  , bf16_t* __restrict__ A3, const int gtid, const int nthr) {
;     ...
;         for (int i = 0; i < 32; ++i) {
;             const int t = t0 + i, s = s0 + i;
;             const u32x4 uu = *(const u32x4*)(U + (size_t)t * LDU + c);
;             float cu[8] = {bflo(uu.x), bfhi(uu.x), bflo(uu.y), bfhi(uu.y), bflo(uu.z), bfhi(uu.z), bflo(uu.w), bfhi(uu.w)};
;             const float rc = 1.0f / (float)((s + 1) < w ? (s + 1) : w);
;             float o[8];
; #pragma unroll
;             for (int e = 0; e < 8; ++e) { sum[e] += cu[e]; o[e] = sum[e] * rc - cu[e]; }
;             u32x4 ww; ww.x = pk2(o[0], o[1]); ww.y = pk2(o[2], o[3]); ww.z = pk2(o[4], o[5]); ww.w = pk2(o[6], o[7]);
;             *(u32x4*)(A3 + (size_t)t * DM + c) = ww;
;             if (s + 1 >= w) { const u32x4 ud = *(const u32x4*)(U + (size_t)(t - w + 1) * LDU + c);
;                 sum[0] -= bflo(ud.x); sum[1] -= bfhi(ud.x); sum[2] -= bflo(ud.y); sum[3] -= bfhi(ud.y); sum[4] -= bflo(ud.z); sum[5] -= bfhi(ud.z); sum[6] -= bflo(ud.w); sum[7] -= bfhi(ud.w); }
;         }
	v_pk_add_f32 v[16:17], v[16:17], v[46:47] neg_lo:[0,1] neg_hi:[0,1]
	v_pk_add_f32 v[18:19], v[18:19], v[48:49] neg_lo:[0,1] neg_hi:[0,1]
	v_pk_add_f32 v[12:13], v[12:13], v[50:51] neg_lo:[0,1] neg_hi:[0,1]
	v_lshl_add_u64 v[10:11], v[10:11], 0, s[26:27]
	v_lshlrev_b32_e32 v44, 16, v192
	v_and_b32_e32 v45, 0xffff0000, v192
	v_lshlrev_b32_e32 v46, 16, v193
	v_and_b32_e32 v47, 0xffff0000, v193
	v_lshlrev_b32_e32 v48, 16, v194
	v_and_b32_e32 v49, 0xffff0000, v194
	v_lshlrev_b32_e32 v50, 16, v195
	v_and_b32_e32 v51, 0xffff0000, v195
	v_pk_add_f32 v[14:15], v[14:15], v[44:45]
	v_pk_add_f32 v[16:17], v[16:17], v[46:47]
	v_pk_add_f32 v[18:19], v[18:19], v[48:49]
	v_pk_add_f32 v[12:13], v[12:13], v[50:51]
	v_pk_fma_f32 v[36:37], v[34:35], v[14:15], v[44:45] op_sel_hi:[0,1,1] neg_lo:[0,0,1] neg_hi:[0,0,1]
	v_pk_fma_f32 v[38:39], v[34:35], v[16:17], v[46:47] op_sel_hi:[0,1,1] neg_lo:[0,0,1] neg_hi:[0,0,1]
	v_pk_fma_f32 v[40:41], v[34:35], v[18:19], v[48:49] op_sel_hi:[0,1,1] neg_lo:[0,0,1] neg_hi:[0,0,1]
	v_pk_fma_f32 v[42:43], v[34:35], v[12:13], v[50:51] op_sel_hi:[0,1,1] neg_lo:[0,0,1] neg_hi:[0,0,1]
	v_cvt_pk_bf16_f32 v28, v36, v37
	v_cvt_pk_bf16_f32 v29, v38, v39
	v_cvt_pk_bf16_f32 v30, v40, v41
	v_cvt_pk_bf16_f32 v31, v42, v43
	global_store_dwordx4 v[10:11], v[28:31], off
	v_lshlrev_b32_e32 v44, 16, v164
	v_and_b32_e32 v45, 0xffff0000, v164
	v_lshlrev_b32_e32 v46, 16, v165
	v_and_b32_e32 v47, 0xffff0000, v165
	v_lshlrev_b32_e32 v48, 16, v166
	v_and_b32_e32 v49, 0xffff0000, v166
	v_lshlrev_b32_e32 v50, 16, v167
	v_and_b32_e32 v51, 0xffff0000, v167
	v_pk_add_f32 v[14:15], v[14:15], v[44:45] neg_lo:[0,1] neg_hi:[0,1]
	v_pk_add_f32 v[16:17], v[16:17], v[46:47] neg_lo:[0,1] neg_hi:[0,1]
	v_pk_add_f32 v[18:19], v[18:19], v[48:49] neg_lo:[0,1] neg_hi:[0,1]
	v_pk_add_f32 v[12:13], v[12:13], v[50:51] neg_lo:[0,1] neg_hi:[0,1]
	v_lshl_add_u64 v[10:11], v[10:11], 0, s[26:27]
	v_lshlrev_b32_e32 v44, 16, v196
	v_and_b32_e32 v45, 0xffff0000, v196
	v_lshlrev_b32_e32 v46, 16, v197
	v_and_b32_e32 v47, 0xffff0000, v197
	v_lshlrev_b32_e32 v48, 16, v198
	v_and_b32_e32 v49, 0xffff0000, v198
	v_lshlrev_b32_e32 v50, 16, v199
	v_and_b32_e32 v51, 0xffff0000, v199
	v_pk_add_f32 v[14:15], v[14:15], v[44:45]
	v_pk_add_f32 v[16:17], v[16:17], v[46:47]
	v_pk_add_f32 v[18:19], v[18:19], v[48:49]
	v_pk_add_f32 v[12:13], v[12:13], v[50:51]
	v_pk_fma_f32 v[36:37], v[34:35], v[14:15], v[44:45] op_sel_hi:[0,1,1] neg_lo:[0,0,1] neg_hi:[0,0,1]
	v_pk_fma_f32 v[38:39], v[34:35], v[16:17], v[46:47] op_sel_hi:[0,1,1] neg_lo:[0,0,1] neg_hi:[0,0,1]
	v_pk_fma_f32 v[40:41], v[34:35], v[18:19], v[48:49] op_sel_hi:[0,1,1] neg_lo:[0,0,1] neg_hi:[0,0,1]
	v_pk_fma_f32 v[42:43], v[34:35], v[12:13], v[50:51] op_sel_hi:[0,1,1] neg_lo:[0,0,1] neg_hi:[0,0,1]
	v_cvt_pk_bf16_f32 v28, v36, v37
	v_cvt_pk_bf16_f32 v29, v38, v39
	v_cvt_pk_bf16_f32 v30, v40, v41
	v_cvt_pk_bf16_f32 v31, v42, v43
	global_store_dwordx4 v[10:11], v[28:31], off
	v_lshlrev_b32_e32 v44, 16, v168
	v_and_b32_e32 v45, 0xffff0000, v168
	v_lshlrev_b32_e32 v46, 16, v169
	v_and_b32_e32 v47, 0xffff0000, v169
	v_lshlrev_b32_e32 v48, 16, v170
	v_and_b32_e32 v49, 0xffff0000, v170
	v_lshlrev_b32_e32 v50, 16, v171
	v_and_b32_e32 v51, 0xffff0000, v171
	v_pk_add_f32 v[14:15], v[14:15], v[44:45] neg_lo:[0,1] neg_hi:[0,1]
	v_pk_add_f32 v[16:17], v[16:17], v[46:47] neg_lo:[0,1] neg_hi:[0,1]
	v_pk_add_f32 v[18:19], v[18:19], v[48:49] neg_lo:[0,1] neg_hi:[0,1]
	v_pk_add_f32 v[12:13], v[12:13], v[50:51] neg_lo:[0,1] neg_hi:[0,1]
	v_lshl_add_u64 v[10:11], v[10:11], 0, s[26:27]
	v_lshlrev_b32_e32 v44, 16, v200
	v_and_b32_e32 v45, 0xffff0000, v200
	v_lshlrev_b32_e32 v46, 16, v201
	v_and_b32_e32 v47, 0xffff0000, v201
	v_lshlrev_b32_e32 v48, 16, v202
	v_and_b32_e32 v49, 0xffff0000, v202
	v_lshlrev_b32_e32 v50, 16, v203
	v_and_b32_e32 v51, 0xffff0000, v203
	v_pk_add_f32 v[14:15], v[14:15], v[44:45]
	v_pk_add_f32 v[16:17], v[16:17], v[46:47]
	v_pk_add_f32 v[18:19], v[18:19], v[48:49]
	v_pk_add_f32 v[12:13], v[12:13], v[50:51]
	v_pk_fma_f32 v[36:37], v[34:35], v[14:15], v[44:45] op_sel_hi:[0,1,1] neg_lo:[0,0,1] neg_hi:[0,0,1]
	v_pk_fma_f32 v[38:39], v[34:35], v[16:17], v[46:47] op_sel_hi:[0,1,1] neg_lo:[0,0,1] neg_hi:[0,0,1]
	v_pk_fma_f32 v[40:41], v[34:35], v[18:19], v[48:49] op_sel_hi:[0,1,1] neg_lo:[0,0,1] neg_hi:[0,0,1]
	v_pk_fma_f32 v[42:43], v[34:35], v[12:13], v[50:51] op_sel_hi:[0,1,1] neg_lo:[0,0,1] neg_hi:[0,0,1]
	v_cvt_pk_bf16_f32 v28, v36, v37
	v_cvt_pk_bf16_f32 v29, v38, v39
	v_cvt_pk_bf16_f32 v30, v40, v41
	v_cvt_pk_bf16_f32 v31, v42, v43
	global_store_dwordx4 v[10:11], v[28:31], off
	v_lshlrev_b32_e32 v44, 16, v172
	v_and_b32_e32 v45, 0xffff0000, v172
	v_lshlrev_b32_e32 v46, 16, v173
	v_and_b32_e32 v47, 0xffff0000, v173
	v_lshlrev_b32_e32 v48, 16, v174
	v_and_b32_e32 v49, 0xffff0000, v174
	v_lshlrev_b32_e32 v50, 16, v175
	v_and_b32_e32 v51, 0xffff0000, v175
	v_pk_add_f32 v[14:15], v[14:15], v[44:45] neg_lo:[0,1] neg_hi:[0,1]
	v_pk_add_f32 v[16:17], v[16:17], v[46:47] neg_lo:[0,1] neg_hi:[0,1]
	v_pk_add_f32 v[18:19], v[18:19], v[48:49] neg_lo:[0,1] neg_hi:[0,1]
	v_pk_add_f32 v[12:13], v[12:13], v[50:51] neg_lo:[0,1] neg_hi:[0,1]
	v_lshl_add_u64 v[10:11], v[10:11], 0, s[26:27]
	v_lshlrev_b32_e32 v44, 16, v204
	v_and_b32_e32 v45, 0xffff0000, v204
	v_lshlrev_b32_e32 v46, 16, v205
	v_and_b32_e32 v47, 0xffff0000, v205
	v_lshlrev_b32_e32 v48, 16, v206
	v_and_b32_e32 v49, 0xffff0000, v206
	v_lshlrev_b32_e32 v50, 16, v207
	v_and_b32_e32 v51, 0xffff0000, v207
	v_pk_add_f32 v[14:15], v[14:15], v[44:45]
	v_pk_add_f32 v[16:17], v[16:17], v[46:47]
	v_pk_add_f32 v[18:19], v[18:19], v[48:49]
	v_pk_add_f32 v[12:13], v[12:13], v[50:51]
; __device__ __forceinline__ unsigned pk2(float lo, float hi) { f32x2 v = {lo, hi}; bf16x2_t b = __builtin_convertvector(v, bf16x2_t); return __builtin_bit_cast(unsigned, b); }
; __device__ __forceinline__ void pool_window(const bf16_t* __restrict__ U  , bf16_t* __restrict__ A3, const int gtid, const int nthr) {
;     ...
;         for (int i = 0; i < 32; ++i) {
;             const int t = t0 + i, s = s0 + i;
;             const u32x4 uu = *(const u32x4*)(U + (size_t)t * LDU + c);
;             float cu[8] = {bflo(uu.x), bfhi(uu.x), bflo(uu.y), bfhi(uu.y), bflo(uu.z), bfhi(uu.z), bflo(uu.w), bfhi(uu.w)};
;             const float rc = 1.0f / (float)((s + 1) < w ? (s + 1) : w);
;             float o[8];
; #pragma unroll
;             for (int e = 0; e < 8; ++e) { sum[e] += cu[e]; o[e] = sum[e] * rc - cu[e]; }
;             u32x4 ww; ww.x = pk2(o[0], o[1]); ww.y = pk2(o[2], o[3]); ww.z = pk2(o[4], o[5]); ww.w = pk2(o[6], o[7]);
;             *(u32x4*)(A3 + (size_t)t * DM + c) = ww;
;             if (s + 1 >= w) { const u32x4 ud = *(const u32x4*)(U + (size_t)(t - w + 1) * LDU + c);
;                 sum[0] -= bflo(ud.x); sum[1] -= bfhi(ud.x); sum[2] -= bflo(ud.y); sum[3] -= bfhi(ud.y); sum[4] -= bflo(ud.z); sum[5] -= bfhi(ud.z); sum[6] -= bflo(ud.w); sum[7] -= bfhi(ud.w); }
;         }
	v_pk_fma_f32 v[36:37], v[34:35], v[14:15], v[44:45] op_sel_hi:[0,1,1] neg_lo:[0,0,1] neg_hi:[0,0,1]
	v_pk_fma_f32 v[38:39], v[34:35], v[16:17], v[46:47] op_sel_hi:[0,1,1] neg_lo:[0,0,1] neg_hi:[0,0,1]
	v_pk_fma_f32 v[40:41], v[34:35], v[18:19], v[48:49] op_sel_hi:[0,1,1] neg_lo:[0,0,1] neg_hi:[0,0,1]
	v_pk_fma_f32 v[42:43], v[34:35], v[12:13], v[50:51] op_sel_hi:[0,1,1] neg_lo:[0,0,1] neg_hi:[0,0,1]
	v_cvt_pk_bf16_f32 v28, v36, v37
	v_cvt_pk_bf16_f32 v29, v38, v39
	v_cvt_pk_bf16_f32 v30, v40, v41
	v_cvt_pk_bf16_f32 v31, v42, v43
	global_store_dwordx4 v[10:11], v[28:31], off
	v_lshlrev_b32_e32 v44, 16, v176
	v_and_b32_e32 v45, 0xffff0000, v176
	v_lshlrev_b32_e32 v46, 16, v177
	v_and_b32_e32 v47, 0xffff0000, v177
	v_lshlrev_b32_e32 v48, 16, v178
	v_and_b32_e32 v49, 0xffff0000, v178
	v_lshlrev_b32_e32 v50, 16, v179
	v_and_b32_e32 v51, 0xffff0000, v179
	v_pk_add_f32 v[14:15], v[14:15], v[44:45] neg_lo:[0,1] neg_hi:[0,1]
	v_pk_add_f32 v[16:17], v[16:17], v[46:47] neg_lo:[0,1] neg_hi:[0,1]
	v_pk_add_f32 v[18:19], v[18:19], v[48:49] neg_lo:[0,1] neg_hi:[0,1]
	v_pk_add_f32 v[12:13], v[12:13], v[50:51] neg_lo:[0,1] neg_hi:[0,1]
	v_lshl_add_u64 v[10:11], v[10:11], 0, s[26:27]
	v_lshlrev_b32_e32 v44, 16, v208
	v_and_b32_e32 v45, 0xffff0000, v208
	v_lshlrev_b32_e32 v46, 16, v209
	v_and_b32_e32 v47, 0xffff0000, v209
	v_lshlrev_b32_e32 v48, 16, v210
	v_and_b32_e32 v49, 0xffff0000, v210
	v_lshlrev_b32_e32 v50, 16, v211
	v_and_b32_e32 v51, 0xffff0000, v211
	v_pk_add_f32 v[14:15], v[14:15], v[44:45]
	v_pk_add_f32 v[16:17], v[16:17], v[46:47]
	v_pk_add_f32 v[18:19], v[18:19], v[48:49]
	v_pk_add_f32 v[12:13], v[12:13], v[50:51]
	v_pk_fma_f32 v[36:37], v[34:35], v[14:15], v[44:45] op_sel_hi:[0,1,1] neg_lo:[0,0,1] neg_hi:[0,0,1]
	v_pk_fma_f32 v[38:39], v[34:35], v[16:17], v[46:47] op_sel_hi:[0,1,1] neg_lo:[0,0,1] neg_hi:[0,0,1]
	v_pk_fma_f32 v[40:41], v[34:35], v[18:19], v[48:49] op_sel_hi:[0,1,1] neg_lo:[0,0,1] neg_hi:[0,0,1]
	v_pk_fma_f32 v[42:43], v[34:35], v[12:13], v[50:51] op_sel_hi:[0,1,1] neg_lo:[0,0,1] neg_hi:[0,0,1]
	v_cvt_pk_bf16_f32 v28, v36, v37
	v_cvt_pk_bf16_f32 v29, v38, v39
	v_cvt_pk_bf16_f32 v30, v40, v41
	v_cvt_pk_bf16_f32 v31, v42, v43
	global_store_dwordx4 v[10:11], v[28:31], off
	v_lshlrev_b32_e32 v44, 16, v180
	v_and_b32_e32 v45, 0xffff0000, v180
	v_lshlrev_b32_e32 v46, 16, v181
	v_and_b32_e32 v47, 0xffff0000, v181
	v_lshlrev_b32_e32 v48, 16, v182
	v_and_b32_e32 v49, 0xffff0000, v182
	v_lshlrev_b32_e32 v50, 16, v183
	v_and_b32_e32 v51, 0xffff0000, v183
	v_pk_add_f32 v[14:15], v[14:15], v[44:45] neg_lo:[0,1] neg_hi:[0,1]
	v_pk_add_f32 v[16:17], v[16:17], v[46:47] neg_lo:[0,1] neg_hi:[0,1]
	v_pk_add_f32 v[18:19], v[18:19], v[48:49] neg_lo:[0,1] neg_hi:[0,1]
	v_pk_add_f32 v[12:13], v[12:13], v[50:51] neg_lo:[0,1] neg_hi:[0,1]
	v_lshl_add_u64 v[10:11], v[10:11], 0, s[26:27]
	v_lshlrev_b32_e32 v44, 16, v214
	v_and_b32_e32 v45, 0xffff0000, v214
	v_lshlrev_b32_e32 v46, 16, v215
	v_and_b32_e32 v47, 0xffff0000, v215
	v_lshlrev_b32_e32 v48, 16, v216
	v_and_b32_e32 v49, 0xffff0000, v216
	v_lshlrev_b32_e32 v50, 16, v217
	v_and_b32_e32 v51, 0xffff0000, v217
	v_pk_add_f32 v[14:15], v[14:15], v[44:45]
	v_pk_add_f32 v[16:17], v[16:17], v[46:47]
	v_pk_add_f32 v[18:19], v[18:19], v[48:49]
	v_pk_add_f32 v[12:13], v[12:13], v[50:51]
	v_pk_fma_f32 v[36:37], v[34:35], v[14:15], v[44:45] op_sel_hi:[0,1,1] neg_lo:[0,0,1] neg_hi:[0,0,1]
	v_pk_fma_f32 v[38:39], v[34:35], v[16:17], v[46:47] op_sel_hi:[0,1,1] neg_lo:[0,0,1] neg_hi:[0,0,1]
	v_pk_fma_f32 v[40:41], v[34:35], v[18:19], v[48:49] op_sel_hi:[0,1,1] neg_lo:[0,0,1] neg_hi:[0,0,1]
	v_pk_fma_f32 v[42:43], v[34:35], v[12:13], v[50:51] op_sel_hi:[0,1,1] neg_lo:[0,0,1] neg_hi:[0,0,1]
	v_cvt_pk_bf16_f32 v28, v36, v37
	v_cvt_pk_bf16_f32 v29, v38, v39
	v_cvt_pk_bf16_f32 v30, v40, v41
	v_cvt_pk_bf16_f32 v31, v42, v43
	global_store_dwordx4 v[10:11], v[28:31], off
	v_lshlrev_b32_e32 v44, 16, v184
	v_and_b32_e32 v45, 0xffff0000, v184
	v_lshlrev_b32_e32 v46, 16, v185
	v_and_b32_e32 v47, 0xffff0000, v185
	v_lshlrev_b32_e32 v48, 16, v186
	v_and_b32_e32 v49, 0xffff0000, v186
	v_lshlrev_b32_e32 v50, 16, v187
	v_and_b32_e32 v51, 0xffff0000, v187
	v_pk_add_f32 v[14:15], v[14:15], v[44:45] neg_lo:[0,1] neg_hi:[0,1]
	v_pk_add_f32 v[16:17], v[16:17], v[46:47] neg_lo:[0,1] neg_hi:[0,1]
	v_pk_add_f32 v[18:19], v[18:19], v[48:49] neg_lo:[0,1] neg_hi:[0,1]
	v_pk_add_f32 v[12:13], v[12:13], v[50:51] neg_lo:[0,1] neg_hi:[0,1]
	v_lshl_add_u64 v[10:11], v[10:11], 0, s[26:27]
	v_lshlrev_b32_e32 v44, 16, v218
	v_and_b32_e32 v45, 0xffff0000, v218
	v_lshlrev_b32_e32 v46, 16, v219
	v_and_b32_e32 v47, 0xffff0000, v219
	v_lshlrev_b32_e32 v48, 16, v220
	v_and_b32_e32 v49, 0xffff0000, v220
	v_lshlrev_b32_e32 v50, 16, v221
	v_and_b32_e32 v51, 0xffff0000, v221
	v_pk_add_f32 v[14:15], v[14:15], v[44:45]
	v_pk_add_f32 v[16:17], v[16:17], v[46:47]
	v_pk_add_f32 v[18:19], v[18:19], v[48:49]
	v_pk_add_f32 v[12:13], v[12:13], v[50:51]
	v_pk_fma_f32 v[36:37], v[34:35], v[14:15], v[44:45] op_sel_hi:[0,1,1] neg_lo:[0,0,1] neg_hi:[0,0,1]
	v_pk_fma_f32 v[38:39], v[34:35], v[16:17], v[46:47] op_sel_hi:[0,1,1] neg_lo:[0,0,1] neg_hi:[0,0,1]
	v_pk_fma_f32 v[40:41], v[34:35], v[18:19], v[48:49] op_sel_hi:[0,1,1] neg_lo:[0,0,1] neg_hi:[0,0,1]
	v_pk_fma_f32 v[42:43], v[34:35], v[12:13], v[50:51] op_sel_hi:[0,1,1] neg_lo:[0,0,1] neg_hi:[0,0,1]
	v_cvt_pk_bf16_f32 v28, v36, v37
	v_cvt_pk_bf16_f32 v29, v38, v39
	v_cvt_pk_bf16_f32 v30, v40, v41
	v_cvt_pk_bf16_f32 v31, v42, v43
	global_store_dwordx4 v[10:11], v[28:31], off
	v_lshlrev_b32_e32 v44, 16, v188
	v_and_b32_e32 v45, 0xffff0000, v188
	v_lshlrev_b32_e32 v46, 16, v189
	v_and_b32_e32 v47, 0xffff0000, v189
; __device__ __forceinline__ unsigned pk2(float lo, float hi) { f32x2 v = {lo, hi}; bf16x2_t b = __builtin_convertvector(v, bf16x2_t); return __builtin_bit_cast(unsigned, b); }
; __device__ __forceinline__ void pool_window(const bf16_t* __restrict__ U  , bf16_t* __restrict__ A3, const int gtid, const int nthr) {
;     ...
;         for (int i = 0; i < 32; ++i) {
;             const int t = t0 + i, s = s0 + i;
;             const u32x4 uu = *(const u32x4*)(U + (size_t)t * LDU + c);
;             float cu[8] = {bflo(uu.x), bfhi(uu.x), bflo(uu.y), bfhi(uu.y), bflo(uu.z), bfhi(uu.z), bflo(uu.w), bfhi(uu.w)};
;             const float rc = 1.0f / (float)((s + 1) < w ? (s + 1) : w);
;             float o[8];
; #pragma unroll
;             for (int e = 0; e < 8; ++e) { sum[e] += cu[e]; o[e] = sum[e] * rc - cu[e]; }
;             u32x4 ww; ww.x = pk2(o[0], o[1]); ww.y = pk2(o[2], o[3]); ww.z = pk2(o[4], o[5]); ww.w = pk2(o[6], o[7]);
;             *(u32x4*)(A3 + (size_t)t * DM + c) = ww;
;             if (s + 1 >= w) { const u32x4 ud = *(const u32x4*)(U + (size_t)(t - w + 1) * LDU + c);
;                 sum[0] -= bflo(ud.x); sum[1] -= bfhi(ud.x); sum[2] -= bflo(ud.y); sum[3] -= bfhi(ud.y); sum[4] -= bflo(ud.z); sum[5] -= bfhi(ud.z); sum[6] -= bflo(ud.w); sum[7] -= bfhi(ud.w); }
;         }
	v_lshlrev_b32_e32 v48, 16, v190
	v_and_b32_e32 v49, 0xffff0000, v190
	v_lshlrev_b32_e32 v50, 16, v191
	v_and_b32_e32 v51, 0xffff0000, v191
	v_pk_add_f32 v[14:15], v[14:15], v[44:45] neg_lo:[0,1] neg_hi:[0,1]
	v_pk_add_f32 v[16:17], v[16:17], v[46:47] neg_lo:[0,1] neg_hi:[0,1]
	v_pk_add_f32 v[18:19], v[18:19], v[48:49] neg_lo:[0,1] neg_hi:[0,1]
	v_pk_add_f32 v[12:13], v[12:13], v[50:51] neg_lo:[0,1] neg_hi:[0,1]
	v_lshl_add_u64 v[10:11], v[10:11], 0, s[26:27]
	v_lshlrev_b32_e32 v44, 16, v222
	v_and_b32_e32 v45, 0xffff0000, v222
	v_lshlrev_b32_e32 v46, 16, v223
	v_and_b32_e32 v47, 0xffff0000, v223
	v_lshlrev_b32_e32 v48, 16, v224
	v_and_b32_e32 v49, 0xffff0000, v224
	v_lshlrev_b32_e32 v50, 16, v225
	v_and_b32_e32 v51, 0xffff0000, v225
	v_pk_add_f32 v[14:15], v[14:15], v[44:45]
	v_pk_add_f32 v[16:17], v[16:17], v[46:47]
	v_pk_add_f32 v[18:19], v[18:19], v[48:49]
	v_pk_add_f32 v[12:13], v[12:13], v[50:51]
	v_pk_fma_f32 v[36:37], v[34:35], v[14:15], v[44:45] op_sel_hi:[0,1,1] neg_lo:[0,0,1] neg_hi:[0,0,1]
	v_pk_fma_f32 v[38:39], v[34:35], v[16:17], v[46:47] op_sel_hi:[0,1,1] neg_lo:[0,0,1] neg_hi:[0,0,1]
	v_pk_fma_f32 v[40:41], v[34:35], v[18:19], v[48:49] op_sel_hi:[0,1,1] neg_lo:[0,0,1] neg_hi:[0,0,1]
	v_pk_fma_f32 v[42:43], v[34:35], v[12:13], v[50:51] op_sel_hi:[0,1,1] neg_lo:[0,0,1] neg_hi:[0,0,1]
	v_cvt_pk_bf16_f32 v28, v36, v37
	v_cvt_pk_bf16_f32 v29, v38, v39
	v_cvt_pk_bf16_f32 v30, v40, v41
	v_cvt_pk_bf16_f32 v31, v42, v43
	global_store_dwordx4 v[10:11], v[28:31], off
	v_lshlrev_b32_e32 v44, 16, v192
	v_and_b32_e32 v45, 0xffff0000, v192
	v_lshlrev_b32_e32 v46, 16, v193
	v_and_b32_e32 v47, 0xffff0000, v193
	v_lshlrev_b32_e32 v48, 16, v194
	v_and_b32_e32 v49, 0xffff0000, v194
	v_lshlrev_b32_e32 v50, 16, v195
	v_and_b32_e32 v51, 0xffff0000, v195
	v_pk_add_f32 v[14:15], v[14:15], v[44:45] neg_lo:[0,1] neg_hi:[0,1]
	v_pk_add_f32 v[16:17], v[16:17], v[46:47] neg_lo:[0,1] neg_hi:[0,1]
	v_pk_add_f32 v[18:19], v[18:19], v[48:49] neg_lo:[0,1] neg_hi:[0,1]
	v_pk_add_f32 v[12:13], v[12:13], v[50:51] neg_lo:[0,1] neg_hi:[0,1]
	v_lshl_add_u64 v[10:11], v[10:11], 0, s[26:27]
	v_lshlrev_b32_e32 v44, 16, v226
	v_and_b32_e32 v45, 0xffff0000, v226
	v_lshlrev_b32_e32 v46, 16, v227
	v_and_b32_e32 v47, 0xffff0000, v227
	v_lshlrev_b32_e32 v48, 16, v228
	v_and_b32_e32 v49, 0xffff0000, v228
	v_lshlrev_b32_e32 v50, 16, v229
	v_and_b32_e32 v51, 0xffff0000, v229
	v_pk_add_f32 v[14:15], v[14:15], v[44:45]
	v_pk_add_f32 v[16:17], v[16:17], v[46:47]
	v_pk_add_f32 v[18:19], v[18:19], v[48:49]
	v_pk_add_f32 v[12:13], v[12:13], v[50:51]
	v_pk_fma_f32 v[36:37], v[34:35], v[14:15], v[44:45] op_sel_hi:[0,1,1] neg_lo:[0,0,1] neg_hi:[0,0,1]
	v_pk_fma_f32 v[38:39], v[34:35], v[16:17], v[46:47] op_sel_hi:[0,1,1] neg_lo:[0,0,1] neg_hi:[0,0,1]
	v_pk_fma_f32 v[40:41], v[34:35], v[18:19], v[48:49] op_sel_hi:[0,1,1] neg_lo:[0,0,1] neg_hi:[0,0,1]
	v_pk_fma_f32 v[42:43], v[34:35], v[12:13], v[50:51] op_sel_hi:[0,1,1] neg_lo:[0,0,1] neg_hi:[0,0,1]
	v_cvt_pk_bf16_f32 v28, v36, v37
	v_cvt_pk_bf16_f32 v29, v38, v39
	v_cvt_pk_bf16_f32 v30, v40, v41
	v_cvt_pk_bf16_f32 v31, v42, v43
	global_store_dwordx4 v[10:11], v[28:31], off
	v_lshlrev_b32_e32 v44, 16, v196
	v_and_b32_e32 v45, 0xffff0000, v196
	v_lshlrev_b32_e32 v46, 16, v197
	v_and_b32_e32 v47, 0xffff0000, v197
	v_lshlrev_b32_e32 v48, 16, v198
	v_and_b32_e32 v49, 0xffff0000, v198
	v_lshlrev_b32_e32 v50, 16, v199
	v_and_b32_e32 v51, 0xffff0000, v199
	v_pk_add_f32 v[14:15], v[14:15], v[44:45] neg_lo:[0,1] neg_hi:[0,1]
	v_pk_add_f32 v[16:17], v[16:17], v[46:47] neg_lo:[0,1] neg_hi:[0,1]
	v_pk_add_f32 v[18:19], v[18:19], v[48:49] neg_lo:[0,1] neg_hi:[0,1]
	v_pk_add_f32 v[12:13], v[12:13], v[50:51] neg_lo:[0,1] neg_hi:[0,1]
	v_lshl_add_u64 v[10:11], v[10:11], 0, s[26:27]
	v_lshlrev_b32_e32 v44, 16, v230
	v_and_b32_e32 v45, 0xffff0000, v230
	v_lshlrev_b32_e32 v46, 16, v231
	v_and_b32_e32 v47, 0xffff0000, v231
	v_lshlrev_b32_e32 v48, 16, v232
	v_and_b32_e32 v49, 0xffff0000, v232
	v_lshlrev_b32_e32 v50, 16, v233
	v_and_b32_e32 v51, 0xffff0000, v233
	v_pk_add_f32 v[14:15], v[14:15], v[44:45]
	v_pk_add_f32 v[16:17], v[16:17], v[46:47]
	v_pk_add_f32 v[18:19], v[18:19], v[48:49]
	v_pk_add_f32 v[12:13], v[12:13], v[50:51]
	v_pk_fma_f32 v[36:37], v[34:35], v[14:15], v[44:45] op_sel_hi:[0,1,1] neg_lo:[0,0,1] neg_hi:[0,0,1]
	v_pk_fma_f32 v[38:39], v[34:35], v[16:17], v[46:47] op_sel_hi:[0,1,1] neg_lo:[0,0,1] neg_hi:[0,0,1]
	v_pk_fma_f32 v[40:41], v[34:35], v[18:19], v[48:49] op_sel_hi:[0,1,1] neg_lo:[0,0,1] neg_hi:[0,0,1]
	v_pk_fma_f32 v[42:43], v[34:35], v[12:13], v[50:51] op_sel_hi:[0,1,1] neg_lo:[0,0,1] neg_hi:[0,0,1]
	v_cvt_pk_bf16_f32 v28, v36, v37
	v_cvt_pk_bf16_f32 v29, v38, v39
	v_cvt_pk_bf16_f32 v30, v40, v41
	v_cvt_pk_bf16_f32 v31, v42, v43
	global_store_dwordx4 v[10:11], v[28:31], off
	v_lshlrev_b32_e32 v44, 16, v200
	v_and_b32_e32 v45, 0xffff0000, v200
	v_lshlrev_b32_e32 v46, 16, v201
	v_and_b32_e32 v47, 0xffff0000, v201
	v_lshlrev_b32_e32 v48, 16, v202
	v_and_b32_e32 v49, 0xffff0000, v202
	v_lshlrev_b32_e32 v50, 16, v203
	v_and_b32_e32 v51, 0xffff0000, v203
	v_pk_add_f32 v[14:15], v[14:15], v[44:45] neg_lo:[0,1] neg_hi:[0,1]
	v_pk_add_f32 v[16:17], v[16:17], v[46:47] neg_lo:[0,1] neg_hi:[0,1]
	v_pk_add_f32 v[18:19], v[18:19], v[48:49] neg_lo:[0,1] neg_hi:[0,1]
	v_pk_add_f32 v[12:13], v[12:13], v[50:51] neg_lo:[0,1] neg_hi:[0,1]
	v_lshl_add_u64 v[10:11], v[10:11], 0, s[26:27]
	v_lshlrev_b32_e32 v44, 16, v234
	v_and_b32_e32 v45, 0xffff0000, v234
	v_lshlrev_b32_e32 v46, 16, v235
	v_and_b32_e32 v47, 0xffff0000, v235
	v_lshlrev_b32_e32 v48, 16, v236
	v_and_b32_e32 v49, 0xffff0000, v236
	v_lshlrev_b32_e32 v50, 16, v237
	v_and_b32_e32 v51, 0xffff0000, v237
; __device__ __forceinline__ unsigned pk2(float lo, float hi) { f32x2 v = {lo, hi}; bf16x2_t b = __builtin_convertvector(v, bf16x2_t); return __builtin_bit_cast(unsigned, b); }
; __device__ __forceinline__ void pool_window(const bf16_t* __restrict__ U  , bf16_t* __restrict__ A3, const int gtid, const int nthr) {
;     ...
;         for (int i = 0; i < 32; ++i) {
;             const int t = t0 + i, s = s0 + i;
;             const u32x4 uu = *(const u32x4*)(U + (size_t)t * LDU + c);
;             float cu[8] = {bflo(uu.x), bfhi(uu.x), bflo(uu.y), bfhi(uu.y), bflo(uu.z), bfhi(uu.z), bflo(uu.w), bfhi(uu.w)};
;             const float rc = 1.0f / (float)((s + 1) < w ? (s + 1) : w);
;             float o[8];
; #pragma unroll
;             for (int e = 0; e < 8; ++e) { sum[e] += cu[e]; o[e] = sum[e] * rc - cu[e]; }
;             u32x4 ww; ww.x = pk2(o[0], o[1]); ww.y = pk2(o[2], o[3]); ww.z = pk2(o[4], o[5]); ww.w = pk2(o[6], o[7]);
;             *(u32x4*)(A3 + (size_t)t * DM + c) = ww;
;             if (s + 1 >= w) { const u32x4 ud = *(const u32x4*)(U + (size_t)(t - w + 1) * LDU + c);
;                 sum[0] -= bflo(ud.x); sum[1] -= bfhi(ud.x); sum[2] -= bflo(ud.y); sum[3] -= bfhi(ud.y); sum[4] -= bflo(ud.z); sum[5] -= bfhi(ud.z); sum[6] -= bflo(ud.w); sum[7] -= bfhi(ud.w); }
;         }
	v_pk_add_f32 v[14:15], v[14:15], v[44:45]
	v_pk_add_f32 v[16:17], v[16:17], v[46:47]
	v_pk_add_f32 v[18:19], v[18:19], v[48:49]
	v_pk_add_f32 v[12:13], v[12:13], v[50:51]
	v_pk_fma_f32 v[36:37], v[34:35], v[14:15], v[44:45] op_sel_hi:[0,1,1] neg_lo:[0,0,1] neg_hi:[0,0,1]
	v_pk_fma_f32 v[38:39], v[34:35], v[16:17], v[46:47] op_sel_hi:[0,1,1] neg_lo:[0,0,1] neg_hi:[0,0,1]
	v_pk_fma_f32 v[40:41], v[34:35], v[18:19], v[48:49] op_sel_hi:[0,1,1] neg_lo:[0,0,1] neg_hi:[0,0,1]
	v_pk_fma_f32 v[42:43], v[34:35], v[12:13], v[50:51] op_sel_hi:[0,1,1] neg_lo:[0,0,1] neg_hi:[0,0,1]
	v_cvt_pk_bf16_f32 v28, v36, v37
	v_cvt_pk_bf16_f32 v29, v38, v39
	v_cvt_pk_bf16_f32 v30, v40, v41
	v_cvt_pk_bf16_f32 v31, v42, v43
	global_store_dwordx4 v[10:11], v[28:31], off
	v_lshlrev_b32_e32 v44, 16, v204
	v_and_b32_e32 v45, 0xffff0000, v204
	v_lshlrev_b32_e32 v46, 16, v205
	v_and_b32_e32 v47, 0xffff0000, v205
	v_lshlrev_b32_e32 v48, 16, v206
	v_and_b32_e32 v49, 0xffff0000, v206
	v_lshlrev_b32_e32 v50, 16, v207
	v_and_b32_e32 v51, 0xffff0000, v207
	v_pk_add_f32 v[14:15], v[14:15], v[44:45] neg_lo:[0,1] neg_hi:[0,1]
	v_pk_add_f32 v[16:17], v[16:17], v[46:47] neg_lo:[0,1] neg_hi:[0,1]
	v_pk_add_f32 v[18:19], v[18:19], v[48:49] neg_lo:[0,1] neg_hi:[0,1]
	v_pk_add_f32 v[12:13], v[12:13], v[50:51] neg_lo:[0,1] neg_hi:[0,1]
	v_lshl_add_u64 v[10:11], v[10:11], 0, s[26:27]
	v_lshlrev_b32_e32 v44, 16, v238
	v_and_b32_e32 v45, 0xffff0000, v238
	v_lshlrev_b32_e32 v46, 16, v239
	v_and_b32_e32 v47, 0xffff0000, v239
	v_lshlrev_b32_e32 v48, 16, v240
	v_and_b32_e32 v49, 0xffff0000, v240
	v_lshlrev_b32_e32 v50, 16, v241
	v_and_b32_e32 v51, 0xffff0000, v241
	v_pk_add_f32 v[14:15], v[14:15], v[44:45]
	v_pk_add_f32 v[16:17], v[16:17], v[46:47]
	v_pk_add_f32 v[18:19], v[18:19], v[48:49]
	v_pk_add_f32 v[12:13], v[12:13], v[50:51]
	v_pk_fma_f32 v[36:37], v[34:35], v[14:15], v[44:45] op_sel_hi:[0,1,1] neg_lo:[0,0,1] neg_hi:[0,0,1]
	v_pk_fma_f32 v[38:39], v[34:35], v[16:17], v[46:47] op_sel_hi:[0,1,1] neg_lo:[0,0,1] neg_hi:[0,0,1]
	v_pk_fma_f32 v[40:41], v[34:35], v[18:19], v[48:49] op_sel_hi:[0,1,1] neg_lo:[0,0,1] neg_hi:[0,0,1]
	v_pk_fma_f32 v[42:43], v[34:35], v[12:13], v[50:51] op_sel_hi:[0,1,1] neg_lo:[0,0,1] neg_hi:[0,0,1]
	v_cvt_pk_bf16_f32 v28, v36, v37
	v_cvt_pk_bf16_f32 v29, v38, v39
	v_cvt_pk_bf16_f32 v30, v40, v41
	v_cvt_pk_bf16_f32 v31, v42, v43
	global_store_dwordx4 v[10:11], v[28:31], off
	v_lshlrev_b32_e32 v44, 16, v208
	v_and_b32_e32 v45, 0xffff0000, v208
	v_lshlrev_b32_e32 v46, 16, v209
	v_and_b32_e32 v47, 0xffff0000, v209
	v_lshlrev_b32_e32 v48, 16, v210
	v_and_b32_e32 v49, 0xffff0000, v210
	v_lshlrev_b32_e32 v50, 16, v211
	v_and_b32_e32 v51, 0xffff0000, v211
	v_pk_add_f32 v[14:15], v[14:15], v[44:45] neg_lo:[0,1] neg_hi:[0,1]
	v_pk_add_f32 v[16:17], v[16:17], v[46:47] neg_lo:[0,1] neg_hi:[0,1]
	v_pk_add_f32 v[18:19], v[18:19], v[48:49] neg_lo:[0,1] neg_hi:[0,1]
	v_pk_add_f32 v[12:13], v[12:13], v[50:51] neg_lo:[0,1] neg_hi:[0,1]
	v_lshl_add_u64 v[10:11], v[10:11], 0, s[26:27]
	v_lshlrev_b32_e32 v44, 16, v242
	v_and_b32_e32 v45, 0xffff0000, v242
	v_lshlrev_b32_e32 v46, 16, v243
	v_and_b32_e32 v47, 0xffff0000, v243
	v_lshlrev_b32_e32 v48, 16, v244
	v_and_b32_e32 v49, 0xffff0000, v244
	v_lshlrev_b32_e32 v50, 16, v245
	v_and_b32_e32 v51, 0xffff0000, v245
	v_pk_add_f32 v[14:15], v[14:15], v[44:45]
	v_pk_add_f32 v[16:17], v[16:17], v[46:47]
	v_pk_add_f32 v[18:19], v[18:19], v[48:49]
	v_pk_add_f32 v[12:13], v[12:13], v[50:51]
	v_pk_fma_f32 v[36:37], v[34:35], v[14:15], v[44:45] op_sel_hi:[0,1,1] neg_lo:[0,0,1] neg_hi:[0,0,1]
	v_pk_fma_f32 v[38:39], v[34:35], v[16:17], v[46:47] op_sel_hi:[0,1,1] neg_lo:[0,0,1] neg_hi:[0,0,1]
	v_pk_fma_f32 v[40:41], v[34:35], v[18:19], v[48:49] op_sel_hi:[0,1,1] neg_lo:[0,0,1] neg_hi:[0,0,1]
	v_pk_fma_f32 v[42:43], v[34:35], v[12:13], v[50:51] op_sel_hi:[0,1,1] neg_lo:[0,0,1] neg_hi:[0,0,1]
	v_cvt_pk_bf16_f32 v28, v36, v37
	v_cvt_pk_bf16_f32 v29, v38, v39
	v_cvt_pk_bf16_f32 v30, v40, v41
; __device__ __forceinline__ unsigned pk2(float lo, float hi) { f32x2 v = {lo, hi}; bf16x2_t b = __builtin_convertvector(v, bf16x2_t); return __builtin_bit_cast(unsigned, b); }
; __device__ __forceinline__ void pool_window(const bf16_t* __restrict__ U  , bf16_t* __restrict__ A3, const int gtid, const int nthr) {
;     ...
;         for (int i = 0; i < 32; ++i) {
;             const int t = t0 + i, s = s0 + i;
;             const u32x4 uu = *(const u32x4*)(U + (size_t)t * LDU + c);
;             float cu[8] = {bflo(uu.x), bfhi(uu.x), bflo(uu.y), bfhi(uu.y), bflo(uu.z), bfhi(uu.z), bflo(uu.w), bfhi(uu.w)};
;             const float rc = 1.0f / (float)((s + 1) < w ? (s + 1) : w);
;             float o[8];
; #pragma unroll
;             for (int e = 0; e < 8; ++e) { sum[e] += cu[e]; o[e] = sum[e] * rc - cu[e]; }
;             u32x4 ww; ww.x = pk2(o[0], o[1]); ww.y = pk2(o[2], o[3]); ww.z = pk2(o[4], o[5]); ww.w = pk2(o[6], o[7]);
;             *(u32x4*)(A3 + (size_t)t * DM + c) = ww;
;             if (s + 1 >= w) { const u32x4 ud = *(const u32x4*)(U + (size_t)(t - w + 1) * LDU + c);
;                 sum[0] -= bflo(ud.x); sum[1] -= bfhi(ud.x); sum[2] -= bflo(ud.y); sum[3] -= bfhi(ud.y); sum[4] -= bflo(ud.z); sum[5] -= bfhi(ud.z); sum[6] -= bflo(ud.w); sum[7] -= bfhi(ud.w); }
;         }
	v_cvt_pk_bf16_f32 v31, v42, v43
	global_store_dwordx4 v[10:11], v[28:31], off
	v_lshlrev_b32_e32 v44, 16, v214
	v_and_b32_e32 v45, 0xffff0000, v214
	v_lshlrev_b32_e32 v46, 16, v215
	v_and_b32_e32 v47, 0xffff0000, v215
	v_lshlrev_b32_e32 v48, 16, v216
	v_and_b32_e32 v49, 0xffff0000, v216
	v_lshlrev_b32_e32 v50, 16, v217
	v_and_b32_e32 v51, 0xffff0000, v217
	v_pk_add_f32 v[14:15], v[14:15], v[44:45] neg_lo:[0,1] neg_hi:[0,1]
	v_pk_add_f32 v[16:17], v[16:17], v[46:47] neg_lo:[0,1] neg_hi:[0,1]
	v_pk_add_f32 v[18:19], v[18:19], v[48:49] neg_lo:[0,1] neg_hi:[0,1]
	v_pk_add_f32 v[12:13], v[12:13], v[50:51] neg_lo:[0,1] neg_hi:[0,1]
	v_lshl_add_u64 v[10:11], v[10:11], 0, s[26:27]
	v_lshlrev_b32_e32 v44, 16, v246
	v_and_b32_e32 v45, 0xffff0000, v246
	v_lshlrev_b32_e32 v46, 16, v247
	v_and_b32_e32 v47, 0xffff0000, v247
	v_lshlrev_b32_e32 v48, 16, v248
	v_and_b32_e32 v49, 0xffff0000, v248
	v_lshlrev_b32_e32 v50, 16, v249
	v_and_b32_e32 v51, 0xffff0000, v249
	v_pk_add_f32 v[14:15], v[14:15], v[44:45]
	v_pk_add_f32 v[16:17], v[16:17], v[46:47]
	v_pk_add_f32 v[18:19], v[18:19], v[48:49]
	v_pk_add_f32 v[12:13], v[12:13], v[50:51]
	v_pk_fma_f32 v[36:37], v[34:35], v[14:15], v[44:45] op_sel_hi:[0,1,1] neg_lo:[0,0,1] neg_hi:[0,0,1]
	v_pk_fma_f32 v[38:39], v[34:35], v[16:17], v[46:47] op_sel_hi:[0,1,1] neg_lo:[0,0,1] neg_hi:[0,0,1]
	v_pk_fma_f32 v[40:41], v[34:35], v[18:19], v[48:49] op_sel_hi:[0,1,1] neg_lo:[0,0,1] neg_hi:[0,0,1]
	v_pk_fma_f32 v[42:43], v[34:35], v[12:13], v[50:51] op_sel_hi:[0,1,1] neg_lo:[0,0,1] neg_hi:[0,0,1]
	v_cvt_pk_bf16_f32 v28, v36, v37
	v_cvt_pk_bf16_f32 v29, v38, v39
	v_cvt_pk_bf16_f32 v30, v40, v41
	v_cvt_pk_bf16_f32 v31, v42, v43
	global_store_dwordx4 v[10:11], v[28:31], off
	v_lshlrev_b32_e32 v44, 16, v218
	v_and_b32_e32 v45, 0xffff0000, v218
	v_lshlrev_b32_e32 v46, 16, v219
	v_and_b32_e32 v47, 0xffff0000, v219
	v_lshlrev_b32_e32 v48, 16, v220
	v_and_b32_e32 v49, 0xffff0000, v220
	v_lshlrev_b32_e32 v50, 16, v221
	v_and_b32_e32 v51, 0xffff0000, v221
	v_pk_add_f32 v[14:15], v[14:15], v[44:45] neg_lo:[0,1] neg_hi:[0,1]
	v_pk_add_f32 v[16:17], v[16:17], v[46:47] neg_lo:[0,1] neg_hi:[0,1]
	v_pk_add_f32 v[18:19], v[18:19], v[48:49] neg_lo:[0,1] neg_hi:[0,1]
	v_pk_add_f32 v[12:13], v[12:13], v[50:51] neg_lo:[0,1] neg_hi:[0,1]
	v_lshl_add_u64 v[10:11], v[10:11], 0, s[26:27]
	v_lshlrev_b32_e32 v44, 16, v250
	v_and_b32_e32 v45, 0xffff0000, v250
	v_lshlrev_b32_e32 v46, 16, v251
	v_and_b32_e32 v47, 0xffff0000, v251
	v_lshlrev_b32_e32 v48, 16, v252
	v_and_b32_e32 v49, 0xffff0000, v252
	v_lshlrev_b32_e32 v50, 16, v253
	v_and_b32_e32 v51, 0xffff0000, v253
	v_pk_add_f32 v[14:15], v[14:15], v[44:45]
	v_pk_add_f32 v[16:17], v[16:17], v[46:47]
	v_pk_add_f32 v[18:19], v[18:19], v[48:49]
	v_pk_add_f32 v[12:13], v[12:13], v[50:51]
	v_pk_fma_f32 v[36:37], v[34:35], v[14:15], v[44:45] op_sel_hi:[0,1,1] neg_lo:[0,0,1] neg_hi:[0,0,1]
	v_pk_fma_f32 v[38:39], v[34:35], v[16:17], v[46:47] op_sel_hi:[0,1,1] neg_lo:[0,0,1] neg_hi:[0,0,1]
	v_pk_fma_f32 v[40:41], v[34:35], v[18:19], v[48:49] op_sel_hi:[0,1,1] neg_lo:[0,0,1] neg_hi:[0,0,1]
	v_pk_fma_f32 v[42:43], v[34:35], v[12:13], v[50:51] op_sel_hi:[0,1,1] neg_lo:[0,0,1] neg_hi:[0,0,1]
	v_cvt_pk_bf16_f32 v28, v36, v37
	v_cvt_pk_bf16_f32 v29, v38, v39
	v_cvt_pk_bf16_f32 v30, v40, v41
	v_cvt_pk_bf16_f32 v31, v42, v43
	global_store_dwordx4 v[10:11], v[28:31], off
	v_lshlrev_b32_e32 v44, 16, v222
	v_and_b32_e32 v45, 0xffff0000, v222
	v_lshlrev_b32_e32 v46, 16, v223
	v_and_b32_e32 v47, 0xffff0000, v223
	v_lshlrev_b32_e32 v48, 16, v224
	v_and_b32_e32 v49, 0xffff0000, v224
	v_lshlrev_b32_e32 v50, 16, v225
	v_and_b32_e32 v51, 0xffff0000, v225
	v_pk_add_f32 v[14:15], v[14:15], v[44:45] neg_lo:[0,1] neg_hi:[0,1]
	v_pk_add_f32 v[16:17], v[16:17], v[46:47] neg_lo:[0,1] neg_hi:[0,1]
	v_pk_add_f32 v[18:19], v[18:19], v[48:49] neg_lo:[0,1] neg_hi:[0,1]
	v_pk_add_f32 v[12:13], v[12:13], v[50:51] neg_lo:[0,1] neg_hi:[0,1]
	s_branch .LBB0_1331
